# t38 + GEMM MFMA segments start right at the barrier: s_setprio toggles and the redundant post-barrier lgkmcnt(0) moved into the load segments (pure reorder, same bytes)
# speedup vs baseline: 1.0052x; 1.0052x over previous
; #define PG8_STAGE(bufoff, gbase, voff) do { _Pragma("unroll") for (int _i = 0; _i < 2; ++_i) \
;         __builtin_amdgcn_global_load_lds((const unsigned*)((const char*)(gbase) + (voff)[_i]), (PG8_LAS unsigned*)(lds + (bufoff) + ldsw + _i * 8192), 16, 0, 0); } while (0)
; #define PG8_LDA(dst, b, h) do { _Pragma("unroll") for (int m = 0; m < 4; ++m) _Pragma("unroll") for (int k = 0; k < 2; ++k) dst[m][k] = *(const PG8_LAS bf16x8*)(lds + PG8_SA(b, h) + aoff + m * 2048 + k * 1024); } while (0)
; #define PG8_LDB(dst, b, h) do { _Pragma("unroll") for (int n = 0; n < 2; ++n) _Pragma("unroll") for (int k = 0; k < 2; ++k) dst[n][k] = *(const PG8_LAS bf16x8*)(lds + PG8_SB(b, h) + boff + n * 2048 + k * 1024); } while (0)
; #define PG8_MMA(ai, bj, At, Bt) do { __builtin_amdgcn_s_setprio(1); _Pragma("unroll") for (int m = 0; m < 4; ++m) _Pragma("unroll") for (int n = 0; n < 2; ++n) _Pragma("unroll") for (int k = 0; k < 2; ++k) \
;         acc[ai][bj][m][n] = __builtin_amdgcn_mfma_f32_16x16x32_bf16(Bt[n][k], At[m][k], acc[ai][bj][m][n], 0, 0, 0); __builtin_amdgcn_s_setprio(0); } while (0)
; #define PG8_BAR __builtin_amdgcn_s_barrier()
; template <class Epi, class Sched, bool ALIGN_EPI = false, bool SP2 = false>
; __device__ __forceinline__ void gemm_phase(PG8_LAS unsigned char* lds, const Gemm g, const Sched& S, const Epi& E) {
;     ...
;         const char* nA = has_next ? (const char*)g.A + (size_t)nxt.pm * tstep + (size_t)nxt.ko * 2 : cA; const char* nB = has_next ? (const char*)g.Bt + (size_t)nxt.pn * tstep + (size_t)nxt.ko * 2 : cB;
;         for (int t = 0; t < nt; t += 2) {
;             const bool last = (t == nt - 2);
;             const char* a1 = cA + (size_t)(t + 1) * kstep;
;             const char* a2 = last ? nA : cA + (size_t)(t + 2) * kstep; const char* b2 = last ? nB : cB + (size_t)(t + 2) * kstep;
;             const char* a3 = a2 + kstep; const char* b3 = b2 + kstep;
;             if (last && has_next) S.a_ready(nxt);
;             if constexpr (SP2) {
;             PG8_LDB(B0, 0, 0); PG8_LDB(B1, 0, 1); PG8_SCHED; PG8_LDA(At, 0, 0); PG8_STAGE(PG8_SA(1, 1), a1 + hstep, voffA);
;             PG8_WAIT_V(8); PG8_WAIT_L(0); PG8_BAR; PG8_MMA(0, 0, At, B0); PG8_MMA(0, 1, At, B1); PG8_BAR; PG8_SCHED;
;             PG8_LDA(At, 0, 1); PG8_STAGE(PG8_SB(0, 0), b2, voffB); PG8_STAGE(PG8_SB(0, 1), b2 + hstep, voffB); PG8_STAGE(PG8_SA(0, 0), a2, voffA);
.LBB0_239:
	s_add_u32 s48, s12, 0xfff80080
	s_addc_u32 s49, s13, -1
	s_cmp_eq_u32 s47, 28
	s_cselect_b32 s51, s1, s49
	s_cselect_b32 s50, s2, s48
	s_cselect_b32 s49, s3, s37
	s_cselect_b32 s48, s15, s35
	s_add_i32 s65, 0, 0x10000
	v_add_u32_e32 v0, s65, v185
	s_add_i32 s68, 0, 0x14000
	ds_read_b128 v[132:135], v0
	ds_read_b128 v[136:139], v0 offset:1024
	ds_read_b128 v[140:143], v0 offset:2048
	ds_read_b128 v[144:147], v0 offset:3072
	v_add_u32_e32 v0, s68, v185
	ds_read_b128 v[148:151], v0
	ds_read_b128 v[152:155], v0 offset:1024
	ds_read_b128 v[172:175], v0 offset:2048
	ds_read_b128 v[176:179], v0 offset:3072
	v_lshl_add_u64 v[228:229], s[12:13], 0, v[168:169]
	s_add_i32 m0, s53, 0xc000
	ds_read_b128 v[180:183], v190
	ds_read_b128 v[192:195], v190 offset:1024
	ds_read_b128 v[196:199], v190 offset:2048
	ds_read_b128 v[200:203], v190 offset:3072
	ds_read_b128 v[204:207], v190 offset:4096
	ds_read_b128 v[208:211], v190 offset:5120
	ds_read_b128 v[220:223], v190 offset:6144
	ds_read_b128 v[224:227], v190 offset:7168
	global_load_lds_dwordx4 v[228:229], off
	v_lshl_add_u64 v[228:229], s[12:13], 0, v[170:171]
	s_add_i32 m0, s53, 0xe000
	s_nop 0
	global_load_lds_dwordx4 v[228:229], off
	s_setprio 1
	s_waitcnt vmcnt(8)
	s_waitcnt lgkmcnt(0)
	s_barrier
	v_mfma_f32_16x16x32_bf16 v[128:131], v[132:135], v[180:183], v[128:131]
	v_mfma_f32_16x16x32_bf16 v[124:127], v[140:143], v[180:183], v[124:127]
	v_mfma_f32_16x16x32_bf16 v[112:115], v[132:135], v[196:199], v[112:115]
	v_mfma_f32_16x16x32_bf16 v[108:111], v[140:143], v[196:199], v[108:111]
	v_mfma_f32_16x16x32_bf16 v[96:99], v[132:135], v[204:207], v[96:99]
	v_mfma_f32_16x16x32_bf16 v[92:95], v[140:143], v[204:207], v[92:95]
	v_mfma_f32_16x16x32_bf16 v[80:83], v[132:135], v[220:223], v[80:83]
	v_mfma_f32_16x16x32_bf16 v[76:79], v[140:143], v[220:223], v[76:79]
	v_mfma_f32_16x16x32_bf16 v[128:131], v[136:139], v[192:195], v[128:131]
	v_mfma_f32_16x16x32_bf16 v[124:127], v[144:147], v[192:195], v[124:127]
	v_mfma_f32_16x16x32_bf16 v[112:115], v[136:139], v[200:203], v[112:115]
	v_mfma_f32_16x16x32_bf16 v[108:111], v[144:147], v[200:203], v[108:111]
	v_mfma_f32_16x16x32_bf16 v[96:99], v[136:139], v[208:211], v[96:99]
	v_mfma_f32_16x16x32_bf16 v[92:95], v[144:147], v[208:211], v[92:95]
	v_mfma_f32_16x16x32_bf16 v[80:83], v[136:139], v[224:227], v[80:83]
	v_mfma_f32_16x16x32_bf16 v[76:79], v[144:147], v[224:227], v[76:79]
	v_mfma_f32_16x16x32_bf16 v[120:123], v[148:151], v[180:183], v[120:123]
	v_mfma_f32_16x16x32_bf16 v[116:119], v[172:175], v[180:183], v[116:119]
	v_mfma_f32_16x16x32_bf16 v[104:107], v[148:151], v[196:199], v[104:107]
	v_mfma_f32_16x16x32_bf16 v[100:103], v[172:175], v[196:199], v[100:103]
	v_mfma_f32_16x16x32_bf16 v[88:91], v[148:151], v[204:207], v[88:91]
	v_mfma_f32_16x16x32_bf16 v[84:87], v[172:175], v[204:207], v[84:87]
	v_mfma_f32_16x16x32_bf16 v[72:75], v[148:151], v[220:223], v[72:75]
	v_mfma_f32_16x16x32_bf16 v[68:71], v[172:175], v[220:223], v[68:71]
	v_mfma_f32_16x16x32_bf16 v[120:123], v[152:155], v[192:195], v[120:123]
	v_mfma_f32_16x16x32_bf16 v[116:119], v[176:179], v[192:195], v[116:119]
	v_mfma_f32_16x16x32_bf16 v[104:107], v[152:155], v[200:203], v[104:107]
	v_mfma_f32_16x16x32_bf16 v[100:103], v[176:179], v[200:203], v[100:103]
	v_mfma_f32_16x16x32_bf16 v[88:91], v[152:155], v[208:211], v[88:91]
	v_mfma_f32_16x16x32_bf16 v[84:87], v[176:179], v[208:211], v[84:87]
	v_mfma_f32_16x16x32_bf16 v[72:75], v[152:155], v[224:227], v[72:75]
	v_mfma_f32_16x16x32_bf16 v[68:71], v[176:179], v[224:227], v[68:71]
	s_barrier
	s_setprio 0
	s_setprio 1
	s_setprio 0
	s_waitcnt lgkmcnt(0)
	s_add_i32 s65, s65, s52
	v_lshl_add_u64 v[228:229], s[48:49], 0, v[158:159]
	s_mov_b32 m0, s65
	ds_read_b128 v[180:183], v190 offset:16384
	ds_read_b128 v[192:195], v190 offset:17408
	ds_read_b128 v[196:199], v190 offset:18432
	ds_read_b128 v[200:203], v190 offset:19456
	ds_read_b128 v[204:207], v190 offset:20480
	ds_read_b128 v[208:211], v190 offset:21504
	ds_read_b128 v[220:223], v190 offset:22528
	ds_read_b128 v[224:227], v190 offset:23552
	global_load_lds_dwordx4 v[228:229], off
	s_add_i32 m0, s65, 0x2000
	s_add_u32 s66, s48, 0x80000
	v_lshl_add_u64 v[230:231], s[48:49], 0, v[162:163]
	s_addc_u32 s67, s49, 0
	s_add_i32 s65, s68, s52
	global_load_lds_dwordx4 v[230:231], off
	v_lshl_add_u64 v[232:233], s[66:67], 0, v[158:159]
	s_mov_b32 m0, s65
	v_lshl_add_u64 v[234:235], s[50:51], 0, v[160:161]
	global_load_lds_dwordx4 v[232:233], off
	v_lshl_add_u64 v[232:233], s[66:67], 0, v[162:163]
	s_add_i32 m0, s65, 0x2000
	s_nop 0
	global_load_lds_dwordx4 v[232:233], off
	v_lshl_add_u64 v[232:233], s[50:51], 0, v[156:157]
	s_mov_b32 m0, s53
	s_nop 0
	global_load_lds_dwordx4 v[232:233], off
	s_mov_b32 m0, s54
	s_nop 0
	global_load_lds_dwordx4 v[234:235], off
	s_setprio 1
	s_waitcnt vmcnt(8)
	s_waitcnt lgkmcnt(0)
	s_barrier
; #define PG8_STAGE(bufoff, gbase, voff) do { _Pragma("unroll") for (int _i = 0; _i < 2; ++_i) \
;         __builtin_amdgcn_global_load_lds((const unsigned*)((const char*)(gbase) + (voff)[_i]), (PG8_LAS unsigned*)(lds + (bufoff) + ldsw + _i * 8192), 16, 0, 0); } while (0)
; #define PG8_LDA(dst, b, h) do { _Pragma("unroll") for (int m = 0; m < 4; ++m) _Pragma("unroll") for (int k = 0; k < 2; ++k) dst[m][k] = *(const PG8_LAS bf16x8*)(lds + PG8_SA(b, h) + aoff + m * 2048 + k * 1024); } while (0)
; #define PG8_LDB(dst, b, h) do { _Pragma("unroll") for (int n = 0; n < 2; ++n) _Pragma("unroll") for (int k = 0; k < 2; ++k) dst[n][k] = *(const PG8_LAS bf16x8*)(lds + PG8_SB(b, h) + boff + n * 2048 + k * 1024); } while (0)
; #define PG8_MMA(ai, bj, At, Bt) do { __builtin_amdgcn_s_setprio(1); _Pragma("unroll") for (int m = 0; m < 4; ++m) _Pragma("unroll") for (int n = 0; n < 2; ++n) _Pragma("unroll") for (int k = 0; k < 2; ++k) \
;         acc[ai][bj][m][n] = __builtin_amdgcn_mfma_f32_16x16x32_bf16(Bt[n][k], At[m][k], acc[ai][bj][m][n], 0, 0, 0); __builtin_amdgcn_s_setprio(0); } while (0)
; #define PG8_WAIT_V(n) asm volatile("s_waitcnt vmcnt(" #n ")" ::: "memory")
; #define PG8_WAIT_L(n) asm volatile("s_waitcnt lgkmcnt(" #n ")" ::: "memory")
; #define PG8_BAR __builtin_amdgcn_s_barrier()
; #define PG8_SCHED __builtin_amdgcn_sched_barrier(0)
; template <class Epi, class Sched, bool ALIGN_EPI = false, bool SP2 = false>
; __device__ __forceinline__ void gemm_phase(PG8_LAS unsigned char* lds, const Gemm g, const Sched& S, const Epi& E) {
;     ...
;             PG8_WAIT_V(8); PG8_WAIT_L(0); PG8_BAR; PG8_MMA(1, 0, At, B0); PG8_MMA(1, 1, At, B1); PG8_BAR; PG8_SCHED;
;             PG8_LDB(B0, 1, 0); PG8_LDB(B1, 1, 1); PG8_SCHED; PG8_LDA(At, 1, 0); PG8_STAGE(PG8_SA(0, 1), a2 + hstep, voffA);
;             PG8_WAIT_V(8); PG8_WAIT_L(0); PG8_BAR; PG8_MMA(0, 0, At, B0); PG8_MMA(0, 1, At, B1); PG8_BAR; PG8_SCHED;
	v_mfma_f32_16x16x32_bf16 v[62:65], v[132:135], v[180:183], v[62:65]
	v_mfma_f32_16x16x32_bf16 v[58:61], v[140:143], v[180:183], v[58:61]
	v_mfma_f32_16x16x32_bf16 v[46:49], v[132:135], v[196:199], v[46:49]
	v_mfma_f32_16x16x32_bf16 v[42:45], v[140:143], v[196:199], v[42:45]
	v_mfma_f32_16x16x32_bf16 v[30:33], v[132:135], v[204:207], v[30:33]
	v_mfma_f32_16x16x32_bf16 v[26:29], v[140:143], v[204:207], v[26:29]
	v_mfma_f32_16x16x32_bf16 v[14:17], v[132:135], v[220:223], v[14:17]
	v_mfma_f32_16x16x32_bf16 v[10:13], v[140:143], v[220:223], v[10:13]
	v_mfma_f32_16x16x32_bf16 v[62:65], v[136:139], v[192:195], v[62:65]
	v_mfma_f32_16x16x32_bf16 v[58:61], v[144:147], v[192:195], v[58:61]
	v_mfma_f32_16x16x32_bf16 v[46:49], v[136:139], v[200:203], v[46:49]
	v_mfma_f32_16x16x32_bf16 v[42:45], v[144:147], v[200:203], v[42:45]
	v_mfma_f32_16x16x32_bf16 v[30:33], v[136:139], v[208:211], v[30:33]
	v_mfma_f32_16x16x32_bf16 v[26:29], v[144:147], v[208:211], v[26:29]
	v_mfma_f32_16x16x32_bf16 v[14:17], v[136:139], v[224:227], v[14:17]
	v_mfma_f32_16x16x32_bf16 v[10:13], v[144:147], v[224:227], v[10:13]
	v_mfma_f32_16x16x32_bf16 v[54:57], v[148:151], v[180:183], v[54:57]
	v_mfma_f32_16x16x32_bf16 v[50:53], v[172:175], v[180:183], v[50:53]
	v_mfma_f32_16x16x32_bf16 v[38:41], v[148:151], v[196:199], v[38:41]
	v_mfma_f32_16x16x32_bf16 v[34:37], v[172:175], v[196:199], v[34:37]
	v_mfma_f32_16x16x32_bf16 v[22:25], v[148:151], v[204:207], v[22:25]
	v_mfma_f32_16x16x32_bf16 v[18:21], v[172:175], v[204:207], v[18:21]
	v_mfma_f32_16x16x32_bf16 v[6:9], v[148:151], v[220:223], v[6:9]
	v_mfma_f32_16x16x32_bf16 v[2:5], v[172:175], v[220:223], v[2:5]
	v_mfma_f32_16x16x32_bf16 v[54:57], v[152:155], v[192:195], v[54:57]
	v_mfma_f32_16x16x32_bf16 v[50:53], v[176:179], v[192:195], v[50:53]
	v_mfma_f32_16x16x32_bf16 v[38:41], v[152:155], v[200:203], v[38:41]
	v_mfma_f32_16x16x32_bf16 v[34:37], v[176:179], v[200:203], v[34:37]
	v_mfma_f32_16x16x32_bf16 v[22:25], v[152:155], v[208:211], v[22:25]
	v_mfma_f32_16x16x32_bf16 v[18:21], v[176:179], v[208:211], v[18:21]
	v_mfma_f32_16x16x32_bf16 v[6:9], v[152:155], v[224:227], v[6:9]
	v_mfma_f32_16x16x32_bf16 v[2:5], v[176:179], v[224:227], v[2:5]
	s_barrier
	s_setprio 0
	s_setprio 1
	s_setprio 0
	s_waitcnt lgkmcnt(0)
	s_add_i32 s65, 0, 0x18000
	v_add_u32_e32 v0, s65, v185
	s_add_i32 s66, 0, 0x1c000
	ds_read_b128 v[132:135], v0
	ds_read_b128 v[136:139], v0 offset:1024
	ds_read_b128 v[140:143], v0 offset:2048
	ds_read_b128 v[144:147], v0 offset:3072
	v_add_u32_e32 v0, s66, v185
	ds_read_b128 v[148:151], v0
	ds_read_b128 v[152:155], v0 offset:1024
	ds_read_b128 v[172:175], v0 offset:2048
	ds_read_b128 v[176:179], v0 offset:3072
	s_add_u32 s50, s50, 0x80000
	s_addc_u32 s51, s51, 0
	s_mov_b32 m0, s55
	v_lshl_add_u64 v[246:247], s[50:51], 0, v[156:157]
	ds_read_b128 v[180:183], v190 offset:32768
	ds_read_b128 v[192:195], v190 offset:33792
	ds_read_b128 v[196:199], v190 offset:34816
	ds_read_b128 v[200:203], v190 offset:35840
	ds_read_b128 v[204:207], v190 offset:36864
	ds_read_b128 v[208:211], v190 offset:37888
	ds_read_b128 v[220:223], v190 offset:38912
	ds_read_b128 v[224:227], v190 offset:39936
	global_load_lds_dwordx4 v[246:247], off
	v_lshl_add_u64 v[246:247], s[50:51], 0, v[160:161]
	s_mov_b32 m0, s56
	s_nop 0
	global_load_lds_dwordx4 v[246:247], off
	s_setprio 1
	s_waitcnt vmcnt(8)
	s_waitcnt lgkmcnt(0)
	s_barrier
	v_mfma_f32_16x16x32_bf16 v[128:131], v[132:135], v[180:183], v[128:131]
	v_mfma_f32_16x16x32_bf16 v[124:127], v[140:143], v[180:183], v[124:127]
	v_mfma_f32_16x16x32_bf16 v[112:115], v[132:135], v[196:199], v[112:115]
	v_mfma_f32_16x16x32_bf16 v[108:111], v[140:143], v[196:199], v[108:111]
	v_mfma_f32_16x16x32_bf16 v[96:99], v[132:135], v[204:207], v[96:99]
	v_mfma_f32_16x16x32_bf16 v[92:95], v[140:143], v[204:207], v[92:95]
	v_mfma_f32_16x16x32_bf16 v[80:83], v[132:135], v[220:223], v[80:83]
	v_mfma_f32_16x16x32_bf16 v[76:79], v[140:143], v[220:223], v[76:79]
	v_mfma_f32_16x16x32_bf16 v[128:131], v[136:139], v[192:195], v[128:131]
	v_mfma_f32_16x16x32_bf16 v[124:127], v[144:147], v[192:195], v[124:127]
	v_mfma_f32_16x16x32_bf16 v[112:115], v[136:139], v[200:203], v[112:115]
	v_mfma_f32_16x16x32_bf16 v[108:111], v[144:147], v[200:203], v[108:111]
	v_mfma_f32_16x16x32_bf16 v[96:99], v[136:139], v[208:211], v[96:99]
	v_mfma_f32_16x16x32_bf16 v[92:95], v[144:147], v[208:211], v[92:95]
	v_mfma_f32_16x16x32_bf16 v[80:83], v[136:139], v[224:227], v[80:83]
	v_mfma_f32_16x16x32_bf16 v[76:79], v[144:147], v[224:227], v[76:79]
	v_mfma_f32_16x16x32_bf16 v[120:123], v[148:151], v[180:183], v[120:123]
	v_mfma_f32_16x16x32_bf16 v[116:119], v[172:175], v[180:183], v[116:119]
	v_mfma_f32_16x16x32_bf16 v[104:107], v[148:151], v[196:199], v[104:107]
	v_mfma_f32_16x16x32_bf16 v[100:103], v[172:175], v[196:199], v[100:103]
	v_mfma_f32_16x16x32_bf16 v[88:91], v[148:151], v[204:207], v[88:91]
	v_mfma_f32_16x16x32_bf16 v[84:87], v[172:175], v[204:207], v[84:87]
	v_mfma_f32_16x16x32_bf16 v[72:75], v[148:151], v[220:223], v[72:75]
	v_mfma_f32_16x16x32_bf16 v[68:71], v[172:175], v[220:223], v[68:71]
	v_mfma_f32_16x16x32_bf16 v[120:123], v[152:155], v[192:195], v[120:123]
	v_mfma_f32_16x16x32_bf16 v[116:119], v[176:179], v[192:195], v[116:119]
	v_mfma_f32_16x16x32_bf16 v[104:107], v[152:155], v[200:203], v[104:107]
	v_mfma_f32_16x16x32_bf16 v[100:103], v[176:179], v[200:203], v[100:103]
	v_mfma_f32_16x16x32_bf16 v[88:91], v[152:155], v[208:211], v[88:91]
	v_mfma_f32_16x16x32_bf16 v[84:87], v[176:179], v[208:211], v[84:87]
	v_mfma_f32_16x16x32_bf16 v[72:75], v[152:155], v[224:227], v[72:75]
	v_mfma_f32_16x16x32_bf16 v[68:71], v[176:179], v[224:227], v[68:71]
	s_barrier
; #define PG8_STAGE(bufoff, gbase, voff) do { _Pragma("unroll") for (int _i = 0; _i < 2; ++_i) \
;         __builtin_amdgcn_global_load_lds((const unsigned*)((const char*)(gbase) + (voff)[_i]), (PG8_LAS unsigned*)(lds + (bufoff) + ldsw + _i * 8192), 16, 0, 0); } while (0)
; #define PG8_LDA(dst, b, h) do { _Pragma("unroll") for (int m = 0; m < 4; ++m) _Pragma("unroll") for (int k = 0; k < 2; ++k) dst[m][k] = *(const PG8_LAS bf16x8*)(lds + PG8_SA(b, h) + aoff + m * 2048 + k * 1024); } while (0)
; #define PG8_MMA(ai, bj, At, Bt) do { __builtin_amdgcn_s_setprio(1); _Pragma("unroll") for (int m = 0; m < 4; ++m) _Pragma("unroll") for (int n = 0; n < 2; ++n) _Pragma("unroll") for (int k = 0; k < 2; ++k) \
;         acc[ai][bj][m][n] = __builtin_amdgcn_mfma_f32_16x16x32_bf16(Bt[n][k], At[m][k], acc[ai][bj][m][n], 0, 0, 0); __builtin_amdgcn_s_setprio(0); } while (0)
; #define PG8_WAIT_V(n) asm volatile("s_waitcnt vmcnt(" #n ")" ::: "memory")
; #define PG8_WAIT_L(n) asm volatile("s_waitcnt lgkmcnt(" #n ")" ::: "memory")
; #define PG8_BAR __builtin_amdgcn_s_barrier()
; #define PG8_SCHED __builtin_amdgcn_sched_barrier(0)
; template <class Epi, class Sched, bool ALIGN_EPI = false, bool SP2 = false>
; __device__ __forceinline__ void gemm_phase(PG8_LAS unsigned char* lds, const Gemm g, const Sched& S, const Epi& E) {
;     ...
;             PG8_LDA(At, 1, 1); PG8_STAGE(PG8_SB(1, 0), b3, voffB); PG8_STAGE(PG8_SB(1, 1), b3 + hstep, voffB); PG8_STAGE(PG8_SA(1, 0), a3, voffA);
;             PG8_WAIT_V(8); PG8_WAIT_L(0); PG8_BAR; PG8_MMA(1, 0, At, B0); PG8_MMA(1, 1, At, B1); PG8_BAR; PG8_SCHED;
;     ...
;         if constexpr (ALIGN_EPI) { if (wr == 0) PG8_BAR; }
	s_setprio 0
	s_setprio 1
	s_setprio 0
	s_waitcnt lgkmcnt(0)
	s_add_i32 s50, s65, s52
	v_lshl_add_u64 v[228:229], v[228:229], 0, s[88:89]
	s_mov_b32 m0, s50
	ds_read_b128 v[180:183], v190 offset:49152
	ds_read_b128 v[192:195], v190 offset:50176
	ds_read_b128 v[196:199], v190 offset:51200
	ds_read_b128 v[200:203], v190 offset:52224
	ds_read_b128 v[204:207], v190 offset:53248
	ds_read_b128 v[208:211], v190 offset:54272
	ds_read_b128 v[220:223], v190 offset:55296
	ds_read_b128 v[224:227], v190 offset:56320
	global_load_lds_dwordx4 v[228:229], off
	s_add_i32 m0, s50, 0x2000
	s_add_u32 s48, s48, 0x80080
	v_lshl_add_u64 v[228:229], v[230:231], 0, s[88:89]
	s_addc_u32 s49, s49, 0
	s_add_i32 s50, s66, s52
	global_load_lds_dwordx4 v[228:229], off
	v_lshl_add_u64 v[228:229], s[48:49], 0, v[158:159]
	s_mov_b32 m0, s50
	s_nop 0
	global_load_lds_dwordx4 v[228:229], off
	v_lshl_add_u64 v[228:229], s[48:49], 0, v[162:163]
	s_add_i32 m0, s50, 0x2000
	s_nop 0
	global_load_lds_dwordx4 v[228:229], off
	v_lshl_add_u64 v[228:229], v[232:233], 0, s[88:89]
	s_mov_b32 m0, s58
	s_nop 0
	global_load_lds_dwordx4 v[228:229], off
	v_lshl_add_u64 v[228:229], v[234:235], 0, s[88:89]
	s_mov_b32 m0, s59
	s_nop 0
	global_load_lds_dwordx4 v[228:229], off
	s_setprio 1
	s_waitcnt vmcnt(8)
	s_waitcnt lgkmcnt(0)
	s_barrier
	v_mfma_f32_16x16x32_bf16 v[62:65], v[132:135], v[180:183], v[62:65]
	v_mfma_f32_16x16x32_bf16 v[58:61], v[140:143], v[180:183], v[58:61]
	v_mfma_f32_16x16x32_bf16 v[46:49], v[132:135], v[196:199], v[46:49]
	v_mfma_f32_16x16x32_bf16 v[42:45], v[140:143], v[196:199], v[42:45]
	v_mfma_f32_16x16x32_bf16 v[30:33], v[132:135], v[204:207], v[30:33]
	v_mfma_f32_16x16x32_bf16 v[26:29], v[140:143], v[204:207], v[26:29]
	v_mfma_f32_16x16x32_bf16 v[14:17], v[132:135], v[220:223], v[14:17]
	v_mfma_f32_16x16x32_bf16 v[10:13], v[140:143], v[220:223], v[10:13]
	v_mfma_f32_16x16x32_bf16 v[62:65], v[136:139], v[192:195], v[62:65]
	v_mfma_f32_16x16x32_bf16 v[58:61], v[144:147], v[192:195], v[58:61]
	v_mfma_f32_16x16x32_bf16 v[46:49], v[136:139], v[200:203], v[46:49]
	v_mfma_f32_16x16x32_bf16 v[42:45], v[144:147], v[200:203], v[42:45]
	v_mfma_f32_16x16x32_bf16 v[30:33], v[136:139], v[208:211], v[30:33]
	v_mfma_f32_16x16x32_bf16 v[26:29], v[144:147], v[208:211], v[26:29]
	v_mfma_f32_16x16x32_bf16 v[14:17], v[136:139], v[224:227], v[14:17]
	v_mfma_f32_16x16x32_bf16 v[10:13], v[144:147], v[224:227], v[10:13]
	v_mfma_f32_16x16x32_bf16 v[54:57], v[148:151], v[180:183], v[54:57]
	v_mfma_f32_16x16x32_bf16 v[50:53], v[172:175], v[180:183], v[50:53]
	v_mfma_f32_16x16x32_bf16 v[38:41], v[148:151], v[196:199], v[38:41]
	v_mfma_f32_16x16x32_bf16 v[34:37], v[172:175], v[196:199], v[34:37]
	v_mfma_f32_16x16x32_bf16 v[22:25], v[148:151], v[204:207], v[22:25]
	v_mfma_f32_16x16x32_bf16 v[18:21], v[172:175], v[204:207], v[18:21]
	v_mfma_f32_16x16x32_bf16 v[6:9], v[148:151], v[220:223], v[6:9]
	v_mfma_f32_16x16x32_bf16 v[2:5], v[172:175], v[220:223], v[2:5]
	v_mfma_f32_16x16x32_bf16 v[54:57], v[152:155], v[192:195], v[54:57]
	v_mfma_f32_16x16x32_bf16 v[50:53], v[176:179], v[192:195], v[50:53]
	v_mfma_f32_16x16x32_bf16 v[38:41], v[152:155], v[200:203], v[38:41]
	v_mfma_f32_16x16x32_bf16 v[34:37], v[176:179], v[200:203], v[34:37]
	v_mfma_f32_16x16x32_bf16 v[22:25], v[152:155], v[208:211], v[22:25]
	v_mfma_f32_16x16x32_bf16 v[18:21], v[176:179], v[208:211], v[18:21]
	v_mfma_f32_16x16x32_bf16 v[6:9], v[152:155], v[224:227], v[6:9]
	v_mfma_f32_16x16x32_bf16 v[2:5], v[176:179], v[224:227], v[2:5]
	s_barrier
	s_setprio 0
	s_setprio 1
	s_setprio 0
	s_waitcnt lgkmcnt(0)
	s_add_i32 s47, s47, 2
	s_add_u32 s12, s12, 0x100
	s_addc_u32 s13, s13, 0
	s_add_u32 s35, s35, 0x100
	s_addc_u32 s37, s37, 0
	s_cmp_gt_u32 s47, 29
	s_cbranch_scc0 .LBB0_239
	s_and_b64 vcc, exec, s[30:31]
	s_cbranch_vccz .LBB0_242
	s_barrier

; #define PG8_STAGE(bufoff, gbase, voff) do { _Pragma("unroll") for (int _i = 0; _i < 2; ++_i) \
;         __builtin_amdgcn_global_load_lds((const unsigned*)((const char*)(gbase) + (voff)[_i]), (PG8_LAS unsigned*)(lds + (bufoff) + ldsw + _i * 8192), 16, 0, 0); } while (0)
; #define PG8_LDA(dst, b, h) do { _Pragma("unroll") for (int m = 0; m < 4; ++m) _Pragma("unroll") for (int k = 0; k < 2; ++k) dst[m][k] = *(const PG8_LAS bf16x8*)(lds + PG8_SA(b, h) + aoff + m * 2048 + k * 1024); } while (0)
; #define PG8_LDB(dst, b, h) do { _Pragma("unroll") for (int n = 0; n < 2; ++n) _Pragma("unroll") for (int k = 0; k < 2; ++k) dst[n][k] = *(const PG8_LAS bf16x8*)(lds + PG8_SB(b, h) + boff + n * 2048 + k * 1024); } while (0)
; #define PG8_MMA(ai, bj, At, Bt) do { __builtin_amdgcn_s_setprio(1); _Pragma("unroll") for (int m = 0; m < 4; ++m) _Pragma("unroll") for (int n = 0; n < 2; ++n) _Pragma("unroll") for (int k = 0; k < 2; ++k) \
;         acc[ai][bj][m][n] = __builtin_amdgcn_mfma_f32_16x16x32_bf16(Bt[n][k], At[m][k], acc[ai][bj][m][n], 0, 0, 0); __builtin_amdgcn_s_setprio(0); } while (0)
; #define PG8_BAR __builtin_amdgcn_s_barrier()
; template <class Epi, class Sched, bool ALIGN_EPI = false, bool SP2 = false>
; __device__ __forceinline__ void gemm_phase(PG8_LAS unsigned char* lds, const Gemm g, const Sched& S, const Epi& E) {
;     ...
;         const char* nA = has_next ? (const char*)g.A + (size_t)nxt.pm * tstep + (size_t)nxt.ko * 2 : cA; const char* nB = has_next ? (const char*)g.Bt + (size_t)nxt.pn * tstep + (size_t)nxt.ko * 2 : cB;
;         for (int t = 0; t < nt; t += 2) {
;             const bool last = (t == nt - 2);
;             const char* a1 = cA + (size_t)(t + 1) * kstep;
;             const char* a2 = last ? nA : cA + (size_t)(t + 2) * kstep; const char* b2 = last ? nB : cB + (size_t)(t + 2) * kstep;
;             const char* a3 = a2 + kstep; const char* b3 = b2 + kstep;
;             if (last && has_next) S.a_ready(nxt);
;             if constexpr (SP2) {
;             PG8_LDB(B0, 0, 0); PG8_LDB(B1, 0, 1); PG8_SCHED; PG8_LDA(At, 0, 0); PG8_STAGE(PG8_SA(1, 1), a1 + hstep, voffA);
;             PG8_WAIT_V(8); PG8_WAIT_L(0); PG8_BAR; PG8_MMA(0, 0, At, B0); PG8_MMA(0, 1, At, B1); PG8_BAR; PG8_SCHED;
;             PG8_LDA(At, 0, 1); PG8_STAGE(PG8_SB(0, 0), b2, voffB); PG8_STAGE(PG8_SB(0, 1), b2 + hstep, voffB); PG8_STAGE(PG8_SA(0, 0), a2, voffA);
.LBB0_398:
	s_lshl_b32 s54, s43, 7
	s_add_u32 s55, s30, s54
	s_addc_u32 s56, s31, 0
	s_add_u32 s57, s55, 0x100
	s_addc_u32 s58, s56, 0
	s_and_b64 s[52:53], s[12:13], exec
	s_cselect_b32 s53, s58, s1
	s_cselect_b32 s52, s57, s2
	s_add_u32 s54, s34, s54
	s_addc_u32 s57, s35, 0
	s_add_u32 s54, s54, 0x100
	s_addc_u32 s57, s57, 0
	s_and_b64 s[12:13], s[12:13], exec
	s_cselect_b32 s13, s57, s3
	s_cselect_b32 s12, s54, s41
	s_add_i32 s57, 0, 0x10000
	v_add_u32_e32 v0, s57, v181
	s_add_i32 s58, 0, 0x14000
	ds_read_b128 v[132:135], v0
	ds_read_b128 v[136:139], v0 offset:1024
	ds_read_b128 v[140:143], v0 offset:2048
	ds_read_b128 v[144:147], v0 offset:3072
	v_add_u32_e32 v0, s58, v181
	ds_read_b128 v[148:151], v0
	ds_read_b128 v[152:155], v0 offset:1024
	ds_read_b128 v[168:171], v0 offset:2048
	ds_read_b128 v[172:175], v0 offset:3072
	s_add_u32 s54, s55, 0x80080
	s_addc_u32 s55, s56, 0
	v_lshl_add_u64 v[224:225], s[54:55], 0, v[156:157]
	s_add_i32 m0, s29, 0xc000
	ds_read_b128 v[176:179], v187
	ds_read_b128 v[188:191], v187 offset:1024
	ds_read_b128 v[192:195], v187 offset:2048
	ds_read_b128 v[196:199], v187 offset:3072
	ds_read_b128 v[200:203], v187 offset:4096
	ds_read_b128 v[204:207], v187 offset:5120
	ds_read_b128 v[208:211], v187 offset:6144
	ds_read_b128 v[220:223], v187 offset:7168
	global_load_lds_dwordx4 v[224:225], off
	v_lshl_add_u64 v[224:225], s[54:55], 0, v[160:161]
	s_add_i32 m0, s29, 0xe000
	s_nop 0
	global_load_lds_dwordx4 v[224:225], off
	s_setprio 1
	s_waitcnt vmcnt(8)
	s_waitcnt lgkmcnt(0)
	s_barrier
	v_mfma_f32_16x16x32_bf16 v[128:131], v[132:135], v[176:179], v[128:131]
	v_mfma_f32_16x16x32_bf16 v[124:127], v[140:143], v[176:179], v[124:127]
	v_mfma_f32_16x16x32_bf16 v[120:123], v[132:135], v[192:195], v[120:123]
	v_mfma_f32_16x16x32_bf16 v[116:119], v[140:143], v[192:195], v[116:119]
	v_mfma_f32_16x16x32_bf16 v[112:115], v[132:135], v[200:203], v[112:115]
	v_mfma_f32_16x16x32_bf16 v[108:111], v[140:143], v[200:203], v[108:111]
	v_mfma_f32_16x16x32_bf16 v[104:107], v[132:135], v[208:211], v[104:107]
	v_mfma_f32_16x16x32_bf16 v[100:103], v[140:143], v[208:211], v[100:103]
	v_mfma_f32_16x16x32_bf16 v[128:131], v[136:139], v[188:191], v[128:131]
	v_mfma_f32_16x16x32_bf16 v[124:127], v[144:147], v[188:191], v[124:127]
	v_mfma_f32_16x16x32_bf16 v[120:123], v[136:139], v[196:199], v[120:123]
	v_mfma_f32_16x16x32_bf16 v[116:119], v[144:147], v[196:199], v[116:119]
	v_mfma_f32_16x16x32_bf16 v[112:115], v[136:139], v[204:207], v[112:115]
	v_mfma_f32_16x16x32_bf16 v[108:111], v[144:147], v[204:207], v[108:111]
	v_mfma_f32_16x16x32_bf16 v[104:107], v[136:139], v[220:223], v[104:107]
	v_mfma_f32_16x16x32_bf16 v[100:103], v[144:147], v[220:223], v[100:103]
	v_mfma_f32_16x16x32_bf16 v[96:99], v[148:151], v[176:179], v[96:99]
	v_mfma_f32_16x16x32_bf16 v[92:95], v[168:171], v[176:179], v[92:95]
	v_mfma_f32_16x16x32_bf16 v[88:91], v[148:151], v[192:195], v[88:91]
	v_mfma_f32_16x16x32_bf16 v[84:87], v[168:171], v[192:195], v[84:87]
	v_mfma_f32_16x16x32_bf16 v[80:83], v[148:151], v[200:203], v[80:83]
	v_mfma_f32_16x16x32_bf16 v[76:79], v[168:171], v[200:203], v[76:79]
	v_mfma_f32_16x16x32_bf16 v[72:75], v[148:151], v[208:211], v[72:75]
	v_mfma_f32_16x16x32_bf16 v[68:71], v[168:171], v[208:211], v[68:71]
	v_mfma_f32_16x16x32_bf16 v[96:99], v[152:155], v[188:191], v[96:99]
	v_mfma_f32_16x16x32_bf16 v[92:95], v[172:175], v[188:191], v[92:95]
	v_mfma_f32_16x16x32_bf16 v[88:91], v[152:155], v[196:199], v[88:91]
	v_mfma_f32_16x16x32_bf16 v[84:87], v[172:175], v[196:199], v[84:87]
	v_mfma_f32_16x16x32_bf16 v[80:83], v[152:155], v[204:207], v[80:83]
	v_mfma_f32_16x16x32_bf16 v[76:79], v[172:175], v[204:207], v[76:79]
	v_mfma_f32_16x16x32_bf16 v[72:75], v[152:155], v[220:223], v[72:75]
	v_mfma_f32_16x16x32_bf16 v[68:71], v[172:175], v[220:223], v[68:71]
	s_barrier
	s_setprio 0
	s_setprio 1
	s_setprio 0
	s_waitcnt lgkmcnt(0)
	s_add_i32 s54, s57, s15
	v_lshl_add_u64 v[224:225], s[12:13], 0, v[158:159]
	s_mov_b32 m0, s54
	ds_read_b128 v[176:179], v187 offset:16384
	ds_read_b128 v[188:191], v187 offset:17408
	ds_read_b128 v[192:195], v187 offset:18432
	ds_read_b128 v[196:199], v187 offset:19456
	ds_read_b128 v[200:203], v187 offset:20480
	ds_read_b128 v[204:207], v187 offset:21504
	ds_read_b128 v[208:211], v187 offset:22528
	ds_read_b128 v[220:223], v187 offset:23552
	global_load_lds_dwordx4 v[224:225], off
	s_add_i32 m0, s54, 0x2000
	s_add_u32 s54, s12, 0x80000
	v_lshl_add_u64 v[226:227], s[12:13], 0, v[162:163]
	s_addc_u32 s55, s13, 0
	s_add_i32 s56, s58, s15
	global_load_lds_dwordx4 v[226:227], off
	v_lshl_add_u64 v[228:229], s[54:55], 0, v[158:159]
	s_mov_b32 m0, s56
	v_lshl_add_u64 v[230:231], s[52:53], 0, v[160:161]
	global_load_lds_dwordx4 v[228:229], off
	v_lshl_add_u64 v[228:229], s[54:55], 0, v[162:163]
	s_add_i32 m0, s56, 0x2000
	s_nop 0
	global_load_lds_dwordx4 v[228:229], off
	v_lshl_add_u64 v[228:229], s[52:53], 0, v[156:157]
	s_mov_b32 m0, s29
	s_nop 0
	global_load_lds_dwordx4 v[228:229], off
	s_mov_b32 m0, s65
	s_nop 0
	global_load_lds_dwordx4 v[230:231], off
	s_setprio 1
	s_waitcnt vmcnt(8)
	s_waitcnt lgkmcnt(0)
	s_barrier
; #define PG8_STAGE(bufoff, gbase, voff) do { _Pragma("unroll") for (int _i = 0; _i < 2; ++_i) \
;         __builtin_amdgcn_global_load_lds((const unsigned*)((const char*)(gbase) + (voff)[_i]), (PG8_LAS unsigned*)(lds + (bufoff) + ldsw + _i * 8192), 16, 0, 0); } while (0)
; #define PG8_LDA(dst, b, h) do { _Pragma("unroll") for (int m = 0; m < 4; ++m) _Pragma("unroll") for (int k = 0; k < 2; ++k) dst[m][k] = *(const PG8_LAS bf16x8*)(lds + PG8_SA(b, h) + aoff + m * 2048 + k * 1024); } while (0)
; #define PG8_LDB(dst, b, h) do { _Pragma("unroll") for (int n = 0; n < 2; ++n) _Pragma("unroll") for (int k = 0; k < 2; ++k) dst[n][k] = *(const PG8_LAS bf16x8*)(lds + PG8_SB(b, h) + boff + n * 2048 + k * 1024); } while (0)
; #define PG8_MMA(ai, bj, At, Bt) do { __builtin_amdgcn_s_setprio(1); _Pragma("unroll") for (int m = 0; m < 4; ++m) _Pragma("unroll") for (int n = 0; n < 2; ++n) _Pragma("unroll") for (int k = 0; k < 2; ++k) \
;         acc[ai][bj][m][n] = __builtin_amdgcn_mfma_f32_16x16x32_bf16(Bt[n][k], At[m][k], acc[ai][bj][m][n], 0, 0, 0); __builtin_amdgcn_s_setprio(0); } while (0)
; #define PG8_WAIT_V(n) asm volatile("s_waitcnt vmcnt(" #n ")" ::: "memory")
; #define PG8_WAIT_L(n) asm volatile("s_waitcnt lgkmcnt(" #n ")" ::: "memory")
; #define PG8_BAR __builtin_amdgcn_s_barrier()
; #define PG8_SCHED __builtin_amdgcn_sched_barrier(0)
; template <class Epi, class Sched, bool ALIGN_EPI = false, bool SP2 = false>
; __device__ __forceinline__ void gemm_phase(PG8_LAS unsigned char* lds, const Gemm g, const Sched& S, const Epi& E) {
;     ...
;             PG8_WAIT_V(8); PG8_WAIT_L(0); PG8_BAR; PG8_MMA(1, 0, At, B0); PG8_MMA(1, 1, At, B1); PG8_BAR; PG8_SCHED;
;             PG8_LDB(B0, 1, 0); PG8_LDB(B1, 1, 1); PG8_SCHED; PG8_LDA(At, 1, 0); PG8_STAGE(PG8_SA(0, 1), a2 + hstep, voffA);
;             PG8_WAIT_V(8); PG8_WAIT_L(0); PG8_BAR; PG8_MMA(0, 0, At, B0); PG8_MMA(0, 1, At, B1); PG8_BAR; PG8_SCHED;
	v_mfma_f32_16x16x32_bf16 v[62:65], v[132:135], v[176:179], v[62:65]
	v_mfma_f32_16x16x32_bf16 v[58:61], v[140:143], v[176:179], v[58:61]
	v_mfma_f32_16x16x32_bf16 v[54:57], v[132:135], v[192:195], v[54:57]
	v_mfma_f32_16x16x32_bf16 v[50:53], v[140:143], v[192:195], v[50:53]
	v_mfma_f32_16x16x32_bf16 v[46:49], v[132:135], v[200:203], v[46:49]
	v_mfma_f32_16x16x32_bf16 v[42:45], v[140:143], v[200:203], v[42:45]
	v_mfma_f32_16x16x32_bf16 v[38:41], v[132:135], v[208:211], v[38:41]
	v_mfma_f32_16x16x32_bf16 v[34:37], v[140:143], v[208:211], v[34:37]
	v_mfma_f32_16x16x32_bf16 v[62:65], v[136:139], v[188:191], v[62:65]
	v_mfma_f32_16x16x32_bf16 v[58:61], v[144:147], v[188:191], v[58:61]
	v_mfma_f32_16x16x32_bf16 v[54:57], v[136:139], v[196:199], v[54:57]
	v_mfma_f32_16x16x32_bf16 v[50:53], v[144:147], v[196:199], v[50:53]
	v_mfma_f32_16x16x32_bf16 v[46:49], v[136:139], v[204:207], v[46:49]
	v_mfma_f32_16x16x32_bf16 v[42:45], v[144:147], v[204:207], v[42:45]
	v_mfma_f32_16x16x32_bf16 v[38:41], v[136:139], v[220:223], v[38:41]
	v_mfma_f32_16x16x32_bf16 v[34:37], v[144:147], v[220:223], v[34:37]
	v_mfma_f32_16x16x32_bf16 v[30:33], v[148:151], v[176:179], v[30:33]
	v_mfma_f32_16x16x32_bf16 v[26:29], v[168:171], v[176:179], v[26:29]
	v_mfma_f32_16x16x32_bf16 v[22:25], v[148:151], v[192:195], v[22:25]
	v_mfma_f32_16x16x32_bf16 v[18:21], v[168:171], v[192:195], v[18:21]
	v_mfma_f32_16x16x32_bf16 v[14:17], v[148:151], v[200:203], v[14:17]
	v_mfma_f32_16x16x32_bf16 v[10:13], v[168:171], v[200:203], v[10:13]
	v_mfma_f32_16x16x32_bf16 v[6:9], v[148:151], v[208:211], v[6:9]
	v_mfma_f32_16x16x32_bf16 v[2:5], v[168:171], v[208:211], v[2:5]
	v_mfma_f32_16x16x32_bf16 v[30:33], v[152:155], v[188:191], v[30:33]
	v_mfma_f32_16x16x32_bf16 v[26:29], v[172:175], v[188:191], v[26:29]
	v_mfma_f32_16x16x32_bf16 v[22:25], v[152:155], v[196:199], v[22:25]
	v_mfma_f32_16x16x32_bf16 v[18:21], v[172:175], v[196:199], v[18:21]
	v_mfma_f32_16x16x32_bf16 v[14:17], v[152:155], v[204:207], v[14:17]
	v_mfma_f32_16x16x32_bf16 v[10:13], v[172:175], v[204:207], v[10:13]
	v_mfma_f32_16x16x32_bf16 v[6:9], v[152:155], v[220:223], v[6:9]
	v_mfma_f32_16x16x32_bf16 v[2:5], v[172:175], v[220:223], v[2:5]
	s_barrier
	s_setprio 0
	s_setprio 1
	s_setprio 0
	s_waitcnt lgkmcnt(0)
	s_add_i32 s54, 0, 0x18000
	v_add_u32_e32 v0, s54, v181
	s_add_i32 s55, 0, 0x1c000
	ds_read_b128 v[132:135], v0
	ds_read_b128 v[136:139], v0 offset:1024
	ds_read_b128 v[140:143], v0 offset:2048
	ds_read_b128 v[144:147], v0 offset:3072
	v_add_u32_e32 v0, s55, v181
	ds_read_b128 v[148:151], v0
	ds_read_b128 v[152:155], v0 offset:1024
	ds_read_b128 v[168:171], v0 offset:2048
	ds_read_b128 v[172:175], v0 offset:3072
	s_add_u32 s52, s52, 0x80000
	s_addc_u32 s53, s53, 0
	s_mov_b32 m0, s66
	v_lshl_add_u64 v[232:233], s[52:53], 0, v[156:157]
	ds_read_b128 v[176:179], v187 offset:32768
	ds_read_b128 v[188:191], v187 offset:33792
	ds_read_b128 v[192:195], v187 offset:34816
	ds_read_b128 v[196:199], v187 offset:35840
	ds_read_b128 v[200:203], v187 offset:36864
	ds_read_b128 v[204:207], v187 offset:37888
	ds_read_b128 v[208:211], v187 offset:38912
	ds_read_b128 v[220:223], v187 offset:39936
	global_load_lds_dwordx4 v[232:233], off
	v_lshl_add_u64 v[232:233], s[52:53], 0, v[160:161]
	s_mov_b32 m0, s67
	s_nop 0
	global_load_lds_dwordx4 v[232:233], off
	s_setprio 1
	s_waitcnt vmcnt(8)
	s_waitcnt lgkmcnt(0)
	s_barrier
	v_mfma_f32_16x16x32_bf16 v[128:131], v[132:135], v[176:179], v[128:131]
	v_mfma_f32_16x16x32_bf16 v[124:127], v[140:143], v[176:179], v[124:127]
	v_mfma_f32_16x16x32_bf16 v[120:123], v[132:135], v[192:195], v[120:123]
	v_mfma_f32_16x16x32_bf16 v[116:119], v[140:143], v[192:195], v[116:119]
	v_mfma_f32_16x16x32_bf16 v[112:115], v[132:135], v[200:203], v[112:115]
	v_mfma_f32_16x16x32_bf16 v[108:111], v[140:143], v[200:203], v[108:111]
	v_mfma_f32_16x16x32_bf16 v[104:107], v[132:135], v[208:211], v[104:107]
	v_mfma_f32_16x16x32_bf16 v[100:103], v[140:143], v[208:211], v[100:103]
	v_mfma_f32_16x16x32_bf16 v[128:131], v[136:139], v[188:191], v[128:131]
	v_mfma_f32_16x16x32_bf16 v[124:127], v[144:147], v[188:191], v[124:127]
	v_mfma_f32_16x16x32_bf16 v[120:123], v[136:139], v[196:199], v[120:123]
	v_mfma_f32_16x16x32_bf16 v[116:119], v[144:147], v[196:199], v[116:119]
	v_mfma_f32_16x16x32_bf16 v[112:115], v[136:139], v[204:207], v[112:115]
	v_mfma_f32_16x16x32_bf16 v[108:111], v[144:147], v[204:207], v[108:111]
	v_mfma_f32_16x16x32_bf16 v[104:107], v[136:139], v[220:223], v[104:107]
	v_mfma_f32_16x16x32_bf16 v[100:103], v[144:147], v[220:223], v[100:103]
	v_mfma_f32_16x16x32_bf16 v[96:99], v[148:151], v[176:179], v[96:99]
	v_mfma_f32_16x16x32_bf16 v[92:95], v[168:171], v[176:179], v[92:95]
	v_mfma_f32_16x16x32_bf16 v[88:91], v[148:151], v[192:195], v[88:91]
	v_mfma_f32_16x16x32_bf16 v[84:87], v[168:171], v[192:195], v[84:87]
	v_mfma_f32_16x16x32_bf16 v[80:83], v[148:151], v[200:203], v[80:83]
	v_mfma_f32_16x16x32_bf16 v[76:79], v[168:171], v[200:203], v[76:79]
	v_mfma_f32_16x16x32_bf16 v[72:75], v[148:151], v[208:211], v[72:75]
	v_mfma_f32_16x16x32_bf16 v[68:71], v[168:171], v[208:211], v[68:71]
	v_mfma_f32_16x16x32_bf16 v[96:99], v[152:155], v[188:191], v[96:99]
	v_mfma_f32_16x16x32_bf16 v[92:95], v[172:175], v[188:191], v[92:95]
	v_mfma_f32_16x16x32_bf16 v[88:91], v[152:155], v[196:199], v[88:91]
	v_mfma_f32_16x16x32_bf16 v[84:87], v[172:175], v[196:199], v[84:87]
	v_mfma_f32_16x16x32_bf16 v[80:83], v[152:155], v[204:207], v[80:83]
	v_mfma_f32_16x16x32_bf16 v[76:79], v[172:175], v[204:207], v[76:79]
	v_mfma_f32_16x16x32_bf16 v[72:75], v[152:155], v[220:223], v[72:75]
	v_mfma_f32_16x16x32_bf16 v[68:71], v[172:175], v[220:223], v[68:71]
	s_barrier
; #define PG8_STAGE(bufoff, gbase, voff) do { _Pragma("unroll") for (int _i = 0; _i < 2; ++_i) \
;         __builtin_amdgcn_global_load_lds((const unsigned*)((const char*)(gbase) + (voff)[_i]), (PG8_LAS unsigned*)(lds + (bufoff) + ldsw + _i * 8192), 16, 0, 0); } while (0)
; #define PG8_LDA(dst, b, h) do { _Pragma("unroll") for (int m = 0; m < 4; ++m) _Pragma("unroll") for (int k = 0; k < 2; ++k) dst[m][k] = *(const PG8_LAS bf16x8*)(lds + PG8_SA(b, h) + aoff + m * 2048 + k * 1024); } while (0)
; #define PG8_MMA(ai, bj, At, Bt) do { __builtin_amdgcn_s_setprio(1); _Pragma("unroll") for (int m = 0; m < 4; ++m) _Pragma("unroll") for (int n = 0; n < 2; ++n) _Pragma("unroll") for (int k = 0; k < 2; ++k) \
;         acc[ai][bj][m][n] = __builtin_amdgcn_mfma_f32_16x16x32_bf16(Bt[n][k], At[m][k], acc[ai][bj][m][n], 0, 0, 0); __builtin_amdgcn_s_setprio(0); } while (0)
; #define PG8_WAIT_V(n) asm volatile("s_waitcnt vmcnt(" #n ")" ::: "memory")
; #define PG8_WAIT_L(n) asm volatile("s_waitcnt lgkmcnt(" #n ")" ::: "memory")
; #define PG8_BAR __builtin_amdgcn_s_barrier()
; #define PG8_SCHED __builtin_amdgcn_sched_barrier(0)
; template <class Epi, class Sched, bool ALIGN_EPI = false, bool SP2 = false>
; __device__ __forceinline__ void gemm_phase(PG8_LAS unsigned char* lds, const Gemm g, const Sched& S, const Epi& E) {
;     ...
;             PG8_LDA(At, 1, 1); PG8_STAGE(PG8_SB(1, 0), b3, voffB); PG8_STAGE(PG8_SB(1, 1), b3 + hstep, voffB); PG8_STAGE(PG8_SA(1, 0), a3, voffA);
;             PG8_WAIT_V(8); PG8_WAIT_L(0); PG8_BAR; PG8_MMA(1, 0, At, B0); PG8_MMA(1, 1, At, B1); PG8_BAR; PG8_SCHED;
	s_setprio 0
	s_setprio 1
	s_setprio 0
	s_waitcnt lgkmcnt(0)
	s_add_i32 s52, s54, s15
	v_lshl_add_u64 v[224:225], v[224:225], 0, s[88:89]
	s_mov_b32 m0, s52
	ds_read_b128 v[176:179], v187 offset:49152
	ds_read_b128 v[188:191], v187 offset:50176
	ds_read_b128 v[192:195], v187 offset:51200
	ds_read_b128 v[196:199], v187 offset:52224
	ds_read_b128 v[200:203], v187 offset:53248
	ds_read_b128 v[204:207], v187 offset:54272
	ds_read_b128 v[208:211], v187 offset:55296
	ds_read_b128 v[220:223], v187 offset:56320
	global_load_lds_dwordx4 v[224:225], off
	s_add_i32 m0, s52, 0x2000
	s_add_u32 s12, s12, 0x80080
	v_lshl_add_u64 v[224:225], v[226:227], 0, s[88:89]
	s_addc_u32 s13, s13, 0
	s_add_i32 s52, s55, s15
	global_load_lds_dwordx4 v[224:225], off
	v_lshl_add_u64 v[224:225], s[12:13], 0, v[158:159]
	s_mov_b32 m0, s52
	s_nop 0
	global_load_lds_dwordx4 v[224:225], off
	v_lshl_add_u64 v[224:225], s[12:13], 0, v[162:163]
	s_add_i32 m0, s52, 0x2000
	s_nop 0
	global_load_lds_dwordx4 v[224:225], off
	v_lshl_add_u64 v[224:225], v[228:229], 0, s[88:89]
	s_mov_b32 m0, s69
	s_nop 0
	global_load_lds_dwordx4 v[224:225], off
	v_lshl_add_u64 v[224:225], v[230:231], 0, s[88:89]
	s_mov_b32 m0, s70
	s_nop 0
	global_load_lds_dwordx4 v[224:225], off
	s_setprio 1
	s_waitcnt vmcnt(8)
	s_waitcnt lgkmcnt(0)
	s_barrier
	v_mfma_f32_16x16x32_bf16 v[62:65], v[132:135], v[176:179], v[62:65]
	v_mfma_f32_16x16x32_bf16 v[58:61], v[140:143], v[176:179], v[58:61]
	v_mfma_f32_16x16x32_bf16 v[54:57], v[132:135], v[192:195], v[54:57]
	v_mfma_f32_16x16x32_bf16 v[50:53], v[140:143], v[192:195], v[50:53]
	v_mfma_f32_16x16x32_bf16 v[46:49], v[132:135], v[200:203], v[46:49]
	v_mfma_f32_16x16x32_bf16 v[42:45], v[140:143], v[200:203], v[42:45]
	v_mfma_f32_16x16x32_bf16 v[38:41], v[132:135], v[208:211], v[38:41]
	v_mfma_f32_16x16x32_bf16 v[34:37], v[140:143], v[208:211], v[34:37]
	v_mfma_f32_16x16x32_bf16 v[62:65], v[136:139], v[188:191], v[62:65]
	v_mfma_f32_16x16x32_bf16 v[58:61], v[144:147], v[188:191], v[58:61]
	v_mfma_f32_16x16x32_bf16 v[54:57], v[136:139], v[196:199], v[54:57]
	v_mfma_f32_16x16x32_bf16 v[50:53], v[144:147], v[196:199], v[50:53]
	v_mfma_f32_16x16x32_bf16 v[46:49], v[136:139], v[204:207], v[46:49]
	v_mfma_f32_16x16x32_bf16 v[42:45], v[144:147], v[204:207], v[42:45]
	v_mfma_f32_16x16x32_bf16 v[38:41], v[136:139], v[220:223], v[38:41]
	v_mfma_f32_16x16x32_bf16 v[34:37], v[144:147], v[220:223], v[34:37]
	v_mfma_f32_16x16x32_bf16 v[30:33], v[148:151], v[176:179], v[30:33]
	v_mfma_f32_16x16x32_bf16 v[26:29], v[168:171], v[176:179], v[26:29]
	v_mfma_f32_16x16x32_bf16 v[22:25], v[148:151], v[192:195], v[22:25]
	v_mfma_f32_16x16x32_bf16 v[18:21], v[168:171], v[192:195], v[18:21]
	v_mfma_f32_16x16x32_bf16 v[14:17], v[148:151], v[200:203], v[14:17]
	v_mfma_f32_16x16x32_bf16 v[10:13], v[168:171], v[200:203], v[10:13]
	v_mfma_f32_16x16x32_bf16 v[6:9], v[148:151], v[208:211], v[6:9]
	v_mfma_f32_16x16x32_bf16 v[2:5], v[168:171], v[208:211], v[2:5]
	v_mfma_f32_16x16x32_bf16 v[30:33], v[152:155], v[188:191], v[30:33]
	v_mfma_f32_16x16x32_bf16 v[26:29], v[172:175], v[188:191], v[26:29]
	v_mfma_f32_16x16x32_bf16 v[22:25], v[152:155], v[196:199], v[22:25]
	v_mfma_f32_16x16x32_bf16 v[18:21], v[172:175], v[196:199], v[18:21]
	v_mfma_f32_16x16x32_bf16 v[14:17], v[152:155], v[204:207], v[14:17]
	v_mfma_f32_16x16x32_bf16 v[10:13], v[172:175], v[204:207], v[10:13]
	v_mfma_f32_16x16x32_bf16 v[6:9], v[152:155], v[220:223], v[6:9]
	v_mfma_f32_16x16x32_bf16 v[2:5], v[172:175], v[220:223], v[2:5]
	s_barrier
	s_setprio 0
	s_setprio 1
	s_setprio 0
	s_waitcnt lgkmcnt(0)
	s_add_i32 s12, s43, 2
	s_cmp_gt_u32 s43, 29
	s_cbranch_scc1 .LBB0_400
	s_mov_b32 s43, s12
	s_branch .LBB0_384

; #define PG8_STAGE(bufoff, gbase, voff) do { _Pragma("unroll") for (int _i = 0; _i < 2; ++_i) \
;         __builtin_amdgcn_global_load_lds((const unsigned*)((const char*)(gbase) + (voff)[_i]), (PG8_LAS unsigned*)(lds + (bufoff) + ldsw + _i * 8192), 16, 0, 0); } while (0)
; #define PG8_LDA(dst, b, h) do { _Pragma("unroll") for (int m = 0; m < 4; ++m) _Pragma("unroll") for (int k = 0; k < 2; ++k) dst[m][k] = *(const PG8_LAS bf16x8*)(lds + PG8_SA(b, h) + aoff + m * 2048 + k * 1024); } while (0)
; #define PG8_LDB(dst, b, h) do { _Pragma("unroll") for (int n = 0; n < 2; ++n) _Pragma("unroll") for (int k = 0; k < 2; ++k) dst[n][k] = *(const PG8_LAS bf16x8*)(lds + PG8_SB(b, h) + boff + n * 2048 + k * 1024); } while (0)
; #define PG8_MMA(ai, bj, At, Bt) do { __builtin_amdgcn_s_setprio(1); _Pragma("unroll") for (int m = 0; m < 4; ++m) _Pragma("unroll") for (int n = 0; n < 2; ++n) _Pragma("unroll") for (int k = 0; k < 2; ++k) \
;         acc[ai][bj][m][n] = __builtin_amdgcn_mfma_f32_16x16x32_bf16(Bt[n][k], At[m][k], acc[ai][bj][m][n], 0, 0, 0); __builtin_amdgcn_s_setprio(0); } while (0)
; #define PG8_BAR __builtin_amdgcn_s_barrier()
; template <class Epi, class Sched, bool ALIGN_EPI = false, bool SP2 = false>
; __device__ __forceinline__ void gemm_phase(PG8_LAS unsigned char* lds, const Gemm g, const Sched& S, const Epi& E) {
;     ...
;         const char* nA = has_next ? (const char*)g.A + (size_t)nxt.pm * tstep + (size_t)nxt.ko * 2 : cA; const char* nB = has_next ? (const char*)g.Bt + (size_t)nxt.pn * tstep + (size_t)nxt.ko * 2 : cB;
;         for (int t = 0; t < nt; t += 2) {
;             const bool last = (t == nt - 2);
;             const char* a1 = cA + (size_t)(t + 1) * kstep;
;             const char* a2 = last ? nA : cA + (size_t)(t + 2) * kstep; const char* b2 = last ? nB : cB + (size_t)(t + 2) * kstep;
;             const char* a3 = a2 + kstep; const char* b3 = b2 + kstep;
;             if (last && has_next) S.a_ready(nxt);
;             if constexpr (SP2) {
;             PG8_LDB(B0, 0, 0); PG8_LDB(B1, 0, 1); PG8_SCHED; PG8_LDA(At, 0, 0); PG8_STAGE(PG8_SA(1, 1), a1 + hstep, voffA);
;             PG8_WAIT_V(8); PG8_WAIT_L(0); PG8_BAR; PG8_MMA(0, 0, At, B0); PG8_MMA(0, 1, At, B1); PG8_BAR; PG8_SCHED;
;             PG8_LDA(At, 0, 1); PG8_STAGE(PG8_SB(0, 0), b2, voffB); PG8_STAGE(PG8_SB(0, 1), b2 + hstep, voffB); PG8_STAGE(PG8_SA(0, 0), a2, voffA);
.LBB0_702:
	s_add_u32 s14, s26, s12
	s_addc_u32 s15, s27, s13
	s_add_u32 s14, s14, 0x5800100
	s_addc_u32 s15, s15, 0
	s_add_u32 s31, s28, s12
	s_addc_u32 s34, s29, s13
	s_add_i32 s35, 0, 0x10000
	s_cmpk_eq_i32 s12, 0xf00
	s_cselect_b32 s17, s9, s15
	s_cselect_b32 s16, s8, s14
	v_add_u32_e32 v89, s35, v87
	s_cselect_b32 s15, s7, s34
	s_cselect_b32 s14, s6, s31
	s_add_i32 s31, 0, 0x14000
	ds_read_b128 v[148:151], v89
	ds_read_b128 v[152:155], v89 offset:1024
	ds_read_b128 v[156:159], v89 offset:2048
	ds_read_b128 v[160:163], v89 offset:3072
	v_add_u32_e32 v89, s31, v87
	ds_read_b128 v[166:169], v89
	ds_read_b128 v[170:173], v89 offset:1024
	ds_read_b128 v[174:177], v89 offset:2048
	ds_read_b128 v[178:181], v89 offset:3072
	v_lshl_add_u64 v[90:91], v[74:75], 0, s[12:13]
	s_add_i32 m0, s20, 0xc000
	ds_read_b128 v[182:185], v88
	ds_read_b128 v[186:189], v88 offset:1024
	ds_read_b128 v[190:193], v88 offset:2048
	ds_read_b128 v[194:197], v88 offset:3072
	ds_read_b128 v[200:203], v88 offset:4096
	ds_read_b128 v[204:207], v88 offset:5120
	ds_read_b128 v[208:211], v88 offset:6144
	ds_read_b128 v[220:223], v88 offset:7168
	global_load_lds_dwordx4 v[90:91], off
	v_lshl_add_u64 v[90:91], v[84:85], 0, s[12:13]
	s_add_i32 m0, s20, 0xe000
	s_nop 0
	global_load_lds_dwordx4 v[90:91], off
	s_setprio 1
	s_waitcnt vmcnt(8)
	s_waitcnt lgkmcnt(0)
	s_barrier
	v_mfma_f32_16x16x32_bf16 v[144:147], v[148:151], v[182:185], v[144:147]
	v_mfma_f32_16x16x32_bf16 v[140:143], v[156:159], v[182:185], v[140:143]
	v_mfma_f32_16x16x32_bf16 v[128:131], v[148:151], v[190:193], v[128:131]
	v_mfma_f32_16x16x32_bf16 v[124:127], v[156:159], v[190:193], v[124:127]
	v_mfma_f32_16x16x32_bf16 v[112:115], v[148:151], v[200:203], v[112:115]
	v_mfma_f32_16x16x32_bf16 v[108:111], v[156:159], v[200:203], v[108:111]
	v_mfma_f32_16x16x32_bf16 v[96:99], v[148:151], v[208:211], v[96:99]
	v_mfma_f32_16x16x32_bf16 v[90:93], v[156:159], v[208:211], v[92:95]
	v_mfma_f32_16x16x32_bf16 v[144:147], v[152:155], v[186:189], v[144:147]
	v_mfma_f32_16x16x32_bf16 v[140:143], v[160:163], v[186:189], v[140:143]
	v_mfma_f32_16x16x32_bf16 v[128:131], v[152:155], v[194:197], v[128:131]
	v_mfma_f32_16x16x32_bf16 v[124:127], v[160:163], v[194:197], v[124:127]
	v_mfma_f32_16x16x32_bf16 v[112:115], v[152:155], v[204:207], v[112:115]
	v_mfma_f32_16x16x32_bf16 v[108:111], v[160:163], v[204:207], v[108:111]
	v_mfma_f32_16x16x32_bf16 v[96:99], v[152:155], v[220:223], v[96:99]
	v_mfma_f32_16x16x32_bf16 v[90:93], v[160:163], v[220:223], v[90:93]
	v_mfma_f32_16x16x32_bf16 v[136:139], v[166:169], v[182:185], v[136:139]
	v_mfma_f32_16x16x32_bf16 v[132:135], v[174:177], v[182:185], v[132:135]
	v_mfma_f32_16x16x32_bf16 v[120:123], v[166:169], v[190:193], v[120:123]
	v_mfma_f32_16x16x32_bf16 v[116:119], v[174:177], v[190:193], v[116:119]
	v_mfma_f32_16x16x32_bf16 v[104:107], v[166:169], v[200:203], v[104:107]
	v_mfma_f32_16x16x32_bf16 v[100:103], v[174:177], v[200:203], v[100:103]
	v_mfma_f32_16x16x32_bf16 v[80:83], v[166:169], v[208:211], v[80:83]
	v_mfma_f32_16x16x32_bf16 v[76:79], v[174:177], v[208:211], v[76:79]
	v_mfma_f32_16x16x32_bf16 v[136:139], v[170:173], v[186:189], v[136:139]
	v_mfma_f32_16x16x32_bf16 v[132:135], v[178:181], v[186:189], v[132:135]
	v_mfma_f32_16x16x32_bf16 v[120:123], v[170:173], v[194:197], v[120:123]
	v_mfma_f32_16x16x32_bf16 v[116:119], v[178:181], v[194:197], v[116:119]
	v_mfma_f32_16x16x32_bf16 v[104:107], v[170:173], v[204:207], v[104:107]
	v_mfma_f32_16x16x32_bf16 v[100:103], v[178:181], v[204:207], v[100:103]
	v_mfma_f32_16x16x32_bf16 v[80:83], v[170:173], v[220:223], v[80:83]
	v_mfma_f32_16x16x32_bf16 v[76:79], v[178:181], v[220:223], v[76:79]
	s_barrier
	s_setprio 0
	s_setprio 1
	s_setprio 0
	s_waitcnt lgkmcnt(0)
	s_add_i32 s34, s35, s18
	v_lshl_add_u64 v[224:225], s[14:15], 0, v[66:67]
	s_mov_b32 m0, s34
	ds_read_b128 v[182:185], v88 offset:16384
	ds_read_b128 v[186:189], v88 offset:17408
	ds_read_b128 v[190:193], v88 offset:18432
	ds_read_b128 v[194:197], v88 offset:19456
	ds_read_b128 v[200:203], v88 offset:20480
	ds_read_b128 v[204:207], v88 offset:21504
	ds_read_b128 v[208:211], v88 offset:22528
	ds_read_b128 v[220:223], v88 offset:23552
	global_load_lds_dwordx4 v[224:225], off
	s_add_i32 m0, s34, 0x2000
	s_add_u32 s34, s14, 0x80000
	v_lshl_add_u64 v[226:227], s[14:15], 0, v[72:73]
	s_addc_u32 s35, s15, 0
	s_add_i32 s31, s31, s18
	global_load_lds_dwordx4 v[226:227], off
	v_lshl_add_u64 v[94:95], s[34:35], 0, v[66:67]
	s_mov_b32 m0, s31
	v_lshl_add_u64 v[228:229], s[16:17], 0, v[68:69]
	global_load_lds_dwordx4 v[94:95], off
	v_lshl_add_u64 v[94:95], s[34:35], 0, v[72:73]
	s_add_i32 m0, s31, 0x2000
	v_lshl_add_u64 v[230:231], s[16:17], 0, v[70:71]
	global_load_lds_dwordx4 v[94:95], off
	s_mov_b32 m0, s20
	s_nop 0
	global_load_lds_dwordx4 v[228:229], off
	s_mov_b32 m0, s3
	s_nop 0
	global_load_lds_dwordx4 v[230:231], off
	s_setprio 1
	s_waitcnt vmcnt(8)
	s_waitcnt lgkmcnt(0)
	s_barrier
; #define PG8_STAGE(bufoff, gbase, voff) do { _Pragma("unroll") for (int _i = 0; _i < 2; ++_i) \
;         __builtin_amdgcn_global_load_lds((const unsigned*)((const char*)(gbase) + (voff)[_i]), (PG8_LAS unsigned*)(lds + (bufoff) + ldsw + _i * 8192), 16, 0, 0); } while (0)
; #define PG8_LDA(dst, b, h) do { _Pragma("unroll") for (int m = 0; m < 4; ++m) _Pragma("unroll") for (int k = 0; k < 2; ++k) dst[m][k] = *(const PG8_LAS bf16x8*)(lds + PG8_SA(b, h) + aoff + m * 2048 + k * 1024); } while (0)
; #define PG8_LDB(dst, b, h) do { _Pragma("unroll") for (int n = 0; n < 2; ++n) _Pragma("unroll") for (int k = 0; k < 2; ++k) dst[n][k] = *(const PG8_LAS bf16x8*)(lds + PG8_SB(b, h) + boff + n * 2048 + k * 1024); } while (0)
; #define PG8_MMA(ai, bj, At, Bt) do { __builtin_amdgcn_s_setprio(1); _Pragma("unroll") for (int m = 0; m < 4; ++m) _Pragma("unroll") for (int n = 0; n < 2; ++n) _Pragma("unroll") for (int k = 0; k < 2; ++k) \
;         acc[ai][bj][m][n] = __builtin_amdgcn_mfma_f32_16x16x32_bf16(Bt[n][k], At[m][k], acc[ai][bj][m][n], 0, 0, 0); __builtin_amdgcn_s_setprio(0); } while (0)
; #define PG8_WAIT_V(n) asm volatile("s_waitcnt vmcnt(" #n ")" ::: "memory")
; #define PG8_WAIT_L(n) asm volatile("s_waitcnt lgkmcnt(" #n ")" ::: "memory")
; #define PG8_BAR __builtin_amdgcn_s_barrier()
; #define PG8_SCHED __builtin_amdgcn_sched_barrier(0)
; template <class Epi, class Sched, bool ALIGN_EPI = false, bool SP2 = false>
; __device__ __forceinline__ void gemm_phase(PG8_LAS unsigned char* lds, const Gemm g, const Sched& S, const Epi& E) {
;     ...
;             PG8_WAIT_V(8); PG8_WAIT_L(0); PG8_BAR; PG8_MMA(1, 0, At, B0); PG8_MMA(1, 1, At, B1); PG8_BAR; PG8_SCHED;
;             PG8_LDB(B0, 1, 0); PG8_LDB(B1, 1, 1); PG8_SCHED; PG8_LDA(At, 1, 0); PG8_STAGE(PG8_SA(0, 1), a2 + hstep, voffA);
;             PG8_WAIT_V(8); PG8_WAIT_L(0); PG8_BAR; PG8_MMA(0, 0, At, B0); PG8_MMA(0, 1, At, B1); PG8_BAR; PG8_SCHED;
	v_mfma_f32_16x16x32_bf16 v[62:65], v[148:151], v[182:185], v[62:65]
	v_mfma_f32_16x16x32_bf16 v[58:61], v[156:159], v[182:185], v[58:61]
	v_mfma_f32_16x16x32_bf16 v[46:49], v[148:151], v[190:193], v[46:49]
	v_mfma_f32_16x16x32_bf16 v[42:45], v[156:159], v[190:193], v[42:45]
	v_mfma_f32_16x16x32_bf16 v[30:33], v[148:151], v[200:203], v[30:33]
	v_mfma_f32_16x16x32_bf16 v[26:29], v[156:159], v[200:203], v[26:29]
	v_mfma_f32_16x16x32_bf16 v[14:17], v[148:151], v[208:211], v[14:17]
	v_mfma_f32_16x16x32_bf16 v[10:13], v[156:159], v[208:211], v[10:13]
	v_mfma_f32_16x16x32_bf16 v[62:65], v[152:155], v[186:189], v[62:65]
	v_mfma_f32_16x16x32_bf16 v[58:61], v[160:163], v[186:189], v[58:61]
	v_mfma_f32_16x16x32_bf16 v[46:49], v[152:155], v[194:197], v[46:49]
	v_mfma_f32_16x16x32_bf16 v[42:45], v[160:163], v[194:197], v[42:45]
	v_mfma_f32_16x16x32_bf16 v[30:33], v[152:155], v[204:207], v[30:33]
	v_mfma_f32_16x16x32_bf16 v[26:29], v[160:163], v[204:207], v[26:29]
	v_mfma_f32_16x16x32_bf16 v[14:17], v[152:155], v[220:223], v[14:17]
	v_mfma_f32_16x16x32_bf16 v[10:13], v[160:163], v[220:223], v[10:13]
	v_mfma_f32_16x16x32_bf16 v[54:57], v[166:169], v[182:185], v[54:57]
	v_mfma_f32_16x16x32_bf16 v[50:53], v[174:177], v[182:185], v[50:53]
	v_mfma_f32_16x16x32_bf16 v[38:41], v[166:169], v[190:193], v[38:41]
	v_mfma_f32_16x16x32_bf16 v[34:37], v[174:177], v[190:193], v[34:37]
	v_mfma_f32_16x16x32_bf16 v[22:25], v[166:169], v[200:203], v[22:25]
	v_mfma_f32_16x16x32_bf16 v[18:21], v[174:177], v[200:203], v[18:21]
	v_mfma_f32_16x16x32_bf16 v[6:9], v[166:169], v[208:211], v[6:9]
	v_mfma_f32_16x16x32_bf16 v[2:5], v[174:177], v[208:211], v[2:5]
	v_mfma_f32_16x16x32_bf16 v[54:57], v[170:173], v[186:189], v[54:57]
	v_mfma_f32_16x16x32_bf16 v[50:53], v[178:181], v[186:189], v[50:53]
	v_mfma_f32_16x16x32_bf16 v[38:41], v[170:173], v[194:197], v[38:41]
	v_mfma_f32_16x16x32_bf16 v[34:37], v[178:181], v[194:197], v[34:37]
	v_mfma_f32_16x16x32_bf16 v[22:25], v[170:173], v[204:207], v[22:25]
	v_mfma_f32_16x16x32_bf16 v[18:21], v[178:181], v[204:207], v[18:21]
	v_mfma_f32_16x16x32_bf16 v[6:9], v[170:173], v[220:223], v[6:9]
	v_mfma_f32_16x16x32_bf16 v[2:5], v[178:181], v[220:223], v[2:5]
	s_barrier
	s_setprio 0
	s_setprio 1
	s_setprio 0
	s_waitcnt lgkmcnt(0)
	s_add_i32 s31, 0, 0x18000
	v_add_u32_e32 v89, s31, v87
	s_add_i32 s34, 0, 0x1c000
	ds_read_b128 v[148:151], v89
	ds_read_b128 v[152:155], v89 offset:1024
	ds_read_b128 v[156:159], v89 offset:2048
	ds_read_b128 v[160:163], v89 offset:3072
	v_add_u32_e32 v89, s34, v87
	ds_read_b128 v[166:169], v89
	ds_read_b128 v[170:173], v89 offset:1024
	ds_read_b128 v[174:177], v89 offset:2048
	ds_read_b128 v[178:181], v89 offset:3072
	s_add_u32 s16, s16, 0x80000
	s_addc_u32 s17, s17, 0
	s_mov_b32 m0, s21
	v_lshl_add_u64 v[94:95], s[16:17], 0, v[68:69]
	ds_read_b128 v[182:185], v88 offset:32768
	ds_read_b128 v[186:189], v88 offset:33792
	ds_read_b128 v[190:193], v88 offset:34816
	ds_read_b128 v[194:197], v88 offset:35840
	ds_read_b128 v[200:203], v88 offset:36864
	ds_read_b128 v[204:207], v88 offset:37888
	ds_read_b128 v[208:211], v88 offset:38912
	ds_read_b128 v[220:223], v88 offset:39936
	global_load_lds_dwordx4 v[94:95], off
	v_lshl_add_u64 v[94:95], s[16:17], 0, v[70:71]
	s_mov_b32 m0, s22
	s_nop 0
	global_load_lds_dwordx4 v[94:95], off
	s_setprio 1
	s_waitcnt vmcnt(8)
	s_waitcnt lgkmcnt(0)
	s_barrier
	v_mfma_f32_16x16x32_bf16 v[144:147], v[148:151], v[182:185], v[144:147]
	v_mfma_f32_16x16x32_bf16 v[140:143], v[156:159], v[182:185], v[140:143]
	v_mfma_f32_16x16x32_bf16 v[128:131], v[148:151], v[190:193], v[128:131]
	v_mfma_f32_16x16x32_bf16 v[124:127], v[156:159], v[190:193], v[124:127]
	v_mfma_f32_16x16x32_bf16 v[112:115], v[148:151], v[200:203], v[112:115]
	v_mfma_f32_16x16x32_bf16 v[108:111], v[156:159], v[200:203], v[108:111]
	v_mfma_f32_16x16x32_bf16 v[94:97], v[148:151], v[208:211], v[96:99]
	v_mfma_f32_16x16x32_bf16 v[90:93], v[156:159], v[208:211], v[90:93]
	v_mfma_f32_16x16x32_bf16 v[144:147], v[152:155], v[186:189], v[144:147]
	v_mfma_f32_16x16x32_bf16 v[140:143], v[160:163], v[186:189], v[140:143]
	v_mfma_f32_16x16x32_bf16 v[128:131], v[152:155], v[194:197], v[128:131]
	v_mfma_f32_16x16x32_bf16 v[124:127], v[160:163], v[194:197], v[124:127]
	v_mfma_f32_16x16x32_bf16 v[112:115], v[152:155], v[204:207], v[112:115]
	v_mfma_f32_16x16x32_bf16 v[108:111], v[160:163], v[204:207], v[108:111]
	v_mfma_f32_16x16x32_bf16 v[96:99], v[152:155], v[220:223], v[94:97]
	v_mfma_f32_16x16x32_bf16 v[92:95], v[160:163], v[220:223], v[90:93]
	v_mfma_f32_16x16x32_bf16 v[136:139], v[166:169], v[182:185], v[136:139]
	v_mfma_f32_16x16x32_bf16 v[132:135], v[174:177], v[182:185], v[132:135]
	v_mfma_f32_16x16x32_bf16 v[120:123], v[166:169], v[190:193], v[120:123]
	v_mfma_f32_16x16x32_bf16 v[116:119], v[174:177], v[190:193], v[116:119]
	v_mfma_f32_16x16x32_bf16 v[104:107], v[166:169], v[200:203], v[104:107]
	v_mfma_f32_16x16x32_bf16 v[100:103], v[174:177], v[200:203], v[100:103]
	v_mfma_f32_16x16x32_bf16 v[80:83], v[166:169], v[208:211], v[80:83]
	v_mfma_f32_16x16x32_bf16 v[76:79], v[174:177], v[208:211], v[76:79]
	v_mfma_f32_16x16x32_bf16 v[136:139], v[170:173], v[186:189], v[136:139]
	v_mfma_f32_16x16x32_bf16 v[132:135], v[178:181], v[186:189], v[132:135]
	v_mfma_f32_16x16x32_bf16 v[120:123], v[170:173], v[194:197], v[120:123]
	v_mfma_f32_16x16x32_bf16 v[116:119], v[178:181], v[194:197], v[116:119]
	v_mfma_f32_16x16x32_bf16 v[104:107], v[170:173], v[204:207], v[104:107]
	v_mfma_f32_16x16x32_bf16 v[100:103], v[178:181], v[204:207], v[100:103]
	v_mfma_f32_16x16x32_bf16 v[80:83], v[170:173], v[220:223], v[80:83]
	v_mfma_f32_16x16x32_bf16 v[76:79], v[178:181], v[220:223], v[76:79]
	s_barrier
; #define PG8_STAGE(bufoff, gbase, voff) do { _Pragma("unroll") for (int _i = 0; _i < 2; ++_i) \
;         __builtin_amdgcn_global_load_lds((const unsigned*)((const char*)(gbase) + (voff)[_i]), (PG8_LAS unsigned*)(lds + (bufoff) + ldsw + _i * 8192), 16, 0, 0); } while (0)
; #define PG8_LDA(dst, b, h) do { _Pragma("unroll") for (int m = 0; m < 4; ++m) _Pragma("unroll") for (int k = 0; k < 2; ++k) dst[m][k] = *(const PG8_LAS bf16x8*)(lds + PG8_SA(b, h) + aoff + m * 2048 + k * 1024); } while (0)
; #define PG8_MMA(ai, bj, At, Bt) do { __builtin_amdgcn_s_setprio(1); _Pragma("unroll") for (int m = 0; m < 4; ++m) _Pragma("unroll") for (int n = 0; n < 2; ++n) _Pragma("unroll") for (int k = 0; k < 2; ++k) \
;         acc[ai][bj][m][n] = __builtin_amdgcn_mfma_f32_16x16x32_bf16(Bt[n][k], At[m][k], acc[ai][bj][m][n], 0, 0, 0); __builtin_amdgcn_s_setprio(0); } while (0)
; #define PG8_WAIT_V(n) asm volatile("s_waitcnt vmcnt(" #n ")" ::: "memory")
; #define PG8_WAIT_L(n) asm volatile("s_waitcnt lgkmcnt(" #n ")" ::: "memory")
; #define PG8_BAR __builtin_amdgcn_s_barrier()
; #define PG8_SCHED __builtin_amdgcn_sched_barrier(0)
; template <class Epi, class Sched, bool ALIGN_EPI = false, bool SP2 = false>
; __device__ __forceinline__ void gemm_phase(PG8_LAS unsigned char* lds, const Gemm g, const Sched& S, const Epi& E) {
;     ...
;             PG8_LDA(At, 1, 1); PG8_STAGE(PG8_SB(1, 0), b3, voffB); PG8_STAGE(PG8_SB(1, 1), b3 + hstep, voffB); PG8_STAGE(PG8_SA(1, 0), a3, voffA);
;             PG8_WAIT_V(8); PG8_WAIT_L(0); PG8_BAR; PG8_MMA(1, 0, At, B0); PG8_MMA(1, 1, At, B1); PG8_BAR; PG8_SCHED;
	s_setprio 0
	s_setprio 1
	s_setprio 0
	s_waitcnt lgkmcnt(0)
	s_add_i32 s16, s31, s18
	v_lshl_add_u64 v[90:91], v[224:225], 0, s[88:89]
	s_mov_b32 m0, s16
	ds_read_b128 v[182:185], v88 offset:49152
	ds_read_b128 v[186:189], v88 offset:50176
	ds_read_b128 v[190:193], v88 offset:51200
	ds_read_b128 v[194:197], v88 offset:52224
	ds_read_b128 v[200:203], v88 offset:53248
	ds_read_b128 v[204:207], v88 offset:54272
	ds_read_b128 v[208:211], v88 offset:55296
	ds_read_b128 v[220:223], v88 offset:56320
	global_load_lds_dwordx4 v[90:91], off
	s_add_i32 m0, s16, 0x2000
	s_add_u32 s14, s14, 0x80080
	v_lshl_add_u64 v[90:91], v[226:227], 0, s[88:89]
	s_addc_u32 s15, s15, 0
	s_add_i32 s16, s34, s18
	global_load_lds_dwordx4 v[90:91], off
	v_lshl_add_u64 v[90:91], s[14:15], 0, v[66:67]
	s_mov_b32 m0, s16
	s_nop 0
	global_load_lds_dwordx4 v[90:91], off
	v_lshl_add_u64 v[90:91], s[14:15], 0, v[72:73]
	s_add_i32 m0, s16, 0x2000
	s_nop 0
	global_load_lds_dwordx4 v[90:91], off
	v_lshl_add_u64 v[90:91], v[228:229], 0, s[88:89]
	s_mov_b32 m0, s24
	s_nop 0
	global_load_lds_dwordx4 v[90:91], off
	v_lshl_add_u64 v[90:91], v[230:231], 0, s[88:89]
	s_mov_b32 m0, s25
	s_nop 0
	global_load_lds_dwordx4 v[90:91], off
	s_setprio 1
	s_waitcnt vmcnt(8)
	s_waitcnt lgkmcnt(0)
	s_barrier
	v_mfma_f32_16x16x32_bf16 v[62:65], v[148:151], v[182:185], v[62:65]
	v_mfma_f32_16x16x32_bf16 v[58:61], v[156:159], v[182:185], v[58:61]
	v_mfma_f32_16x16x32_bf16 v[46:49], v[148:151], v[190:193], v[46:49]
	v_mfma_f32_16x16x32_bf16 v[42:45], v[156:159], v[190:193], v[42:45]
	v_mfma_f32_16x16x32_bf16 v[30:33], v[148:151], v[200:203], v[30:33]
	v_mfma_f32_16x16x32_bf16 v[26:29], v[156:159], v[200:203], v[26:29]
	v_mfma_f32_16x16x32_bf16 v[14:17], v[148:151], v[208:211], v[14:17]
	v_mfma_f32_16x16x32_bf16 v[10:13], v[156:159], v[208:211], v[10:13]
	v_mfma_f32_16x16x32_bf16 v[62:65], v[152:155], v[186:189], v[62:65]
	v_mfma_f32_16x16x32_bf16 v[58:61], v[160:163], v[186:189], v[58:61]
	v_mfma_f32_16x16x32_bf16 v[46:49], v[152:155], v[194:197], v[46:49]
	v_mfma_f32_16x16x32_bf16 v[42:45], v[160:163], v[194:197], v[42:45]
	v_mfma_f32_16x16x32_bf16 v[30:33], v[152:155], v[204:207], v[30:33]
	v_mfma_f32_16x16x32_bf16 v[26:29], v[160:163], v[204:207], v[26:29]
	v_mfma_f32_16x16x32_bf16 v[14:17], v[152:155], v[220:223], v[14:17]
	v_mfma_f32_16x16x32_bf16 v[10:13], v[160:163], v[220:223], v[10:13]
	v_mfma_f32_16x16x32_bf16 v[54:57], v[166:169], v[182:185], v[54:57]
	v_mfma_f32_16x16x32_bf16 v[50:53], v[174:177], v[182:185], v[50:53]
	v_mfma_f32_16x16x32_bf16 v[38:41], v[166:169], v[190:193], v[38:41]
	v_mfma_f32_16x16x32_bf16 v[34:37], v[174:177], v[190:193], v[34:37]
	v_mfma_f32_16x16x32_bf16 v[22:25], v[166:169], v[200:203], v[22:25]
	v_mfma_f32_16x16x32_bf16 v[18:21], v[174:177], v[200:203], v[18:21]
	v_mfma_f32_16x16x32_bf16 v[6:9], v[166:169], v[208:211], v[6:9]
	v_mfma_f32_16x16x32_bf16 v[2:5], v[174:177], v[208:211], v[2:5]
	v_mfma_f32_16x16x32_bf16 v[54:57], v[170:173], v[186:189], v[54:57]
	v_mfma_f32_16x16x32_bf16 v[50:53], v[178:181], v[186:189], v[50:53]
	v_mfma_f32_16x16x32_bf16 v[38:41], v[170:173], v[194:197], v[38:41]
	v_mfma_f32_16x16x32_bf16 v[34:37], v[178:181], v[194:197], v[34:37]
	v_mfma_f32_16x16x32_bf16 v[22:25], v[170:173], v[204:207], v[22:25]
	v_mfma_f32_16x16x32_bf16 v[18:21], v[178:181], v[204:207], v[18:21]
	v_mfma_f32_16x16x32_bf16 v[6:9], v[170:173], v[220:223], v[6:9]
	v_mfma_f32_16x16x32_bf16 v[2:5], v[178:181], v[220:223], v[2:5]
	s_barrier
	s_setprio 0
	s_setprio 1
	s_setprio 0
	s_waitcnt lgkmcnt(0)
	s_add_i32 s30, s30, 2
	s_add_u32 s12, s12, 0x100
	s_addc_u32 s13, s13, 0
	s_cmp_gt_u32 s30, 29
	s_cbranch_scc0 .LBB0_702
	s_cmpk_lt_u32 s1, 0x100
	s_cbranch_scc0 .LBB0_705
	s_barrier

; #define PG8_STAGE(bufoff, gbase, voff) do { _Pragma("unroll") for (int _i = 0; _i < 2; ++_i) \
;         __builtin_amdgcn_global_load_lds((const unsigned*)((const char*)(gbase) + (voff)[_i]), (PG8_LAS unsigned*)(lds + (bufoff) + ldsw + _i * 8192), 16, 0, 0); } while (0)
; #define PG8_LDA(dst, b, h) do { _Pragma("unroll") for (int m = 0; m < 4; ++m) _Pragma("unroll") for (int k = 0; k < 2; ++k) dst[m][k] = *(const PG8_LAS bf16x8*)(lds + PG8_SA(b, h) + aoff + m * 2048 + k * 1024); } while (0)
; #define PG8_LDB(dst, b, h) do { _Pragma("unroll") for (int n = 0; n < 2; ++n) _Pragma("unroll") for (int k = 0; k < 2; ++k) dst[n][k] = *(const PG8_LAS bf16x8*)(lds + PG8_SB(b, h) + boff + n * 2048 + k * 1024); } while (0)
; #define PG8_MMA(ai, bj, At, Bt) do { __builtin_amdgcn_s_setprio(1); _Pragma("unroll") for (int m = 0; m < 4; ++m) _Pragma("unroll") for (int n = 0; n < 2; ++n) _Pragma("unroll") for (int k = 0; k < 2; ++k) \
;         acc[ai][bj][m][n] = __builtin_amdgcn_mfma_f32_16x16x32_bf16(Bt[n][k], At[m][k], acc[ai][bj][m][n], 0, 0, 0); __builtin_amdgcn_s_setprio(0); } while (0)
; #define PG8_WAIT_V(n) asm volatile("s_waitcnt vmcnt(" #n ")" ::: "memory")
; #define PG8_WAIT_L(n) asm volatile("s_waitcnt lgkmcnt(" #n ")" ::: "memory")
; #define PG8_BAR __builtin_amdgcn_s_barrier()
; #define PG8_SCHED __builtin_amdgcn_sched_barrier(0)
; template <class Epi, class Sched, bool ALIGN_EPI = false, bool SP2 = false>
; __device__ __forceinline__ void gemm_phase(PG8_LAS unsigned char* lds, const Gemm g, const Sched& S, const Epi& E) {
;     ...
;             const char* a1 = cA + (size_t)(t + 1) * kstep;
;             const char* a2 = last ? nA : cA + (size_t)(t + 2) * kstep; const char* b2 = last ? nB : cB + (size_t)(t + 2) * kstep;
;             const char* a3 = a2 + kstep; const char* b3 = b2 + kstep;
;             if (last && has_next) S.a_ready(nxt);
;             if constexpr (SP2) {
;             PG8_LDB(B0, 0, 0); PG8_LDB(B1, 0, 1); PG8_SCHED; PG8_LDA(At, 0, 0); PG8_STAGE(PG8_SA(1, 1), a1 + hstep, voffA);
;             PG8_WAIT_V(8); PG8_WAIT_L(0); PG8_BAR; PG8_MMA(0, 0, At, B0); PG8_MMA(0, 1, At, B1); PG8_BAR; PG8_SCHED;
;             PG8_LDA(At, 0, 1); PG8_STAGE(PG8_SB(0, 0), b2, voffB); PG8_STAGE(PG8_SB(0, 1), b2 + hstep, voffB); PG8_STAGE(PG8_SA(0, 0), a2, voffA);
.LBB0_782:
	s_add_u32 s1, s26, 0xfff80080
	s_addc_u32 s2, s27, -1
	s_add_i32 s3, 0, 0x10000
	s_cmpk_eq_i32 s28, 0x1e00
	s_cselect_b32 s35, s21, s2
	s_cselect_b32 s34, s50, s1
	v_add_u32_e32 v66, s3, v206
	s_cselect_b32 s31, s19, s53
	s_cselect_b32 s30, s51, s52
	s_add_i32 s1, 0, 0x14000
	ds_read_b128 v[152:155], v66
	ds_read_b128 v[156:159], v66 offset:1024
	ds_read_b128 v[160:163], v66 offset:2048
	ds_read_b128 v[164:167], v66 offset:3072
	v_add_u32_e32 v66, s1, v206
	ds_read_b128 v[168:171], v66
	ds_read_b128 v[172:175], v66 offset:1024
	ds_read_b128 v[176:179], v66 offset:2048
	ds_read_b128 v[180:183], v66 offset:3072
	v_lshl_add_u64 v[68:69], s[26:27], 0, v[142:143]
	s_add_i32 m0, s43, 0xc000
	ds_read_b128 v[184:187], v208
	ds_read_b128 v[188:191], v208 offset:1024
	ds_read_b128 v[192:195], v208 offset:2048
	ds_read_b128 v[196:199], v208 offset:3072
	ds_read_b128 v[200:203], v208 offset:4096
	ds_read_b128 v[220:223], v208 offset:5120
	ds_read_b128 v[224:227], v208 offset:6144
	ds_read_b128 v[228:231], v208 offset:7168
	global_load_lds_dwordx4 v[68:69], off
	v_lshl_add_u64 v[68:69], s[26:27], 0, v[144:145]
	s_add_i32 m0, s43, 0xe000
	s_nop 0
	global_load_lds_dwordx4 v[68:69], off
	s_setprio 1
	s_waitcnt vmcnt(8)
	s_waitcnt lgkmcnt(0)
	s_barrier
	v_mfma_f32_16x16x32_bf16 v[130:133], v[152:155], v[184:187], v[130:133]
	v_mfma_f32_16x16x32_bf16 v[126:129], v[160:163], v[184:187], v[126:129]
	v_mfma_f32_16x16x32_bf16 v[114:117], v[152:155], v[192:195], v[114:117]
	v_mfma_f32_16x16x32_bf16 v[110:113], v[160:163], v[192:195], v[110:113]
	v_mfma_f32_16x16x32_bf16 v[98:101], v[152:155], v[200:203], v[98:101]
	v_mfma_f32_16x16x32_bf16 v[94:97], v[160:163], v[200:203], v[94:97]
	v_mfma_f32_16x16x32_bf16 v[82:85], v[152:155], v[224:227], v[82:85]
	v_mfma_f32_16x16x32_bf16 v[78:81], v[160:163], v[224:227], v[78:81]
	v_mfma_f32_16x16x32_bf16 v[130:133], v[156:159], v[188:191], v[130:133]
	v_mfma_f32_16x16x32_bf16 v[126:129], v[164:167], v[188:191], v[126:129]
	v_mfma_f32_16x16x32_bf16 v[114:117], v[156:159], v[196:199], v[114:117]
	v_mfma_f32_16x16x32_bf16 v[110:113], v[164:167], v[196:199], v[110:113]
	v_mfma_f32_16x16x32_bf16 v[98:101], v[156:159], v[220:223], v[98:101]
	v_mfma_f32_16x16x32_bf16 v[94:97], v[164:167], v[220:223], v[94:97]
	v_mfma_f32_16x16x32_bf16 v[82:85], v[156:159], v[228:231], v[82:85]
	v_mfma_f32_16x16x32_bf16 v[78:81], v[164:167], v[228:231], v[78:81]
	v_mfma_f32_16x16x32_bf16 v[122:125], v[168:171], v[184:187], v[122:125]
	v_mfma_f32_16x16x32_bf16 v[118:121], v[176:179], v[184:187], v[118:121]
	v_mfma_f32_16x16x32_bf16 v[106:109], v[168:171], v[192:195], v[106:109]
	v_mfma_f32_16x16x32_bf16 v[102:105], v[176:179], v[192:195], v[102:105]
	v_mfma_f32_16x16x32_bf16 v[90:93], v[168:171], v[200:203], v[90:93]
	v_mfma_f32_16x16x32_bf16 v[86:89], v[176:179], v[200:203], v[86:89]
	v_mfma_f32_16x16x32_bf16 v[74:77], v[168:171], v[224:227], v[74:77]
	v_mfma_f32_16x16x32_bf16 v[68:71], v[176:179], v[224:227], v[70:73]
	v_mfma_f32_16x16x32_bf16 v[122:125], v[172:175], v[188:191], v[122:125]
	v_mfma_f32_16x16x32_bf16 v[118:121], v[180:183], v[188:191], v[118:121]
	v_mfma_f32_16x16x32_bf16 v[106:109], v[172:175], v[196:199], v[106:109]
	v_mfma_f32_16x16x32_bf16 v[102:105], v[180:183], v[196:199], v[102:105]
	v_mfma_f32_16x16x32_bf16 v[90:93], v[172:175], v[220:223], v[90:93]
	v_mfma_f32_16x16x32_bf16 v[86:89], v[180:183], v[220:223], v[86:89]
	v_mfma_f32_16x16x32_bf16 v[74:77], v[172:175], v[228:231], v[74:77]
	v_mfma_f32_16x16x32_bf16 v[68:71], v[180:183], v[228:231], v[68:71]
	s_barrier
	s_setprio 0
	s_setprio 1
	s_setprio 0
	s_waitcnt lgkmcnt(0)
	s_add_i32 s2, s3, s42
	v_lshl_add_u64 v[204:205], s[30:31], 0, v[138:139]
	s_mov_b32 m0, s2
	ds_read_b128 v[184:187], v208 offset:16384
	ds_read_b128 v[188:191], v208 offset:17408
	ds_read_b128 v[192:195], v208 offset:18432
	ds_read_b128 v[196:199], v208 offset:19456
	ds_read_b128 v[200:203], v208 offset:20480
	ds_read_b128 v[220:223], v208 offset:21504
	ds_read_b128 v[224:227], v208 offset:22528
	ds_read_b128 v[228:231], v208 offset:23552
	global_load_lds_dwordx4 v[204:205], off
	s_add_i32 m0, s2, 0x2000
	s_add_u32 s2, s30, 0x80000
	v_lshl_add_u64 v[210:211], s[30:31], 0, v[134:135]
	s_addc_u32 s3, s31, 0
	s_add_i32 s1, s1, s42
	global_load_lds_dwordx4 v[210:211], off
	v_lshl_add_u64 v[72:73], s[2:3], 0, v[138:139]
	s_mov_b32 m0, s1
	v_lshl_add_u64 v[232:233], s[34:35], 0, v[140:141]
	global_load_lds_dwordx4 v[72:73], off
	v_lshl_add_u64 v[72:73], s[2:3], 0, v[134:135]
	s_add_i32 m0, s1, 0x2000
	v_lshl_add_u64 v[234:235], s[34:35], 0, v[136:137]
	global_load_lds_dwordx4 v[72:73], off
	s_mov_b32 m0, s43
	s_nop 0
	global_load_lds_dwordx4 v[232:233], off
	s_mov_b32 m0, s44
	s_nop 0
	global_load_lds_dwordx4 v[234:235], off
	s_setprio 1
	s_waitcnt vmcnt(8)
	s_waitcnt lgkmcnt(0)
	s_barrier
; #define PG8_STAGE(bufoff, gbase, voff) do { _Pragma("unroll") for (int _i = 0; _i < 2; ++_i) \
;         __builtin_amdgcn_global_load_lds((const unsigned*)((const char*)(gbase) + (voff)[_i]), (PG8_LAS unsigned*)(lds + (bufoff) + ldsw + _i * 8192), 16, 0, 0); } while (0)
; #define PG8_LDA(dst, b, h) do { _Pragma("unroll") for (int m = 0; m < 4; ++m) _Pragma("unroll") for (int k = 0; k < 2; ++k) dst[m][k] = *(const PG8_LAS bf16x8*)(lds + PG8_SA(b, h) + aoff + m * 2048 + k * 1024); } while (0)
; #define PG8_LDB(dst, b, h) do { _Pragma("unroll") for (int n = 0; n < 2; ++n) _Pragma("unroll") for (int k = 0; k < 2; ++k) dst[n][k] = *(const PG8_LAS bf16x8*)(lds + PG8_SB(b, h) + boff + n * 2048 + k * 1024); } while (0)
; #define PG8_MMA(ai, bj, At, Bt) do { __builtin_amdgcn_s_setprio(1); _Pragma("unroll") for (int m = 0; m < 4; ++m) _Pragma("unroll") for (int n = 0; n < 2; ++n) _Pragma("unroll") for (int k = 0; k < 2; ++k) \
;         acc[ai][bj][m][n] = __builtin_amdgcn_mfma_f32_16x16x32_bf16(Bt[n][k], At[m][k], acc[ai][bj][m][n], 0, 0, 0); __builtin_amdgcn_s_setprio(0); } while (0)
; #define PG8_WAIT_V(n) asm volatile("s_waitcnt vmcnt(" #n ")" ::: "memory")
; #define PG8_WAIT_L(n) asm volatile("s_waitcnt lgkmcnt(" #n ")" ::: "memory")
; #define PG8_BAR __builtin_amdgcn_s_barrier()
; #define PG8_SCHED __builtin_amdgcn_sched_barrier(0)
; template <class Epi, class Sched, bool ALIGN_EPI = false, bool SP2 = false>
; __device__ __forceinline__ void gemm_phase(PG8_LAS unsigned char* lds, const Gemm g, const Sched& S, const Epi& E) {
;     ...
;             PG8_WAIT_V(8); PG8_WAIT_L(0); PG8_BAR; PG8_MMA(1, 0, At, B0); PG8_MMA(1, 1, At, B1); PG8_BAR; PG8_SCHED;
;             PG8_LDB(B0, 1, 0); PG8_LDB(B1, 1, 1); PG8_SCHED; PG8_LDA(At, 1, 0); PG8_STAGE(PG8_SA(0, 1), a2 + hstep, voffA);
;             PG8_WAIT_V(8); PG8_WAIT_L(0); PG8_BAR; PG8_MMA(0, 0, At, B0); PG8_MMA(0, 1, At, B1); PG8_BAR; PG8_SCHED;
	v_mfma_f32_16x16x32_bf16 v[62:65], v[152:155], v[184:187], v[62:65]
	v_mfma_f32_16x16x32_bf16 v[58:61], v[160:163], v[184:187], v[58:61]
	v_mfma_f32_16x16x32_bf16 v[46:49], v[152:155], v[192:195], v[46:49]
	v_mfma_f32_16x16x32_bf16 v[42:45], v[160:163], v[192:195], v[42:45]
	v_mfma_f32_16x16x32_bf16 v[30:33], v[152:155], v[200:203], v[30:33]
	v_mfma_f32_16x16x32_bf16 v[26:29], v[160:163], v[200:203], v[26:29]
	v_mfma_f32_16x16x32_bf16 v[14:17], v[152:155], v[224:227], v[14:17]
	v_mfma_f32_16x16x32_bf16 v[10:13], v[160:163], v[224:227], v[10:13]
	v_mfma_f32_16x16x32_bf16 v[62:65], v[156:159], v[188:191], v[62:65]
	v_mfma_f32_16x16x32_bf16 v[58:61], v[164:167], v[188:191], v[58:61]
	v_mfma_f32_16x16x32_bf16 v[46:49], v[156:159], v[196:199], v[46:49]
	v_mfma_f32_16x16x32_bf16 v[42:45], v[164:167], v[196:199], v[42:45]
	v_mfma_f32_16x16x32_bf16 v[30:33], v[156:159], v[220:223], v[30:33]
	v_mfma_f32_16x16x32_bf16 v[26:29], v[164:167], v[220:223], v[26:29]
	v_mfma_f32_16x16x32_bf16 v[14:17], v[156:159], v[228:231], v[14:17]
	v_mfma_f32_16x16x32_bf16 v[10:13], v[164:167], v[228:231], v[10:13]
	v_mfma_f32_16x16x32_bf16 v[54:57], v[168:171], v[184:187], v[54:57]
	v_mfma_f32_16x16x32_bf16 v[50:53], v[176:179], v[184:187], v[50:53]
	v_mfma_f32_16x16x32_bf16 v[38:41], v[168:171], v[192:195], v[38:41]
	v_mfma_f32_16x16x32_bf16 v[34:37], v[176:179], v[192:195], v[34:37]
	v_mfma_f32_16x16x32_bf16 v[22:25], v[168:171], v[200:203], v[22:25]
	v_mfma_f32_16x16x32_bf16 v[18:21], v[176:179], v[200:203], v[18:21]
	v_mfma_f32_16x16x32_bf16 v[6:9], v[168:171], v[224:227], v[6:9]
	v_mfma_f32_16x16x32_bf16 v[2:5], v[176:179], v[224:227], v[2:5]
	v_mfma_f32_16x16x32_bf16 v[54:57], v[172:175], v[188:191], v[54:57]
	v_mfma_f32_16x16x32_bf16 v[50:53], v[180:183], v[188:191], v[50:53]
	v_mfma_f32_16x16x32_bf16 v[38:41], v[172:175], v[196:199], v[38:41]
	v_mfma_f32_16x16x32_bf16 v[34:37], v[180:183], v[196:199], v[34:37]
	v_mfma_f32_16x16x32_bf16 v[22:25], v[172:175], v[220:223], v[22:25]
	v_mfma_f32_16x16x32_bf16 v[18:21], v[180:183], v[220:223], v[18:21]
	v_mfma_f32_16x16x32_bf16 v[6:9], v[172:175], v[228:231], v[6:9]
	v_mfma_f32_16x16x32_bf16 v[2:5], v[180:183], v[228:231], v[2:5]
	s_barrier
	s_setprio 0
	s_setprio 1
	s_setprio 0
	s_waitcnt lgkmcnt(0)
	s_add_i32 s1, 0, 0x18000
	v_add_u32_e32 v66, s1, v206
	s_add_i32 s55, 0, 0x1c000
	ds_read_b128 v[152:155], v66
	ds_read_b128 v[156:159], v66 offset:1024
	ds_read_b128 v[160:163], v66 offset:2048
	ds_read_b128 v[164:167], v66 offset:3072
	v_add_u32_e32 v66, s55, v206
	ds_read_b128 v[168:171], v66
	ds_read_b128 v[172:175], v66 offset:1024
	ds_read_b128 v[176:179], v66 offset:2048
	ds_read_b128 v[180:183], v66 offset:3072
	s_add_u32 s2, s34, 0x80000
	s_addc_u32 s3, s35, 0
	s_mov_b32 m0, s45
	v_lshl_add_u64 v[72:73], s[2:3], 0, v[140:141]
	ds_read_b128 v[184:187], v208 offset:32768
	ds_read_b128 v[188:191], v208 offset:33792
	ds_read_b128 v[192:195], v208 offset:34816
	ds_read_b128 v[196:199], v208 offset:35840
	ds_read_b128 v[200:203], v208 offset:36864
	ds_read_b128 v[220:223], v208 offset:37888
	ds_read_b128 v[224:227], v208 offset:38912
	ds_read_b128 v[228:231], v208 offset:39936
	global_load_lds_dwordx4 v[72:73], off
	v_lshl_add_u64 v[72:73], s[2:3], 0, v[136:137]
	s_mov_b32 m0, s46
	s_nop 0
	global_load_lds_dwordx4 v[72:73], off
	s_setprio 1
	s_waitcnt vmcnt(8)
	s_waitcnt lgkmcnt(0)
	s_barrier
	v_mfma_f32_16x16x32_bf16 v[130:133], v[152:155], v[184:187], v[130:133]
	v_mfma_f32_16x16x32_bf16 v[126:129], v[160:163], v[184:187], v[126:129]
	v_mfma_f32_16x16x32_bf16 v[114:117], v[152:155], v[192:195], v[114:117]
	v_mfma_f32_16x16x32_bf16 v[110:113], v[160:163], v[192:195], v[110:113]
	v_mfma_f32_16x16x32_bf16 v[98:101], v[152:155], v[200:203], v[98:101]
	v_mfma_f32_16x16x32_bf16 v[94:97], v[160:163], v[200:203], v[94:97]
	v_mfma_f32_16x16x32_bf16 v[82:85], v[152:155], v[224:227], v[82:85]
	v_mfma_f32_16x16x32_bf16 v[78:81], v[160:163], v[224:227], v[78:81]
	v_mfma_f32_16x16x32_bf16 v[130:133], v[156:159], v[188:191], v[130:133]
	v_mfma_f32_16x16x32_bf16 v[126:129], v[164:167], v[188:191], v[126:129]
	v_mfma_f32_16x16x32_bf16 v[114:117], v[156:159], v[196:199], v[114:117]
	v_mfma_f32_16x16x32_bf16 v[110:113], v[164:167], v[196:199], v[110:113]
	v_mfma_f32_16x16x32_bf16 v[98:101], v[156:159], v[220:223], v[98:101]
	v_mfma_f32_16x16x32_bf16 v[94:97], v[164:167], v[220:223], v[94:97]
	v_mfma_f32_16x16x32_bf16 v[82:85], v[156:159], v[228:231], v[82:85]
	v_mfma_f32_16x16x32_bf16 v[78:81], v[164:167], v[228:231], v[78:81]
	v_mfma_f32_16x16x32_bf16 v[122:125], v[168:171], v[184:187], v[122:125]
	v_mfma_f32_16x16x32_bf16 v[118:121], v[176:179], v[184:187], v[118:121]
	v_mfma_f32_16x16x32_bf16 v[106:109], v[168:171], v[192:195], v[106:109]
	v_mfma_f32_16x16x32_bf16 v[102:105], v[176:179], v[192:195], v[102:105]
	v_mfma_f32_16x16x32_bf16 v[90:93], v[168:171], v[200:203], v[90:93]
	v_mfma_f32_16x16x32_bf16 v[86:89], v[176:179], v[200:203], v[86:89]
	v_mfma_f32_16x16x32_bf16 v[72:75], v[168:171], v[224:227], v[74:77]
	v_mfma_f32_16x16x32_bf16 v[68:71], v[176:179], v[224:227], v[68:71]
	v_mfma_f32_16x16x32_bf16 v[122:125], v[172:175], v[188:191], v[122:125]
	v_mfma_f32_16x16x32_bf16 v[118:121], v[180:183], v[188:191], v[118:121]
	v_mfma_f32_16x16x32_bf16 v[106:109], v[172:175], v[196:199], v[106:109]
	v_mfma_f32_16x16x32_bf16 v[102:105], v[180:183], v[196:199], v[102:105]
	v_mfma_f32_16x16x32_bf16 v[90:93], v[172:175], v[220:223], v[90:93]
	v_mfma_f32_16x16x32_bf16 v[86:89], v[180:183], v[220:223], v[86:89]
	v_mfma_f32_16x16x32_bf16 v[74:77], v[172:175], v[228:231], v[72:75]
	v_mfma_f32_16x16x32_bf16 v[70:73], v[180:183], v[228:231], v[68:71]
	s_barrier
; #define PG8_STAGE(bufoff, gbase, voff) do { _Pragma("unroll") for (int _i = 0; _i < 2; ++_i) \
;         __builtin_amdgcn_global_load_lds((const unsigned*)((const char*)(gbase) + (voff)[_i]), (PG8_LAS unsigned*)(lds + (bufoff) + ldsw + _i * 8192), 16, 0, 0); } while (0)
; #define PG8_LDA(dst, b, h) do { _Pragma("unroll") for (int m = 0; m < 4; ++m) _Pragma("unroll") for (int k = 0; k < 2; ++k) dst[m][k] = *(const PG8_LAS bf16x8*)(lds + PG8_SA(b, h) + aoff + m * 2048 + k * 1024); } while (0)
; #define PG8_MMA(ai, bj, At, Bt) do { __builtin_amdgcn_s_setprio(1); _Pragma("unroll") for (int m = 0; m < 4; ++m) _Pragma("unroll") for (int n = 0; n < 2; ++n) _Pragma("unroll") for (int k = 0; k < 2; ++k) \
;         acc[ai][bj][m][n] = __builtin_amdgcn_mfma_f32_16x16x32_bf16(Bt[n][k], At[m][k], acc[ai][bj][m][n], 0, 0, 0); __builtin_amdgcn_s_setprio(0); } while (0)
; #define PG8_WAIT_V(n) asm volatile("s_waitcnt vmcnt(" #n ")" ::: "memory")
; #define PG8_WAIT_L(n) asm volatile("s_waitcnt lgkmcnt(" #n ")" ::: "memory")
; #define PG8_BAR __builtin_amdgcn_s_barrier()
; #define PG8_SCHED __builtin_amdgcn_sched_barrier(0)
;     __device__ __forceinline__ void mid(f32x4 (&acc)[2][2][4][2], const Unit& u, int seg, int wr, int wc, int fr, int fq) const {
;     ...
;             for (int m = 0; m < 4; ++m) { const unsigned char* rowp = G + (size_t)(row0 + ai * HALF + m * 16) * 8192 + col0 + seg * 2048;
; #pragma unroll
;                 for (int bj = 0; bj < 2; ++bj) { ga[ai][m][bj] = *(const u32x2v*)(rowp + bj * HALF); gb[ai][m][bj] = *(const u32x2v*)(rowp + 2048 + bj * HALF); } }
; template <class Epi, class Sched, bool ALIGN_EPI = false, bool SP2 = false>
; __device__ __forceinline__ void gemm_phase(PG8_LAS unsigned char* lds, const Gemm g, const Sched& S, const Epi& E) {
;     ...
;             PG8_LDA(At, 1, 1); PG8_STAGE(PG8_SB(1, 0), b3, voffB); PG8_STAGE(PG8_SB(1, 1), b3 + hstep, voffB); PG8_STAGE(PG8_SA(1, 0), a3, voffA);
;             PG8_WAIT_V(8); PG8_WAIT_L(0); PG8_BAR; PG8_MMA(1, 0, At, B0); PG8_MMA(1, 1, At, B1); PG8_BAR; PG8_SCHED;
	s_setprio 0
	s_setprio 1
	s_setprio 0
	s_waitcnt lgkmcnt(0)
	s_add_i32 s1, s1, s42
	v_lshl_add_u64 v[68:69], v[204:205], 0, s[88:89]
	s_mov_b32 m0, s1
	ds_read_b128 v[184:187], v208 offset:49152
	ds_read_b128 v[188:191], v208 offset:50176
	ds_read_b128 v[192:195], v208 offset:51200
	ds_read_b128 v[196:199], v208 offset:52224
	ds_read_b128 v[200:203], v208 offset:53248
	ds_read_b128 v[220:223], v208 offset:54272
	ds_read_b128 v[224:227], v208 offset:55296
	ds_read_b128 v[228:231], v208 offset:56320
	global_load_lds_dwordx4 v[68:69], off
	s_add_i32 m0, s1, 0x2000
	s_add_u32 s2, s30, 0x80080
	v_lshl_add_u64 v[68:69], v[210:211], 0, s[88:89]
	s_addc_u32 s3, s31, 0
	s_add_i32 s1, s55, s42
	global_load_lds_dwordx4 v[68:69], off
	v_lshl_add_u64 v[68:69], s[2:3], 0, v[138:139]
	s_mov_b32 m0, s1
	s_nop 0
	global_load_lds_dwordx4 v[68:69], off
	v_lshl_add_u64 v[68:69], s[2:3], 0, v[134:135]
	s_add_i32 m0, s1, 0x2000
	s_nop 0
	global_load_lds_dwordx4 v[68:69], off
	v_lshl_add_u64 v[68:69], v[232:233], 0, s[88:89]
	s_mov_b32 m0, s47
	s_nop 0
	global_load_lds_dwordx4 v[68:69], off
	v_lshl_add_u64 v[68:69], v[234:235], 0, s[88:89]
	s_mov_b32 m0, s48
	s_nop 0
	global_load_lds_dwordx4 v[68:69], off
	s_setprio 1
	s_waitcnt vmcnt(8)
	s_waitcnt lgkmcnt(0)
	s_barrier
	v_mfma_f32_16x16x32_bf16 v[62:65], v[152:155], v[184:187], v[62:65]
	v_mfma_f32_16x16x32_bf16 v[58:61], v[160:163], v[184:187], v[58:61]
	v_mfma_f32_16x16x32_bf16 v[46:49], v[152:155], v[192:195], v[46:49]
	v_mfma_f32_16x16x32_bf16 v[42:45], v[160:163], v[192:195], v[42:45]
	v_mfma_f32_16x16x32_bf16 v[30:33], v[152:155], v[200:203], v[30:33]
	v_mfma_f32_16x16x32_bf16 v[26:29], v[160:163], v[200:203], v[26:29]
	v_mfma_f32_16x16x32_bf16 v[14:17], v[152:155], v[224:227], v[14:17]
	v_mfma_f32_16x16x32_bf16 v[10:13], v[160:163], v[224:227], v[10:13]
	v_mfma_f32_16x16x32_bf16 v[62:65], v[156:159], v[188:191], v[62:65]
	v_mfma_f32_16x16x32_bf16 v[58:61], v[164:167], v[188:191], v[58:61]
	v_mfma_f32_16x16x32_bf16 v[46:49], v[156:159], v[196:199], v[46:49]
	v_mfma_f32_16x16x32_bf16 v[42:45], v[164:167], v[196:199], v[42:45]
	v_mfma_f32_16x16x32_bf16 v[30:33], v[156:159], v[220:223], v[30:33]
	v_mfma_f32_16x16x32_bf16 v[26:29], v[164:167], v[220:223], v[26:29]
	v_mfma_f32_16x16x32_bf16 v[14:17], v[156:159], v[228:231], v[14:17]
	v_mfma_f32_16x16x32_bf16 v[10:13], v[164:167], v[228:231], v[10:13]
	v_mfma_f32_16x16x32_bf16 v[54:57], v[168:171], v[184:187], v[54:57]
	v_mfma_f32_16x16x32_bf16 v[50:53], v[176:179], v[184:187], v[50:53]
	v_mfma_f32_16x16x32_bf16 v[38:41], v[168:171], v[192:195], v[38:41]
	v_mfma_f32_16x16x32_bf16 v[34:37], v[176:179], v[192:195], v[34:37]
	v_mfma_f32_16x16x32_bf16 v[22:25], v[168:171], v[200:203], v[22:25]
	v_mfma_f32_16x16x32_bf16 v[18:21], v[176:179], v[200:203], v[18:21]
	v_mfma_f32_16x16x32_bf16 v[6:9], v[168:171], v[224:227], v[6:9]
	v_mfma_f32_16x16x32_bf16 v[2:5], v[176:179], v[224:227], v[2:5]
	v_mfma_f32_16x16x32_bf16 v[54:57], v[172:175], v[188:191], v[54:57]
	v_mfma_f32_16x16x32_bf16 v[50:53], v[180:183], v[188:191], v[50:53]
	v_mfma_f32_16x16x32_bf16 v[38:41], v[172:175], v[196:199], v[38:41]
	v_mfma_f32_16x16x32_bf16 v[34:37], v[180:183], v[196:199], v[34:37]
	v_mfma_f32_16x16x32_bf16 v[22:25], v[172:175], v[220:223], v[22:25]
	v_mfma_f32_16x16x32_bf16 v[18:21], v[180:183], v[220:223], v[18:21]
	v_mfma_f32_16x16x32_bf16 v[6:9], v[172:175], v[228:231], v[6:9]
	v_mfma_f32_16x16x32_bf16 v[2:5], v[180:183], v[228:231], v[2:5]
	s_barrier
	s_setprio 0
	s_setprio 1
	s_setprio 0
	s_waitcnt lgkmcnt(0)
	s_mov_b32 s1, s54
	s_add_i32 s54, s54, 2
	s_and_b32 s2, s54, 6
	s_cmp_eq_u32 s2, 0
	s_cselect_b64 s[2:3], -1, 0
	s_cmp_gt_u32 s1, 29
	s_cselect_b64 s[30:31], -1, 0
	s_cmp_lt_u32 s1, 30
	s_cselect_b64 s[34:35], -1, 0
	s_and_b64 s[2:3], s[2:3], s[34:35]
	s_andn2_b64 vcc, exec, s[2:3]
	s_cbranch_vccnz .LBB0_781
	v_mov_b32_e32 v68, v148
	s_nop 0
	v_ashrrev_i32_e32 v69, 31, v68
	v_lshlrev_b64 v[68:69], 13, v[68:69]
	v_lshl_add_u64 v[68:69], s[28:29], 0, v[68:69]
	v_lshl_add_u64 v[68:69], v[150:151], 0, v[68:69]
	v_add_co_u32_e32 v152, vcc, 0xcbff000, v68
	s_nop 1
	v_addc_co_u32_e32 v153, vcc, 0, v69, vcc
	v_add_co_u32_e32 v154, vcc, 0xcc00000, v68
	s_nop 1
	v_addc_co_u32_e32 v155, vcc, 0, v69, vcc
	global_load_dwordx2 v[210:211], v[152:153], off offset:2560
	global_load_dwordx2 v[220:221], v[154:155], off offset:512
	global_load_dwordx2 v[222:223], v[154:155], off offset:640
	global_load_dwordx2 v[224:225], v[152:153], off offset:2688
	v_add_co_u32_e32 v152, vcc, 0xcc1f000, v68
	s_nop 1
	v_addc_co_u32_e32 v153, vcc, 0, v69, vcc
	v_add_co_u32_e32 v154, vcc, 0xcc20000, v68
	s_nop 0
	s_nop 0
	v_addc_co_u32_e32 v155, vcc, 0, v69, vcc
	global_load_dwordx2 v[202:203], v[152:153], off offset:2560
	global_load_dwordx2 v[204:205], v[154:155], off offset:512
	global_load_dwordx2 v[200:201], v[154:155], off offset:640
	global_load_dwordx2 v[198:199], v[152:153], off offset:2688
	v_add_co_u32_e32 v152, vcc, 0xcc3f000, v68
	s_nop 0
	s_nop 0
	v_addc_co_u32_e32 v153, vcc, 0, v69, vcc
	v_add_co_u32_e32 v154, vcc, 0xcc40000, v68
	s_nop 0
	s_nop 0
	v_addc_co_u32_e32 v155, vcc, 0, v69, vcc
	global_load_dwordx2 v[194:195], v[152:153], off offset:2560
	global_load_dwordx2 v[196:197], v[154:155], off offset:512
	global_load_dwordx2 v[192:193], v[154:155], off offset:640
	global_load_dwordx2 v[190:191], v[152:153], off offset:2688
	v_add_co_u32_e32 v152, vcc, 0xcc5f000, v68
	s_nop 0
	s_nop 0
	v_addc_co_u32_e32 v153, vcc, 0, v69, vcc
	v_add_co_u32_e32 v154, vcc, 0xcc60000, v68
	s_nop 1
	v_addc_co_u32_e32 v155, vcc, 0, v69, vcc
	global_load_dwordx2 v[186:187], v[152:153], off offset:2560
; __device__ __forceinline__ float gate_v(unsigned q) { return (float)q; }
;     __device__ __forceinline__ void mid(f32x4 (&acc)[2][2][4][2], const Unit& u, int seg, int wr, int wc, int fr, int fq) const {
;     ...
;             for (int m = 0; m < 4; ++m) { const unsigned char* rowp = G + (size_t)(row0 + ai * HALF + m * 16) * 8192 + col0 + seg * 2048;
; #pragma unroll
;                 for (int bj = 0; bj < 2; ++bj) { ga[ai][m][bj] = *(const u32x2v*)(rowp + bj * HALF); gb[ai][m][bj] = *(const u32x2v*)(rowp + 2048 + bj * HALF); } }
; #pragma unroll
;         for (int ai = 0; ai < 2; ++ai)
; #pragma unroll
;             for (int m = 0; m < 4; ++m)
; #pragma unroll
;                 for (int bj = 0; bj < 2; ++bj)
; #pragma unroll
;                     for (int e = 0; e < 8; ++e) { const unsigned a = (ga[ai][m][bj][e >> 2] >> (8 * (e & 3))) & 255u, b = (gb[ai][m][bj][e >> 2] >> (8 * (e & 3))) & 255u;
;                         acc[ai][bj][m][e >> 2][e & 3] *= gate_v(a) * __builtin_amdgcn_rcpf(gate_v(b)); }
	global_load_dwordx2 v[188:189], v[154:155], off offset:512
	global_load_dwordx2 v[184:185], v[154:155], off offset:640
	global_load_dwordx2 v[182:183], v[152:153], off offset:2688
	v_add_co_u32_e32 v152, vcc, 0xccff000, v68
	s_nop 1
	v_addc_co_u32_e32 v153, vcc, 0, v69, vcc
	v_add_co_u32_e32 v154, vcc, 0xcd00000, v68
	s_nop 1
	v_addc_co_u32_e32 v155, vcc, 0, v69, vcc
	global_load_dwordx2 v[178:179], v[152:153], off offset:2560
	global_load_dwordx2 v[180:181], v[154:155], off offset:512
	global_load_dwordx2 v[176:177], v[154:155], off offset:640
	global_load_dwordx2 v[174:175], v[152:153], off offset:2688
	v_add_co_u32_e32 v152, vcc, 0xcd1f000, v68
	s_nop 1
	v_addc_co_u32_e32 v153, vcc, 0, v69, vcc
	v_add_co_u32_e32 v154, vcc, 0xcd20000, v68
	s_nop 1
	v_addc_co_u32_e32 v155, vcc, 0, v69, vcc
	global_load_dwordx2 v[170:171], v[152:153], off offset:2560
	global_load_dwordx2 v[172:173], v[154:155], off offset:512
	global_load_dwordx2 v[168:169], v[154:155], off offset:640
	global_load_dwordx2 v[166:167], v[152:153], off offset:2688
	v_add_co_u32_e32 v152, vcc, 0xcd3f000, v68
	s_nop 1
	v_addc_co_u32_e32 v153, vcc, 0, v69, vcc
	v_add_co_u32_e32 v154, vcc, 0xcd40000, v68
	s_nop 1
	v_addc_co_u32_e32 v155, vcc, 0, v69, vcc
	v_add_co_u32_e32 v226, vcc, 0xcd5f000, v68
	global_load_dwordx2 v[162:163], v[152:153], off offset:2560
	global_load_dwordx2 v[164:165], v[154:155], off offset:512
	global_load_dwordx2 v[160:161], v[154:155], off offset:640
	global_load_dwordx2 v[158:159], v[152:153], off offset:2688
	v_addc_co_u32_e32 v227, vcc, 0, v69, vcc
	v_add_co_u32_e32 v68, vcc, 0xcd60000, v68
	s_nop 1
	v_addc_co_u32_e32 v69, vcc, 0, v69, vcc
	global_load_dwordx2 v[154:155], v[226:227], off offset:2560
	global_load_dwordx2 v[156:157], v[68:69], off offset:512
	global_load_dwordx2 v[152:153], v[68:69], off offset:640
	s_nop 0
	global_load_dwordx2 v[68:69], v[226:227], off offset:2688
	s_waitcnt vmcnt(28)
	v_cvt_f32_ubyte1_e32 v233, v210
	v_cvt_f32_ubyte0_e32 v66, v220
	v_cvt_f32_ubyte0_e32 v232, v210
	v_cvt_f32_ubyte3_e32 v231, v210
	v_cvt_f32_ubyte2_e32 v230, v210
	v_rcp_iflag_f32_e32 v226, v66
	v_cvt_f32_ubyte1_e32 v66, v220
	v_rcp_iflag_f32_e32 v227, v66
	v_cvt_f32_ubyte2_e32 v66, v220
	v_rcp_iflag_f32_e32 v228, v66
	v_cvt_f32_ubyte3_e32 v66, v220
	v_rcp_iflag_f32_e32 v229, v66
	v_pk_mul_f32 v[226:227], v[226:227], v[232:233]
	v_cvt_f32_ubyte0_e32 v66, v221
	v_pk_mul_f32 v[130:131], v[130:131], v[226:227]
	v_rcp_iflag_f32_e32 v226, v66
	v_cvt_f32_ubyte1_e32 v66, v221
	v_rcp_iflag_f32_e32 v227, v66
	v_cvt_f32_ubyte2_e32 v66, v221
	v_pk_mul_f32 v[228:229], v[228:229], v[230:231]
	v_rcp_iflag_f32_e32 v220, v66
	v_cvt_f32_ubyte3_e32 v66, v221
	v_cvt_f32_ubyte1_e32 v231, v211
	v_cvt_f32_ubyte0_e32 v230, v211
	v_pk_mul_f32 v[132:133], v[132:133], v[228:229]
	v_rcp_iflag_f32_e32 v221, v66
	v_cvt_f32_ubyte3_e32 v229, v211
	v_cvt_f32_ubyte2_e32 v228, v211
	v_pk_mul_f32 v[210:211], v[226:227], v[230:231]
	v_cvt_f32_ubyte0_e32 v66, v222
	v_pk_mul_f32 v[126:127], v[126:127], v[210:211]
	v_rcp_iflag_f32_e32 v210, v66
	v_cvt_f32_ubyte1_e32 v66, v222
	v_rcp_iflag_f32_e32 v211, v66
	v_pk_mul_f32 v[220:221], v[220:221], v[228:229]
	v_cvt_f32_ubyte2_e32 v66, v222
	v_pk_mul_f32 v[128:129], v[128:129], v[220:221]
	v_rcp_iflag_f32_e32 v220, v66
	v_cvt_f32_ubyte3_e32 v66, v222
	v_cvt_f32_ubyte1_e32 v229, v224
	v_cvt_f32_ubyte0_e32 v228, v224
	v_rcp_iflag_f32_e32 v221, v66
	v_pk_mul_f32 v[210:211], v[210:211], v[228:229]
	v_cvt_f32_ubyte0_e32 v66, v223
	v_pk_mul_f32 v[122:123], v[122:123], v[210:211]
	v_rcp_iflag_f32_e32 v210, v66
	v_cvt_f32_ubyte1_e32 v66, v223
	v_rcp_iflag_f32_e32 v211, v66
	v_cvt_f32_ubyte3_e32 v227, v224
	v_cvt_f32_ubyte2_e32 v226, v224
	v_pk_mul_f32 v[220:221], v[220:221], v[226:227]
	v_cvt_f32_ubyte2_e32 v66, v223
	v_pk_mul_f32 v[124:125], v[124:125], v[220:221]
	v_rcp_iflag_f32_e32 v220, v66
	v_cvt_f32_ubyte3_e32 v66, v223
	v_cvt_f32_ubyte1_e32 v227, v225
	v_cvt_f32_ubyte0_e32 v226, v225
	v_rcp_iflag_f32_e32 v221, v66
	v_pk_mul_f32 v[210:211], v[210:211], v[226:227]
	s_waitcnt vmcnt(26)
	v_cvt_f32_ubyte0_e32 v66, v204
	v_pk_mul_f32 v[118:119], v[118:119], v[210:211]
	v_rcp_iflag_f32_e32 v210, v66
	v_cvt_f32_ubyte1_e32 v66, v204
	v_rcp_iflag_f32_e32 v211, v66
	v_cvt_f32_ubyte3_e32 v223, v225
	v_cvt_f32_ubyte2_e32 v222, v225
	v_pk_mul_f32 v[220:221], v[220:221], v[222:223]
	v_cvt_f32_ubyte2_e32 v66, v204
	v_pk_mul_f32 v[120:121], v[120:121], v[220:221]
	v_rcp_iflag_f32_e32 v220, v66
	v_cvt_f32_ubyte3_e32 v66, v204
	v_cvt_f32_ubyte1_e32 v225, v202
	v_cvt_f32_ubyte0_e32 v224, v202
	v_rcp_iflag_f32_e32 v221, v66
	v_pk_mul_f32 v[210:211], v[210:211], v[224:225]
	v_cvt_f32_ubyte0_e32 v66, v205
	v_pk_mul_f32 v[114:115], v[114:115], v[210:211]
	v_rcp_iflag_f32_e32 v210, v66
	v_cvt_f32_ubyte1_e32 v66, v205
	v_rcp_iflag_f32_e32 v211, v66
	v_cvt_f32_ubyte3_e32 v223, v202
	v_cvt_f32_ubyte2_e32 v222, v202
	v_cvt_f32_ubyte2_e32 v66, v205
	v_pk_mul_f32 v[220:221], v[220:221], v[222:223]
	v_rcp_iflag_f32_e32 v204, v66
	v_cvt_f32_ubyte3_e32 v66, v205
	v_cvt_f32_ubyte1_e32 v223, v203
	v_cvt_f32_ubyte0_e32 v222, v203
	v_pk_mul_f32 v[116:117], v[116:117], v[220:221]
	v_rcp_iflag_f32_e32 v205, v66
	v_cvt_f32_ubyte3_e32 v221, v203
	v_cvt_f32_ubyte2_e32 v220, v203
	v_pk_mul_f32 v[202:203], v[210:211], v[222:223]
	s_waitcnt vmcnt(25)
	v_cvt_f32_ubyte0_e32 v66, v200
	v_pk_mul_f32 v[110:111], v[110:111], v[202:203]
	v_rcp_iflag_f32_e32 v202, v66
	v_cvt_f32_ubyte1_e32 v66, v200
	v_rcp_iflag_f32_e32 v203, v66
	v_pk_mul_f32 v[204:205], v[204:205], v[220:221]
	v_cvt_f32_ubyte2_e32 v66, v200
	v_pk_mul_f32 v[112:113], v[112:113], v[204:205]
	v_rcp_iflag_f32_e32 v204, v66
	v_cvt_f32_ubyte3_e32 v66, v200
	s_waitcnt vmcnt(24)
; __device__ __forceinline__ float gate_v(unsigned q) { return (float)q; }
;     __device__ __forceinline__ void mid(f32x4 (&acc)[2][2][4][2], const Unit& u, int seg, int wr, int wc, int fr, int fq) const {
;     ...
;         for (int ai = 0; ai < 2; ++ai)
; #pragma unroll
;             for (int m = 0; m < 4; ++m)
; #pragma unroll
;                 for (int bj = 0; bj < 2; ++bj)
; #pragma unroll
;                     for (int e = 0; e < 8; ++e) { const unsigned a = (ga[ai][m][bj][e >> 2] >> (8 * (e & 3))) & 255u, b = (gb[ai][m][bj][e >> 2] >> (8 * (e & 3))) & 255u;
;                         acc[ai][bj][m][e >> 2][e & 3] *= gate_v(a) * __builtin_amdgcn_rcpf(gate_v(b)); }
	v_cvt_f32_ubyte1_e32 v221, v198
	v_cvt_f32_ubyte0_e32 v220, v198
	v_rcp_iflag_f32_e32 v205, v66
	v_pk_mul_f32 v[202:203], v[202:203], v[220:221]
	v_cvt_f32_ubyte0_e32 v66, v201
	v_pk_mul_f32 v[106:107], v[106:107], v[202:203]
	v_rcp_iflag_f32_e32 v202, v66
	v_cvt_f32_ubyte1_e32 v66, v201
	v_rcp_iflag_f32_e32 v203, v66
	v_cvt_f32_ubyte3_e32 v211, v198
	v_cvt_f32_ubyte2_e32 v210, v198
	v_cvt_f32_ubyte2_e32 v66, v201
	v_pk_mul_f32 v[204:205], v[204:205], v[210:211]
	v_rcp_iflag_f32_e32 v200, v66
	v_cvt_f32_ubyte3_e32 v66, v201
	v_cvt_f32_ubyte1_e32 v211, v199
	v_cvt_f32_ubyte0_e32 v210, v199
	v_pk_mul_f32 v[108:109], v[108:109], v[204:205]
	v_rcp_iflag_f32_e32 v201, v66
	v_cvt_f32_ubyte3_e32 v205, v199
	v_cvt_f32_ubyte2_e32 v204, v199
	v_pk_mul_f32 v[198:199], v[202:203], v[210:211]
	s_waitcnt vmcnt(22)
	v_cvt_f32_ubyte0_e32 v66, v196
	v_pk_mul_f32 v[102:103], v[102:103], v[198:199]
	v_rcp_iflag_f32_e32 v198, v66
	v_cvt_f32_ubyte1_e32 v66, v196
	v_rcp_iflag_f32_e32 v199, v66
	v_pk_mul_f32 v[200:201], v[200:201], v[204:205]
	v_cvt_f32_ubyte2_e32 v66, v196
	v_pk_mul_f32 v[104:105], v[104:105], v[200:201]
	v_rcp_iflag_f32_e32 v200, v66
	v_cvt_f32_ubyte3_e32 v66, v196
	v_cvt_f32_ubyte1_e32 v205, v194
	v_cvt_f32_ubyte0_e32 v204, v194
	v_rcp_iflag_f32_e32 v201, v66
	v_pk_mul_f32 v[198:199], v[198:199], v[204:205]
	v_cvt_f32_ubyte0_e32 v66, v197
	v_pk_mul_f32 v[98:99], v[98:99], v[198:199]
	v_rcp_iflag_f32_e32 v198, v66
	v_cvt_f32_ubyte1_e32 v66, v197
	v_rcp_iflag_f32_e32 v199, v66
	v_cvt_f32_ubyte3_e32 v203, v194
	v_cvt_f32_ubyte2_e32 v202, v194
	v_cvt_f32_ubyte2_e32 v66, v197
	v_pk_mul_f32 v[200:201], v[200:201], v[202:203]
	v_rcp_iflag_f32_e32 v196, v66
	v_cvt_f32_ubyte3_e32 v66, v197
	v_cvt_f32_ubyte1_e32 v203, v195
	v_cvt_f32_ubyte0_e32 v202, v195
	v_pk_mul_f32 v[100:101], v[100:101], v[200:201]
	v_rcp_iflag_f32_e32 v197, v66
	v_cvt_f32_ubyte3_e32 v201, v195
	v_cvt_f32_ubyte2_e32 v200, v195
	v_pk_mul_f32 v[194:195], v[198:199], v[202:203]
	s_waitcnt vmcnt(21)
	v_cvt_f32_ubyte0_e32 v66, v192
	v_pk_mul_f32 v[94:95], v[94:95], v[194:195]
	v_rcp_iflag_f32_e32 v194, v66
	v_cvt_f32_ubyte1_e32 v66, v192
	v_rcp_iflag_f32_e32 v195, v66
	v_pk_mul_f32 v[196:197], v[196:197], v[200:201]
	v_cvt_f32_ubyte2_e32 v66, v192
	v_pk_mul_f32 v[96:97], v[96:97], v[196:197]
	v_rcp_iflag_f32_e32 v196, v66
	v_cvt_f32_ubyte3_e32 v66, v192
	s_waitcnt vmcnt(20)
	v_cvt_f32_ubyte1_e32 v201, v190
	v_cvt_f32_ubyte0_e32 v200, v190
	v_rcp_iflag_f32_e32 v197, v66
	v_pk_mul_f32 v[194:195], v[194:195], v[200:201]
	v_cvt_f32_ubyte0_e32 v66, v193
	v_pk_mul_f32 v[90:91], v[90:91], v[194:195]
	v_rcp_iflag_f32_e32 v194, v66
	v_cvt_f32_ubyte1_e32 v66, v193
	v_rcp_iflag_f32_e32 v195, v66
	v_cvt_f32_ubyte3_e32 v199, v190
	v_cvt_f32_ubyte2_e32 v198, v190
	v_cvt_f32_ubyte2_e32 v66, v193
	v_pk_mul_f32 v[196:197], v[196:197], v[198:199]
	v_rcp_iflag_f32_e32 v192, v66
	v_cvt_f32_ubyte3_e32 v66, v193
	v_cvt_f32_ubyte1_e32 v199, v191
	v_cvt_f32_ubyte0_e32 v198, v191
	v_pk_mul_f32 v[92:93], v[92:93], v[196:197]
	v_rcp_iflag_f32_e32 v193, v66
	v_cvt_f32_ubyte3_e32 v197, v191
	v_cvt_f32_ubyte2_e32 v196, v191
	v_pk_mul_f32 v[190:191], v[194:195], v[198:199]
	s_waitcnt vmcnt(18)
	v_cvt_f32_ubyte0_e32 v66, v188
	v_pk_mul_f32 v[86:87], v[86:87], v[190:191]
	v_rcp_iflag_f32_e32 v190, v66
	v_cvt_f32_ubyte1_e32 v66, v188
	v_rcp_iflag_f32_e32 v191, v66
	v_pk_mul_f32 v[192:193], v[192:193], v[196:197]
	v_cvt_f32_ubyte2_e32 v66, v188
	v_pk_mul_f32 v[88:89], v[88:89], v[192:193]
	v_rcp_iflag_f32_e32 v192, v66
	v_cvt_f32_ubyte3_e32 v66, v188
	v_cvt_f32_ubyte1_e32 v197, v186
	v_cvt_f32_ubyte0_e32 v196, v186
	v_rcp_iflag_f32_e32 v193, v66
	v_pk_mul_f32 v[190:191], v[190:191], v[196:197]
	v_cvt_f32_ubyte0_e32 v66, v189
	v_pk_mul_f32 v[82:83], v[82:83], v[190:191]
	v_rcp_iflag_f32_e32 v190, v66
	v_cvt_f32_ubyte1_e32 v66, v189
	v_rcp_iflag_f32_e32 v191, v66
	v_cvt_f32_ubyte3_e32 v195, v186
	v_cvt_f32_ubyte2_e32 v194, v186
	v_cvt_f32_ubyte2_e32 v66, v189
	v_pk_mul_f32 v[192:193], v[192:193], v[194:195]
	v_rcp_iflag_f32_e32 v188, v66
	v_cvt_f32_ubyte3_e32 v66, v189
	v_cvt_f32_ubyte1_e32 v195, v187
	v_cvt_f32_ubyte0_e32 v194, v187
	v_pk_mul_f32 v[84:85], v[84:85], v[192:193]
	v_rcp_iflag_f32_e32 v189, v66
	v_cvt_f32_ubyte3_e32 v193, v187
	v_cvt_f32_ubyte2_e32 v192, v187
	v_pk_mul_f32 v[186:187], v[190:191], v[194:195]
	s_waitcnt vmcnt(17)
	v_cvt_f32_ubyte0_e32 v66, v184
	v_pk_mul_f32 v[78:79], v[78:79], v[186:187]
	v_rcp_iflag_f32_e32 v186, v66
	v_cvt_f32_ubyte1_e32 v66, v184
	v_rcp_iflag_f32_e32 v187, v66
	v_pk_mul_f32 v[188:189], v[188:189], v[192:193]
	v_cvt_f32_ubyte2_e32 v66, v184
	v_pk_mul_f32 v[80:81], v[80:81], v[188:189]
	v_rcp_iflag_f32_e32 v188, v66
	v_cvt_f32_ubyte3_e32 v66, v184
	s_waitcnt vmcnt(16)
	v_cvt_f32_ubyte1_e32 v193, v182
	v_cvt_f32_ubyte0_e32 v192, v182
	v_rcp_iflag_f32_e32 v189, v66
	v_pk_mul_f32 v[186:187], v[186:187], v[192:193]
	v_cvt_f32_ubyte0_e32 v66, v185
	v_pk_mul_f32 v[74:75], v[74:75], v[186:187]
	v_rcp_iflag_f32_e32 v186, v66
	v_cvt_f32_ubyte1_e32 v66, v185
	v_rcp_iflag_f32_e32 v187, v66
	v_cvt_f32_ubyte3_e32 v191, v182
	v_cvt_f32_ubyte2_e32 v190, v182
	v_cvt_f32_ubyte2_e32 v66, v185
	v_pk_mul_f32 v[188:189], v[188:189], v[190:191]
	v_rcp_iflag_f32_e32 v184, v66
	v_cvt_f32_ubyte3_e32 v66, v185
	v_cvt_f32_ubyte1_e32 v191, v183
	v_cvt_f32_ubyte0_e32 v190, v183
	v_pk_mul_f32 v[76:77], v[76:77], v[188:189]
	v_rcp_iflag_f32_e32 v185, v66
	v_cvt_f32_ubyte3_e32 v189, v183
	v_cvt_f32_ubyte2_e32 v188, v183
	v_pk_mul_f32 v[182:183], v[186:187], v[190:191]
	s_waitcnt vmcnt(14)
; __device__ __forceinline__ float gate_v(unsigned q) { return (float)q; }
;     __device__ __forceinline__ void mid(f32x4 (&acc)[2][2][4][2], const Unit& u, int seg, int wr, int wc, int fr, int fq) const {
;     ...
;         for (int ai = 0; ai < 2; ++ai)
; #pragma unroll
;             for (int m = 0; m < 4; ++m)
; #pragma unroll
;                 for (int bj = 0; bj < 2; ++bj)
; #pragma unroll
;                     for (int e = 0; e < 8; ++e) { const unsigned a = (ga[ai][m][bj][e >> 2] >> (8 * (e & 3))) & 255u, b = (gb[ai][m][bj][e >> 2] >> (8 * (e & 3))) & 255u;
;                         acc[ai][bj][m][e >> 2][e & 3] *= gate_v(a) * __builtin_amdgcn_rcpf(gate_v(b)); }
	v_cvt_f32_ubyte0_e32 v66, v180
	v_pk_mul_f32 v[70:71], v[70:71], v[182:183]
	v_rcp_iflag_f32_e32 v182, v66
	v_cvt_f32_ubyte1_e32 v66, v180
	v_rcp_iflag_f32_e32 v183, v66
	v_pk_mul_f32 v[184:185], v[184:185], v[188:189]
	v_cvt_f32_ubyte2_e32 v66, v180
	v_pk_mul_f32 v[72:73], v[72:73], v[184:185]
	v_rcp_iflag_f32_e32 v184, v66
	v_cvt_f32_ubyte3_e32 v66, v180
	v_cvt_f32_ubyte1_e32 v189, v178
	v_cvt_f32_ubyte0_e32 v188, v178
	v_rcp_iflag_f32_e32 v185, v66
	v_pk_mul_f32 v[182:183], v[182:183], v[188:189]
	v_cvt_f32_ubyte0_e32 v66, v181
	v_pk_mul_f32 v[62:63], v[62:63], v[182:183]
	v_rcp_iflag_f32_e32 v182, v66
	v_cvt_f32_ubyte1_e32 v66, v181
	v_rcp_iflag_f32_e32 v183, v66
	v_cvt_f32_ubyte3_e32 v187, v178
	v_cvt_f32_ubyte2_e32 v186, v178
	v_cvt_f32_ubyte2_e32 v66, v181
	v_pk_mul_f32 v[184:185], v[184:185], v[186:187]
	v_rcp_iflag_f32_e32 v180, v66
	v_cvt_f32_ubyte3_e32 v66, v181
	v_cvt_f32_ubyte1_e32 v187, v179
	v_cvt_f32_ubyte0_e32 v186, v179
	v_pk_mul_f32 v[64:65], v[64:65], v[184:185]
	v_rcp_iflag_f32_e32 v181, v66
	v_cvt_f32_ubyte3_e32 v185, v179
	v_cvt_f32_ubyte2_e32 v184, v179
	v_pk_mul_f32 v[178:179], v[182:183], v[186:187]
	s_waitcnt vmcnt(13)
	v_cvt_f32_ubyte0_e32 v66, v176
	v_pk_mul_f32 v[58:59], v[58:59], v[178:179]
	v_rcp_iflag_f32_e32 v178, v66
	v_cvt_f32_ubyte1_e32 v66, v176
	v_rcp_iflag_f32_e32 v179, v66
	v_pk_mul_f32 v[180:181], v[180:181], v[184:185]
	v_cvt_f32_ubyte2_e32 v66, v176
	v_pk_mul_f32 v[60:61], v[60:61], v[180:181]
	v_rcp_iflag_f32_e32 v180, v66
	v_cvt_f32_ubyte3_e32 v66, v176
	s_waitcnt vmcnt(12)
	v_cvt_f32_ubyte1_e32 v185, v174
	v_cvt_f32_ubyte0_e32 v184, v174
	v_rcp_iflag_f32_e32 v181, v66
	v_pk_mul_f32 v[178:179], v[178:179], v[184:185]
	v_cvt_f32_ubyte0_e32 v66, v177
	v_pk_mul_f32 v[54:55], v[54:55], v[178:179]
	v_rcp_iflag_f32_e32 v178, v66
	v_cvt_f32_ubyte1_e32 v66, v177
	v_rcp_iflag_f32_e32 v179, v66
	v_cvt_f32_ubyte3_e32 v183, v174
	v_cvt_f32_ubyte2_e32 v182, v174
	v_cvt_f32_ubyte2_e32 v66, v177
	v_pk_mul_f32 v[180:181], v[180:181], v[182:183]
	v_rcp_iflag_f32_e32 v176, v66
	v_cvt_f32_ubyte3_e32 v66, v177
	v_cvt_f32_ubyte1_e32 v183, v175
	v_cvt_f32_ubyte0_e32 v182, v175
	v_pk_mul_f32 v[56:57], v[56:57], v[180:181]
	v_rcp_iflag_f32_e32 v177, v66
	v_cvt_f32_ubyte3_e32 v181, v175
	v_cvt_f32_ubyte2_e32 v180, v175
	v_pk_mul_f32 v[174:175], v[178:179], v[182:183]
	s_waitcnt vmcnt(10)
	v_cvt_f32_ubyte0_e32 v66, v172
	v_pk_mul_f32 v[50:51], v[50:51], v[174:175]
	v_rcp_iflag_f32_e32 v174, v66
	v_cvt_f32_ubyte1_e32 v66, v172
	v_rcp_iflag_f32_e32 v175, v66
	v_pk_mul_f32 v[176:177], v[176:177], v[180:181]
	v_cvt_f32_ubyte2_e32 v66, v172
	v_pk_mul_f32 v[52:53], v[52:53], v[176:177]
	v_rcp_iflag_f32_e32 v176, v66
	v_cvt_f32_ubyte3_e32 v66, v172
	v_cvt_f32_ubyte1_e32 v181, v170
	v_cvt_f32_ubyte0_e32 v180, v170
	v_rcp_iflag_f32_e32 v177, v66
	v_pk_mul_f32 v[174:175], v[174:175], v[180:181]
	v_cvt_f32_ubyte0_e32 v66, v173
	v_pk_mul_f32 v[46:47], v[46:47], v[174:175]
	v_rcp_iflag_f32_e32 v174, v66
	v_cvt_f32_ubyte1_e32 v66, v173
	v_rcp_iflag_f32_e32 v175, v66
	v_cvt_f32_ubyte3_e32 v179, v170
	v_cvt_f32_ubyte2_e32 v178, v170
	v_cvt_f32_ubyte2_e32 v66, v173
	v_pk_mul_f32 v[176:177], v[176:177], v[178:179]
	v_rcp_iflag_f32_e32 v172, v66
	v_cvt_f32_ubyte3_e32 v66, v173
	v_cvt_f32_ubyte1_e32 v179, v171
	v_cvt_f32_ubyte0_e32 v178, v171
	v_pk_mul_f32 v[48:49], v[48:49], v[176:177]
	v_rcp_iflag_f32_e32 v173, v66
	v_cvt_f32_ubyte3_e32 v177, v171
	v_cvt_f32_ubyte2_e32 v176, v171
	v_pk_mul_f32 v[170:171], v[174:175], v[178:179]
	s_waitcnt vmcnt(9)
	v_cvt_f32_ubyte0_e32 v66, v168
	v_pk_mul_f32 v[42:43], v[42:43], v[170:171]
	v_rcp_iflag_f32_e32 v170, v66
	v_cvt_f32_ubyte1_e32 v66, v168
	v_rcp_iflag_f32_e32 v171, v66
	v_pk_mul_f32 v[172:173], v[172:173], v[176:177]
	v_cvt_f32_ubyte2_e32 v66, v168
	v_pk_mul_f32 v[44:45], v[44:45], v[172:173]
	v_rcp_iflag_f32_e32 v172, v66
	v_cvt_f32_ubyte3_e32 v66, v168
	s_waitcnt vmcnt(8)
	v_cvt_f32_ubyte1_e32 v177, v166
	v_cvt_f32_ubyte0_e32 v176, v166
	v_rcp_iflag_f32_e32 v173, v66
	v_pk_mul_f32 v[170:171], v[170:171], v[176:177]
	v_cvt_f32_ubyte0_e32 v66, v169
	v_pk_mul_f32 v[38:39], v[38:39], v[170:171]
	v_rcp_iflag_f32_e32 v170, v66
	v_cvt_f32_ubyte1_e32 v66, v169
	v_rcp_iflag_f32_e32 v171, v66
	v_cvt_f32_ubyte3_e32 v175, v166
	v_cvt_f32_ubyte2_e32 v174, v166
	v_cvt_f32_ubyte2_e32 v66, v169
	v_pk_mul_f32 v[172:173], v[172:173], v[174:175]
	v_rcp_iflag_f32_e32 v168, v66
	v_cvt_f32_ubyte3_e32 v66, v169
	v_cvt_f32_ubyte1_e32 v175, v167
	v_cvt_f32_ubyte0_e32 v174, v167
	v_pk_mul_f32 v[40:41], v[40:41], v[172:173]
	v_rcp_iflag_f32_e32 v169, v66
	v_cvt_f32_ubyte3_e32 v173, v167
	v_cvt_f32_ubyte2_e32 v172, v167
	v_pk_mul_f32 v[166:167], v[170:171], v[174:175]
	s_waitcnt vmcnt(6)
; __device__ __forceinline__ float gate_v(unsigned q) { return (float)q; }
;     __device__ __forceinline__ void mid(f32x4 (&acc)[2][2][4][2], const Unit& u, int seg, int wr, int wc, int fr, int fq) const {
;     ...
;         for (int ai = 0; ai < 2; ++ai)
; #pragma unroll
;             for (int m = 0; m < 4; ++m)
; #pragma unroll
;                 for (int bj = 0; bj < 2; ++bj)
; #pragma unroll
;                     for (int e = 0; e < 8; ++e) { const unsigned a = (ga[ai][m][bj][e >> 2] >> (8 * (e & 3))) & 255u, b = (gb[ai][m][bj][e >> 2] >> (8 * (e & 3))) & 255u;
;                         acc[ai][bj][m][e >> 2][e & 3] *= gate_v(a) * __builtin_amdgcn_rcpf(gate_v(b)); }
	v_cvt_f32_ubyte0_e32 v66, v164
	v_pk_mul_f32 v[34:35], v[34:35], v[166:167]
	v_rcp_iflag_f32_e32 v166, v66
	v_cvt_f32_ubyte1_e32 v66, v164
	v_rcp_iflag_f32_e32 v167, v66
	v_pk_mul_f32 v[168:169], v[168:169], v[172:173]
	v_cvt_f32_ubyte2_e32 v66, v164
	v_pk_mul_f32 v[36:37], v[36:37], v[168:169]
	v_rcp_iflag_f32_e32 v168, v66
	v_cvt_f32_ubyte3_e32 v66, v164
	v_cvt_f32_ubyte1_e32 v173, v162
	v_cvt_f32_ubyte0_e32 v172, v162
	v_rcp_iflag_f32_e32 v169, v66
	v_pk_mul_f32 v[166:167], v[166:167], v[172:173]
	v_cvt_f32_ubyte0_e32 v66, v165
	v_pk_mul_f32 v[30:31], v[30:31], v[166:167]
	v_rcp_iflag_f32_e32 v166, v66
	v_cvt_f32_ubyte1_e32 v66, v165
	v_rcp_iflag_f32_e32 v167, v66
	v_cvt_f32_ubyte3_e32 v171, v162
	v_cvt_f32_ubyte2_e32 v170, v162
	v_cvt_f32_ubyte2_e32 v66, v165
	v_pk_mul_f32 v[168:169], v[168:169], v[170:171]
	v_rcp_iflag_f32_e32 v164, v66
	v_cvt_f32_ubyte3_e32 v66, v165
	v_cvt_f32_ubyte1_e32 v171, v163
	v_cvt_f32_ubyte0_e32 v170, v163
	v_pk_mul_f32 v[32:33], v[32:33], v[168:169]
	v_rcp_iflag_f32_e32 v165, v66
	v_cvt_f32_ubyte3_e32 v169, v163
	v_cvt_f32_ubyte2_e32 v168, v163
	v_pk_mul_f32 v[162:163], v[166:167], v[170:171]
	s_waitcnt vmcnt(5)
	v_cvt_f32_ubyte0_e32 v66, v160
	v_pk_mul_f32 v[26:27], v[26:27], v[162:163]
	v_rcp_iflag_f32_e32 v162, v66
	v_cvt_f32_ubyte1_e32 v66, v160
	v_rcp_iflag_f32_e32 v163, v66
	v_pk_mul_f32 v[164:165], v[164:165], v[168:169]
	v_cvt_f32_ubyte2_e32 v66, v160
	v_pk_mul_f32 v[28:29], v[28:29], v[164:165]
	v_rcp_iflag_f32_e32 v164, v66
	v_cvt_f32_ubyte3_e32 v66, v160
	s_waitcnt vmcnt(4)
	v_cvt_f32_ubyte1_e32 v169, v158
	v_cvt_f32_ubyte0_e32 v168, v158
	v_rcp_iflag_f32_e32 v165, v66
	v_pk_mul_f32 v[162:163], v[162:163], v[168:169]
	v_cvt_f32_ubyte0_e32 v66, v161
	v_pk_mul_f32 v[22:23], v[22:23], v[162:163]
	v_rcp_iflag_f32_e32 v162, v66
	v_cvt_f32_ubyte1_e32 v66, v161
	v_rcp_iflag_f32_e32 v163, v66
	v_cvt_f32_ubyte3_e32 v167, v158
	v_cvt_f32_ubyte2_e32 v166, v158
	v_cvt_f32_ubyte2_e32 v66, v161
	v_pk_mul_f32 v[164:165], v[164:165], v[166:167]
	v_rcp_iflag_f32_e32 v160, v66
	v_cvt_f32_ubyte3_e32 v66, v161
	v_cvt_f32_ubyte1_e32 v167, v159
	v_cvt_f32_ubyte0_e32 v166, v159
	v_pk_mul_f32 v[24:25], v[24:25], v[164:165]
	v_rcp_iflag_f32_e32 v161, v66
	v_cvt_f32_ubyte3_e32 v165, v159
	v_cvt_f32_ubyte2_e32 v164, v159
	v_pk_mul_f32 v[158:159], v[162:163], v[166:167]
	s_waitcnt vmcnt(2)
	v_cvt_f32_ubyte0_e32 v66, v156
	v_pk_mul_f32 v[18:19], v[18:19], v[158:159]
	v_rcp_iflag_f32_e32 v158, v66
	v_cvt_f32_ubyte1_e32 v66, v156
	v_rcp_iflag_f32_e32 v159, v66
	v_pk_mul_f32 v[160:161], v[160:161], v[164:165]
	v_cvt_f32_ubyte2_e32 v66, v156
	v_pk_mul_f32 v[20:21], v[20:21], v[160:161]
	v_rcp_iflag_f32_e32 v160, v66
	v_cvt_f32_ubyte3_e32 v66, v156
	v_cvt_f32_ubyte1_e32 v165, v154
	v_cvt_f32_ubyte0_e32 v164, v154
	v_rcp_iflag_f32_e32 v161, v66
	v_pk_mul_f32 v[158:159], v[158:159], v[164:165]
	v_cvt_f32_ubyte0_e32 v66, v157
	v_pk_mul_f32 v[14:15], v[14:15], v[158:159]
	v_rcp_iflag_f32_e32 v158, v66
	v_cvt_f32_ubyte1_e32 v66, v157
	v_rcp_iflag_f32_e32 v159, v66
	v_cvt_f32_ubyte3_e32 v163, v154
	v_cvt_f32_ubyte2_e32 v162, v154
	v_cvt_f32_ubyte2_e32 v66, v157
	v_pk_mul_f32 v[160:161], v[160:161], v[162:163]
	v_rcp_iflag_f32_e32 v156, v66
	v_cvt_f32_ubyte3_e32 v66, v157
	v_cvt_f32_ubyte1_e32 v163, v155
	v_cvt_f32_ubyte0_e32 v162, v155
	v_pk_mul_f32 v[16:17], v[16:17], v[160:161]
	v_rcp_iflag_f32_e32 v157, v66
	v_cvt_f32_ubyte3_e32 v161, v155
	v_cvt_f32_ubyte2_e32 v160, v155
	v_pk_mul_f32 v[154:155], v[158:159], v[162:163]
	s_waitcnt vmcnt(1)
	v_cvt_f32_ubyte0_e32 v66, v152
	v_pk_mul_f32 v[10:11], v[10:11], v[154:155]
	v_rcp_iflag_f32_e32 v154, v66
	v_cvt_f32_ubyte1_e32 v66, v152
	v_rcp_iflag_f32_e32 v155, v66
	v_pk_mul_f32 v[156:157], v[156:157], v[160:161]
	v_cvt_f32_ubyte2_e32 v66, v152
	v_pk_mul_f32 v[12:13], v[12:13], v[156:157]
	v_rcp_iflag_f32_e32 v156, v66
	v_cvt_f32_ubyte3_e32 v66, v152
	s_waitcnt vmcnt(0)
	v_cvt_f32_ubyte1_e32 v161, v68
	v_cvt_f32_ubyte0_e32 v160, v68
	v_rcp_iflag_f32_e32 v157, v66
	v_pk_mul_f32 v[154:155], v[154:155], v[160:161]
	v_cvt_f32_ubyte0_e32 v66, v153
	v_pk_mul_f32 v[6:7], v[6:7], v[154:155]
	v_rcp_iflag_f32_e32 v154, v66
	v_cvt_f32_ubyte1_e32 v66, v153
	v_rcp_iflag_f32_e32 v155, v66
	v_cvt_f32_ubyte2_e32 v66, v153
	v_rcp_iflag_f32_e32 v152, v66
	v_cvt_f32_ubyte3_e32 v66, v153
	v_rcp_iflag_f32_e32 v153, v66
	v_cvt_f32_ubyte3_e32 v159, v68
	v_cvt_f32_ubyte2_e32 v158, v68
	v_pk_mul_f32 v[156:157], v[156:157], v[158:159]
	v_cvt_f32_ubyte1_e32 v159, v69
	v_pk_mul_f32 v[8:9], v[8:9], v[156:157]
	v_cvt_f32_ubyte3_e32 v157, v69
	v_cvt_f32_ubyte2_e32 v156, v69
	v_cvt_f32_ubyte0_e32 v158, v69
	v_pk_mul_f32 v[68:69], v[154:155], v[158:159]
	v_pk_mul_f32 v[152:153], v[152:153], v[156:157]
	v_pk_mul_f32 v[2:3], v[2:3], v[68:69]
	v_pk_mul_f32 v[4:5], v[4:5], v[152:153]
	s_branch .LBB0_781

; #define PG8_STAGE(bufoff, gbase, voff) do { _Pragma("unroll") for (int _i = 0; _i < 2; ++_i) \
;         __builtin_amdgcn_global_load_lds((const unsigned*)((const char*)(gbase) + (voff)[_i]), (PG8_LAS unsigned*)(lds + (bufoff) + ldsw + _i * 8192), 16, 0, 0); } while (0)
; #define PG8_LDA(dst, b, h) do { _Pragma("unroll") for (int m = 0; m < 4; ++m) _Pragma("unroll") for (int k = 0; k < 2; ++k) dst[m][k] = *(const PG8_LAS bf16x8*)(lds + PG8_SA(b, h) + aoff + m * 2048 + k * 1024); } while (0)
; #define PG8_LDB(dst, b, h) do { _Pragma("unroll") for (int n = 0; n < 2; ++n) _Pragma("unroll") for (int k = 0; k < 2; ++k) dst[n][k] = *(const PG8_LAS bf16x8*)(lds + PG8_SB(b, h) + boff + n * 2048 + k * 1024); } while (0)
; #define PG8_MMA(ai, bj, At, Bt) do { __builtin_amdgcn_s_setprio(1); _Pragma("unroll") for (int m = 0; m < 4; ++m) _Pragma("unroll") for (int n = 0; n < 2; ++n) _Pragma("unroll") for (int k = 0; k < 2; ++k) \
;         acc[ai][bj][m][n] = __builtin_amdgcn_mfma_f32_16x16x32_bf16(Bt[n][k], At[m][k], acc[ai][bj][m][n], 0, 0, 0); __builtin_amdgcn_s_setprio(0); } while (0)
; #define PG8_WAIT_V(n) asm volatile("s_waitcnt vmcnt(" #n ")" ::: "memory")
; #define PG8_WAIT_L(n) asm volatile("s_waitcnt lgkmcnt(" #n ")" ::: "memory")
; #define PG8_BAR __builtin_amdgcn_s_barrier()
; #define PG8_SCHED __builtin_amdgcn_sched_barrier(0)
; template <class Epi, class Sched, bool ALIGN_EPI = false, bool SP2 = false>
; __device__ __forceinline__ void gemm_phase(PG8_LAS unsigned char* lds, const Gemm g, const Sched& S, const Epi& E) {
;     ...
;             const char* a1 = cA + (size_t)(t + 1) * kstep;
;             const char* a2 = last ? nA : cA + (size_t)(t + 2) * kstep; const char* b2 = last ? nB : cB + (size_t)(t + 2) * kstep;
;             const char* a3 = a2 + kstep; const char* b3 = b2 + kstep;
;             if (last && has_next) S.a_ready(nxt);
;             if constexpr (SP2) {
;             PG8_LDB(B0, 0, 0); PG8_LDB(B1, 0, 1); PG8_SCHED; PG8_LDA(At, 0, 0); PG8_STAGE(PG8_SA(1, 1), a1 + hstep, voffA);
;             PG8_WAIT_V(8); PG8_WAIT_L(0); PG8_BAR; PG8_MMA(0, 0, At, B0); PG8_MMA(0, 1, At, B1); PG8_BAR; PG8_SCHED;
;             PG8_LDA(At, 0, 1); PG8_STAGE(PG8_SB(0, 0), b2, voffB); PG8_STAGE(PG8_SB(0, 1), b2 + hstep, voffB); PG8_STAGE(PG8_SA(0, 0), a2, voffA);
.LBB0_802:
	s_add_u32 s22, s20, 0x100
	s_addc_u32 s23, s21, 0
	s_cmp_eq_u32 s43, 4
	s_cselect_b32 s27, s19, s23
	s_cselect_b32 s26, s18, s22
	s_cselect_b32 s25, s17, s15
	s_cselect_b32 s24, s16, s13
	s_add_i32 s44, 0, 0x10000
	s_add_i32 s45, 0, 0x14000
	v_add_u32_e32 v168, s44, v0
	v_add_u32_e32 v184, s45, v0
	ds_read_b128 v[156:159], v168
	ds_read_b128 v[160:163], v168 offset:1024
	ds_read_b128 v[164:167], v168 offset:2048
	ds_read_b128 v[168:171], v168 offset:3072
	ds_read_b128 v[172:175], v184
	ds_read_b128 v[176:179], v184 offset:1024
	ds_read_b128 v[180:183], v184 offset:2048
	ds_read_b128 v[184:187], v184 offset:3072
	v_lshl_add_u64 v[228:229], s[20:21], 0, v[150:151]
	s_add_i32 m0, s30, 0xc000
	ds_read_b128 v[188:191], v155
	ds_read_b128 v[192:195], v155 offset:1024
	ds_read_b128 v[196:199], v155 offset:2048
	ds_read_b128 v[200:203], v155 offset:3072
	ds_read_b128 v[204:207], v155 offset:4096
	ds_read_b128 v[208:211], v155 offset:5120
	ds_read_b128 v[220:223], v155 offset:6144
	ds_read_b128 v[224:227], v155 offset:7168
	global_load_lds_dwordx4 v[228:229], off
	v_lshl_add_u64 v[228:229], s[20:21], 0, v[152:153]
	s_add_i32 m0, s30, 0xe000
	s_nop 0
	global_load_lds_dwordx4 v[228:229], off
	s_setprio 1
	s_waitcnt vmcnt(8)
	s_waitcnt lgkmcnt(0)
	s_barrier
	v_mfma_f32_16x16x32_bf16 v[128:131], v[156:159], v[188:191], v[128:131]
	v_mfma_f32_16x16x32_bf16 v[124:127], v[164:167], v[188:191], v[124:127]
	v_mfma_f32_16x16x32_bf16 v[120:123], v[156:159], v[196:199], v[120:123]
	v_mfma_f32_16x16x32_bf16 v[116:119], v[164:167], v[196:199], v[116:119]
	v_mfma_f32_16x16x32_bf16 v[112:115], v[156:159], v[204:207], v[112:115]
	v_mfma_f32_16x16x32_bf16 v[108:111], v[164:167], v[204:207], v[108:111]
	v_mfma_f32_16x16x32_bf16 v[100:103], v[156:159], v[220:223], v[100:103]
	v_mfma_f32_16x16x32_bf16 v[92:95], v[164:167], v[220:223], v[92:95]
	v_mfma_f32_16x16x32_bf16 v[128:131], v[160:163], v[192:195], v[128:131]
	v_mfma_f32_16x16x32_bf16 v[124:127], v[168:171], v[192:195], v[124:127]
	v_mfma_f32_16x16x32_bf16 v[120:123], v[160:163], v[200:203], v[120:123]
	v_mfma_f32_16x16x32_bf16 v[116:119], v[168:171], v[200:203], v[116:119]
	v_mfma_f32_16x16x32_bf16 v[112:115], v[160:163], v[208:211], v[112:115]
	v_mfma_f32_16x16x32_bf16 v[108:111], v[168:171], v[208:211], v[108:111]
	v_mfma_f32_16x16x32_bf16 v[100:103], v[160:163], v[224:227], v[100:103]
	v_mfma_f32_16x16x32_bf16 v[92:95], v[168:171], v[224:227], v[92:95]
	v_mfma_f32_16x16x32_bf16 v[104:107], v[172:175], v[188:191], v[104:107]
	v_mfma_f32_16x16x32_bf16 v[96:99], v[180:183], v[188:191], v[96:99]
	v_mfma_f32_16x16x32_bf16 v[88:91], v[172:175], v[196:199], v[88:91]
	v_mfma_f32_16x16x32_bf16 v[84:87], v[180:183], v[196:199], v[84:87]
	v_mfma_f32_16x16x32_bf16 v[80:83], v[172:175], v[204:207], v[80:83]
	v_mfma_f32_16x16x32_bf16 v[76:79], v[180:183], v[204:207], v[76:79]
	v_mfma_f32_16x16x32_bf16 v[72:75], v[172:175], v[220:223], v[72:75]
	v_mfma_f32_16x16x32_bf16 v[68:71], v[180:183], v[220:223], v[68:71]
	v_mfma_f32_16x16x32_bf16 v[104:107], v[176:179], v[192:195], v[104:107]
	v_mfma_f32_16x16x32_bf16 v[96:99], v[184:187], v[192:195], v[96:99]
	v_mfma_f32_16x16x32_bf16 v[88:91], v[176:179], v[200:203], v[88:91]
	v_mfma_f32_16x16x32_bf16 v[84:87], v[184:187], v[200:203], v[84:87]
	v_mfma_f32_16x16x32_bf16 v[80:83], v[176:179], v[208:211], v[80:83]
	v_mfma_f32_16x16x32_bf16 v[76:79], v[184:187], v[208:211], v[76:79]
	v_mfma_f32_16x16x32_bf16 v[72:75], v[176:179], v[224:227], v[72:75]
	v_mfma_f32_16x16x32_bf16 v[68:71], v[184:187], v[224:227], v[68:71]
	s_barrier
	s_setprio 0
	s_setprio 1
	s_setprio 0
	s_waitcnt lgkmcnt(0)
	s_add_i32 s20, s44, s1
	v_lshl_add_u64 v[228:229], s[24:25], 0, v[66:67]
	s_mov_b32 m0, s20
	ds_read_b128 v[188:191], v155 offset:16384
	ds_read_b128 v[192:195], v155 offset:17408
	ds_read_b128 v[196:199], v155 offset:18432
	ds_read_b128 v[200:203], v155 offset:19456
	ds_read_b128 v[204:207], v155 offset:20480
	ds_read_b128 v[208:211], v155 offset:21504
	ds_read_b128 v[220:223], v155 offset:22528
	ds_read_b128 v[224:227], v155 offset:23552
	global_load_lds_dwordx4 v[228:229], off
	s_add_i32 m0, s20, 0x2000
	s_add_u32 s20, s24, 0x80000
	v_lshl_add_u64 v[230:231], s[24:25], 0, v[132:133]
	s_addc_u32 s21, s25, 0
	s_add_i32 s44, s45, s1
	global_load_lds_dwordx4 v[230:231], off
	v_lshl_add_u64 v[232:233], s[20:21], 0, v[66:67]
	s_mov_b32 m0, s44
	v_lshl_add_u64 v[234:235], s[26:27], 0, v[132:133]
	global_load_lds_dwordx4 v[232:233], off
	v_lshl_add_u64 v[232:233], s[20:21], 0, v[132:133]
	s_add_i32 m0, s44, 0x2000
	s_nop 0
	global_load_lds_dwordx4 v[232:233], off
	v_lshl_add_u64 v[232:233], s[26:27], 0, v[66:67]
	s_mov_b32 m0, s30
	s_nop 0
	global_load_lds_dwordx4 v[232:233], off
	s_mov_b32 m0, s31
	s_nop 0
	global_load_lds_dwordx4 v[234:235], off
	s_setprio 1
	s_waitcnt vmcnt(8)
	s_waitcnt lgkmcnt(0)
	s_barrier
; #define PG8_STAGE(bufoff, gbase, voff) do { _Pragma("unroll") for (int _i = 0; _i < 2; ++_i) \
;         __builtin_amdgcn_global_load_lds((const unsigned*)((const char*)(gbase) + (voff)[_i]), (PG8_LAS unsigned*)(lds + (bufoff) + ldsw + _i * 8192), 16, 0, 0); } while (0)
; #define PG8_LDA(dst, b, h) do { _Pragma("unroll") for (int m = 0; m < 4; ++m) _Pragma("unroll") for (int k = 0; k < 2; ++k) dst[m][k] = *(const PG8_LAS bf16x8*)(lds + PG8_SA(b, h) + aoff + m * 2048 + k * 1024); } while (0)
; #define PG8_LDB(dst, b, h) do { _Pragma("unroll") for (int n = 0; n < 2; ++n) _Pragma("unroll") for (int k = 0; k < 2; ++k) dst[n][k] = *(const PG8_LAS bf16x8*)(lds + PG8_SB(b, h) + boff + n * 2048 + k * 1024); } while (0)
; #define PG8_MMA(ai, bj, At, Bt) do { __builtin_amdgcn_s_setprio(1); _Pragma("unroll") for (int m = 0; m < 4; ++m) _Pragma("unroll") for (int n = 0; n < 2; ++n) _Pragma("unroll") for (int k = 0; k < 2; ++k) \
;         acc[ai][bj][m][n] = __builtin_amdgcn_mfma_f32_16x16x32_bf16(Bt[n][k], At[m][k], acc[ai][bj][m][n], 0, 0, 0); __builtin_amdgcn_s_setprio(0); } while (0)
; #define PG8_WAIT_V(n) asm volatile("s_waitcnt vmcnt(" #n ")" ::: "memory")
; #define PG8_WAIT_L(n) asm volatile("s_waitcnt lgkmcnt(" #n ")" ::: "memory")
; #define PG8_BAR __builtin_amdgcn_s_barrier()
; #define PG8_SCHED __builtin_amdgcn_sched_barrier(0)
; template <class Epi, class Sched, bool ALIGN_EPI = false, bool SP2 = false>
; __device__ __forceinline__ void gemm_phase(PG8_LAS unsigned char* lds, const Gemm g, const Sched& S, const Epi& E) {
;     ...
;             PG8_WAIT_V(8); PG8_WAIT_L(0); PG8_BAR; PG8_MMA(1, 0, At, B0); PG8_MMA(1, 1, At, B1); PG8_BAR; PG8_SCHED;
;             PG8_LDB(B0, 1, 0); PG8_LDB(B1, 1, 1); PG8_SCHED; PG8_LDA(At, 1, 0); PG8_STAGE(PG8_SA(0, 1), a2 + hstep, voffA);
;             PG8_WAIT_V(8); PG8_WAIT_L(0); PG8_BAR; PG8_MMA(0, 0, At, B0); PG8_MMA(0, 1, At, B1); PG8_BAR; PG8_SCHED;
	v_mfma_f32_16x16x32_bf16 v[62:65], v[156:159], v[188:191], v[62:65]
	v_mfma_f32_16x16x32_bf16 v[58:61], v[164:167], v[188:191], v[58:61]
	v_mfma_f32_16x16x32_bf16 v[54:57], v[156:159], v[196:199], v[54:57]
	v_mfma_f32_16x16x32_bf16 v[50:53], v[164:167], v[196:199], v[50:53]
	v_mfma_f32_16x16x32_bf16 v[46:49], v[156:159], v[204:207], v[46:49]
	v_mfma_f32_16x16x32_bf16 v[42:45], v[164:167], v[204:207], v[42:45]
	v_mfma_f32_16x16x32_bf16 v[34:37], v[156:159], v[220:223], v[34:37]
	v_mfma_f32_16x16x32_bf16 v[26:29], v[164:167], v[220:223], v[26:29]
	v_mfma_f32_16x16x32_bf16 v[62:65], v[160:163], v[192:195], v[62:65]
	v_mfma_f32_16x16x32_bf16 v[58:61], v[168:171], v[192:195], v[58:61]
	v_mfma_f32_16x16x32_bf16 v[54:57], v[160:163], v[200:203], v[54:57]
	v_mfma_f32_16x16x32_bf16 v[50:53], v[168:171], v[200:203], v[50:53]
	v_mfma_f32_16x16x32_bf16 v[46:49], v[160:163], v[208:211], v[46:49]
	v_mfma_f32_16x16x32_bf16 v[42:45], v[168:171], v[208:211], v[42:45]
	v_mfma_f32_16x16x32_bf16 v[34:37], v[160:163], v[224:227], v[34:37]
	v_mfma_f32_16x16x32_bf16 v[26:29], v[168:171], v[224:227], v[26:29]
	v_mfma_f32_16x16x32_bf16 v[38:41], v[172:175], v[188:191], v[38:41]
	v_mfma_f32_16x16x32_bf16 v[30:33], v[180:183], v[188:191], v[30:33]
	v_mfma_f32_16x16x32_bf16 v[22:25], v[172:175], v[196:199], v[22:25]
	v_mfma_f32_16x16x32_bf16 v[18:21], v[180:183], v[196:199], v[18:21]
	v_mfma_f32_16x16x32_bf16 v[14:17], v[172:175], v[204:207], v[14:17]
	v_mfma_f32_16x16x32_bf16 v[10:13], v[180:183], v[204:207], v[10:13]
	v_mfma_f32_16x16x32_bf16 v[6:9], v[172:175], v[220:223], v[6:9]
	v_mfma_f32_16x16x32_bf16 v[2:5], v[180:183], v[220:223], v[2:5]
	v_mfma_f32_16x16x32_bf16 v[38:41], v[176:179], v[192:195], v[38:41]
	v_mfma_f32_16x16x32_bf16 v[30:33], v[184:187], v[192:195], v[30:33]
	v_mfma_f32_16x16x32_bf16 v[22:25], v[176:179], v[200:203], v[22:25]
	v_mfma_f32_16x16x32_bf16 v[18:21], v[184:187], v[200:203], v[18:21]
	v_mfma_f32_16x16x32_bf16 v[14:17], v[176:179], v[208:211], v[14:17]
	v_mfma_f32_16x16x32_bf16 v[10:13], v[184:187], v[208:211], v[10:13]
	v_mfma_f32_16x16x32_bf16 v[6:9], v[176:179], v[224:227], v[6:9]
	v_mfma_f32_16x16x32_bf16 v[2:5], v[184:187], v[224:227], v[2:5]
	s_barrier
	s_setprio 0
	s_setprio 1
	s_setprio 0
	s_waitcnt lgkmcnt(0)
	s_add_i32 s44, 0, 0x18000
	s_add_i32 s45, 0, 0x1c000
	v_add_u32_e32 v168, s44, v0
	v_add_u32_e32 v184, s45, v0
	ds_read_b128 v[156:159], v168
	ds_read_b128 v[160:163], v168 offset:1024
	ds_read_b128 v[164:167], v168 offset:2048
	ds_read_b128 v[168:171], v168 offset:3072
	ds_read_b128 v[172:175], v184
	ds_read_b128 v[176:179], v184 offset:1024
	ds_read_b128 v[180:183], v184 offset:2048
	ds_read_b128 v[184:187], v184 offset:3072
	s_add_u32 s20, s26, 0x80000
	s_addc_u32 s21, s27, 0
	s_mov_b32 m0, s34
	v_lshl_add_u64 v[246:247], s[20:21], 0, v[66:67]
	ds_read_b128 v[188:191], v155 offset:32768
	ds_read_b128 v[192:195], v155 offset:33792
	ds_read_b128 v[196:199], v155 offset:34816
	ds_read_b128 v[200:203], v155 offset:35840
	ds_read_b128 v[204:207], v155 offset:36864
	ds_read_b128 v[208:211], v155 offset:37888
	ds_read_b128 v[220:223], v155 offset:38912
	ds_read_b128 v[224:227], v155 offset:39936
	global_load_lds_dwordx4 v[246:247], off
	v_lshl_add_u64 v[246:247], s[20:21], 0, v[132:133]
	s_mov_b32 m0, s35
	s_nop 0
	global_load_lds_dwordx4 v[246:247], off
	s_setprio 1
	s_waitcnt vmcnt(8)
	s_waitcnt lgkmcnt(0)
	s_barrier
	v_mfma_f32_16x16x32_bf16 v[128:131], v[156:159], v[188:191], v[128:131]
	v_mfma_f32_16x16x32_bf16 v[124:127], v[164:167], v[188:191], v[124:127]
	v_mfma_f32_16x16x32_bf16 v[120:123], v[156:159], v[196:199], v[120:123]
	v_mfma_f32_16x16x32_bf16 v[116:119], v[164:167], v[196:199], v[116:119]
	v_mfma_f32_16x16x32_bf16 v[112:115], v[156:159], v[204:207], v[112:115]
	v_mfma_f32_16x16x32_bf16 v[108:111], v[164:167], v[204:207], v[108:111]
	v_mfma_f32_16x16x32_bf16 v[100:103], v[156:159], v[220:223], v[100:103]
	v_mfma_f32_16x16x32_bf16 v[92:95], v[164:167], v[220:223], v[92:95]
	v_mfma_f32_16x16x32_bf16 v[128:131], v[160:163], v[192:195], v[128:131]
	v_mfma_f32_16x16x32_bf16 v[124:127], v[168:171], v[192:195], v[124:127]
	v_mfma_f32_16x16x32_bf16 v[120:123], v[160:163], v[200:203], v[120:123]
	v_mfma_f32_16x16x32_bf16 v[116:119], v[168:171], v[200:203], v[116:119]
	v_mfma_f32_16x16x32_bf16 v[112:115], v[160:163], v[208:211], v[112:115]
	v_mfma_f32_16x16x32_bf16 v[108:111], v[168:171], v[208:211], v[108:111]
	v_mfma_f32_16x16x32_bf16 v[100:103], v[160:163], v[224:227], v[100:103]
	v_mfma_f32_16x16x32_bf16 v[92:95], v[168:171], v[224:227], v[92:95]
	v_mfma_f32_16x16x32_bf16 v[104:107], v[172:175], v[188:191], v[104:107]
	v_mfma_f32_16x16x32_bf16 v[96:99], v[180:183], v[188:191], v[96:99]
	v_mfma_f32_16x16x32_bf16 v[88:91], v[172:175], v[196:199], v[88:91]
	v_mfma_f32_16x16x32_bf16 v[84:87], v[180:183], v[196:199], v[84:87]
	v_mfma_f32_16x16x32_bf16 v[80:83], v[172:175], v[204:207], v[80:83]
	v_mfma_f32_16x16x32_bf16 v[76:79], v[180:183], v[204:207], v[76:79]
	v_mfma_f32_16x16x32_bf16 v[72:75], v[172:175], v[220:223], v[72:75]
	v_mfma_f32_16x16x32_bf16 v[68:71], v[180:183], v[220:223], v[68:71]
	v_mfma_f32_16x16x32_bf16 v[104:107], v[176:179], v[192:195], v[104:107]
	v_mfma_f32_16x16x32_bf16 v[96:99], v[184:187], v[192:195], v[96:99]
	v_mfma_f32_16x16x32_bf16 v[88:91], v[176:179], v[200:203], v[88:91]
	v_mfma_f32_16x16x32_bf16 v[84:87], v[184:187], v[200:203], v[84:87]
	v_mfma_f32_16x16x32_bf16 v[80:83], v[176:179], v[208:211], v[80:83]
	v_mfma_f32_16x16x32_bf16 v[76:79], v[184:187], v[208:211], v[76:79]
	v_mfma_f32_16x16x32_bf16 v[72:75], v[176:179], v[224:227], v[72:75]
	v_mfma_f32_16x16x32_bf16 v[68:71], v[184:187], v[224:227], v[68:71]
	s_barrier
; #define PG8_STAGE(bufoff, gbase, voff) do { _Pragma("unroll") for (int _i = 0; _i < 2; ++_i) \
;         __builtin_amdgcn_global_load_lds((const unsigned*)((const char*)(gbase) + (voff)[_i]), (PG8_LAS unsigned*)(lds + (bufoff) + ldsw + _i * 8192), 16, 0, 0); } while (0)
; #define PG8_LDA(dst, b, h) do { _Pragma("unroll") for (int m = 0; m < 4; ++m) _Pragma("unroll") for (int k = 0; k < 2; ++k) dst[m][k] = *(const PG8_LAS bf16x8*)(lds + PG8_SA(b, h) + aoff + m * 2048 + k * 1024); } while (0)
; #define PG8_MMA(ai, bj, At, Bt) do { __builtin_amdgcn_s_setprio(1); _Pragma("unroll") for (int m = 0; m < 4; ++m) _Pragma("unroll") for (int n = 0; n < 2; ++n) _Pragma("unroll") for (int k = 0; k < 2; ++k) \
;         acc[ai][bj][m][n] = __builtin_amdgcn_mfma_f32_16x16x32_bf16(Bt[n][k], At[m][k], acc[ai][bj][m][n], 0, 0, 0); __builtin_amdgcn_s_setprio(0); } while (0)
; #define PG8_WAIT_V(n) asm volatile("s_waitcnt vmcnt(" #n ")" ::: "memory")
; #define PG8_WAIT_L(n) asm volatile("s_waitcnt lgkmcnt(" #n ")" ::: "memory")
; #define PG8_BAR __builtin_amdgcn_s_barrier()
; #define PG8_SCHED __builtin_amdgcn_sched_barrier(0)
; template <class Epi, class Sched, bool ALIGN_EPI = false, bool SP2 = false>
; __device__ __forceinline__ void gemm_phase(PG8_LAS unsigned char* lds, const Gemm g, const Sched& S, const Epi& E) {
;     ...
;             PG8_LDA(At, 1, 1); PG8_STAGE(PG8_SB(1, 0), b3, voffB); PG8_STAGE(PG8_SB(1, 1), b3 + hstep, voffB); PG8_STAGE(PG8_SA(1, 0), a3, voffA);
;             PG8_WAIT_V(8); PG8_WAIT_L(0); PG8_BAR; PG8_MMA(1, 0, At, B0); PG8_MMA(1, 1, At, B1); PG8_BAR; PG8_SCHED;
	s_setprio 0
	s_setprio 1
	s_setprio 0
	s_waitcnt lgkmcnt(0)
	s_add_i32 s20, s44, s1
	v_lshl_add_u64 v[228:229], v[228:229], 0, s[88:89]
	s_mov_b32 m0, s20
	ds_read_b128 v[188:191], v155 offset:49152
	ds_read_b128 v[192:195], v155 offset:50176
	ds_read_b128 v[196:199], v155 offset:51200
	ds_read_b128 v[200:203], v155 offset:52224
	ds_read_b128 v[204:207], v155 offset:53248
	ds_read_b128 v[208:211], v155 offset:54272
	ds_read_b128 v[220:223], v155 offset:55296
	ds_read_b128 v[224:227], v155 offset:56320
	global_load_lds_dwordx4 v[228:229], off
	s_add_i32 m0, s20, 0x2000
	s_add_u32 s20, s24, 0x80080
	v_lshl_add_u64 v[228:229], v[230:231], 0, s[88:89]
	s_addc_u32 s21, s25, 0
	s_add_i32 s24, s45, s1
	global_load_lds_dwordx4 v[228:229], off
	v_lshl_add_u64 v[228:229], s[20:21], 0, v[66:67]
	s_mov_b32 m0, s24
	s_nop 0
	global_load_lds_dwordx4 v[228:229], off
	v_lshl_add_u64 v[228:229], s[20:21], 0, v[132:133]
	s_add_i32 m0, s24, 0x2000
	s_nop 0
	global_load_lds_dwordx4 v[228:229], off
	v_lshl_add_u64 v[228:229], v[232:233], 0, s[88:89]
	s_mov_b32 m0, s40
	s_nop 0
	global_load_lds_dwordx4 v[228:229], off
	v_lshl_add_u64 v[228:229], v[234:235], 0, s[88:89]
	s_mov_b32 m0, s41
	s_nop 0
	global_load_lds_dwordx4 v[228:229], off
	s_setprio 1
	s_waitcnt vmcnt(8)
	s_waitcnt lgkmcnt(0)
	s_barrier
	v_mfma_f32_16x16x32_bf16 v[62:65], v[156:159], v[188:191], v[62:65]
	v_mfma_f32_16x16x32_bf16 v[58:61], v[164:167], v[188:191], v[58:61]
	v_mfma_f32_16x16x32_bf16 v[54:57], v[156:159], v[196:199], v[54:57]
	v_mfma_f32_16x16x32_bf16 v[50:53], v[164:167], v[196:199], v[50:53]
	v_mfma_f32_16x16x32_bf16 v[46:49], v[156:159], v[204:207], v[46:49]
	v_mfma_f32_16x16x32_bf16 v[42:45], v[164:167], v[204:207], v[42:45]
	v_mfma_f32_16x16x32_bf16 v[34:37], v[156:159], v[220:223], v[34:37]
	v_mfma_f32_16x16x32_bf16 v[26:29], v[164:167], v[220:223], v[26:29]
	v_mfma_f32_16x16x32_bf16 v[62:65], v[160:163], v[192:195], v[62:65]
	v_mfma_f32_16x16x32_bf16 v[58:61], v[168:171], v[192:195], v[58:61]
	v_mfma_f32_16x16x32_bf16 v[54:57], v[160:163], v[200:203], v[54:57]
	v_mfma_f32_16x16x32_bf16 v[50:53], v[168:171], v[200:203], v[50:53]
	v_mfma_f32_16x16x32_bf16 v[46:49], v[160:163], v[208:211], v[46:49]
	v_mfma_f32_16x16x32_bf16 v[42:45], v[168:171], v[208:211], v[42:45]
	v_mfma_f32_16x16x32_bf16 v[34:37], v[160:163], v[224:227], v[34:37]
	v_mfma_f32_16x16x32_bf16 v[26:29], v[168:171], v[224:227], v[26:29]
	v_mfma_f32_16x16x32_bf16 v[38:41], v[172:175], v[188:191], v[38:41]
	v_mfma_f32_16x16x32_bf16 v[30:33], v[180:183], v[188:191], v[30:33]
	v_mfma_f32_16x16x32_bf16 v[22:25], v[172:175], v[196:199], v[22:25]
	v_mfma_f32_16x16x32_bf16 v[18:21], v[180:183], v[196:199], v[18:21]
	v_mfma_f32_16x16x32_bf16 v[14:17], v[172:175], v[204:207], v[14:17]
	v_mfma_f32_16x16x32_bf16 v[10:13], v[180:183], v[204:207], v[10:13]
	v_mfma_f32_16x16x32_bf16 v[6:9], v[172:175], v[220:223], v[6:9]
	v_mfma_f32_16x16x32_bf16 v[2:5], v[180:183], v[220:223], v[2:5]
	v_mfma_f32_16x16x32_bf16 v[38:41], v[176:179], v[192:195], v[38:41]
	v_mfma_f32_16x16x32_bf16 v[30:33], v[184:187], v[192:195], v[30:33]
	v_mfma_f32_16x16x32_bf16 v[22:25], v[176:179], v[200:203], v[22:25]
	v_mfma_f32_16x16x32_bf16 v[18:21], v[184:187], v[200:203], v[18:21]
	v_mfma_f32_16x16x32_bf16 v[14:17], v[176:179], v[208:211], v[14:17]
	v_mfma_f32_16x16x32_bf16 v[10:13], v[184:187], v[208:211], v[10:13]
	v_mfma_f32_16x16x32_bf16 v[6:9], v[176:179], v[224:227], v[6:9]
	v_mfma_f32_16x16x32_bf16 v[2:5], v[184:187], v[224:227], v[2:5]
	s_barrier
	s_setprio 0
	s_setprio 1
	s_setprio 0
	s_waitcnt lgkmcnt(0)
	s_add_i32 s43, s43, 2
	s_add_u32 s13, s13, 0x100
	s_addc_u32 s15, s15, 0
	s_cmp_gt_u32 s43, 5
	s_mov_b64 s[20:21], s[22:23]
	s_cbranch_scc0 .LBB0_802
	s_and_b64 vcc, exec, s[8:9]
	s_cbranch_vccz .LBB0_805
	s_barrier

; #define PG8_STAGE(bufoff, gbase, voff) do { _Pragma("unroll") for (int _i = 0; _i < 2; ++_i) \
;         __builtin_amdgcn_global_load_lds((const unsigned*)((const char*)(gbase) + (voff)[_i]), (PG8_LAS unsigned*)(lds + (bufoff) + ldsw + _i * 8192), 16, 0, 0); } while (0)
; #define PG8_LDA(dst, b, h) do { _Pragma("unroll") for (int m = 0; m < 4; ++m) _Pragma("unroll") for (int k = 0; k < 2; ++k) dst[m][k] = *(const PG8_LAS bf16x8*)(lds + PG8_SA(b, h) + aoff + m * 2048 + k * 1024); } while (0)
; #define PG8_LDB(dst, b, h) do { _Pragma("unroll") for (int n = 0; n < 2; ++n) _Pragma("unroll") for (int k = 0; k < 2; ++k) dst[n][k] = *(const PG8_LAS bf16x8*)(lds + PG8_SB(b, h) + boff + n * 2048 + k * 1024); } while (0)
; #define PG8_MMA(ai, bj, At, Bt) do { __builtin_amdgcn_s_setprio(1); _Pragma("unroll") for (int m = 0; m < 4; ++m) _Pragma("unroll") for (int n = 0; n < 2; ++n) _Pragma("unroll") for (int k = 0; k < 2; ++k) \
;         acc[ai][bj][m][n] = __builtin_amdgcn_mfma_f32_16x16x32_bf16(Bt[n][k], At[m][k], acc[ai][bj][m][n], 0, 0, 0); __builtin_amdgcn_s_setprio(0); } while (0)
; #define PG8_WAIT_V(n) asm volatile("s_waitcnt vmcnt(" #n ")" ::: "memory")
; #define PG8_WAIT_L(n) asm volatile("s_waitcnt lgkmcnt(" #n ")" ::: "memory")
; #define PG8_BAR __builtin_amdgcn_s_barrier()
; #define PG8_SCHED __builtin_amdgcn_sched_barrier(0)
; template <class Epi, class Sched, bool ALIGN_EPI = false, bool SP2 = false>
; __device__ __forceinline__ void gemm_phase(PG8_LAS unsigned char* lds, const Gemm g, const Sched& S, const Epi& E) {
;     ...
;             const char* a1 = cA + (size_t)(t + 1) * kstep;
;             const char* a2 = last ? nA : cA + (size_t)(t + 2) * kstep; const char* b2 = last ? nB : cB + (size_t)(t + 2) * kstep;
;             const char* a3 = a2 + kstep; const char* b3 = b2 + kstep;
;             if (last && has_next) S.a_ready(nxt);
;             if constexpr (SP2) {
;             PG8_LDB(B0, 0, 0); PG8_LDB(B1, 0, 1); PG8_SCHED; PG8_LDA(At, 0, 0); PG8_STAGE(PG8_SA(1, 1), a1 + hstep, voffA);
;             PG8_WAIT_V(8); PG8_WAIT_L(0); PG8_BAR; PG8_MMA(0, 0, At, B0); PG8_MMA(0, 1, At, B1); PG8_BAR; PG8_SCHED;
;             PG8_LDA(At, 0, 1); PG8_STAGE(PG8_SB(0, 0), b2, voffB); PG8_STAGE(PG8_SB(0, 1), b2 + hstep, voffB); PG8_STAGE(PG8_SA(0, 0), a2, voffA);
.LBB0_881:
	s_add_u32 s30, s28, 0x100
	s_addc_u32 s31, s29, 0
	s_add_i32 s59, 0, 0x10000
	s_cmp_eq_u32 s57, 28
	s_cselect_b32 s37, s2, s31
	s_cselect_b32 s36, s3, s30
	s_cselect_b32 s35, s21, s56
	s_cselect_b32 s34, s23, s55
	s_add_i32 s60, 0, 0x14000
	v_add_u32_e32 v144, s59, v156
	v_add_u32_e32 v154, s60, v156
	ds_read_b128 v[132:135], v144
	ds_read_b128 v[136:139], v144 offset:1024
	ds_read_b128 v[140:143], v144 offset:2048
	ds_read_b128 v[144:147], v144 offset:3072
	ds_read_b128 v[160:163], v154
	ds_read_b128 v[164:167], v154 offset:1024
	ds_read_b128 v[168:171], v154 offset:2048
	ds_read_b128 v[172:175], v154 offset:3072
	v_lshl_add_u64 v[154:155], s[28:29], 0, v[150:151]
	s_add_i32 m0, s39, 0xc000
	ds_read_b128 v[176:179], v158
	ds_read_b128 v[180:183], v158 offset:1024
	ds_read_b128 v[184:187], v158 offset:2048
	ds_read_b128 v[188:191], v158 offset:3072
	ds_read_b128 v[192:195], v158 offset:4096
	ds_read_b128 v[196:199], v158 offset:5120
	ds_read_b128 v[200:203], v158 offset:6144
	ds_read_b128 v[204:207], v158 offset:7168
	global_load_lds_dwordx4 v[154:155], off
	v_lshl_add_u64 v[154:155], s[28:29], 0, v[152:153]
	s_add_i32 m0, s39, 0xe000
	s_nop 0
	global_load_lds_dwordx4 v[154:155], off
	s_setprio 1
	s_waitcnt vmcnt(8)
	s_waitcnt lgkmcnt(0)
	s_barrier
	v_mfma_f32_16x16x32_bf16 v[128:131], v[132:135], v[176:179], v[128:131]
	v_mfma_f32_16x16x32_bf16 v[124:127], v[140:143], v[176:179], v[124:127]
	v_mfma_f32_16x16x32_bf16 v[120:123], v[132:135], v[184:187], v[120:123]
	v_mfma_f32_16x16x32_bf16 v[112:115], v[140:143], v[184:187], v[112:115]
	v_mfma_f32_16x16x32_bf16 v[104:107], v[132:135], v[192:195], v[104:107]
	v_mfma_f32_16x16x32_bf16 v[96:99], v[140:143], v[192:195], v[96:99]
	v_mfma_f32_16x16x32_bf16 v[88:91], v[132:135], v[200:203], v[88:91]
	v_mfma_f32_16x16x32_bf16 v[76:79], v[140:143], v[200:203], v[76:79]
	v_mfma_f32_16x16x32_bf16 v[128:131], v[136:139], v[180:183], v[128:131]
	v_mfma_f32_16x16x32_bf16 v[124:127], v[144:147], v[180:183], v[124:127]
	v_mfma_f32_16x16x32_bf16 v[120:123], v[136:139], v[188:191], v[120:123]
	v_mfma_f32_16x16x32_bf16 v[112:115], v[144:147], v[188:191], v[112:115]
	v_mfma_f32_16x16x32_bf16 v[104:107], v[136:139], v[196:199], v[104:107]
	v_mfma_f32_16x16x32_bf16 v[96:99], v[144:147], v[196:199], v[96:99]
	v_mfma_f32_16x16x32_bf16 v[88:91], v[136:139], v[204:207], v[88:91]
	v_mfma_f32_16x16x32_bf16 v[76:79], v[144:147], v[204:207], v[76:79]
	v_mfma_f32_16x16x32_bf16 v[116:119], v[160:163], v[176:179], v[116:119]
	v_mfma_f32_16x16x32_bf16 v[108:111], v[168:171], v[176:179], v[108:111]
	v_mfma_f32_16x16x32_bf16 v[100:103], v[160:163], v[184:187], v[100:103]
	v_mfma_f32_16x16x32_bf16 v[92:95], v[168:171], v[184:187], v[92:95]
	v_mfma_f32_16x16x32_bf16 v[84:87], v[160:163], v[192:195], v[84:87]
	v_mfma_f32_16x16x32_bf16 v[80:83], v[168:171], v[192:195], v[80:83]
	v_mfma_f32_16x16x32_bf16 v[72:75], v[160:163], v[200:203], v[72:75]
	v_mfma_f32_16x16x32_bf16 v[68:71], v[168:171], v[200:203], v[68:71]
	v_mfma_f32_16x16x32_bf16 v[116:119], v[164:167], v[180:183], v[116:119]
	v_mfma_f32_16x16x32_bf16 v[108:111], v[172:175], v[180:183], v[108:111]
	v_mfma_f32_16x16x32_bf16 v[100:103], v[164:167], v[188:191], v[100:103]
	v_mfma_f32_16x16x32_bf16 v[92:95], v[172:175], v[188:191], v[92:95]
	v_mfma_f32_16x16x32_bf16 v[84:87], v[164:167], v[196:199], v[84:87]
	v_mfma_f32_16x16x32_bf16 v[80:83], v[172:175], v[196:199], v[80:83]
	v_mfma_f32_16x16x32_bf16 v[72:75], v[164:167], v[204:207], v[72:75]
	v_mfma_f32_16x16x32_bf16 v[68:71], v[172:175], v[204:207], v[68:71]
	s_barrier
	s_setprio 0
	s_setprio 1
	s_setprio 0
	s_waitcnt lgkmcnt(0)
	s_add_i32 s28, s59, s38
	v_lshl_add_u64 v[154:155], s[34:35], 0, v[66:67]
	s_mov_b32 m0, s28
	ds_read_b128 v[176:179], v158 offset:16384
	ds_read_b128 v[180:183], v158 offset:17408
	ds_read_b128 v[184:187], v158 offset:18432
	ds_read_b128 v[188:191], v158 offset:19456
	ds_read_b128 v[192:195], v158 offset:20480
	ds_read_b128 v[196:199], v158 offset:21504
	ds_read_b128 v[200:203], v158 offset:22528
	ds_read_b128 v[204:207], v158 offset:23552
	global_load_lds_dwordx4 v[154:155], off
	s_add_i32 m0, s28, 0x2000
	s_add_u32 s28, s34, 0x80000
	v_lshl_add_u64 v[208:209], s[34:35], 0, v[148:149]
	s_addc_u32 s29, s35, 0
	s_add_i32 s59, s60, s38
	global_load_lds_dwordx4 v[208:209], off
	v_lshl_add_u64 v[210:211], s[28:29], 0, v[66:67]
	s_mov_b32 m0, s59
	v_lshl_add_u64 v[220:221], s[36:37], 0, v[148:149]
	global_load_lds_dwordx4 v[210:211], off
	v_lshl_add_u64 v[210:211], s[28:29], 0, v[148:149]
	s_add_i32 m0, s59, 0x2000
	s_nop 0
	global_load_lds_dwordx4 v[210:211], off
	v_lshl_add_u64 v[210:211], s[36:37], 0, v[66:67]
	s_mov_b32 m0, s39
	s_nop 0
	global_load_lds_dwordx4 v[210:211], off
	s_mov_b32 m0, s40
	s_nop 0
	global_load_lds_dwordx4 v[220:221], off
	s_setprio 1
	s_waitcnt vmcnt(8)
	s_waitcnt lgkmcnt(0)
	s_barrier
; #define PG8_STAGE(bufoff, gbase, voff) do { _Pragma("unroll") for (int _i = 0; _i < 2; ++_i) \
;         __builtin_amdgcn_global_load_lds((const unsigned*)((const char*)(gbase) + (voff)[_i]), (PG8_LAS unsigned*)(lds + (bufoff) + ldsw + _i * 8192), 16, 0, 0); } while (0)
; #define PG8_LDA(dst, b, h) do { _Pragma("unroll") for (int m = 0; m < 4; ++m) _Pragma("unroll") for (int k = 0; k < 2; ++k) dst[m][k] = *(const PG8_LAS bf16x8*)(lds + PG8_SA(b, h) + aoff + m * 2048 + k * 1024); } while (0)
; #define PG8_LDB(dst, b, h) do { _Pragma("unroll") for (int n = 0; n < 2; ++n) _Pragma("unroll") for (int k = 0; k < 2; ++k) dst[n][k] = *(const PG8_LAS bf16x8*)(lds + PG8_SB(b, h) + boff + n * 2048 + k * 1024); } while (0)
; #define PG8_MMA(ai, bj, At, Bt) do { __builtin_amdgcn_s_setprio(1); _Pragma("unroll") for (int m = 0; m < 4; ++m) _Pragma("unroll") for (int n = 0; n < 2; ++n) _Pragma("unroll") for (int k = 0; k < 2; ++k) \
;         acc[ai][bj][m][n] = __builtin_amdgcn_mfma_f32_16x16x32_bf16(Bt[n][k], At[m][k], acc[ai][bj][m][n], 0, 0, 0); __builtin_amdgcn_s_setprio(0); } while (0)
; #define PG8_WAIT_V(n) asm volatile("s_waitcnt vmcnt(" #n ")" ::: "memory")
; #define PG8_WAIT_L(n) asm volatile("s_waitcnt lgkmcnt(" #n ")" ::: "memory")
; #define PG8_BAR __builtin_amdgcn_s_barrier()
; #define PG8_SCHED __builtin_amdgcn_sched_barrier(0)
; template <class Epi, class Sched, bool ALIGN_EPI = false, bool SP2 = false>
; __device__ __forceinline__ void gemm_phase(PG8_LAS unsigned char* lds, const Gemm g, const Sched& S, const Epi& E) {
;     ...
;             PG8_WAIT_V(8); PG8_WAIT_L(0); PG8_BAR; PG8_MMA(1, 0, At, B0); PG8_MMA(1, 1, At, B1); PG8_BAR; PG8_SCHED;
;             PG8_LDB(B0, 1, 0); PG8_LDB(B1, 1, 1); PG8_SCHED; PG8_LDA(At, 1, 0); PG8_STAGE(PG8_SA(0, 1), a2 + hstep, voffA);
;             PG8_WAIT_V(8); PG8_WAIT_L(0); PG8_BAR; PG8_MMA(0, 0, At, B0); PG8_MMA(0, 1, At, B1); PG8_BAR; PG8_SCHED;
	v_mfma_f32_16x16x32_bf16 v[62:65], v[132:135], v[176:179], v[62:65]
	v_mfma_f32_16x16x32_bf16 v[58:61], v[140:143], v[176:179], v[58:61]
	v_mfma_f32_16x16x32_bf16 v[54:57], v[132:135], v[184:187], v[54:57]
	v_mfma_f32_16x16x32_bf16 v[46:49], v[140:143], v[184:187], v[46:49]
	v_mfma_f32_16x16x32_bf16 v[38:41], v[132:135], v[192:195], v[38:41]
	v_mfma_f32_16x16x32_bf16 v[30:33], v[140:143], v[192:195], v[30:33]
	v_mfma_f32_16x16x32_bf16 v[22:25], v[132:135], v[200:203], v[22:25]
	v_mfma_f32_16x16x32_bf16 v[10:13], v[140:143], v[200:203], v[10:13]
	v_mfma_f32_16x16x32_bf16 v[62:65], v[136:139], v[180:183], v[62:65]
	v_mfma_f32_16x16x32_bf16 v[58:61], v[144:147], v[180:183], v[58:61]
	v_mfma_f32_16x16x32_bf16 v[54:57], v[136:139], v[188:191], v[54:57]
	v_mfma_f32_16x16x32_bf16 v[46:49], v[144:147], v[188:191], v[46:49]
	v_mfma_f32_16x16x32_bf16 v[38:41], v[136:139], v[196:199], v[38:41]
	v_mfma_f32_16x16x32_bf16 v[30:33], v[144:147], v[196:199], v[30:33]
	v_mfma_f32_16x16x32_bf16 v[22:25], v[136:139], v[204:207], v[22:25]
	v_mfma_f32_16x16x32_bf16 v[10:13], v[144:147], v[204:207], v[10:13]
	v_mfma_f32_16x16x32_bf16 v[50:53], v[160:163], v[176:179], v[50:53]
	v_mfma_f32_16x16x32_bf16 v[42:45], v[168:171], v[176:179], v[42:45]
	v_mfma_f32_16x16x32_bf16 v[34:37], v[160:163], v[184:187], v[34:37]
	v_mfma_f32_16x16x32_bf16 v[26:29], v[168:171], v[184:187], v[26:29]
	v_mfma_f32_16x16x32_bf16 v[18:21], v[160:163], v[192:195], v[18:21]
	v_mfma_f32_16x16x32_bf16 v[14:17], v[168:171], v[192:195], v[14:17]
	v_mfma_f32_16x16x32_bf16 v[6:9], v[160:163], v[200:203], v[6:9]
	v_mfma_f32_16x16x32_bf16 v[2:5], v[168:171], v[200:203], v[2:5]
	v_mfma_f32_16x16x32_bf16 v[50:53], v[164:167], v[180:183], v[50:53]
	v_mfma_f32_16x16x32_bf16 v[42:45], v[172:175], v[180:183], v[42:45]
	v_mfma_f32_16x16x32_bf16 v[34:37], v[164:167], v[188:191], v[34:37]
	v_mfma_f32_16x16x32_bf16 v[26:29], v[172:175], v[188:191], v[26:29]
	v_mfma_f32_16x16x32_bf16 v[18:21], v[164:167], v[196:199], v[18:21]
	v_mfma_f32_16x16x32_bf16 v[14:17], v[172:175], v[196:199], v[14:17]
	v_mfma_f32_16x16x32_bf16 v[6:9], v[164:167], v[204:207], v[6:9]
	v_mfma_f32_16x16x32_bf16 v[2:5], v[172:175], v[204:207], v[2:5]
	s_barrier
	s_setprio 0
	s_setprio 1
	s_setprio 0
	s_waitcnt lgkmcnt(0)
	s_add_i32 s59, 0, 0x18000
	s_add_i32 s60, 0, 0x1c000
	v_add_u32_e32 v144, s59, v156
	v_add_u32_e32 v159, s60, v156
	ds_read_b128 v[132:135], v144
	ds_read_b128 v[136:139], v144 offset:1024
	ds_read_b128 v[140:143], v144 offset:2048
	ds_read_b128 v[144:147], v144 offset:3072
	ds_read_b128 v[160:163], v159
	ds_read_b128 v[164:167], v159 offset:1024
	ds_read_b128 v[168:171], v159 offset:2048
	ds_read_b128 v[172:175], v159 offset:3072
	s_add_u32 s28, s36, 0x80000
	s_addc_u32 s29, s37, 0
	s_mov_b32 m0, s41
	v_lshl_add_u64 v[222:223], s[28:29], 0, v[66:67]
	ds_read_b128 v[176:179], v158 offset:32768
	ds_read_b128 v[180:183], v158 offset:33792
	ds_read_b128 v[184:187], v158 offset:34816
	ds_read_b128 v[188:191], v158 offset:35840
	ds_read_b128 v[192:195], v158 offset:36864
	ds_read_b128 v[196:199], v158 offset:37888
	ds_read_b128 v[200:203], v158 offset:38912
	ds_read_b128 v[204:207], v158 offset:39936
	global_load_lds_dwordx4 v[222:223], off
	v_lshl_add_u64 v[222:223], s[28:29], 0, v[148:149]
	s_mov_b32 m0, s44
	s_nop 0
	global_load_lds_dwordx4 v[222:223], off
	s_setprio 1
	s_waitcnt vmcnt(8)
	s_waitcnt lgkmcnt(0)
	s_barrier
	v_mfma_f32_16x16x32_bf16 v[128:131], v[132:135], v[176:179], v[128:131]
	v_mfma_f32_16x16x32_bf16 v[124:127], v[140:143], v[176:179], v[124:127]
	v_mfma_f32_16x16x32_bf16 v[120:123], v[132:135], v[184:187], v[120:123]
	v_mfma_f32_16x16x32_bf16 v[112:115], v[140:143], v[184:187], v[112:115]
	v_mfma_f32_16x16x32_bf16 v[104:107], v[132:135], v[192:195], v[104:107]
	v_mfma_f32_16x16x32_bf16 v[96:99], v[140:143], v[192:195], v[96:99]
	v_mfma_f32_16x16x32_bf16 v[88:91], v[132:135], v[200:203], v[88:91]
	v_mfma_f32_16x16x32_bf16 v[76:79], v[140:143], v[200:203], v[76:79]
	v_mfma_f32_16x16x32_bf16 v[128:131], v[136:139], v[180:183], v[128:131]
	v_mfma_f32_16x16x32_bf16 v[124:127], v[144:147], v[180:183], v[124:127]
	v_mfma_f32_16x16x32_bf16 v[120:123], v[136:139], v[188:191], v[120:123]
	v_mfma_f32_16x16x32_bf16 v[112:115], v[144:147], v[188:191], v[112:115]
	v_mfma_f32_16x16x32_bf16 v[104:107], v[136:139], v[196:199], v[104:107]
	v_mfma_f32_16x16x32_bf16 v[96:99], v[144:147], v[196:199], v[96:99]
	v_mfma_f32_16x16x32_bf16 v[88:91], v[136:139], v[204:207], v[88:91]
	v_mfma_f32_16x16x32_bf16 v[76:79], v[144:147], v[204:207], v[76:79]
	v_mfma_f32_16x16x32_bf16 v[116:119], v[160:163], v[176:179], v[116:119]
	v_mfma_f32_16x16x32_bf16 v[108:111], v[168:171], v[176:179], v[108:111]
	v_mfma_f32_16x16x32_bf16 v[100:103], v[160:163], v[184:187], v[100:103]
	v_mfma_f32_16x16x32_bf16 v[92:95], v[168:171], v[184:187], v[92:95]
	v_mfma_f32_16x16x32_bf16 v[84:87], v[160:163], v[192:195], v[84:87]
	v_mfma_f32_16x16x32_bf16 v[80:83], v[168:171], v[192:195], v[80:83]
	v_mfma_f32_16x16x32_bf16 v[72:75], v[160:163], v[200:203], v[72:75]
	v_mfma_f32_16x16x32_bf16 v[68:71], v[168:171], v[200:203], v[68:71]
	v_mfma_f32_16x16x32_bf16 v[116:119], v[164:167], v[180:183], v[116:119]
	v_mfma_f32_16x16x32_bf16 v[108:111], v[172:175], v[180:183], v[108:111]
	v_mfma_f32_16x16x32_bf16 v[100:103], v[164:167], v[188:191], v[100:103]
	v_mfma_f32_16x16x32_bf16 v[92:95], v[172:175], v[188:191], v[92:95]
	v_mfma_f32_16x16x32_bf16 v[84:87], v[164:167], v[196:199], v[84:87]
	v_mfma_f32_16x16x32_bf16 v[80:83], v[172:175], v[196:199], v[80:83]
	v_mfma_f32_16x16x32_bf16 v[72:75], v[164:167], v[204:207], v[72:75]
	v_mfma_f32_16x16x32_bf16 v[68:71], v[172:175], v[204:207], v[68:71]
	s_barrier
; #define PG8_STAGE(bufoff, gbase, voff) do { _Pragma("unroll") for (int _i = 0; _i < 2; ++_i) \
;         __builtin_amdgcn_global_load_lds((const unsigned*)((const char*)(gbase) + (voff)[_i]), (PG8_LAS unsigned*)(lds + (bufoff) + ldsw + _i * 8192), 16, 0, 0); } while (0)
; #define PG8_LDA(dst, b, h) do { _Pragma("unroll") for (int m = 0; m < 4; ++m) _Pragma("unroll") for (int k = 0; k < 2; ++k) dst[m][k] = *(const PG8_LAS bf16x8*)(lds + PG8_SA(b, h) + aoff + m * 2048 + k * 1024); } while (0)
; #define PG8_MMA(ai, bj, At, Bt) do { __builtin_amdgcn_s_setprio(1); _Pragma("unroll") for (int m = 0; m < 4; ++m) _Pragma("unroll") for (int n = 0; n < 2; ++n) _Pragma("unroll") for (int k = 0; k < 2; ++k) \
;         acc[ai][bj][m][n] = __builtin_amdgcn_mfma_f32_16x16x32_bf16(Bt[n][k], At[m][k], acc[ai][bj][m][n], 0, 0, 0); __builtin_amdgcn_s_setprio(0); } while (0)
; #define PG8_WAIT_V(n) asm volatile("s_waitcnt vmcnt(" #n ")" ::: "memory")
; #define PG8_WAIT_L(n) asm volatile("s_waitcnt lgkmcnt(" #n ")" ::: "memory")
; #define PG8_BAR __builtin_amdgcn_s_barrier()
; #define PG8_SCHED __builtin_amdgcn_sched_barrier(0)
; template <class Epi, class Sched, bool ALIGN_EPI = false, bool SP2 = false>
; __device__ __forceinline__ void gemm_phase(PG8_LAS unsigned char* lds, const Gemm g, const Sched& S, const Epi& E) {
;     ...
;             PG8_LDA(At, 1, 1); PG8_STAGE(PG8_SB(1, 0), b3, voffB); PG8_STAGE(PG8_SB(1, 1), b3 + hstep, voffB); PG8_STAGE(PG8_SA(1, 0), a3, voffA);
;             PG8_WAIT_V(8); PG8_WAIT_L(0); PG8_BAR; PG8_MMA(1, 0, At, B0); PG8_MMA(1, 1, At, B1); PG8_BAR; PG8_SCHED;
	s_setprio 0
	s_setprio 1
	s_setprio 0
	s_waitcnt lgkmcnt(0)
	s_add_i32 s28, s59, s38
	v_lshl_add_u64 v[154:155], v[154:155], 0, s[88:89]
	s_mov_b32 m0, s28
	ds_read_b128 v[176:179], v158 offset:49152
	ds_read_b128 v[180:183], v158 offset:50176
	ds_read_b128 v[184:187], v158 offset:51200
	ds_read_b128 v[188:191], v158 offset:52224
	ds_read_b128 v[192:195], v158 offset:53248
	ds_read_b128 v[196:199], v158 offset:54272
	ds_read_b128 v[200:203], v158 offset:55296
	ds_read_b128 v[204:207], v158 offset:56320
	global_load_lds_dwordx4 v[154:155], off
	s_add_i32 m0, s28, 0x2000
	s_add_u32 s28, s34, 0x80080
	v_lshl_add_u64 v[154:155], v[208:209], 0, s[88:89]
	s_addc_u32 s29, s35, 0
	s_add_i32 s34, s60, s38
	global_load_lds_dwordx4 v[154:155], off
	v_lshl_add_u64 v[154:155], s[28:29], 0, v[66:67]
	s_mov_b32 m0, s34
	s_nop 0
	global_load_lds_dwordx4 v[154:155], off
	v_lshl_add_u64 v[154:155], s[28:29], 0, v[148:149]
	s_add_i32 m0, s34, 0x2000
	s_nop 0
	global_load_lds_dwordx4 v[154:155], off
	v_lshl_add_u64 v[154:155], v[210:211], 0, s[88:89]
	s_mov_b32 m0, s47
	s_nop 0
	global_load_lds_dwordx4 v[154:155], off
	v_lshl_add_u64 v[154:155], v[220:221], 0, s[88:89]
	s_mov_b32 m0, s50
	s_nop 0
	global_load_lds_dwordx4 v[154:155], off
	s_setprio 1
	s_waitcnt vmcnt(8)
	s_waitcnt lgkmcnt(0)
	s_barrier
	v_mfma_f32_16x16x32_bf16 v[62:65], v[132:135], v[176:179], v[62:65]
	v_mfma_f32_16x16x32_bf16 v[58:61], v[140:143], v[176:179], v[58:61]
	v_mfma_f32_16x16x32_bf16 v[54:57], v[132:135], v[184:187], v[54:57]
	v_mfma_f32_16x16x32_bf16 v[46:49], v[140:143], v[184:187], v[46:49]
	v_mfma_f32_16x16x32_bf16 v[38:41], v[132:135], v[192:195], v[38:41]
	v_mfma_f32_16x16x32_bf16 v[30:33], v[140:143], v[192:195], v[30:33]
	v_mfma_f32_16x16x32_bf16 v[22:25], v[132:135], v[200:203], v[22:25]
	v_mfma_f32_16x16x32_bf16 v[10:13], v[140:143], v[200:203], v[10:13]
	v_mfma_f32_16x16x32_bf16 v[62:65], v[136:139], v[180:183], v[62:65]
	v_mfma_f32_16x16x32_bf16 v[58:61], v[144:147], v[180:183], v[58:61]
	v_mfma_f32_16x16x32_bf16 v[54:57], v[136:139], v[188:191], v[54:57]
	v_mfma_f32_16x16x32_bf16 v[46:49], v[144:147], v[188:191], v[46:49]
	v_mfma_f32_16x16x32_bf16 v[38:41], v[136:139], v[196:199], v[38:41]
	v_mfma_f32_16x16x32_bf16 v[30:33], v[144:147], v[196:199], v[30:33]
	v_mfma_f32_16x16x32_bf16 v[22:25], v[136:139], v[204:207], v[22:25]
	v_mfma_f32_16x16x32_bf16 v[10:13], v[144:147], v[204:207], v[10:13]
	v_mfma_f32_16x16x32_bf16 v[50:53], v[160:163], v[176:179], v[50:53]
	v_mfma_f32_16x16x32_bf16 v[42:45], v[168:171], v[176:179], v[42:45]
	v_mfma_f32_16x16x32_bf16 v[34:37], v[160:163], v[184:187], v[34:37]
	v_mfma_f32_16x16x32_bf16 v[26:29], v[168:171], v[184:187], v[26:29]
	v_mfma_f32_16x16x32_bf16 v[18:21], v[160:163], v[192:195], v[18:21]
	v_mfma_f32_16x16x32_bf16 v[14:17], v[168:171], v[192:195], v[14:17]
	v_mfma_f32_16x16x32_bf16 v[6:9], v[160:163], v[200:203], v[6:9]
	v_mfma_f32_16x16x32_bf16 v[2:5], v[168:171], v[200:203], v[2:5]
	v_mfma_f32_16x16x32_bf16 v[50:53], v[164:167], v[180:183], v[50:53]
	v_mfma_f32_16x16x32_bf16 v[42:45], v[172:175], v[180:183], v[42:45]
	v_mfma_f32_16x16x32_bf16 v[34:37], v[164:167], v[188:191], v[34:37]
	v_mfma_f32_16x16x32_bf16 v[26:29], v[172:175], v[188:191], v[26:29]
	v_mfma_f32_16x16x32_bf16 v[18:21], v[164:167], v[196:199], v[18:21]
	v_mfma_f32_16x16x32_bf16 v[14:17], v[172:175], v[196:199], v[14:17]
	v_mfma_f32_16x16x32_bf16 v[6:9], v[164:167], v[204:207], v[6:9]
	v_mfma_f32_16x16x32_bf16 v[2:5], v[172:175], v[204:207], v[2:5]
	s_barrier
	s_setprio 0
	s_setprio 1
	s_setprio 0
	s_waitcnt lgkmcnt(0)
	s_add_i32 s57, s57, 2
	s_add_u32 s55, s55, 0x100
	s_addc_u32 s56, s56, 0
	s_cmp_gt_u32 s57, 29
	s_mov_b64 s[28:29], s[30:31]
	s_cbranch_scc0 .LBB0_881
	s_and_b64 vcc, exec, s[12:13]
	s_cbranch_vccz .LBB0_884
	s_barrier

; #define PG8_STAGE(bufoff, gbase, voff) do { _Pragma("unroll") for (int _i = 0; _i < 2; ++_i) \
;         __builtin_amdgcn_global_load_lds((const unsigned*)((const char*)(gbase) + (voff)[_i]), (PG8_LAS unsigned*)(lds + (bufoff) + ldsw + _i * 8192), 16, 0, 0); } while (0)
; #define PG8_LDA(dst, b, h) do { _Pragma("unroll") for (int m = 0; m < 4; ++m) _Pragma("unroll") for (int k = 0; k < 2; ++k) dst[m][k] = *(const PG8_LAS bf16x8*)(lds + PG8_SA(b, h) + aoff + m * 2048 + k * 1024); } while (0)
; #define PG8_LDB(dst, b, h) do { _Pragma("unroll") for (int n = 0; n < 2; ++n) _Pragma("unroll") for (int k = 0; k < 2; ++k) dst[n][k] = *(const PG8_LAS bf16x8*)(lds + PG8_SB(b, h) + boff + n * 2048 + k * 1024); } while (0)
; #define PG8_MMA(ai, bj, At, Bt) do { __builtin_amdgcn_s_setprio(1); _Pragma("unroll") for (int m = 0; m < 4; ++m) _Pragma("unroll") for (int n = 0; n < 2; ++n) _Pragma("unroll") for (int k = 0; k < 2; ++k) \
;         acc[ai][bj][m][n] = __builtin_amdgcn_mfma_f32_16x16x32_bf16(Bt[n][k], At[m][k], acc[ai][bj][m][n], 0, 0, 0); __builtin_amdgcn_s_setprio(0); } while (0)
; #define PG8_WAIT_V(n) asm volatile("s_waitcnt vmcnt(" #n ")" ::: "memory")
; #define PG8_WAIT_L(n) asm volatile("s_waitcnt lgkmcnt(" #n ")" ::: "memory")
; #define PG8_BAR __builtin_amdgcn_s_barrier()
; #define PG8_SCHED __builtin_amdgcn_sched_barrier(0)
; template <class Epi, class Sched, bool ALIGN_EPI = false, bool SP2 = false>
; __device__ __forceinline__ void gemm_phase(PG8_LAS unsigned char* lds, const Gemm g, const Sched& S, const Epi& E) {
;     ...
;             const char* a1 = cA + (size_t)(t + 1) * kstep;
;             const char* a2 = last ? nA : cA + (size_t)(t + 2) * kstep; const char* b2 = last ? nB : cB + (size_t)(t + 2) * kstep;
;             const char* a3 = a2 + kstep; const char* b3 = b2 + kstep;
;             if (last && has_next) S.a_ready(nxt);
;             if constexpr (SP2) {
;             PG8_LDB(B0, 0, 0); PG8_LDB(B1, 0, 1); PG8_SCHED; PG8_LDA(At, 0, 0); PG8_STAGE(PG8_SA(1, 1), a1 + hstep, voffA);
;             PG8_WAIT_V(8); PG8_WAIT_L(0); PG8_BAR; PG8_MMA(0, 0, At, B0); PG8_MMA(0, 1, At, B1); PG8_BAR; PG8_SCHED;
;             PG8_LDA(At, 0, 1); PG8_STAGE(PG8_SB(0, 0), b2, voffB); PG8_STAGE(PG8_SB(0, 1), b2 + hstep, voffB); PG8_STAGE(PG8_SA(0, 0), a2, voffA);
.LBB0_905:
	s_add_u32 s38, s22, s36
	s_addc_u32 s39, s23, s37
	s_add_u32 s38, s38, 0x100
	s_addc_u32 s39, s39, 0
	s_add_u32 s63, s3, s36
	s_addc_u32 s64, s59, s37
	s_add_i32 s65, 0, 0x10000
	s_cmpk_eq_i32 s36, 0xf00
	s_cselect_b32 s41, s29, s39
	s_cselect_b32 s40, s60, s38
	s_cselect_b32 s39, s27, s64
	s_cselect_b32 s38, s61, s63
	s_add_i32 s63, 0, 0x14000
	v_add_u32_e32 v156, s65, v142
	v_add_u32_e32 v172, s63, v142
	ds_read_b128 v[144:147], v156
	ds_read_b128 v[148:151], v156 offset:1024
	ds_read_b128 v[152:155], v156 offset:2048
	ds_read_b128 v[156:159], v156 offset:3072
	ds_read_b128 v[160:163], v172
	ds_read_b128 v[164:167], v172 offset:1024
	ds_read_b128 v[168:171], v172 offset:2048
	ds_read_b128 v[172:175], v172 offset:3072
	v_lshl_add_u64 v[188:189], v[134:135], 0, s[36:37]
	s_add_i32 m0, s51, 0xc000
	ds_read_b128 v[176:179], v143
	ds_read_b128 v[180:183], v143 offset:1024
	ds_read_b128 v[184:187], v143 offset:2048
	ds_read_b128 v[192:195], v143 offset:3072
	ds_read_b128 v[196:199], v143 offset:4096
	ds_read_b128 v[200:203], v143 offset:5120
	ds_read_b128 v[204:207], v143 offset:6144
	ds_read_b128 v[208:211], v143 offset:7168
	global_load_lds_dwordx4 v[188:189], off
	v_lshl_add_u64 v[188:189], v[140:141], 0, s[36:37]
	s_add_i32 m0, s51, 0xe000
	s_nop 0
	global_load_lds_dwordx4 v[188:189], off
	s_setprio 1
	s_waitcnt vmcnt(8)
	s_waitcnt lgkmcnt(0)
	s_barrier
	v_mfma_f32_16x16x32_bf16 v[68:71], v[144:147], v[176:179], v[68:71]
	v_mfma_f32_16x16x32_bf16 v[72:75], v[152:155], v[176:179], v[72:75]
	v_mfma_f32_16x16x32_bf16 v[92:95], v[144:147], v[184:187], v[92:95]
	v_mfma_f32_16x16x32_bf16 v[80:83], v[152:155], v[184:187], v[80:83]
	v_mfma_f32_16x16x32_bf16 v[128:131], v[144:147], v[196:199], v[128:131]
	v_mfma_f32_16x16x32_bf16 v[112:115], v[152:155], v[196:199], v[112:115]
	v_mfma_f32_16x16x32_bf16 v[136:139], v[144:147], v[204:207], v[136:139]
	v_mfma_f32_16x16x32_bf16 v[120:123], v[152:155], v[204:207], v[120:123]
	v_mfma_f32_16x16x32_bf16 v[68:71], v[148:151], v[180:183], v[68:71]
	v_mfma_f32_16x16x32_bf16 v[72:75], v[156:159], v[180:183], v[72:75]
	v_mfma_f32_16x16x32_bf16 v[92:95], v[148:151], v[192:195], v[92:95]
	v_mfma_f32_16x16x32_bf16 v[80:83], v[156:159], v[192:195], v[80:83]
	v_mfma_f32_16x16x32_bf16 v[128:131], v[148:151], v[200:203], v[128:131]
	v_mfma_f32_16x16x32_bf16 v[112:115], v[156:159], v[200:203], v[112:115]
	v_mfma_f32_16x16x32_bf16 v[136:139], v[148:151], v[208:211], v[136:139]
	v_mfma_f32_16x16x32_bf16 v[120:123], v[156:159], v[208:211], v[120:123]
	v_mfma_f32_16x16x32_bf16 v[58:61], v[160:163], v[176:179], v[58:61]
	v_mfma_f32_16x16x32_bf16 v[46:49], v[168:171], v[176:179], v[46:49]
	v_mfma_f32_16x16x32_bf16 v[76:79], v[160:163], v[184:187], v[76:79]
	v_mfma_f32_16x16x32_bf16 v[50:53], v[168:171], v[184:187], v[50:53]
	v_mfma_f32_16x16x32_bf16 v[124:127], v[160:163], v[196:199], v[124:127]
	v_mfma_f32_16x16x32_bf16 v[116:119], v[168:171], v[196:199], v[116:119]
	v_mfma_f32_16x16x32_bf16 v[108:111], v[160:163], v[204:207], v[108:111]
	v_mfma_f32_16x16x32_bf16 v[104:107], v[168:171], v[204:207], v[104:107]
	v_mfma_f32_16x16x32_bf16 v[58:61], v[164:167], v[180:183], v[58:61]
	v_mfma_f32_16x16x32_bf16 v[46:49], v[172:175], v[180:183], v[46:49]
	v_mfma_f32_16x16x32_bf16 v[76:79], v[164:167], v[192:195], v[76:79]
	v_mfma_f32_16x16x32_bf16 v[50:53], v[172:175], v[192:195], v[50:53]
	v_mfma_f32_16x16x32_bf16 v[124:127], v[164:167], v[200:203], v[124:127]
	v_mfma_f32_16x16x32_bf16 v[116:119], v[172:175], v[200:203], v[116:119]
	v_mfma_f32_16x16x32_bf16 v[108:111], v[164:167], v[208:211], v[108:111]
	v_mfma_f32_16x16x32_bf16 v[104:107], v[172:175], v[208:211], v[104:107]
	s_barrier
	s_setprio 0
	s_setprio 1
	s_setprio 0
	s_waitcnt lgkmcnt(0)
	s_add_i32 s64, s65, s50
	v_lshl_add_u64 v[188:189], s[38:39], 0, v[66:67]
	s_mov_b32 m0, s64
	ds_read_b128 v[176:179], v143 offset:16384
	ds_read_b128 v[180:183], v143 offset:17408
	ds_read_b128 v[184:187], v143 offset:18432
	ds_read_b128 v[192:195], v143 offset:19456
	ds_read_b128 v[196:199], v143 offset:20480
	ds_read_b128 v[200:203], v143 offset:21504
	ds_read_b128 v[204:207], v143 offset:22528
	ds_read_b128 v[208:211], v143 offset:23552
	global_load_lds_dwordx4 v[188:189], off
	s_add_i32 m0, s64, 0x2000
	s_add_u32 s64, s38, 0x80000
	v_lshl_add_u64 v[220:221], s[38:39], 0, v[84:85]
	s_addc_u32 s65, s39, 0
	s_add_i32 s63, s63, s50
	global_load_lds_dwordx4 v[220:221], off
	v_lshl_add_u64 v[222:223], s[64:65], 0, v[66:67]
	s_mov_b32 m0, s63
	v_lshl_add_u64 v[224:225], s[40:41], 0, v[84:85]
	global_load_lds_dwordx4 v[222:223], off
	v_lshl_add_u64 v[222:223], s[64:65], 0, v[84:85]
	s_add_i32 m0, s63, 0x2000
	s_nop 0
	global_load_lds_dwordx4 v[222:223], off
	v_lshl_add_u64 v[222:223], s[40:41], 0, v[66:67]
	s_mov_b32 m0, s51
	s_nop 0
	global_load_lds_dwordx4 v[222:223], off
	s_mov_b32 m0, s52
	s_nop 0
	global_load_lds_dwordx4 v[224:225], off
	s_setprio 1
	s_waitcnt vmcnt(8)
	s_waitcnt lgkmcnt(0)
	s_barrier
; #define PG8_STAGE(bufoff, gbase, voff) do { _Pragma("unroll") for (int _i = 0; _i < 2; ++_i) \
;         __builtin_amdgcn_global_load_lds((const unsigned*)((const char*)(gbase) + (voff)[_i]), (PG8_LAS unsigned*)(lds + (bufoff) + ldsw + _i * 8192), 16, 0, 0); } while (0)
; #define PG8_LDA(dst, b, h) do { _Pragma("unroll") for (int m = 0; m < 4; ++m) _Pragma("unroll") for (int k = 0; k < 2; ++k) dst[m][k] = *(const PG8_LAS bf16x8*)(lds + PG8_SA(b, h) + aoff + m * 2048 + k * 1024); } while (0)
; #define PG8_LDB(dst, b, h) do { _Pragma("unroll") for (int n = 0; n < 2; ++n) _Pragma("unroll") for (int k = 0; k < 2; ++k) dst[n][k] = *(const PG8_LAS bf16x8*)(lds + PG8_SB(b, h) + boff + n * 2048 + k * 1024); } while (0)
; #define PG8_MMA(ai, bj, At, Bt) do { __builtin_amdgcn_s_setprio(1); _Pragma("unroll") for (int m = 0; m < 4; ++m) _Pragma("unroll") for (int n = 0; n < 2; ++n) _Pragma("unroll") for (int k = 0; k < 2; ++k) \
;         acc[ai][bj][m][n] = __builtin_amdgcn_mfma_f32_16x16x32_bf16(Bt[n][k], At[m][k], acc[ai][bj][m][n], 0, 0, 0); __builtin_amdgcn_s_setprio(0); } while (0)
; #define PG8_WAIT_V(n) asm volatile("s_waitcnt vmcnt(" #n ")" ::: "memory")
; #define PG8_WAIT_L(n) asm volatile("s_waitcnt lgkmcnt(" #n ")" ::: "memory")
; #define PG8_BAR __builtin_amdgcn_s_barrier()
; #define PG8_SCHED __builtin_amdgcn_sched_barrier(0)
; template <class Epi, class Sched, bool ALIGN_EPI = false, bool SP2 = false>
; __device__ __forceinline__ void gemm_phase(PG8_LAS unsigned char* lds, const Gemm g, const Sched& S, const Epi& E) {
;     ...
;             PG8_WAIT_V(8); PG8_WAIT_L(0); PG8_BAR; PG8_MMA(1, 0, At, B0); PG8_MMA(1, 1, At, B1); PG8_BAR; PG8_SCHED;
;             PG8_LDB(B0, 1, 0); PG8_LDB(B1, 1, 1); PG8_SCHED; PG8_LDA(At, 1, 0); PG8_STAGE(PG8_SA(0, 1), a2 + hstep, voffA);
;             PG8_WAIT_V(8); PG8_WAIT_L(0); PG8_BAR; PG8_MMA(0, 0, At, B0); PG8_MMA(0, 1, At, B1); PG8_BAR; PG8_SCHED;
	v_mfma_f32_16x16x32_bf16 v[100:103], v[144:147], v[176:179], v[100:103]
	v_mfma_f32_16x16x32_bf16 v[96:99], v[152:155], v[176:179], v[96:99]
	v_mfma_f32_16x16x32_bf16 v[88:91], v[144:147], v[184:187], v[88:91]
	v_mfma_f32_16x16x32_bf16 v[42:45], v[152:155], v[184:187], v[42:45]
	v_mfma_f32_16x16x32_bf16 v[38:41], v[144:147], v[196:199], v[38:41]
	v_mfma_f32_16x16x32_bf16 v[26:29], v[152:155], v[196:199], v[26:29]
	v_mfma_f32_16x16x32_bf16 v[22:25], v[144:147], v[204:207], v[22:25]
	v_mfma_f32_16x16x32_bf16 v[14:17], v[152:155], v[204:207], v[14:17]
	v_mfma_f32_16x16x32_bf16 v[100:103], v[148:151], v[180:183], v[100:103]
	v_mfma_f32_16x16x32_bf16 v[96:99], v[156:159], v[180:183], v[96:99]
	v_mfma_f32_16x16x32_bf16 v[88:91], v[148:151], v[192:195], v[88:91]
	v_mfma_f32_16x16x32_bf16 v[42:45], v[156:159], v[192:195], v[42:45]
	v_mfma_f32_16x16x32_bf16 v[38:41], v[148:151], v[200:203], v[38:41]
	v_mfma_f32_16x16x32_bf16 v[26:29], v[156:159], v[200:203], v[26:29]
	v_mfma_f32_16x16x32_bf16 v[22:25], v[148:151], v[208:211], v[22:25]
	v_mfma_f32_16x16x32_bf16 v[14:17], v[156:159], v[208:211], v[14:17]
	v_mfma_f32_16x16x32_bf16 v[62:65], v[160:163], v[176:179], v[62:65]
	v_mfma_f32_16x16x32_bf16 v[54:57], v[168:171], v[176:179], v[54:57]
	v_mfma_f32_16x16x32_bf16 v[34:37], v[160:163], v[184:187], v[34:37]
	v_mfma_f32_16x16x32_bf16 v[30:33], v[168:171], v[184:187], v[30:33]
	v_mfma_f32_16x16x32_bf16 v[18:21], v[160:163], v[196:199], v[18:21]
	v_mfma_f32_16x16x32_bf16 v[10:13], v[168:171], v[196:199], v[10:13]
	v_mfma_f32_16x16x32_bf16 v[6:9], v[160:163], v[204:207], v[6:9]
	v_mfma_f32_16x16x32_bf16 v[2:5], v[168:171], v[204:207], v[2:5]
	v_mfma_f32_16x16x32_bf16 v[62:65], v[164:167], v[180:183], v[62:65]
	v_mfma_f32_16x16x32_bf16 v[54:57], v[172:175], v[180:183], v[54:57]
	v_mfma_f32_16x16x32_bf16 v[34:37], v[164:167], v[192:195], v[34:37]
	v_mfma_f32_16x16x32_bf16 v[30:33], v[172:175], v[192:195], v[30:33]
	v_mfma_f32_16x16x32_bf16 v[18:21], v[164:167], v[200:203], v[18:21]
	v_mfma_f32_16x16x32_bf16 v[10:13], v[172:175], v[200:203], v[10:13]
	v_mfma_f32_16x16x32_bf16 v[6:9], v[164:167], v[208:211], v[6:9]
	v_mfma_f32_16x16x32_bf16 v[2:5], v[172:175], v[208:211], v[2:5]
	s_barrier
	s_setprio 0
	s_setprio 1
	s_setprio 0
	s_waitcnt lgkmcnt(0)
	s_add_i32 s63, 0, 0x18000
	s_add_i32 s64, 0, 0x1c000
	v_add_u32_e32 v156, s63, v142
	v_add_u32_e32 v172, s64, v142
	ds_read_b128 v[144:147], v156
	ds_read_b128 v[148:151], v156 offset:1024
	ds_read_b128 v[152:155], v156 offset:2048
	ds_read_b128 v[156:159], v156 offset:3072
	ds_read_b128 v[160:163], v172
	ds_read_b128 v[164:167], v172 offset:1024
	ds_read_b128 v[168:171], v172 offset:2048
	ds_read_b128 v[172:175], v172 offset:3072
	s_add_u32 s40, s40, 0x80000
	s_addc_u32 s41, s41, 0
	s_mov_b32 m0, s1
	v_lshl_add_u64 v[226:227], s[40:41], 0, v[66:67]
	ds_read_b128 v[176:179], v143 offset:32768
	ds_read_b128 v[180:183], v143 offset:33792
	ds_read_b128 v[184:187], v143 offset:34816
	ds_read_b128 v[192:195], v143 offset:35840
	ds_read_b128 v[196:199], v143 offset:36864
	ds_read_b128 v[200:203], v143 offset:37888
	ds_read_b128 v[204:207], v143 offset:38912
	ds_read_b128 v[208:211], v143 offset:39936
	global_load_lds_dwordx4 v[226:227], off
	v_lshl_add_u64 v[226:227], s[40:41], 0, v[84:85]
	s_mov_b32 m0, s54
	s_nop 0
	global_load_lds_dwordx4 v[226:227], off
	s_setprio 1
	s_waitcnt vmcnt(8)
	s_waitcnt lgkmcnt(0)
	s_barrier
	v_mfma_f32_16x16x32_bf16 v[68:71], v[144:147], v[176:179], v[68:71]
	v_mfma_f32_16x16x32_bf16 v[72:75], v[152:155], v[176:179], v[72:75]
	v_mfma_f32_16x16x32_bf16 v[92:95], v[144:147], v[184:187], v[92:95]
	v_mfma_f32_16x16x32_bf16 v[80:83], v[152:155], v[184:187], v[80:83]
	v_mfma_f32_16x16x32_bf16 v[128:131], v[144:147], v[196:199], v[128:131]
	v_mfma_f32_16x16x32_bf16 v[112:115], v[152:155], v[196:199], v[112:115]
	v_mfma_f32_16x16x32_bf16 v[136:139], v[144:147], v[204:207], v[136:139]
	v_mfma_f32_16x16x32_bf16 v[120:123], v[152:155], v[204:207], v[120:123]
	v_mfma_f32_16x16x32_bf16 v[68:71], v[148:151], v[180:183], v[68:71]
	v_mfma_f32_16x16x32_bf16 v[72:75], v[156:159], v[180:183], v[72:75]
	v_mfma_f32_16x16x32_bf16 v[92:95], v[148:151], v[192:195], v[92:95]
	v_mfma_f32_16x16x32_bf16 v[80:83], v[156:159], v[192:195], v[80:83]
	v_mfma_f32_16x16x32_bf16 v[128:131], v[148:151], v[200:203], v[128:131]
	v_mfma_f32_16x16x32_bf16 v[112:115], v[156:159], v[200:203], v[112:115]
	v_mfma_f32_16x16x32_bf16 v[136:139], v[148:151], v[208:211], v[136:139]
	v_mfma_f32_16x16x32_bf16 v[120:123], v[156:159], v[208:211], v[120:123]
	v_mfma_f32_16x16x32_bf16 v[58:61], v[160:163], v[176:179], v[58:61]
	v_mfma_f32_16x16x32_bf16 v[46:49], v[168:171], v[176:179], v[46:49]
	v_mfma_f32_16x16x32_bf16 v[76:79], v[160:163], v[184:187], v[76:79]
	v_mfma_f32_16x16x32_bf16 v[50:53], v[168:171], v[184:187], v[50:53]
	v_mfma_f32_16x16x32_bf16 v[124:127], v[160:163], v[196:199], v[124:127]
	v_mfma_f32_16x16x32_bf16 v[116:119], v[168:171], v[196:199], v[116:119]
	v_mfma_f32_16x16x32_bf16 v[108:111], v[160:163], v[204:207], v[108:111]
	v_mfma_f32_16x16x32_bf16 v[104:107], v[168:171], v[204:207], v[104:107]
	v_mfma_f32_16x16x32_bf16 v[58:61], v[164:167], v[180:183], v[58:61]
	v_mfma_f32_16x16x32_bf16 v[46:49], v[172:175], v[180:183], v[46:49]
	v_mfma_f32_16x16x32_bf16 v[76:79], v[164:167], v[192:195], v[76:79]
	v_mfma_f32_16x16x32_bf16 v[50:53], v[172:175], v[192:195], v[50:53]
	v_mfma_f32_16x16x32_bf16 v[124:127], v[164:167], v[200:203], v[124:127]
	v_mfma_f32_16x16x32_bf16 v[116:119], v[172:175], v[200:203], v[116:119]
	v_mfma_f32_16x16x32_bf16 v[108:111], v[164:167], v[208:211], v[108:111]
	v_mfma_f32_16x16x32_bf16 v[104:107], v[172:175], v[208:211], v[104:107]
	s_barrier
; #define PG8_STAGE(bufoff, gbase, voff) do { _Pragma("unroll") for (int _i = 0; _i < 2; ++_i) \
;         __builtin_amdgcn_global_load_lds((const unsigned*)((const char*)(gbase) + (voff)[_i]), (PG8_LAS unsigned*)(lds + (bufoff) + ldsw + _i * 8192), 16, 0, 0); } while (0)
; #define PG8_LDA(dst, b, h) do { _Pragma("unroll") for (int m = 0; m < 4; ++m) _Pragma("unroll") for (int k = 0; k < 2; ++k) dst[m][k] = *(const PG8_LAS bf16x8*)(lds + PG8_SA(b, h) + aoff + m * 2048 + k * 1024); } while (0)
; #define PG8_MMA(ai, bj, At, Bt) do { __builtin_amdgcn_s_setprio(1); _Pragma("unroll") for (int m = 0; m < 4; ++m) _Pragma("unroll") for (int n = 0; n < 2; ++n) _Pragma("unroll") for (int k = 0; k < 2; ++k) \
;         acc[ai][bj][m][n] = __builtin_amdgcn_mfma_f32_16x16x32_bf16(Bt[n][k], At[m][k], acc[ai][bj][m][n], 0, 0, 0); __builtin_amdgcn_s_setprio(0); } while (0)
; #define PG8_WAIT_V(n) asm volatile("s_waitcnt vmcnt(" #n ")" ::: "memory")
; #define PG8_WAIT_L(n) asm volatile("s_waitcnt lgkmcnt(" #n ")" ::: "memory")
; #define PG8_BAR __builtin_amdgcn_s_barrier()
; #define PG8_SCHED __builtin_amdgcn_sched_barrier(0)
; template <class Epi, class Sched, bool ALIGN_EPI = false, bool SP2 = false>
; __device__ __forceinline__ void gemm_phase(PG8_LAS unsigned char* lds, const Gemm g, const Sched& S, const Epi& E) {
;     ...
;             PG8_LDA(At, 1, 1); PG8_STAGE(PG8_SB(1, 0), b3, voffB); PG8_STAGE(PG8_SB(1, 1), b3 + hstep, voffB); PG8_STAGE(PG8_SA(1, 0), a3, voffA);
;             PG8_WAIT_V(8); PG8_WAIT_L(0); PG8_BAR; PG8_MMA(1, 0, At, B0); PG8_MMA(1, 1, At, B1); PG8_BAR; PG8_SCHED;
;     ...
;         if (!has_next) break;
; #pragma unroll
;         for (int a = 0; a < 2; ++a)
; #pragma unroll
;             for (int b = 0; b < 2; ++b)
; #pragma unroll
;                 for (int m = 0; m < 4; ++m)
; #pragma unroll
;                     for (int n = 0; n < 2; ++n) acc[a][b][m][n] = (f32x4){0.f, 0.f, 0.f, 0.f};
;         cur = nxt; cA = nA; cB = nB; ++ui;
	s_setprio 0
	s_setprio 1
	s_setprio 0
	s_waitcnt lgkmcnt(0)
	s_add_i32 s40, s63, s50
	v_lshl_add_u64 v[188:189], v[188:189], 0, s[88:89]
	s_mov_b32 m0, s40
	ds_read_b128 v[176:179], v143 offset:49152
	ds_read_b128 v[180:183], v143 offset:50176
	ds_read_b128 v[184:187], v143 offset:51200
	ds_read_b128 v[192:195], v143 offset:52224
	ds_read_b128 v[196:199], v143 offset:53248
	ds_read_b128 v[200:203], v143 offset:54272
	ds_read_b128 v[204:207], v143 offset:55296
	ds_read_b128 v[208:211], v143 offset:56320
	global_load_lds_dwordx4 v[188:189], off
	s_add_i32 m0, s40, 0x2000
	s_add_u32 s38, s38, 0x80080
	v_lshl_add_u64 v[188:189], v[220:221], 0, s[88:89]
	s_addc_u32 s39, s39, 0
	s_add_i32 s40, s64, s50
	global_load_lds_dwordx4 v[188:189], off
	v_lshl_add_u64 v[188:189], s[38:39], 0, v[66:67]
	s_mov_b32 m0, s40
	s_nop 0
	global_load_lds_dwordx4 v[188:189], off
	v_lshl_add_u64 v[188:189], s[38:39], 0, v[84:85]
	s_add_i32 m0, s40, 0x2000
	s_nop 0
	global_load_lds_dwordx4 v[188:189], off
	v_lshl_add_u64 v[188:189], v[222:223], 0, s[88:89]
	s_mov_b32 m0, s55
	s_nop 0
	global_load_lds_dwordx4 v[188:189], off
	v_lshl_add_u64 v[188:189], v[224:225], 0, s[88:89]
	s_mov_b32 m0, s56
	s_nop 0
	global_load_lds_dwordx4 v[188:189], off
	s_setprio 1
	s_waitcnt vmcnt(8)
	s_waitcnt lgkmcnt(0)
	s_barrier
	v_mfma_f32_16x16x32_bf16 v[100:103], v[144:147], v[176:179], v[100:103]
	v_mfma_f32_16x16x32_bf16 v[96:99], v[152:155], v[176:179], v[96:99]
	v_mfma_f32_16x16x32_bf16 v[88:91], v[144:147], v[184:187], v[88:91]
	v_mfma_f32_16x16x32_bf16 v[42:45], v[152:155], v[184:187], v[42:45]
	v_mfma_f32_16x16x32_bf16 v[38:41], v[144:147], v[196:199], v[38:41]
	v_mfma_f32_16x16x32_bf16 v[26:29], v[152:155], v[196:199], v[26:29]
	v_mfma_f32_16x16x32_bf16 v[22:25], v[144:147], v[204:207], v[22:25]
	v_mfma_f32_16x16x32_bf16 v[14:17], v[152:155], v[204:207], v[14:17]
	v_mfma_f32_16x16x32_bf16 v[100:103], v[148:151], v[180:183], v[100:103]
	v_mfma_f32_16x16x32_bf16 v[96:99], v[156:159], v[180:183], v[96:99]
	v_mfma_f32_16x16x32_bf16 v[88:91], v[148:151], v[192:195], v[88:91]
	v_mfma_f32_16x16x32_bf16 v[42:45], v[156:159], v[192:195], v[42:45]
	v_mfma_f32_16x16x32_bf16 v[38:41], v[148:151], v[200:203], v[38:41]
	v_mfma_f32_16x16x32_bf16 v[26:29], v[156:159], v[200:203], v[26:29]
	v_mfma_f32_16x16x32_bf16 v[22:25], v[148:151], v[208:211], v[22:25]
	v_mfma_f32_16x16x32_bf16 v[14:17], v[156:159], v[208:211], v[14:17]
	v_mfma_f32_16x16x32_bf16 v[62:65], v[160:163], v[176:179], v[62:65]
	v_mfma_f32_16x16x32_bf16 v[54:57], v[168:171], v[176:179], v[54:57]
	v_mfma_f32_16x16x32_bf16 v[34:37], v[160:163], v[184:187], v[34:37]
	v_mfma_f32_16x16x32_bf16 v[30:33], v[168:171], v[184:187], v[30:33]
	v_mfma_f32_16x16x32_bf16 v[18:21], v[160:163], v[196:199], v[18:21]
	v_mfma_f32_16x16x32_bf16 v[10:13], v[168:171], v[196:199], v[10:13]
	v_mfma_f32_16x16x32_bf16 v[6:9], v[160:163], v[204:207], v[6:9]
	v_mfma_f32_16x16x32_bf16 v[2:5], v[168:171], v[204:207], v[2:5]
	v_mfma_f32_16x16x32_bf16 v[62:65], v[164:167], v[180:183], v[62:65]
	v_mfma_f32_16x16x32_bf16 v[54:57], v[172:175], v[180:183], v[54:57]
	v_mfma_f32_16x16x32_bf16 v[34:37], v[164:167], v[192:195], v[34:37]
	v_mfma_f32_16x16x32_bf16 v[30:33], v[172:175], v[192:195], v[30:33]
	v_mfma_f32_16x16x32_bf16 v[18:21], v[164:167], v[200:203], v[18:21]
	v_mfma_f32_16x16x32_bf16 v[10:13], v[172:175], v[200:203], v[10:13]
	v_mfma_f32_16x16x32_bf16 v[6:9], v[164:167], v[208:211], v[6:9]
	v_mfma_f32_16x16x32_bf16 v[2:5], v[172:175], v[208:211], v[2:5]
	s_barrier
	s_setprio 0
	s_setprio 1
	s_setprio 0
	s_waitcnt lgkmcnt(0)
	s_add_i32 s62, s62, 2
	s_add_u32 s36, s36, 0x100
	s_addc_u32 s37, s37, 0
	s_cmp_gt_u32 s62, 29
	s_cbranch_scc0 .LBB0_905
	s_add_u32 s36, s3, 0xffffff00
	s_addc_u32 s37, s59, -1
	s_andn2_b64 vcc, exec, s[10:11]
	s_cbranch_vccnz .LBB0_896
	v_mov_b32_e32 v2, 0
	s_mov_b32 s12, s26
	s_mov_b32 s46, s28
	s_mov_b64 s[22:23], s[34:35]
	s_mov_b32 s57, s2
	v_mov_b32_e32 v3, v2
	v_mov_b32_e32 v4, v2
	v_mov_b32_e32 v5, v2
	v_mov_b32_e32 v6, v2
	v_mov_b32_e32 v7, v2
	v_mov_b32_e32 v8, v2
	v_mov_b32_e32 v9, v2
	v_mov_b32_e32 v10, v2
	v_mov_b32_e32 v11, v2
	v_mov_b32_e32 v12, v2
	v_mov_b32_e32 v13, v2
	v_mov_b32_e32 v18, v2
	v_mov_b32_e32 v19, v2
	v_mov_b32_e32 v20, v2
	v_mov_b32_e32 v21, v2
	v_mov_b32_e32 v30, v2
	v_mov_b32_e32 v31, v2
	v_mov_b32_e32 v32, v2
	v_mov_b32_e32 v33, v2
	v_mov_b32_e32 v34, v2
	v_mov_b32_e32 v35, v2
	v_mov_b32_e32 v36, v2
	v_mov_b32_e32 v37, v2
	v_mov_b32_e32 v54, v2
	v_mov_b32_e32 v55, v2
	v_mov_b32_e32 v56, v2
	v_mov_b32_e32 v57, v2
	v_mov_b32_e32 v62, v2
	v_mov_b32_e32 v63, v2
	v_mov_b32_e32 v64, v2
	v_mov_b32_e32 v65, v2
	v_mov_b32_e32 v14, v2
	v_mov_b32_e32 v15, v2
	v_mov_b32_e32 v16, v2
	v_mov_b32_e32 v17, v2
	v_mov_b32_e32 v22, v2
	v_mov_b32_e32 v23, v2
	v_mov_b32_e32 v24, v2
	v_mov_b32_e32 v25, v2
	v_mov_b32_e32 v26, v2
	v_mov_b32_e32 v27, v2
	v_mov_b32_e32 v28, v2
	v_mov_b32_e32 v29, v2
	v_mov_b32_e32 v38, v2
	v_mov_b32_e32 v39, v2
	v_mov_b32_e32 v40, v2
	v_mov_b32_e32 v41, v2
	v_mov_b32_e32 v42, v2
	v_mov_b32_e32 v43, v2
	v_mov_b32_e32 v44, v2
	v_mov_b32_e32 v45, v2
	v_mov_b32_e32 v88, v2
	v_mov_b32_e32 v89, v2
	v_mov_b32_e32 v90, v2
	v_mov_b32_e32 v91, v2
	v_mov_b32_e32 v96, v2
	v_mov_b32_e32 v97, v2
	v_mov_b32_e32 v98, v2
	v_mov_b32_e32 v99, v2
	v_mov_b32_e32 v100, v2
	v_mov_b32_e32 v101, v2
	v_mov_b32_e32 v102, v2
	v_mov_b32_e32 v103, v2
	v_mov_b32_e32 v104, v2
	v_mov_b32_e32 v105, v2
	v_mov_b32_e32 v106, v2
	v_mov_b32_e32 v107, v2
	v_mov_b32_e32 v108, v2
	v_mov_b32_e32 v109, v2
	v_mov_b32_e32 v110, v2
	v_mov_b32_e32 v111, v2
	v_mov_b32_e32 v116, v2
	v_mov_b32_e32 v117, v2
	v_mov_b32_e32 v118, v2
	v_mov_b32_e32 v119, v2
	v_mov_b32_e32 v124, v2
	v_mov_b32_e32 v125, v2
	v_mov_b32_e32 v126, v2
	v_mov_b32_e32 v127, v2
	v_mov_b32_e32 v50, v2
	v_mov_b32_e32 v51, v2
	v_mov_b32_e32 v52, v2
	v_mov_b32_e32 v53, v2
	v_mov_b32_e32 v76, v2
	v_mov_b32_e32 v77, v2
	v_mov_b32_e32 v78, v2
	v_mov_b32_e32 v79, v2
	v_mov_b32_e32 v46, v2
	v_mov_b32_e32 v47, v2
	v_mov_b32_e32 v48, v2
	v_mov_b32_e32 v49, v2
	v_mov_b32_e32 v58, v2
	v_mov_b32_e32 v59, v2
	v_mov_b32_e32 v60, v2
	v_mov_b32_e32 v61, v2
	v_mov_b32_e32 v120, v2
	v_mov_b32_e32 v121, v2
	v_mov_b32_e32 v122, v2
	v_mov_b32_e32 v123, v2
	v_mov_b32_e32 v136, v2
	v_mov_b32_e32 v137, v2
	v_mov_b32_e32 v138, v2
	v_mov_b32_e32 v139, v2
	v_mov_b32_e32 v112, v2
	v_mov_b32_e32 v113, v2
	v_mov_b32_e32 v114, v2
	v_mov_b32_e32 v115, v2
	v_mov_b32_e32 v128, v2
	v_mov_b32_e32 v129, v2
	v_mov_b32_e32 v130, v2
	v_mov_b32_e32 v131, v2
	v_mov_b32_e32 v80, v2
	v_mov_b32_e32 v81, v2
	v_mov_b32_e32 v82, v2
	v_mov_b32_e32 v83, v2
	v_mov_b32_e32 v92, v2
	v_mov_b32_e32 v93, v2
	v_mov_b32_e32 v94, v2
	v_mov_b32_e32 v95, v2
	v_mov_b32_e32 v72, v2
	v_mov_b32_e32 v73, v2
	v_mov_b32_e32 v74, v2
	v_mov_b32_e32 v75, v2
	v_mov_b32_e32 v68, v2
	v_mov_b32_e32 v69, v2
	v_mov_b32_e32 v70, v2
	v_mov_b32_e32 v71, v2
	s_mov_b64 s[64:65], s[72:73]
	s_andn2_b64 vcc, exec, s[8:9]
	s_mov_b32 s72, s67
	s_cbranch_vccnz .LBB0_897

; #define PG8_STAGE(bufoff, gbase, voff) do { _Pragma("unroll") for (int _i = 0; _i < 2; ++_i) \
;         __builtin_amdgcn_global_load_lds((const unsigned*)((const char*)(gbase) + (voff)[_i]), (PG8_LAS unsigned*)(lds + (bufoff) + ldsw + _i * 8192), 16, 0, 0); } while (0)
; #define PG8_LDA(dst, b, h) do { _Pragma("unroll") for (int m = 0; m < 4; ++m) _Pragma("unroll") for (int k = 0; k < 2; ++k) dst[m][k] = *(const PG8_LAS bf16x8*)(lds + PG8_SA(b, h) + aoff + m * 2048 + k * 1024); } while (0)
; #define PG8_LDB(dst, b, h) do { _Pragma("unroll") for (int n = 0; n < 2; ++n) _Pragma("unroll") for (int k = 0; k < 2; ++k) dst[n][k] = *(const PG8_LAS bf16x8*)(lds + PG8_SB(b, h) + boff + n * 2048 + k * 1024); } while (0)
; #define PG8_MMA(ai, bj, At, Bt) do { __builtin_amdgcn_s_setprio(1); _Pragma("unroll") for (int m = 0; m < 4; ++m) _Pragma("unroll") for (int n = 0; n < 2; ++n) _Pragma("unroll") for (int k = 0; k < 2; ++k) \
;         acc[ai][bj][m][n] = __builtin_amdgcn_mfma_f32_16x16x32_bf16(Bt[n][k], At[m][k], acc[ai][bj][m][n], 0, 0, 0); __builtin_amdgcn_s_setprio(0); } while (0)
; #define PG8_WAIT_V(n) asm volatile("s_waitcnt vmcnt(" #n ")" ::: "memory")
; #define PG8_WAIT_L(n) asm volatile("s_waitcnt lgkmcnt(" #n ")" ::: "memory")
; #define PG8_BAR __builtin_amdgcn_s_barrier()
; #define PG8_SCHED __builtin_amdgcn_sched_barrier(0)
; template <class Epi, class Sched, bool ALIGN_EPI = false, bool SP2 = false>
; __device__ __forceinline__ void gemm_phase(PG8_LAS unsigned char* lds, const Gemm g, const Sched& S, const Epi& E) {
;     ...
;             const char* a1 = cA + (size_t)(t + 1) * kstep;
;             const char* a2 = last ? nA : cA + (size_t)(t + 2) * kstep; const char* b2 = last ? nB : cB + (size_t)(t + 2) * kstep;
;             const char* a3 = a2 + kstep; const char* b3 = b2 + kstep;
;             if (last && has_next) S.a_ready(nxt);
;             if constexpr (SP2) {
;             PG8_LDB(B0, 0, 0); PG8_LDB(B1, 0, 1); PG8_SCHED; PG8_LDA(At, 0, 0); PG8_STAGE(PG8_SA(1, 1), a1 + hstep, voffA);
;             PG8_WAIT_V(8); PG8_WAIT_L(0); PG8_BAR; PG8_MMA(0, 0, At, B0); PG8_MMA(0, 1, At, B1); PG8_BAR; PG8_SCHED;
;             PG8_LDA(At, 0, 1); PG8_STAGE(PG8_SB(0, 0), b2, voffB); PG8_STAGE(PG8_SB(0, 1), b2 + hstep, voffB); PG8_STAGE(PG8_SA(0, 0), a2, voffA);
.LBB0_979:
	s_xor_b64 s[40:41], s[38:39], -1
	s_add_u32 s27, s12, s2
	s_addc_u32 s29, s13, 0
	s_add_u32 s3, s27, 0x100
	s_addc_u32 s44, s29, 0
	s_and_b64 s[42:43], s[38:39], exec
	s_cselect_b32 s43, s44, s35
	s_cselect_b32 s42, s3, s34
	s_add_u32 s2, s20, s2
	s_addc_u32 s3, s21, 0
	s_add_u32 s44, s2, 0x100
	s_addc_u32 s45, s3, 0
	s_and_b64 s[2:3], s[38:39], exec
	s_cselect_b32 s39, s45, s31
	s_cselect_b32 s38, s44, s30
	s_add_i32 s44, 0, 0x10000
	s_add_i32 s45, 0, 0x14000
	v_add_u32_e32 v164, s44, v0
	v_add_u32_e32 v180, s45, v0
	ds_read_b128 v[152:155], v164
	ds_read_b128 v[156:159], v164 offset:1024
	ds_read_b128 v[160:163], v164 offset:2048
	ds_read_b128 v[164:167], v164 offset:3072
	ds_read_b128 v[168:171], v180
	ds_read_b128 v[172:175], v180 offset:1024
	ds_read_b128 v[176:179], v180 offset:2048
	ds_read_b128 v[180:183], v180 offset:3072
	s_add_u32 s2, s27, 0x80080
	s_addc_u32 s3, s29, 0
	v_lshl_add_u64 v[224:225], s[2:3], 0, v[66:67]
	s_add_i32 m0, s52, 0xc000
	ds_read_b128 v[184:187], v151
	ds_read_b128 v[188:191], v151 offset:1024
	ds_read_b128 v[192:195], v151 offset:2048
	ds_read_b128 v[196:199], v151 offset:3072
	ds_read_b128 v[200:203], v151 offset:4096
	ds_read_b128 v[204:207], v151 offset:5120
	ds_read_b128 v[208:211], v151 offset:6144
	ds_read_b128 v[220:223], v151 offset:7168
	global_load_lds_dwordx4 v[224:225], off
	v_lshl_add_u64 v[224:225], s[2:3], 0, v[132:133]
	s_add_i32 m0, s52, 0xe000
	s_nop 0
	global_load_lds_dwordx4 v[224:225], off
	s_setprio 1
	s_waitcnt vmcnt(8)
	s_waitcnt lgkmcnt(0)
	s_barrier
	v_mfma_f32_16x16x32_bf16 v[128:131], v[152:155], v[184:187], v[128:131]
	v_mfma_f32_16x16x32_bf16 v[124:127], v[160:163], v[184:187], v[124:127]
	v_mfma_f32_16x16x32_bf16 v[120:123], v[152:155], v[192:195], v[120:123]
	v_mfma_f32_16x16x32_bf16 v[116:119], v[160:163], v[192:195], v[116:119]
	v_mfma_f32_16x16x32_bf16 v[112:115], v[152:155], v[200:203], v[112:115]
	v_mfma_f32_16x16x32_bf16 v[108:111], v[160:163], v[200:203], v[108:111]
	v_mfma_f32_16x16x32_bf16 v[100:103], v[152:155], v[208:211], v[100:103]
	v_mfma_f32_16x16x32_bf16 v[92:95], v[160:163], v[208:211], v[92:95]
	v_mfma_f32_16x16x32_bf16 v[128:131], v[156:159], v[188:191], v[128:131]
	v_mfma_f32_16x16x32_bf16 v[124:127], v[164:167], v[188:191], v[124:127]
	v_mfma_f32_16x16x32_bf16 v[120:123], v[156:159], v[196:199], v[120:123]
	v_mfma_f32_16x16x32_bf16 v[116:119], v[164:167], v[196:199], v[116:119]
	v_mfma_f32_16x16x32_bf16 v[112:115], v[156:159], v[204:207], v[112:115]
	v_mfma_f32_16x16x32_bf16 v[108:111], v[164:167], v[204:207], v[108:111]
	v_mfma_f32_16x16x32_bf16 v[100:103], v[156:159], v[220:223], v[100:103]
	v_mfma_f32_16x16x32_bf16 v[92:95], v[164:167], v[220:223], v[92:95]
	v_mfma_f32_16x16x32_bf16 v[104:107], v[168:171], v[184:187], v[104:107]
	v_mfma_f32_16x16x32_bf16 v[96:99], v[176:179], v[184:187], v[96:99]
	v_mfma_f32_16x16x32_bf16 v[88:91], v[168:171], v[192:195], v[88:91]
	v_mfma_f32_16x16x32_bf16 v[84:87], v[176:179], v[192:195], v[84:87]
	v_mfma_f32_16x16x32_bf16 v[80:83], v[168:171], v[200:203], v[80:83]
	v_mfma_f32_16x16x32_bf16 v[76:79], v[176:179], v[200:203], v[76:79]
	v_mfma_f32_16x16x32_bf16 v[72:75], v[168:171], v[208:211], v[72:75]
	v_mfma_f32_16x16x32_bf16 v[68:71], v[176:179], v[208:211], v[68:71]
	v_mfma_f32_16x16x32_bf16 v[104:107], v[172:175], v[188:191], v[104:107]
	v_mfma_f32_16x16x32_bf16 v[96:99], v[180:183], v[188:191], v[96:99]
	v_mfma_f32_16x16x32_bf16 v[88:91], v[172:175], v[196:199], v[88:91]
	v_mfma_f32_16x16x32_bf16 v[84:87], v[180:183], v[196:199], v[84:87]
	v_mfma_f32_16x16x32_bf16 v[80:83], v[172:175], v[204:207], v[80:83]
	v_mfma_f32_16x16x32_bf16 v[76:79], v[180:183], v[204:207], v[76:79]
	v_mfma_f32_16x16x32_bf16 v[72:75], v[172:175], v[220:223], v[72:75]
	v_mfma_f32_16x16x32_bf16 v[68:71], v[180:183], v[220:223], v[68:71]
	s_barrier
	s_setprio 0
	s_setprio 1
	s_setprio 0
	s_waitcnt lgkmcnt(0)
	s_add_i32 s2, s44, s51
	v_lshl_add_u64 v[224:225], s[38:39], 0, v[66:67]
	s_mov_b32 m0, s2
	ds_read_b128 v[184:187], v151 offset:16384
	ds_read_b128 v[188:191], v151 offset:17408
	ds_read_b128 v[192:195], v151 offset:18432
	ds_read_b128 v[196:199], v151 offset:19456
	ds_read_b128 v[200:203], v151 offset:20480
	ds_read_b128 v[204:207], v151 offset:21504
	ds_read_b128 v[208:211], v151 offset:22528
	ds_read_b128 v[220:223], v151 offset:23552
	global_load_lds_dwordx4 v[224:225], off
	s_add_i32 m0, s2, 0x2000
	s_add_u32 s2, s38, 0x80000
	v_lshl_add_u64 v[226:227], s[38:39], 0, v[132:133]
	s_addc_u32 s3, s39, 0
	s_add_i32 s27, s45, s51
	global_load_lds_dwordx4 v[226:227], off
	v_lshl_add_u64 v[228:229], s[2:3], 0, v[66:67]
	s_mov_b32 m0, s27
	v_lshl_add_u64 v[230:231], s[42:43], 0, v[132:133]
	global_load_lds_dwordx4 v[228:229], off
	v_lshl_add_u64 v[228:229], s[2:3], 0, v[132:133]
	s_add_i32 m0, s27, 0x2000
	s_nop 0
	global_load_lds_dwordx4 v[228:229], off
	v_lshl_add_u64 v[228:229], s[42:43], 0, v[66:67]
	s_mov_b32 m0, s52
	s_nop 0
	global_load_lds_dwordx4 v[228:229], off
	s_mov_b32 m0, s53
	s_nop 0
	global_load_lds_dwordx4 v[230:231], off
	s_setprio 1
	s_waitcnt vmcnt(8)
	s_waitcnt lgkmcnt(0)
	s_barrier
; #define PG8_STAGE(bufoff, gbase, voff) do { _Pragma("unroll") for (int _i = 0; _i < 2; ++_i) \
;         __builtin_amdgcn_global_load_lds((const unsigned*)((const char*)(gbase) + (voff)[_i]), (PG8_LAS unsigned*)(lds + (bufoff) + ldsw + _i * 8192), 16, 0, 0); } while (0)
; #define PG8_LDA(dst, b, h) do { _Pragma("unroll") for (int m = 0; m < 4; ++m) _Pragma("unroll") for (int k = 0; k < 2; ++k) dst[m][k] = *(const PG8_LAS bf16x8*)(lds + PG8_SA(b, h) + aoff + m * 2048 + k * 1024); } while (0)
; #define PG8_LDB(dst, b, h) do { _Pragma("unroll") for (int n = 0; n < 2; ++n) _Pragma("unroll") for (int k = 0; k < 2; ++k) dst[n][k] = *(const PG8_LAS bf16x8*)(lds + PG8_SB(b, h) + boff + n * 2048 + k * 1024); } while (0)
; #define PG8_MMA(ai, bj, At, Bt) do { __builtin_amdgcn_s_setprio(1); _Pragma("unroll") for (int m = 0; m < 4; ++m) _Pragma("unroll") for (int n = 0; n < 2; ++n) _Pragma("unroll") for (int k = 0; k < 2; ++k) \
;         acc[ai][bj][m][n] = __builtin_amdgcn_mfma_f32_16x16x32_bf16(Bt[n][k], At[m][k], acc[ai][bj][m][n], 0, 0, 0); __builtin_amdgcn_s_setprio(0); } while (0)
; #define PG8_WAIT_V(n) asm volatile("s_waitcnt vmcnt(" #n ")" ::: "memory")
; #define PG8_WAIT_L(n) asm volatile("s_waitcnt lgkmcnt(" #n ")" ::: "memory")
; #define PG8_BAR __builtin_amdgcn_s_barrier()
; #define PG8_SCHED __builtin_amdgcn_sched_barrier(0)
; template <class Epi, class Sched, bool ALIGN_EPI = false, bool SP2 = false>
; __device__ __forceinline__ void gemm_phase(PG8_LAS unsigned char* lds, const Gemm g, const Sched& S, const Epi& E) {
;     ...
;             PG8_WAIT_V(8); PG8_WAIT_L(0); PG8_BAR; PG8_MMA(1, 0, At, B0); PG8_MMA(1, 1, At, B1); PG8_BAR; PG8_SCHED;
;             PG8_LDB(B0, 1, 0); PG8_LDB(B1, 1, 1); PG8_SCHED; PG8_LDA(At, 1, 0); PG8_STAGE(PG8_SA(0, 1), a2 + hstep, voffA);
;             PG8_WAIT_V(8); PG8_WAIT_L(0); PG8_BAR; PG8_MMA(0, 0, At, B0); PG8_MMA(0, 1, At, B1); PG8_BAR; PG8_SCHED;
	v_mfma_f32_16x16x32_bf16 v[62:65], v[152:155], v[184:187], v[62:65]
	v_mfma_f32_16x16x32_bf16 v[58:61], v[160:163], v[184:187], v[58:61]
	v_mfma_f32_16x16x32_bf16 v[54:57], v[152:155], v[192:195], v[54:57]
	v_mfma_f32_16x16x32_bf16 v[50:53], v[160:163], v[192:195], v[50:53]
	v_mfma_f32_16x16x32_bf16 v[46:49], v[152:155], v[200:203], v[46:49]
	v_mfma_f32_16x16x32_bf16 v[42:45], v[160:163], v[200:203], v[42:45]
	v_mfma_f32_16x16x32_bf16 v[34:37], v[152:155], v[208:211], v[34:37]
	v_mfma_f32_16x16x32_bf16 v[26:29], v[160:163], v[208:211], v[26:29]
	v_mfma_f32_16x16x32_bf16 v[62:65], v[156:159], v[188:191], v[62:65]
	v_mfma_f32_16x16x32_bf16 v[58:61], v[164:167], v[188:191], v[58:61]
	v_mfma_f32_16x16x32_bf16 v[54:57], v[156:159], v[196:199], v[54:57]
	v_mfma_f32_16x16x32_bf16 v[50:53], v[164:167], v[196:199], v[50:53]
	v_mfma_f32_16x16x32_bf16 v[46:49], v[156:159], v[204:207], v[46:49]
	v_mfma_f32_16x16x32_bf16 v[42:45], v[164:167], v[204:207], v[42:45]
	v_mfma_f32_16x16x32_bf16 v[34:37], v[156:159], v[220:223], v[34:37]
	v_mfma_f32_16x16x32_bf16 v[26:29], v[164:167], v[220:223], v[26:29]
	v_mfma_f32_16x16x32_bf16 v[38:41], v[168:171], v[184:187], v[38:41]
	v_mfma_f32_16x16x32_bf16 v[30:33], v[176:179], v[184:187], v[30:33]
	v_mfma_f32_16x16x32_bf16 v[22:25], v[168:171], v[192:195], v[22:25]
	v_mfma_f32_16x16x32_bf16 v[18:21], v[176:179], v[192:195], v[18:21]
	v_mfma_f32_16x16x32_bf16 v[14:17], v[168:171], v[200:203], v[14:17]
	v_mfma_f32_16x16x32_bf16 v[10:13], v[176:179], v[200:203], v[10:13]
	v_mfma_f32_16x16x32_bf16 v[6:9], v[168:171], v[208:211], v[6:9]
	v_mfma_f32_16x16x32_bf16 v[2:5], v[176:179], v[208:211], v[2:5]
	v_mfma_f32_16x16x32_bf16 v[38:41], v[172:175], v[188:191], v[38:41]
	v_mfma_f32_16x16x32_bf16 v[30:33], v[180:183], v[188:191], v[30:33]
	v_mfma_f32_16x16x32_bf16 v[22:25], v[172:175], v[196:199], v[22:25]
	v_mfma_f32_16x16x32_bf16 v[18:21], v[180:183], v[196:199], v[18:21]
	v_mfma_f32_16x16x32_bf16 v[14:17], v[172:175], v[204:207], v[14:17]
	v_mfma_f32_16x16x32_bf16 v[10:13], v[180:183], v[204:207], v[10:13]
	v_mfma_f32_16x16x32_bf16 v[6:9], v[172:175], v[220:223], v[6:9]
	v_mfma_f32_16x16x32_bf16 v[2:5], v[180:183], v[220:223], v[2:5]
	s_barrier
	s_setprio 0
	s_setprio 1
	s_setprio 0
	s_waitcnt lgkmcnt(0)
	s_add_i32 s27, 0, 0x18000
	s_add_i32 s29, 0, 0x1c000
	v_add_u32_e32 v164, s27, v0
	v_add_u32_e32 v180, s29, v0
	ds_read_b128 v[152:155], v164
	ds_read_b128 v[156:159], v164 offset:1024
	ds_read_b128 v[160:163], v164 offset:2048
	ds_read_b128 v[164:167], v164 offset:3072
	ds_read_b128 v[168:171], v180
	ds_read_b128 v[172:175], v180 offset:1024
	ds_read_b128 v[176:179], v180 offset:2048
	ds_read_b128 v[180:183], v180 offset:3072
	s_add_u32 s2, s42, 0x80000
	s_addc_u32 s3, s43, 0
	s_mov_b32 m0, s54
	v_lshl_add_u64 v[232:233], s[2:3], 0, v[66:67]
	ds_read_b128 v[184:187], v151 offset:32768
	ds_read_b128 v[188:191], v151 offset:33792
	ds_read_b128 v[192:195], v151 offset:34816
	ds_read_b128 v[196:199], v151 offset:35840
	ds_read_b128 v[200:203], v151 offset:36864
	ds_read_b128 v[204:207], v151 offset:37888
	ds_read_b128 v[208:211], v151 offset:38912
	ds_read_b128 v[220:223], v151 offset:39936
	global_load_lds_dwordx4 v[232:233], off
	v_lshl_add_u64 v[232:233], s[2:3], 0, v[132:133]
	s_mov_b32 m0, s55
	s_nop 0
	global_load_lds_dwordx4 v[232:233], off
	s_setprio 1
	s_waitcnt vmcnt(8)
	s_waitcnt lgkmcnt(0)
	s_barrier
	v_mfma_f32_16x16x32_bf16 v[128:131], v[152:155], v[184:187], v[128:131]
	v_mfma_f32_16x16x32_bf16 v[124:127], v[160:163], v[184:187], v[124:127]
	v_mfma_f32_16x16x32_bf16 v[120:123], v[152:155], v[192:195], v[120:123]
	v_mfma_f32_16x16x32_bf16 v[116:119], v[160:163], v[192:195], v[116:119]
	v_mfma_f32_16x16x32_bf16 v[112:115], v[152:155], v[200:203], v[112:115]
	v_mfma_f32_16x16x32_bf16 v[108:111], v[160:163], v[200:203], v[108:111]
	v_mfma_f32_16x16x32_bf16 v[100:103], v[152:155], v[208:211], v[100:103]
	v_mfma_f32_16x16x32_bf16 v[92:95], v[160:163], v[208:211], v[92:95]
	v_mfma_f32_16x16x32_bf16 v[128:131], v[156:159], v[188:191], v[128:131]
	v_mfma_f32_16x16x32_bf16 v[124:127], v[164:167], v[188:191], v[124:127]
	v_mfma_f32_16x16x32_bf16 v[120:123], v[156:159], v[196:199], v[120:123]
	v_mfma_f32_16x16x32_bf16 v[116:119], v[164:167], v[196:199], v[116:119]
	v_mfma_f32_16x16x32_bf16 v[112:115], v[156:159], v[204:207], v[112:115]
	v_mfma_f32_16x16x32_bf16 v[108:111], v[164:167], v[204:207], v[108:111]
	v_mfma_f32_16x16x32_bf16 v[100:103], v[156:159], v[220:223], v[100:103]
	v_mfma_f32_16x16x32_bf16 v[92:95], v[164:167], v[220:223], v[92:95]
	v_mfma_f32_16x16x32_bf16 v[104:107], v[168:171], v[184:187], v[104:107]
	v_mfma_f32_16x16x32_bf16 v[96:99], v[176:179], v[184:187], v[96:99]
	v_mfma_f32_16x16x32_bf16 v[88:91], v[168:171], v[192:195], v[88:91]
	v_mfma_f32_16x16x32_bf16 v[84:87], v[176:179], v[192:195], v[84:87]
	v_mfma_f32_16x16x32_bf16 v[80:83], v[168:171], v[200:203], v[80:83]
	v_mfma_f32_16x16x32_bf16 v[76:79], v[176:179], v[200:203], v[76:79]
	v_mfma_f32_16x16x32_bf16 v[72:75], v[168:171], v[208:211], v[72:75]
	v_mfma_f32_16x16x32_bf16 v[68:71], v[176:179], v[208:211], v[68:71]
	v_mfma_f32_16x16x32_bf16 v[104:107], v[172:175], v[188:191], v[104:107]
	v_mfma_f32_16x16x32_bf16 v[96:99], v[180:183], v[188:191], v[96:99]
	v_mfma_f32_16x16x32_bf16 v[88:91], v[172:175], v[196:199], v[88:91]
	v_mfma_f32_16x16x32_bf16 v[84:87], v[180:183], v[196:199], v[84:87]
	v_mfma_f32_16x16x32_bf16 v[80:83], v[172:175], v[204:207], v[80:83]
	v_mfma_f32_16x16x32_bf16 v[76:79], v[180:183], v[204:207], v[76:79]
	v_mfma_f32_16x16x32_bf16 v[72:75], v[172:175], v[220:223], v[72:75]
	v_mfma_f32_16x16x32_bf16 v[68:71], v[180:183], v[220:223], v[68:71]
	s_barrier
; #define PG8_STAGE(bufoff, gbase, voff) do { _Pragma("unroll") for (int _i = 0; _i < 2; ++_i) \
;         __builtin_amdgcn_global_load_lds((const unsigned*)((const char*)(gbase) + (voff)[_i]), (PG8_LAS unsigned*)(lds + (bufoff) + ldsw + _i * 8192), 16, 0, 0); } while (0)
; #define PG8_LDA(dst, b, h) do { _Pragma("unroll") for (int m = 0; m < 4; ++m) _Pragma("unroll") for (int k = 0; k < 2; ++k) dst[m][k] = *(const PG8_LAS bf16x8*)(lds + PG8_SA(b, h) + aoff + m * 2048 + k * 1024); } while (0)
; #define PG8_MMA(ai, bj, At, Bt) do { __builtin_amdgcn_s_setprio(1); _Pragma("unroll") for (int m = 0; m < 4; ++m) _Pragma("unroll") for (int n = 0; n < 2; ++n) _Pragma("unroll") for (int k = 0; k < 2; ++k) \
;         acc[ai][bj][m][n] = __builtin_amdgcn_mfma_f32_16x16x32_bf16(Bt[n][k], At[m][k], acc[ai][bj][m][n], 0, 0, 0); __builtin_amdgcn_s_setprio(0); } while (0)
; #define PG8_WAIT_V(n) asm volatile("s_waitcnt vmcnt(" #n ")" ::: "memory")
; #define PG8_WAIT_L(n) asm volatile("s_waitcnt lgkmcnt(" #n ")" ::: "memory")
; #define PG8_BAR __builtin_amdgcn_s_barrier()
; #define PG8_SCHED __builtin_amdgcn_sched_barrier(0)
; template <class Epi, class Sched, bool ALIGN_EPI = false, bool SP2 = false>
; __device__ __forceinline__ void gemm_phase(PG8_LAS unsigned char* lds, const Gemm g, const Sched& S, const Epi& E) {
;     ...
;             PG8_LDA(At, 1, 1); PG8_STAGE(PG8_SB(1, 0), b3, voffB); PG8_STAGE(PG8_SB(1, 1), b3 + hstep, voffB); PG8_STAGE(PG8_SA(1, 0), a3, voffA);
;             PG8_WAIT_V(8); PG8_WAIT_L(0); PG8_BAR; PG8_MMA(1, 0, At, B0); PG8_MMA(1, 1, At, B1); PG8_BAR; PG8_SCHED;
	s_setprio 0
	s_setprio 1
	s_setprio 0
	s_waitcnt lgkmcnt(0)
	s_add_i32 s2, s27, s51
	v_lshl_add_u64 v[224:225], v[224:225], 0, s[88:89]
	s_mov_b32 m0, s2
	ds_read_b128 v[184:187], v151 offset:49152
	ds_read_b128 v[188:191], v151 offset:50176
	ds_read_b128 v[192:195], v151 offset:51200
	ds_read_b128 v[196:199], v151 offset:52224
	ds_read_b128 v[200:203], v151 offset:53248
	ds_read_b128 v[204:207], v151 offset:54272
	ds_read_b128 v[208:211], v151 offset:55296
	ds_read_b128 v[220:223], v151 offset:56320
	global_load_lds_dwordx4 v[224:225], off
	s_add_i32 m0, s2, 0x2000
	s_add_u32 s2, s38, 0x80080
	v_lshl_add_u64 v[224:225], v[226:227], 0, s[88:89]
	s_addc_u32 s3, s39, 0
	s_add_i32 s27, s29, s51
	global_load_lds_dwordx4 v[224:225], off
	v_lshl_add_u64 v[224:225], s[2:3], 0, v[66:67]
	s_mov_b32 m0, s27
	s_nop 0
	global_load_lds_dwordx4 v[224:225], off
	v_lshl_add_u64 v[224:225], s[2:3], 0, v[132:133]
	s_add_i32 m0, s27, 0x2000
	s_nop 0
	global_load_lds_dwordx4 v[224:225], off
	v_lshl_add_u64 v[224:225], v[228:229], 0, s[88:89]
	s_mov_b32 m0, s59
	s_nop 0
	global_load_lds_dwordx4 v[224:225], off
	v_lshl_add_u64 v[224:225], v[230:231], 0, s[88:89]
	s_mov_b32 m0, s60
	s_nop 0
	global_load_lds_dwordx4 v[224:225], off
	s_setprio 1
	s_waitcnt vmcnt(8)
	s_waitcnt lgkmcnt(0)
	s_barrier
	v_mfma_f32_16x16x32_bf16 v[62:65], v[152:155], v[184:187], v[62:65]
	v_mfma_f32_16x16x32_bf16 v[58:61], v[160:163], v[184:187], v[58:61]
	v_mfma_f32_16x16x32_bf16 v[54:57], v[152:155], v[192:195], v[54:57]
	v_mfma_f32_16x16x32_bf16 v[50:53], v[160:163], v[192:195], v[50:53]
	v_mfma_f32_16x16x32_bf16 v[46:49], v[152:155], v[200:203], v[46:49]
	v_mfma_f32_16x16x32_bf16 v[42:45], v[160:163], v[200:203], v[42:45]
	v_mfma_f32_16x16x32_bf16 v[34:37], v[152:155], v[208:211], v[34:37]
	v_mfma_f32_16x16x32_bf16 v[26:29], v[160:163], v[208:211], v[26:29]
	v_mfma_f32_16x16x32_bf16 v[62:65], v[156:159], v[188:191], v[62:65]
	v_mfma_f32_16x16x32_bf16 v[58:61], v[164:167], v[188:191], v[58:61]
	v_mfma_f32_16x16x32_bf16 v[54:57], v[156:159], v[196:199], v[54:57]
	v_mfma_f32_16x16x32_bf16 v[50:53], v[164:167], v[196:199], v[50:53]
	v_mfma_f32_16x16x32_bf16 v[46:49], v[156:159], v[204:207], v[46:49]
	v_mfma_f32_16x16x32_bf16 v[42:45], v[164:167], v[204:207], v[42:45]
	v_mfma_f32_16x16x32_bf16 v[34:37], v[156:159], v[220:223], v[34:37]
	v_mfma_f32_16x16x32_bf16 v[26:29], v[164:167], v[220:223], v[26:29]
	v_mfma_f32_16x16x32_bf16 v[38:41], v[168:171], v[184:187], v[38:41]
	v_mfma_f32_16x16x32_bf16 v[30:33], v[176:179], v[184:187], v[30:33]
	v_mfma_f32_16x16x32_bf16 v[22:25], v[168:171], v[192:195], v[22:25]
	v_mfma_f32_16x16x32_bf16 v[18:21], v[176:179], v[192:195], v[18:21]
	v_mfma_f32_16x16x32_bf16 v[14:17], v[168:171], v[200:203], v[14:17]
	v_mfma_f32_16x16x32_bf16 v[10:13], v[176:179], v[200:203], v[10:13]
	v_mfma_f32_16x16x32_bf16 v[6:9], v[168:171], v[208:211], v[6:9]
	v_mfma_f32_16x16x32_bf16 v[2:5], v[176:179], v[208:211], v[2:5]
	v_mfma_f32_16x16x32_bf16 v[38:41], v[172:175], v[188:191], v[38:41]
	v_mfma_f32_16x16x32_bf16 v[30:33], v[180:183], v[188:191], v[30:33]
	v_mfma_f32_16x16x32_bf16 v[22:25], v[172:175], v[196:199], v[22:25]
	v_mfma_f32_16x16x32_bf16 v[18:21], v[180:183], v[196:199], v[18:21]
	v_mfma_f32_16x16x32_bf16 v[14:17], v[172:175], v[204:207], v[14:17]
	v_mfma_f32_16x16x32_bf16 v[10:13], v[180:183], v[204:207], v[10:13]
	v_mfma_f32_16x16x32_bf16 v[6:9], v[172:175], v[220:223], v[6:9]
	v_mfma_f32_16x16x32_bf16 v[2:5], v[180:183], v[220:223], v[2:5]
	s_barrier
	s_setprio 0
	s_setprio 1
	s_setprio 0
	s_waitcnt lgkmcnt(0)
	s_movk_i32 s2, 0x100
	s_mov_b64 s[38:39], 0
	s_and_b64 vcc, exec, s[40:41]
	s_cbranch_vccnz .LBB0_991

; #define PG8_STAGE(bufoff, gbase, voff) do { _Pragma("unroll") for (int _i = 0; _i < 2; ++_i) \
;         __builtin_amdgcn_global_load_lds((const unsigned*)((const char*)(gbase) + (voff)[_i]), (PG8_LAS unsigned*)(lds + (bufoff) + ldsw + _i * 8192), 16, 0, 0); } while (0)
; #define PG8_LDA(dst, b, h) do { _Pragma("unroll") for (int m = 0; m < 4; ++m) _Pragma("unroll") for (int k = 0; k < 2; ++k) dst[m][k] = *(const PG8_LAS bf16x8*)(lds + PG8_SA(b, h) + aoff + m * 2048 + k * 1024); } while (0)
; #define PG8_LDB(dst, b, h) do { _Pragma("unroll") for (int n = 0; n < 2; ++n) _Pragma("unroll") for (int k = 0; k < 2; ++k) dst[n][k] = *(const PG8_LAS bf16x8*)(lds + PG8_SB(b, h) + boff + n * 2048 + k * 1024); } while (0)
; #define PG8_MMA(ai, bj, At, Bt) do { __builtin_amdgcn_s_setprio(1); _Pragma("unroll") for (int m = 0; m < 4; ++m) _Pragma("unroll") for (int n = 0; n < 2; ++n) _Pragma("unroll") for (int k = 0; k < 2; ++k) \
;         acc[ai][bj][m][n] = __builtin_amdgcn_mfma_f32_16x16x32_bf16(Bt[n][k], At[m][k], acc[ai][bj][m][n], 0, 0, 0); __builtin_amdgcn_s_setprio(0); } while (0)
; #define PG8_WAIT_V(n) asm volatile("s_waitcnt vmcnt(" #n ")" ::: "memory")
; #define PG8_WAIT_L(n) asm volatile("s_waitcnt lgkmcnt(" #n ")" ::: "memory")
; #define PG8_BAR __builtin_amdgcn_s_barrier()
; #define PG8_SCHED __builtin_amdgcn_sched_barrier(0)
; template <class Epi, class Sched, bool ALIGN_EPI = false, bool SP2 = false>
; __device__ __forceinline__ void gemm_phase(PG8_LAS unsigned char* lds, const Gemm g, const Sched& S, const Epi& E) {
;     ...
;             const char* a1 = cA + (size_t)(t + 1) * kstep;
;             const char* a2 = last ? nA : cA + (size_t)(t + 2) * kstep; const char* b2 = last ? nB : cB + (size_t)(t + 2) * kstep;
;             const char* a3 = a2 + kstep; const char* b3 = b2 + kstep;
;             if (last && has_next) S.a_ready(nxt);
;             if constexpr (SP2) {
;             PG8_LDB(B0, 0, 0); PG8_LDB(B1, 0, 1); PG8_SCHED; PG8_LDA(At, 0, 0); PG8_STAGE(PG8_SA(1, 1), a1 + hstep, voffA);
;             PG8_WAIT_V(8); PG8_WAIT_L(0); PG8_BAR; PG8_MMA(0, 0, At, B0); PG8_MMA(0, 1, At, B1); PG8_BAR; PG8_SCHED;
;             PG8_LDA(At, 0, 1); PG8_STAGE(PG8_SB(0, 0), b2, voffB); PG8_STAGE(PG8_SB(0, 1), b2 + hstep, voffB); PG8_STAGE(PG8_SA(0, 0), a2, voffA);
.LBB0_1205:
	s_lshl_b32 s52, s31, 7
	s_add_u32 s53, s42, s52
	s_addc_u32 s54, s43, 0
	s_add_u32 s55, s53, 0x100
	s_addc_u32 s56, s54, 0
	s_and_b64 s[50:51], s[48:49], exec
	s_cselect_b32 s51, s56, s1
	s_cselect_b32 s50, s55, s2
	s_add_u32 s52, s44, s52
	s_addc_u32 s55, s45, 0
	s_add_u32 s52, s52, 0x100
	s_addc_u32 s55, s55, 0
	s_and_b64 s[48:49], s[48:49], exec
	s_cselect_b32 s49, s55, s3
	s_cselect_b32 s48, s52, s29
	s_add_i32 s55, 0, 0x10000
	v_add_u32_e32 v138, s55, v140
	s_add_i32 s56, 0, 0x14000
	ds_read_b128 v[144:147], v138
	ds_read_b128 v[148:151], v138 offset:1024
	ds_read_b128 v[152:155], v138 offset:2048
	ds_read_b128 v[156:159], v138 offset:3072
	v_add_u32_e32 v138, s56, v140
	ds_read_b128 v[160:163], v138
	ds_read_b128 v[164:167], v138 offset:1024
	ds_read_b128 v[168:171], v138 offset:2048
	ds_read_b128 v[172:175], v138 offset:3072
	s_add_u32 s52, s53, 0x80080
	s_addc_u32 s53, s54, 0
	v_lshl_add_u64 v[138:139], s[52:53], 0, v[132:133]
	s_add_i32 m0, s41, 0xc000
	ds_read_b128 v[176:179], v142
	ds_read_b128 v[180:183], v142 offset:1024
	ds_read_b128 v[184:187], v142 offset:2048
	ds_read_b128 v[188:191], v142 offset:3072
	ds_read_b128 v[192:195], v142 offset:4096
	ds_read_b128 v[196:199], v142 offset:5120
	ds_read_b128 v[200:203], v142 offset:6144
	ds_read_b128 v[204:207], v142 offset:7168
	global_load_lds_dwordx4 v[138:139], off
	v_lshl_add_u64 v[138:139], s[52:53], 0, v[134:135]
	s_add_i32 m0, s41, 0xe000
	s_nop 0
	global_load_lds_dwordx4 v[138:139], off
	s_setprio 1
	s_waitcnt vmcnt(8)
	s_waitcnt lgkmcnt(0)
	s_barrier
	v_mfma_f32_16x16x32_bf16 v[128:131], v[144:147], v[176:179], v[128:131]
	v_mfma_f32_16x16x32_bf16 v[124:127], v[152:155], v[176:179], v[124:127]
	v_mfma_f32_16x16x32_bf16 v[112:115], v[144:147], v[184:187], v[112:115]
	v_mfma_f32_16x16x32_bf16 v[108:111], v[152:155], v[184:187], v[108:111]
	v_mfma_f32_16x16x32_bf16 v[96:99], v[144:147], v[192:195], v[96:99]
	v_mfma_f32_16x16x32_bf16 v[92:95], v[152:155], v[192:195], v[92:95]
	v_mfma_f32_16x16x32_bf16 v[80:83], v[144:147], v[200:203], v[80:83]
	v_mfma_f32_16x16x32_bf16 v[76:79], v[152:155], v[200:203], v[76:79]
	v_mfma_f32_16x16x32_bf16 v[128:131], v[148:151], v[180:183], v[128:131]
	v_mfma_f32_16x16x32_bf16 v[124:127], v[156:159], v[180:183], v[124:127]
	v_mfma_f32_16x16x32_bf16 v[112:115], v[148:151], v[188:191], v[112:115]
	v_mfma_f32_16x16x32_bf16 v[108:111], v[156:159], v[188:191], v[108:111]
	v_mfma_f32_16x16x32_bf16 v[96:99], v[148:151], v[196:199], v[96:99]
	v_mfma_f32_16x16x32_bf16 v[92:95], v[156:159], v[196:199], v[92:95]
	v_mfma_f32_16x16x32_bf16 v[80:83], v[148:151], v[204:207], v[80:83]
	v_mfma_f32_16x16x32_bf16 v[76:79], v[156:159], v[204:207], v[76:79]
	v_mfma_f32_16x16x32_bf16 v[120:123], v[160:163], v[176:179], v[120:123]
	v_mfma_f32_16x16x32_bf16 v[116:119], v[168:171], v[176:179], v[116:119]
	v_mfma_f32_16x16x32_bf16 v[104:107], v[160:163], v[184:187], v[104:107]
	v_mfma_f32_16x16x32_bf16 v[100:103], v[168:171], v[184:187], v[100:103]
	v_mfma_f32_16x16x32_bf16 v[88:91], v[160:163], v[192:195], v[88:91]
	v_mfma_f32_16x16x32_bf16 v[84:87], v[168:171], v[192:195], v[84:87]
	v_mfma_f32_16x16x32_bf16 v[72:75], v[160:163], v[200:203], v[72:75]
	v_mfma_f32_16x16x32_bf16 v[68:71], v[168:171], v[200:203], v[68:71]
	v_mfma_f32_16x16x32_bf16 v[120:123], v[164:167], v[180:183], v[120:123]
	v_mfma_f32_16x16x32_bf16 v[116:119], v[172:175], v[180:183], v[116:119]
	v_mfma_f32_16x16x32_bf16 v[104:107], v[164:167], v[188:191], v[104:107]
	v_mfma_f32_16x16x32_bf16 v[100:103], v[172:175], v[188:191], v[100:103]
	v_mfma_f32_16x16x32_bf16 v[88:91], v[164:167], v[196:199], v[88:91]
	v_mfma_f32_16x16x32_bf16 v[84:87], v[172:175], v[196:199], v[84:87]
	v_mfma_f32_16x16x32_bf16 v[72:75], v[164:167], v[204:207], v[72:75]
	v_mfma_f32_16x16x32_bf16 v[68:71], v[172:175], v[204:207], v[68:71]
	s_barrier
	s_setprio 0
	s_setprio 1
	s_setprio 0
	s_waitcnt lgkmcnt(0)
	s_add_i32 s52, s55, s39
	v_lshl_add_u64 v[138:139], s[48:49], 0, v[66:67]
	s_mov_b32 m0, s52
	ds_read_b128 v[176:179], v142 offset:16384
	ds_read_b128 v[180:183], v142 offset:17408
	ds_read_b128 v[184:187], v142 offset:18432
	ds_read_b128 v[188:191], v142 offset:19456
	ds_read_b128 v[192:195], v142 offset:20480
	ds_read_b128 v[196:199], v142 offset:21504
	ds_read_b128 v[200:203], v142 offset:22528
	ds_read_b128 v[204:207], v142 offset:23552
	global_load_lds_dwordx4 v[138:139], off
	s_add_i32 m0, s52, 0x2000
	s_add_u32 s52, s48, 0x80000
	v_lshl_add_u64 v[208:209], s[48:49], 0, v[136:137]
	s_addc_u32 s53, s49, 0
	s_add_i32 s54, s56, s39
	global_load_lds_dwordx4 v[208:209], off
	v_lshl_add_u64 v[210:211], s[52:53], 0, v[66:67]
	s_mov_b32 m0, s54
	v_lshl_add_u64 v[220:221], s[50:51], 0, v[134:135]
	global_load_lds_dwordx4 v[210:211], off
	v_lshl_add_u64 v[210:211], s[52:53], 0, v[136:137]
	s_add_i32 m0, s54, 0x2000
	s_nop 0
	global_load_lds_dwordx4 v[210:211], off
	v_lshl_add_u64 v[210:211], s[50:51], 0, v[132:133]
	s_mov_b32 m0, s41
	s_nop 0
	global_load_lds_dwordx4 v[210:211], off
	s_mov_b32 m0, s68
	s_nop 0
	global_load_lds_dwordx4 v[220:221], off
	s_setprio 1
	s_waitcnt vmcnt(8)
	s_waitcnt lgkmcnt(0)
	s_barrier
; #define PG8_STAGE(bufoff, gbase, voff) do { _Pragma("unroll") for (int _i = 0; _i < 2; ++_i) \
;         __builtin_amdgcn_global_load_lds((const unsigned*)((const char*)(gbase) + (voff)[_i]), (PG8_LAS unsigned*)(lds + (bufoff) + ldsw + _i * 8192), 16, 0, 0); } while (0)
; #define PG8_LDA(dst, b, h) do { _Pragma("unroll") for (int m = 0; m < 4; ++m) _Pragma("unroll") for (int k = 0; k < 2; ++k) dst[m][k] = *(const PG8_LAS bf16x8*)(lds + PG8_SA(b, h) + aoff + m * 2048 + k * 1024); } while (0)
; #define PG8_LDB(dst, b, h) do { _Pragma("unroll") for (int n = 0; n < 2; ++n) _Pragma("unroll") for (int k = 0; k < 2; ++k) dst[n][k] = *(const PG8_LAS bf16x8*)(lds + PG8_SB(b, h) + boff + n * 2048 + k * 1024); } while (0)
; #define PG8_MMA(ai, bj, At, Bt) do { __builtin_amdgcn_s_setprio(1); _Pragma("unroll") for (int m = 0; m < 4; ++m) _Pragma("unroll") for (int n = 0; n < 2; ++n) _Pragma("unroll") for (int k = 0; k < 2; ++k) \
;         acc[ai][bj][m][n] = __builtin_amdgcn_mfma_f32_16x16x32_bf16(Bt[n][k], At[m][k], acc[ai][bj][m][n], 0, 0, 0); __builtin_amdgcn_s_setprio(0); } while (0)
; #define PG8_WAIT_V(n) asm volatile("s_waitcnt vmcnt(" #n ")" ::: "memory")
; #define PG8_WAIT_L(n) asm volatile("s_waitcnt lgkmcnt(" #n ")" ::: "memory")
; #define PG8_BAR __builtin_amdgcn_s_barrier()
; #define PG8_SCHED __builtin_amdgcn_sched_barrier(0)
; template <class Epi, class Sched, bool ALIGN_EPI = false, bool SP2 = false>
; __device__ __forceinline__ void gemm_phase(PG8_LAS unsigned char* lds, const Gemm g, const Sched& S, const Epi& E) {
;     ...
;             PG8_WAIT_V(8); PG8_WAIT_L(0); PG8_BAR; PG8_MMA(1, 0, At, B0); PG8_MMA(1, 1, At, B1); PG8_BAR; PG8_SCHED;
;             PG8_LDB(B0, 1, 0); PG8_LDB(B1, 1, 1); PG8_SCHED; PG8_LDA(At, 1, 0); PG8_STAGE(PG8_SA(0, 1), a2 + hstep, voffA);
;             PG8_WAIT_V(8); PG8_WAIT_L(0); PG8_BAR; PG8_MMA(0, 0, At, B0); PG8_MMA(0, 1, At, B1); PG8_BAR; PG8_SCHED;
	v_mfma_f32_16x16x32_bf16 v[62:65], v[144:147], v[176:179], v[62:65]
	v_mfma_f32_16x16x32_bf16 v[58:61], v[152:155], v[176:179], v[58:61]
	v_mfma_f32_16x16x32_bf16 v[46:49], v[144:147], v[184:187], v[46:49]
	v_mfma_f32_16x16x32_bf16 v[42:45], v[152:155], v[184:187], v[42:45]
	v_mfma_f32_16x16x32_bf16 v[30:33], v[144:147], v[192:195], v[30:33]
	v_mfma_f32_16x16x32_bf16 v[26:29], v[152:155], v[192:195], v[26:29]
	v_mfma_f32_16x16x32_bf16 v[14:17], v[144:147], v[200:203], v[14:17]
	v_mfma_f32_16x16x32_bf16 v[10:13], v[152:155], v[200:203], v[10:13]
	v_mfma_f32_16x16x32_bf16 v[62:65], v[148:151], v[180:183], v[62:65]
	v_mfma_f32_16x16x32_bf16 v[58:61], v[156:159], v[180:183], v[58:61]
	v_mfma_f32_16x16x32_bf16 v[46:49], v[148:151], v[188:191], v[46:49]
	v_mfma_f32_16x16x32_bf16 v[42:45], v[156:159], v[188:191], v[42:45]
	v_mfma_f32_16x16x32_bf16 v[30:33], v[148:151], v[196:199], v[30:33]
	v_mfma_f32_16x16x32_bf16 v[26:29], v[156:159], v[196:199], v[26:29]
	v_mfma_f32_16x16x32_bf16 v[14:17], v[148:151], v[204:207], v[14:17]
	v_mfma_f32_16x16x32_bf16 v[10:13], v[156:159], v[204:207], v[10:13]
	v_mfma_f32_16x16x32_bf16 v[54:57], v[160:163], v[176:179], v[54:57]
	v_mfma_f32_16x16x32_bf16 v[50:53], v[168:171], v[176:179], v[50:53]
	v_mfma_f32_16x16x32_bf16 v[38:41], v[160:163], v[184:187], v[38:41]
	v_mfma_f32_16x16x32_bf16 v[34:37], v[168:171], v[184:187], v[34:37]
	v_mfma_f32_16x16x32_bf16 v[22:25], v[160:163], v[192:195], v[22:25]
	v_mfma_f32_16x16x32_bf16 v[18:21], v[168:171], v[192:195], v[18:21]
	v_mfma_f32_16x16x32_bf16 v[6:9], v[160:163], v[200:203], v[6:9]
	v_mfma_f32_16x16x32_bf16 v[2:5], v[168:171], v[200:203], v[2:5]
	v_mfma_f32_16x16x32_bf16 v[54:57], v[164:167], v[180:183], v[54:57]
	v_mfma_f32_16x16x32_bf16 v[50:53], v[172:175], v[180:183], v[50:53]
	v_mfma_f32_16x16x32_bf16 v[38:41], v[164:167], v[188:191], v[38:41]
	v_mfma_f32_16x16x32_bf16 v[34:37], v[172:175], v[188:191], v[34:37]
	v_mfma_f32_16x16x32_bf16 v[22:25], v[164:167], v[196:199], v[22:25]
	v_mfma_f32_16x16x32_bf16 v[18:21], v[172:175], v[196:199], v[18:21]
	v_mfma_f32_16x16x32_bf16 v[6:9], v[164:167], v[204:207], v[6:9]
	v_mfma_f32_16x16x32_bf16 v[2:5], v[172:175], v[204:207], v[2:5]
	s_barrier
	s_setprio 0
	s_setprio 1
	s_setprio 0
	s_waitcnt lgkmcnt(0)
	s_add_i32 s52, 0, 0x18000
	v_add_u32_e32 v143, s52, v140
	s_add_i32 s53, 0, 0x1c000
	ds_read_b128 v[144:147], v143
	ds_read_b128 v[148:151], v143 offset:1024
	ds_read_b128 v[152:155], v143 offset:2048
	ds_read_b128 v[156:159], v143 offset:3072
	v_add_u32_e32 v143, s53, v140
	ds_read_b128 v[160:163], v143
	ds_read_b128 v[164:167], v143 offset:1024
	ds_read_b128 v[168:171], v143 offset:2048
	ds_read_b128 v[172:175], v143 offset:3072
	s_add_u32 s50, s50, 0x80000
	s_addc_u32 s51, s51, 0
	s_mov_b32 m0, s69
	v_lshl_add_u64 v[222:223], s[50:51], 0, v[132:133]
	ds_read_b128 v[176:179], v142 offset:32768
	ds_read_b128 v[180:183], v142 offset:33792
	ds_read_b128 v[184:187], v142 offset:34816
	ds_read_b128 v[188:191], v142 offset:35840
	ds_read_b128 v[192:195], v142 offset:36864
	ds_read_b128 v[196:199], v142 offset:37888
	ds_read_b128 v[200:203], v142 offset:38912
	ds_read_b128 v[204:207], v142 offset:39936
	global_load_lds_dwordx4 v[222:223], off
	v_lshl_add_u64 v[222:223], s[50:51], 0, v[134:135]
	s_mov_b32 m0, s70
	s_nop 0
	global_load_lds_dwordx4 v[222:223], off
	s_setprio 1
	s_waitcnt vmcnt(8)
	s_waitcnt lgkmcnt(0)
	s_barrier
	v_mfma_f32_16x16x32_bf16 v[128:131], v[144:147], v[176:179], v[128:131]
	v_mfma_f32_16x16x32_bf16 v[124:127], v[152:155], v[176:179], v[124:127]
	v_mfma_f32_16x16x32_bf16 v[112:115], v[144:147], v[184:187], v[112:115]
	v_mfma_f32_16x16x32_bf16 v[108:111], v[152:155], v[184:187], v[108:111]
	v_mfma_f32_16x16x32_bf16 v[96:99], v[144:147], v[192:195], v[96:99]
	v_mfma_f32_16x16x32_bf16 v[92:95], v[152:155], v[192:195], v[92:95]
	v_mfma_f32_16x16x32_bf16 v[80:83], v[144:147], v[200:203], v[80:83]
	v_mfma_f32_16x16x32_bf16 v[76:79], v[152:155], v[200:203], v[76:79]
	v_mfma_f32_16x16x32_bf16 v[128:131], v[148:151], v[180:183], v[128:131]
	v_mfma_f32_16x16x32_bf16 v[124:127], v[156:159], v[180:183], v[124:127]
	v_mfma_f32_16x16x32_bf16 v[112:115], v[148:151], v[188:191], v[112:115]
	v_mfma_f32_16x16x32_bf16 v[108:111], v[156:159], v[188:191], v[108:111]
	v_mfma_f32_16x16x32_bf16 v[96:99], v[148:151], v[196:199], v[96:99]
	v_mfma_f32_16x16x32_bf16 v[92:95], v[156:159], v[196:199], v[92:95]
	v_mfma_f32_16x16x32_bf16 v[80:83], v[148:151], v[204:207], v[80:83]
	v_mfma_f32_16x16x32_bf16 v[76:79], v[156:159], v[204:207], v[76:79]
	v_mfma_f32_16x16x32_bf16 v[120:123], v[160:163], v[176:179], v[120:123]
	v_mfma_f32_16x16x32_bf16 v[116:119], v[168:171], v[176:179], v[116:119]
	v_mfma_f32_16x16x32_bf16 v[104:107], v[160:163], v[184:187], v[104:107]
	v_mfma_f32_16x16x32_bf16 v[100:103], v[168:171], v[184:187], v[100:103]
	v_mfma_f32_16x16x32_bf16 v[88:91], v[160:163], v[192:195], v[88:91]
	v_mfma_f32_16x16x32_bf16 v[84:87], v[168:171], v[192:195], v[84:87]
	v_mfma_f32_16x16x32_bf16 v[72:75], v[160:163], v[200:203], v[72:75]
	v_mfma_f32_16x16x32_bf16 v[68:71], v[168:171], v[200:203], v[68:71]
	v_mfma_f32_16x16x32_bf16 v[120:123], v[164:167], v[180:183], v[120:123]
	v_mfma_f32_16x16x32_bf16 v[116:119], v[172:175], v[180:183], v[116:119]
	v_mfma_f32_16x16x32_bf16 v[104:107], v[164:167], v[188:191], v[104:107]
	v_mfma_f32_16x16x32_bf16 v[100:103], v[172:175], v[188:191], v[100:103]
	v_mfma_f32_16x16x32_bf16 v[88:91], v[164:167], v[196:199], v[88:91]
	v_mfma_f32_16x16x32_bf16 v[84:87], v[172:175], v[196:199], v[84:87]
	v_mfma_f32_16x16x32_bf16 v[72:75], v[164:167], v[204:207], v[72:75]
	v_mfma_f32_16x16x32_bf16 v[68:71], v[172:175], v[204:207], v[68:71]
	s_barrier
; #define PG8_STAGE(bufoff, gbase, voff) do { _Pragma("unroll") for (int _i = 0; _i < 2; ++_i) \
;         __builtin_amdgcn_global_load_lds((const unsigned*)((const char*)(gbase) + (voff)[_i]), (PG8_LAS unsigned*)(lds + (bufoff) + ldsw + _i * 8192), 16, 0, 0); } while (0)
; #define PG8_LDA(dst, b, h) do { _Pragma("unroll") for (int m = 0; m < 4; ++m) _Pragma("unroll") for (int k = 0; k < 2; ++k) dst[m][k] = *(const PG8_LAS bf16x8*)(lds + PG8_SA(b, h) + aoff + m * 2048 + k * 1024); } while (0)
; #define PG8_MMA(ai, bj, At, Bt) do { __builtin_amdgcn_s_setprio(1); _Pragma("unroll") for (int m = 0; m < 4; ++m) _Pragma("unroll") for (int n = 0; n < 2; ++n) _Pragma("unroll") for (int k = 0; k < 2; ++k) \
;         acc[ai][bj][m][n] = __builtin_amdgcn_mfma_f32_16x16x32_bf16(Bt[n][k], At[m][k], acc[ai][bj][m][n], 0, 0, 0); __builtin_amdgcn_s_setprio(0); } while (0)
; #define PG8_WAIT_V(n) asm volatile("s_waitcnt vmcnt(" #n ")" ::: "memory")
; #define PG8_WAIT_L(n) asm volatile("s_waitcnt lgkmcnt(" #n ")" ::: "memory")
; #define PG8_BAR __builtin_amdgcn_s_barrier()
; #define PG8_SCHED __builtin_amdgcn_sched_barrier(0)
; template <class Epi, class Sched, bool ALIGN_EPI = false, bool SP2 = false>
; __device__ __forceinline__ void gemm_phase(PG8_LAS unsigned char* lds, const Gemm g, const Sched& S, const Epi& E) {
;     ...
;             PG8_LDA(At, 1, 1); PG8_STAGE(PG8_SB(1, 0), b3, voffB); PG8_STAGE(PG8_SB(1, 1), b3 + hstep, voffB); PG8_STAGE(PG8_SA(1, 0), a3, voffA);
;             PG8_WAIT_V(8); PG8_WAIT_L(0); PG8_BAR; PG8_MMA(1, 0, At, B0); PG8_MMA(1, 1, At, B1); PG8_BAR; PG8_SCHED;
	s_setprio 0
	s_setprio 1
	s_setprio 0
	s_waitcnt lgkmcnt(0)
	s_add_i32 s50, s52, s39
	v_lshl_add_u64 v[138:139], v[138:139], 0, s[88:89]
	s_mov_b32 m0, s50
	ds_read_b128 v[176:179], v142 offset:49152
	ds_read_b128 v[180:183], v142 offset:50176
	ds_read_b128 v[184:187], v142 offset:51200
	ds_read_b128 v[188:191], v142 offset:52224
	ds_read_b128 v[192:195], v142 offset:53248
	ds_read_b128 v[196:199], v142 offset:54272
	ds_read_b128 v[200:203], v142 offset:55296
	ds_read_b128 v[204:207], v142 offset:56320
	global_load_lds_dwordx4 v[138:139], off
	s_add_i32 m0, s50, 0x2000
	s_add_u32 s48, s48, 0x80080
	v_lshl_add_u64 v[138:139], v[208:209], 0, s[88:89]
	s_addc_u32 s49, s49, 0
	s_add_i32 s50, s53, s39
	global_load_lds_dwordx4 v[138:139], off
	v_lshl_add_u64 v[138:139], s[48:49], 0, v[66:67]
	s_mov_b32 m0, s50
	s_nop 0
	global_load_lds_dwordx4 v[138:139], off
	v_lshl_add_u64 v[138:139], s[48:49], 0, v[136:137]
	s_add_i32 m0, s50, 0x2000
	s_nop 0
	global_load_lds_dwordx4 v[138:139], off
	v_lshl_add_u64 v[138:139], v[210:211], 0, s[88:89]
	s_mov_b32 m0, s71
	s_nop 0
	global_load_lds_dwordx4 v[138:139], off
	v_lshl_add_u64 v[138:139], v[220:221], 0, s[88:89]
	s_mov_b32 m0, s72
	s_nop 0
	global_load_lds_dwordx4 v[138:139], off
	s_setprio 1
	s_waitcnt vmcnt(8)
	s_waitcnt lgkmcnt(0)
	s_barrier
	v_mfma_f32_16x16x32_bf16 v[62:65], v[144:147], v[176:179], v[62:65]
	v_mfma_f32_16x16x32_bf16 v[58:61], v[152:155], v[176:179], v[58:61]
	v_mfma_f32_16x16x32_bf16 v[46:49], v[144:147], v[184:187], v[46:49]
	v_mfma_f32_16x16x32_bf16 v[42:45], v[152:155], v[184:187], v[42:45]
	v_mfma_f32_16x16x32_bf16 v[30:33], v[144:147], v[192:195], v[30:33]
	v_mfma_f32_16x16x32_bf16 v[26:29], v[152:155], v[192:195], v[26:29]
	v_mfma_f32_16x16x32_bf16 v[14:17], v[144:147], v[200:203], v[14:17]
	v_mfma_f32_16x16x32_bf16 v[10:13], v[152:155], v[200:203], v[10:13]
	v_mfma_f32_16x16x32_bf16 v[62:65], v[148:151], v[180:183], v[62:65]
	v_mfma_f32_16x16x32_bf16 v[58:61], v[156:159], v[180:183], v[58:61]
	v_mfma_f32_16x16x32_bf16 v[46:49], v[148:151], v[188:191], v[46:49]
	v_mfma_f32_16x16x32_bf16 v[42:45], v[156:159], v[188:191], v[42:45]
	v_mfma_f32_16x16x32_bf16 v[30:33], v[148:151], v[196:199], v[30:33]
	v_mfma_f32_16x16x32_bf16 v[26:29], v[156:159], v[196:199], v[26:29]
	v_mfma_f32_16x16x32_bf16 v[14:17], v[148:151], v[204:207], v[14:17]
	v_mfma_f32_16x16x32_bf16 v[10:13], v[156:159], v[204:207], v[10:13]
	v_mfma_f32_16x16x32_bf16 v[54:57], v[160:163], v[176:179], v[54:57]
	v_mfma_f32_16x16x32_bf16 v[50:53], v[168:171], v[176:179], v[50:53]
	v_mfma_f32_16x16x32_bf16 v[38:41], v[160:163], v[184:187], v[38:41]
	v_mfma_f32_16x16x32_bf16 v[34:37], v[168:171], v[184:187], v[34:37]
	v_mfma_f32_16x16x32_bf16 v[22:25], v[160:163], v[192:195], v[22:25]
	v_mfma_f32_16x16x32_bf16 v[18:21], v[168:171], v[192:195], v[18:21]
	v_mfma_f32_16x16x32_bf16 v[6:9], v[160:163], v[200:203], v[6:9]
	v_mfma_f32_16x16x32_bf16 v[2:5], v[168:171], v[200:203], v[2:5]
	v_mfma_f32_16x16x32_bf16 v[54:57], v[164:167], v[180:183], v[54:57]
	v_mfma_f32_16x16x32_bf16 v[50:53], v[172:175], v[180:183], v[50:53]
	v_mfma_f32_16x16x32_bf16 v[38:41], v[164:167], v[188:191], v[38:41]
	v_mfma_f32_16x16x32_bf16 v[34:37], v[172:175], v[188:191], v[34:37]
	v_mfma_f32_16x16x32_bf16 v[22:25], v[164:167], v[196:199], v[22:25]
	v_mfma_f32_16x16x32_bf16 v[18:21], v[172:175], v[196:199], v[18:21]
	v_mfma_f32_16x16x32_bf16 v[6:9], v[164:167], v[204:207], v[6:9]
	v_mfma_f32_16x16x32_bf16 v[2:5], v[172:175], v[204:207], v[2:5]
	s_barrier
	s_setprio 0
	s_setprio 1
	s_setprio 0
	s_waitcnt lgkmcnt(0)
	s_add_i32 s48, s31, 2
	s_cmp_gt_u32 s31, 29
	s_mov_b32 s31, s48
	s_cbranch_scc1 .LBB0_1217

; #define PG8_STAGE(bufoff, gbase, voff) do { _Pragma("unroll") for (int _i = 0; _i < 2; ++_i) \
;         __builtin_amdgcn_global_load_lds((const unsigned*)((const char*)(gbase) + (voff)[_i]), (PG8_LAS unsigned*)(lds + (bufoff) + ldsw + _i * 8192), 16, 0, 0); } while (0)
; #define PG8_LDA(dst, b, h) do { _Pragma("unroll") for (int m = 0; m < 4; ++m) _Pragma("unroll") for (int k = 0; k < 2; ++k) dst[m][k] = *(const PG8_LAS bf16x8*)(lds + PG8_SA(b, h) + aoff + m * 2048 + k * 1024); } while (0)
; #define PG8_LDB(dst, b, h) do { _Pragma("unroll") for (int n = 0; n < 2; ++n) _Pragma("unroll") for (int k = 0; k < 2; ++k) dst[n][k] = *(const PG8_LAS bf16x8*)(lds + PG8_SB(b, h) + boff + n * 2048 + k * 1024); } while (0)
; #define PG8_MMA(ai, bj, At, Bt) do { __builtin_amdgcn_s_setprio(1); _Pragma("unroll") for (int m = 0; m < 4; ++m) _Pragma("unroll") for (int n = 0; n < 2; ++n) _Pragma("unroll") for (int k = 0; k < 2; ++k) \
;         acc[ai][bj][m][n] = __builtin_amdgcn_mfma_f32_16x16x32_bf16(Bt[n][k], At[m][k], acc[ai][bj][m][n], 0, 0, 0); __builtin_amdgcn_s_setprio(0); } while (0)
; #define PG8_WAIT_V(n) asm volatile("s_waitcnt vmcnt(" #n ")" ::: "memory")
; #define PG8_WAIT_L(n) asm volatile("s_waitcnt lgkmcnt(" #n ")" ::: "memory")
; #define PG8_BAR __builtin_amdgcn_s_barrier()
; #define PG8_SCHED __builtin_amdgcn_sched_barrier(0)
; template <class Epi, class Sched, bool ALIGN_EPI = false, bool SP2 = false>
; __device__ __forceinline__ void gemm_phase(PG8_LAS unsigned char* lds, const Gemm g, const Sched& S, const Epi& E) {
;     ...
;             const char* a1 = cA + (size_t)(t + 1) * kstep;
;             const char* a2 = last ? nA : cA + (size_t)(t + 2) * kstep; const char* b2 = last ? nB : cB + (size_t)(t + 2) * kstep;
;             const char* a3 = a2 + kstep; const char* b3 = b2 + kstep;
;             if (last && has_next) S.a_ready(nxt);
;             if constexpr (SP2) {
;             PG8_LDB(B0, 0, 0); PG8_LDB(B1, 0, 1); PG8_SCHED; PG8_LDA(At, 0, 0); PG8_STAGE(PG8_SA(1, 1), a1 + hstep, voffA);
;             PG8_WAIT_V(8); PG8_WAIT_L(0); PG8_BAR; PG8_MMA(0, 0, At, B0); PG8_MMA(0, 1, At, B1); PG8_BAR; PG8_SCHED;
;             PG8_LDA(At, 0, 1); PG8_STAGE(PG8_SB(0, 0), b2, voffB); PG8_STAGE(PG8_SB(0, 1), b2 + hstep, voffB); PG8_STAGE(PG8_SA(0, 0), a2, voffA);
.LBB0_1294:
	s_add_u32 s26, s24, 0x100
	s_addc_u32 s27, s25, 0
	s_add_i32 s54, 0, 0x10000
	s_cmpk_eq_i32 s53, 0x54
	s_cselect_b32 s31, s13, s27
	s_cselect_b32 s30, s12, s26
	s_cselect_b32 s29, s23, s3
	s_cselect_b32 s28, s22, s2
	s_add_i32 s55, 0, 0x14000
	v_add_u32_e32 v144, s54, v156
	v_add_u32_e32 v154, s55, v156
	ds_read_b128 v[132:135], v144
	ds_read_b128 v[136:139], v144 offset:1024
	ds_read_b128 v[140:143], v144 offset:2048
	ds_read_b128 v[144:147], v144 offset:3072
	ds_read_b128 v[160:163], v154
	ds_read_b128 v[164:167], v154 offset:1024
	ds_read_b128 v[168:171], v154 offset:2048
	ds_read_b128 v[172:175], v154 offset:3072
	v_lshl_add_u64 v[154:155], s[24:25], 0, v[150:151]
	s_add_i32 m0, s39, 0xc000
	ds_read_b128 v[176:179], v158
	ds_read_b128 v[180:183], v158 offset:1024
	ds_read_b128 v[184:187], v158 offset:2048
	ds_read_b128 v[188:191], v158 offset:3072
	ds_read_b128 v[192:195], v158 offset:4096
	ds_read_b128 v[196:199], v158 offset:5120
	ds_read_b128 v[200:203], v158 offset:6144
	ds_read_b128 v[204:207], v158 offset:7168
	global_load_lds_dwordx4 v[154:155], off
	v_lshl_add_u64 v[154:155], s[24:25], 0, v[152:153]
	s_add_i32 m0, s39, 0xe000
	s_nop 0
	global_load_lds_dwordx4 v[154:155], off
	s_setprio 1
	s_waitcnt vmcnt(8)
	s_waitcnt lgkmcnt(0)
	s_barrier
	v_mfma_f32_16x16x32_bf16 v[128:131], v[132:135], v[176:179], v[128:131]
	v_mfma_f32_16x16x32_bf16 v[124:127], v[140:143], v[176:179], v[124:127]
	v_mfma_f32_16x16x32_bf16 v[120:123], v[132:135], v[184:187], v[120:123]
	v_mfma_f32_16x16x32_bf16 v[112:115], v[140:143], v[184:187], v[112:115]
	v_mfma_f32_16x16x32_bf16 v[104:107], v[132:135], v[192:195], v[104:107]
	v_mfma_f32_16x16x32_bf16 v[96:99], v[140:143], v[192:195], v[96:99]
	v_mfma_f32_16x16x32_bf16 v[88:91], v[132:135], v[200:203], v[88:91]
	v_mfma_f32_16x16x32_bf16 v[76:79], v[140:143], v[200:203], v[76:79]
	v_mfma_f32_16x16x32_bf16 v[128:131], v[136:139], v[180:183], v[128:131]
	v_mfma_f32_16x16x32_bf16 v[124:127], v[144:147], v[180:183], v[124:127]
	v_mfma_f32_16x16x32_bf16 v[120:123], v[136:139], v[188:191], v[120:123]
	v_mfma_f32_16x16x32_bf16 v[112:115], v[144:147], v[188:191], v[112:115]
	v_mfma_f32_16x16x32_bf16 v[104:107], v[136:139], v[196:199], v[104:107]
	v_mfma_f32_16x16x32_bf16 v[96:99], v[144:147], v[196:199], v[96:99]
	v_mfma_f32_16x16x32_bf16 v[88:91], v[136:139], v[204:207], v[88:91]
	v_mfma_f32_16x16x32_bf16 v[76:79], v[144:147], v[204:207], v[76:79]
	v_mfma_f32_16x16x32_bf16 v[116:119], v[160:163], v[176:179], v[116:119]
	v_mfma_f32_16x16x32_bf16 v[108:111], v[168:171], v[176:179], v[108:111]
	v_mfma_f32_16x16x32_bf16 v[100:103], v[160:163], v[184:187], v[100:103]
	v_mfma_f32_16x16x32_bf16 v[92:95], v[168:171], v[184:187], v[92:95]
	v_mfma_f32_16x16x32_bf16 v[84:87], v[160:163], v[192:195], v[84:87]
	v_mfma_f32_16x16x32_bf16 v[80:83], v[168:171], v[192:195], v[80:83]
	v_mfma_f32_16x16x32_bf16 v[72:75], v[160:163], v[200:203], v[72:75]
	v_mfma_f32_16x16x32_bf16 v[68:71], v[168:171], v[200:203], v[68:71]
	v_mfma_f32_16x16x32_bf16 v[116:119], v[164:167], v[180:183], v[116:119]
	v_mfma_f32_16x16x32_bf16 v[108:111], v[172:175], v[180:183], v[108:111]
	v_mfma_f32_16x16x32_bf16 v[100:103], v[164:167], v[188:191], v[100:103]
	v_mfma_f32_16x16x32_bf16 v[92:95], v[172:175], v[188:191], v[92:95]
	v_mfma_f32_16x16x32_bf16 v[84:87], v[164:167], v[196:199], v[84:87]
	v_mfma_f32_16x16x32_bf16 v[80:83], v[172:175], v[196:199], v[80:83]
	v_mfma_f32_16x16x32_bf16 v[72:75], v[164:167], v[204:207], v[72:75]
	v_mfma_f32_16x16x32_bf16 v[68:71], v[172:175], v[204:207], v[68:71]
	s_barrier
	s_setprio 0
	s_setprio 1
	s_setprio 0
	s_waitcnt lgkmcnt(0)
	s_add_i32 s24, s54, s38
	v_lshl_add_u64 v[154:155], s[28:29], 0, v[66:67]
	s_mov_b32 m0, s24
	ds_read_b128 v[176:179], v158 offset:16384
	ds_read_b128 v[180:183], v158 offset:17408
	ds_read_b128 v[184:187], v158 offset:18432
	ds_read_b128 v[188:191], v158 offset:19456
	ds_read_b128 v[192:195], v158 offset:20480
	ds_read_b128 v[196:199], v158 offset:21504
	ds_read_b128 v[200:203], v158 offset:22528
	ds_read_b128 v[204:207], v158 offset:23552
	global_load_lds_dwordx4 v[154:155], off
	s_add_i32 m0, s24, 0x2000
	s_add_u32 s24, s28, 0x160000
	v_lshl_add_u64 v[208:209], s[28:29], 0, v[148:149]
	s_addc_u32 s25, s29, 0
	s_add_i32 s54, s55, s38
	global_load_lds_dwordx4 v[208:209], off
	v_lshl_add_u64 v[210:211], s[24:25], 0, v[66:67]
	s_mov_b32 m0, s54
	v_lshl_add_u64 v[220:221], s[30:31], 0, v[148:149]
	global_load_lds_dwordx4 v[210:211], off
	v_lshl_add_u64 v[210:211], s[24:25], 0, v[148:149]
	s_add_i32 m0, s54, 0x2000
	s_nop 0
	global_load_lds_dwordx4 v[210:211], off
	v_lshl_add_u64 v[210:211], s[30:31], 0, v[66:67]
	s_mov_b32 m0, s39
	s_nop 0
	global_load_lds_dwordx4 v[210:211], off
	s_mov_b32 m0, s40
	s_nop 0
	global_load_lds_dwordx4 v[220:221], off
	s_setprio 1
	s_waitcnt vmcnt(8)
	s_waitcnt lgkmcnt(0)
	s_barrier
; #define PG8_STAGE(bufoff, gbase, voff) do { _Pragma("unroll") for (int _i = 0; _i < 2; ++_i) \
;         __builtin_amdgcn_global_load_lds((const unsigned*)((const char*)(gbase) + (voff)[_i]), (PG8_LAS unsigned*)(lds + (bufoff) + ldsw + _i * 8192), 16, 0, 0); } while (0)
; #define PG8_LDA(dst, b, h) do { _Pragma("unroll") for (int m = 0; m < 4; ++m) _Pragma("unroll") for (int k = 0; k < 2; ++k) dst[m][k] = *(const PG8_LAS bf16x8*)(lds + PG8_SA(b, h) + aoff + m * 2048 + k * 1024); } while (0)
; #define PG8_LDB(dst, b, h) do { _Pragma("unroll") for (int n = 0; n < 2; ++n) _Pragma("unroll") for (int k = 0; k < 2; ++k) dst[n][k] = *(const PG8_LAS bf16x8*)(lds + PG8_SB(b, h) + boff + n * 2048 + k * 1024); } while (0)
; #define PG8_MMA(ai, bj, At, Bt) do { __builtin_amdgcn_s_setprio(1); _Pragma("unroll") for (int m = 0; m < 4; ++m) _Pragma("unroll") for (int n = 0; n < 2; ++n) _Pragma("unroll") for (int k = 0; k < 2; ++k) \
;         acc[ai][bj][m][n] = __builtin_amdgcn_mfma_f32_16x16x32_bf16(Bt[n][k], At[m][k], acc[ai][bj][m][n], 0, 0, 0); __builtin_amdgcn_s_setprio(0); } while (0)
; #define PG8_WAIT_V(n) asm volatile("s_waitcnt vmcnt(" #n ")" ::: "memory")
; #define PG8_WAIT_L(n) asm volatile("s_waitcnt lgkmcnt(" #n ")" ::: "memory")
; #define PG8_BAR __builtin_amdgcn_s_barrier()
; #define PG8_SCHED __builtin_amdgcn_sched_barrier(0)
; template <class Epi, class Sched, bool ALIGN_EPI = false, bool SP2 = false>
; __device__ __forceinline__ void gemm_phase(PG8_LAS unsigned char* lds, const Gemm g, const Sched& S, const Epi& E) {
;     ...
;             PG8_WAIT_V(8); PG8_WAIT_L(0); PG8_BAR; PG8_MMA(0, 0, At, B0); PG8_MMA(0, 1, At, B1); PG8_BAR; PG8_SCHED;
;             PG8_LDA(At, 0, 1); PG8_STAGE(PG8_SB(0, 0), b2, voffB); PG8_STAGE(PG8_SB(0, 1), b2 + hstep, voffB); PG8_STAGE(PG8_SA(0, 0), a2, voffA);
;             PG8_WAIT_V(8); PG8_WAIT_L(0); PG8_BAR; PG8_MMA(1, 0, At, B0); PG8_MMA(1, 1, At, B1); PG8_BAR; PG8_SCHED;
;             PG8_LDB(B0, 1, 0); PG8_LDB(B1, 1, 1); PG8_SCHED; PG8_LDA(At, 1, 0); PG8_STAGE(PG8_SA(0, 1), a2 + hstep, voffA);
;             PG8_WAIT_V(8); PG8_WAIT_L(0); PG8_BAR; PG8_MMA(0, 0, At, B0); PG8_MMA(0, 1, At, B1); PG8_BAR; PG8_SCHED;
;             PG8_LDA(At, 1, 1); PG8_STAGE(PG8_SB(1, 0), b3, voffB); PG8_STAGE(PG8_SB(1, 1), b3 + hstep, voffB); PG8_STAGE(PG8_SA(1, 0), a3, voffA);
	v_mfma_f32_16x16x32_bf16 v[62:65], v[132:135], v[176:179], v[62:65]
	v_mfma_f32_16x16x32_bf16 v[58:61], v[140:143], v[176:179], v[58:61]
	v_mfma_f32_16x16x32_bf16 v[54:57], v[132:135], v[184:187], v[54:57]
	v_mfma_f32_16x16x32_bf16 v[46:49], v[140:143], v[184:187], v[46:49]
	v_mfma_f32_16x16x32_bf16 v[38:41], v[132:135], v[192:195], v[38:41]
	v_mfma_f32_16x16x32_bf16 v[30:33], v[140:143], v[192:195], v[30:33]
	v_mfma_f32_16x16x32_bf16 v[22:25], v[132:135], v[200:203], v[22:25]
	v_mfma_f32_16x16x32_bf16 v[10:13], v[140:143], v[200:203], v[10:13]
	v_mfma_f32_16x16x32_bf16 v[62:65], v[136:139], v[180:183], v[62:65]
	v_mfma_f32_16x16x32_bf16 v[58:61], v[144:147], v[180:183], v[58:61]
	v_mfma_f32_16x16x32_bf16 v[54:57], v[136:139], v[188:191], v[54:57]
	v_mfma_f32_16x16x32_bf16 v[46:49], v[144:147], v[188:191], v[46:49]
	v_mfma_f32_16x16x32_bf16 v[38:41], v[136:139], v[196:199], v[38:41]
	v_mfma_f32_16x16x32_bf16 v[30:33], v[144:147], v[196:199], v[30:33]
	v_mfma_f32_16x16x32_bf16 v[22:25], v[136:139], v[204:207], v[22:25]
	v_mfma_f32_16x16x32_bf16 v[10:13], v[144:147], v[204:207], v[10:13]
	v_mfma_f32_16x16x32_bf16 v[50:53], v[160:163], v[176:179], v[50:53]
	v_mfma_f32_16x16x32_bf16 v[42:45], v[168:171], v[176:179], v[42:45]
	v_mfma_f32_16x16x32_bf16 v[34:37], v[160:163], v[184:187], v[34:37]
	v_mfma_f32_16x16x32_bf16 v[26:29], v[168:171], v[184:187], v[26:29]
	v_mfma_f32_16x16x32_bf16 v[18:21], v[160:163], v[192:195], v[18:21]
	v_mfma_f32_16x16x32_bf16 v[14:17], v[168:171], v[192:195], v[14:17]
	v_mfma_f32_16x16x32_bf16 v[6:9], v[160:163], v[200:203], v[6:9]
	v_mfma_f32_16x16x32_bf16 v[2:5], v[168:171], v[200:203], v[2:5]
	v_mfma_f32_16x16x32_bf16 v[50:53], v[164:167], v[180:183], v[50:53]
	v_mfma_f32_16x16x32_bf16 v[42:45], v[172:175], v[180:183], v[42:45]
	v_mfma_f32_16x16x32_bf16 v[34:37], v[164:167], v[188:191], v[34:37]
	v_mfma_f32_16x16x32_bf16 v[26:29], v[172:175], v[188:191], v[26:29]
	v_mfma_f32_16x16x32_bf16 v[18:21], v[164:167], v[196:199], v[18:21]
	v_mfma_f32_16x16x32_bf16 v[14:17], v[172:175], v[196:199], v[14:17]
	v_mfma_f32_16x16x32_bf16 v[6:9], v[164:167], v[204:207], v[6:9]
	v_mfma_f32_16x16x32_bf16 v[2:5], v[172:175], v[204:207], v[2:5]
	s_barrier
	s_setprio 0
	s_setprio 1
	s_setprio 0
	s_waitcnt lgkmcnt(0)
	s_add_i32 s54, 0, 0x18000
	s_add_i32 s55, 0, 0x1c000
	v_add_u32_e32 v144, s54, v156
	v_add_u32_e32 v159, s55, v156
	ds_read_b128 v[132:135], v144
	ds_read_b128 v[136:139], v144 offset:1024
	ds_read_b128 v[140:143], v144 offset:2048
	ds_read_b128 v[144:147], v144 offset:3072
	ds_read_b128 v[160:163], v159
	ds_read_b128 v[164:167], v159 offset:1024
	ds_read_b128 v[168:171], v159 offset:2048
	ds_read_b128 v[172:175], v159 offset:3072
	s_add_u32 s24, s30, 0x160000
	s_addc_u32 s25, s31, 0
	s_mov_b32 m0, s41
	v_lshl_add_u64 v[222:223], s[24:25], 0, v[66:67]
	ds_read_b128 v[176:179], v158 offset:32768
	ds_read_b128 v[180:183], v158 offset:33792
	ds_read_b128 v[184:187], v158 offset:34816
	ds_read_b128 v[188:191], v158 offset:35840
	ds_read_b128 v[192:195], v158 offset:36864
	ds_read_b128 v[196:199], v158 offset:37888
	ds_read_b128 v[200:203], v158 offset:38912
	ds_read_b128 v[204:207], v158 offset:39936
	global_load_lds_dwordx4 v[222:223], off
	v_lshl_add_u64 v[222:223], s[24:25], 0, v[148:149]
	s_mov_b32 m0, s42
	s_nop 0
	global_load_lds_dwordx4 v[222:223], off
	s_setprio 1
	s_waitcnt vmcnt(8)
	s_waitcnt lgkmcnt(0)
	s_barrier
	v_mfma_f32_16x16x32_bf16 v[128:131], v[132:135], v[176:179], v[128:131]
	v_mfma_f32_16x16x32_bf16 v[124:127], v[140:143], v[176:179], v[124:127]
	v_mfma_f32_16x16x32_bf16 v[120:123], v[132:135], v[184:187], v[120:123]
	v_mfma_f32_16x16x32_bf16 v[112:115], v[140:143], v[184:187], v[112:115]
	v_mfma_f32_16x16x32_bf16 v[104:107], v[132:135], v[192:195], v[104:107]
	v_mfma_f32_16x16x32_bf16 v[96:99], v[140:143], v[192:195], v[96:99]
	v_mfma_f32_16x16x32_bf16 v[88:91], v[132:135], v[200:203], v[88:91]
	v_mfma_f32_16x16x32_bf16 v[76:79], v[140:143], v[200:203], v[76:79]
	v_mfma_f32_16x16x32_bf16 v[128:131], v[136:139], v[180:183], v[128:131]
	v_mfma_f32_16x16x32_bf16 v[124:127], v[144:147], v[180:183], v[124:127]
	v_mfma_f32_16x16x32_bf16 v[120:123], v[136:139], v[188:191], v[120:123]
	v_mfma_f32_16x16x32_bf16 v[112:115], v[144:147], v[188:191], v[112:115]
	v_mfma_f32_16x16x32_bf16 v[104:107], v[136:139], v[196:199], v[104:107]
	v_mfma_f32_16x16x32_bf16 v[96:99], v[144:147], v[196:199], v[96:99]
	v_mfma_f32_16x16x32_bf16 v[88:91], v[136:139], v[204:207], v[88:91]
	v_mfma_f32_16x16x32_bf16 v[76:79], v[144:147], v[204:207], v[76:79]
	v_mfma_f32_16x16x32_bf16 v[116:119], v[160:163], v[176:179], v[116:119]
	v_mfma_f32_16x16x32_bf16 v[108:111], v[168:171], v[176:179], v[108:111]
	v_mfma_f32_16x16x32_bf16 v[100:103], v[160:163], v[184:187], v[100:103]
	v_mfma_f32_16x16x32_bf16 v[92:95], v[168:171], v[184:187], v[92:95]
	v_mfma_f32_16x16x32_bf16 v[84:87], v[160:163], v[192:195], v[84:87]
	v_mfma_f32_16x16x32_bf16 v[80:83], v[168:171], v[192:195], v[80:83]
	v_mfma_f32_16x16x32_bf16 v[72:75], v[160:163], v[200:203], v[72:75]
	v_mfma_f32_16x16x32_bf16 v[68:71], v[168:171], v[200:203], v[68:71]
	v_mfma_f32_16x16x32_bf16 v[116:119], v[164:167], v[180:183], v[116:119]
	v_mfma_f32_16x16x32_bf16 v[108:111], v[172:175], v[180:183], v[108:111]
	v_mfma_f32_16x16x32_bf16 v[100:103], v[164:167], v[188:191], v[100:103]
	v_mfma_f32_16x16x32_bf16 v[92:95], v[172:175], v[188:191], v[92:95]
	v_mfma_f32_16x16x32_bf16 v[84:87], v[164:167], v[196:199], v[84:87]
	v_mfma_f32_16x16x32_bf16 v[80:83], v[172:175], v[196:199], v[80:83]
	v_mfma_f32_16x16x32_bf16 v[72:75], v[164:167], v[204:207], v[72:75]
	v_mfma_f32_16x16x32_bf16 v[68:71], v[172:175], v[204:207], v[68:71]
	s_barrier
; #define PG8_STAGE(bufoff, gbase, voff) do { _Pragma("unroll") for (int _i = 0; _i < 2; ++_i) \
;         __builtin_amdgcn_global_load_lds((const unsigned*)((const char*)(gbase) + (voff)[_i]), (PG8_LAS unsigned*)(lds + (bufoff) + ldsw + _i * 8192), 16, 0, 0); } while (0)
; #define PG8_LDA(dst, b, h) do { _Pragma("unroll") for (int m = 0; m < 4; ++m) _Pragma("unroll") for (int k = 0; k < 2; ++k) dst[m][k] = *(const PG8_LAS bf16x8*)(lds + PG8_SA(b, h) + aoff + m * 2048 + k * 1024); } while (0)
; #define PG8_LDB(dst, b, h) do { _Pragma("unroll") for (int n = 0; n < 2; ++n) _Pragma("unroll") for (int k = 0; k < 2; ++k) dst[n][k] = *(const PG8_LAS bf16x8*)(lds + PG8_SB(b, h) + boff + n * 2048 + k * 1024); } while (0)
; #define PG8_MMA(ai, bj, At, Bt) do { __builtin_amdgcn_s_setprio(1); _Pragma("unroll") for (int m = 0; m < 4; ++m) _Pragma("unroll") for (int n = 0; n < 2; ++n) _Pragma("unroll") for (int k = 0; k < 2; ++k) \
;         acc[ai][bj][m][n] = __builtin_amdgcn_mfma_f32_16x16x32_bf16(Bt[n][k], At[m][k], acc[ai][bj][m][n], 0, 0, 0); __builtin_amdgcn_s_setprio(0); } while (0)
; #define PG8_WAIT_V(n) asm volatile("s_waitcnt vmcnt(" #n ")" ::: "memory")
; template <class Epi, class Sched, bool ALIGN_EPI = false, bool SP2 = false>
; __device__ __forceinline__ void gemm_phase(PG8_LAS unsigned char* lds, const Gemm g, const Sched& S, const Epi& E) {
;     ...
;             PG8_LDB(B0, 0, 0); PG8_LDB(B1, 0, 1); PG8_SCHED; PG8_LDA(At, 0, 0); PG8_STAGE(PG8_SA(1, 1), a1 + hstep, voffA);
;             PG8_WAIT_V(8); PG8_WAIT_L(0); PG8_BAR; PG8_MMA(0, 0, At, B0); PG8_MMA(0, 1, At, B1); PG8_BAR; PG8_SCHED;
;             PG8_LDA(At, 0, 1); PG8_STAGE(PG8_SB(0, 0), b2, voffB); PG8_STAGE(PG8_SB(0, 1), b2 + hstep, voffB); PG8_STAGE(PG8_SA(0, 0), a2, voffA);
;             PG8_WAIT_V(8); PG8_WAIT_L(0); PG8_BAR; PG8_MMA(1, 0, At, B0); PG8_MMA(1, 1, At, B1); PG8_BAR; PG8_SCHED;
;             PG8_LDB(B0, 1, 0); PG8_LDB(B1, 1, 1); PG8_SCHED; PG8_LDA(At, 1, 0); PG8_STAGE(PG8_SA(0, 1), a2 + hstep, voffA);
;             PG8_WAIT_V(8); PG8_WAIT_L(0); PG8_BAR; PG8_MMA(0, 0, At, B0); PG8_MMA(0, 1, At, B1); PG8_BAR; PG8_SCHED;
;             PG8_LDA(At, 1, 1); PG8_STAGE(PG8_SB(1, 0), b3, voffB); PG8_STAGE(PG8_SB(1, 1), b3 + hstep, voffB); PG8_STAGE(PG8_SA(1, 0), a3, voffA);
;             PG8_WAIT_V(8); PG8_WAIT_L(0); PG8_BAR; PG8_MMA(1, 0, At, B0); PG8_MMA(1, 1, At, B1); PG8_BAR; PG8_SCHED;
	s_setprio 0
	s_setprio 1
	s_setprio 0
	s_waitcnt lgkmcnt(0)
	s_add_i32 s24, s54, s38
	v_lshl_add_u64 v[154:155], v[154:155], 0, s[88:89]
	s_mov_b32 m0, s24
	ds_read_b128 v[176:179], v158 offset:49152
	ds_read_b128 v[180:183], v158 offset:50176
	ds_read_b128 v[184:187], v158 offset:51200
	ds_read_b128 v[188:191], v158 offset:52224
	ds_read_b128 v[192:195], v158 offset:53248
	ds_read_b128 v[196:199], v158 offset:54272
	ds_read_b128 v[200:203], v158 offset:55296
	ds_read_b128 v[204:207], v158 offset:56320
	global_load_lds_dwordx4 v[154:155], off
	s_add_i32 m0, s24, 0x2000
	s_add_u32 s24, s28, 0x160080
	v_lshl_add_u64 v[154:155], v[208:209], 0, s[88:89]
	s_addc_u32 s25, s29, 0
	s_add_i32 s28, s55, s38
	global_load_lds_dwordx4 v[154:155], off
	v_lshl_add_u64 v[154:155], s[24:25], 0, v[66:67]
	s_mov_b32 m0, s28
	s_nop 0
	global_load_lds_dwordx4 v[154:155], off
	v_lshl_add_u64 v[154:155], s[24:25], 0, v[148:149]
	s_add_i32 m0, s28, 0x2000
	s_nop 0
	global_load_lds_dwordx4 v[154:155], off
	v_lshl_add_u64 v[154:155], v[210:211], 0, s[88:89]
	s_mov_b32 m0, s45
	s_nop 0
	global_load_lds_dwordx4 v[154:155], off
	v_lshl_add_u64 v[154:155], v[220:221], 0, s[88:89]
	s_mov_b32 m0, s46
	s_nop 0
	global_load_lds_dwordx4 v[154:155], off
	s_setprio 1
	s_waitcnt vmcnt(8)
	s_waitcnt lgkmcnt(0)
	s_barrier
	v_mfma_f32_16x16x32_bf16 v[62:65], v[132:135], v[176:179], v[62:65]
	v_mfma_f32_16x16x32_bf16 v[58:61], v[140:143], v[176:179], v[58:61]
	v_mfma_f32_16x16x32_bf16 v[54:57], v[132:135], v[184:187], v[54:57]
	v_mfma_f32_16x16x32_bf16 v[46:49], v[140:143], v[184:187], v[46:49]
	v_mfma_f32_16x16x32_bf16 v[38:41], v[132:135], v[192:195], v[38:41]
	v_mfma_f32_16x16x32_bf16 v[30:33], v[140:143], v[192:195], v[30:33]
	v_mfma_f32_16x16x32_bf16 v[22:25], v[132:135], v[200:203], v[22:25]
	v_mfma_f32_16x16x32_bf16 v[10:13], v[140:143], v[200:203], v[10:13]
	v_mfma_f32_16x16x32_bf16 v[62:65], v[136:139], v[180:183], v[62:65]
	v_mfma_f32_16x16x32_bf16 v[58:61], v[144:147], v[180:183], v[58:61]
	v_mfma_f32_16x16x32_bf16 v[54:57], v[136:139], v[188:191], v[54:57]
	v_mfma_f32_16x16x32_bf16 v[46:49], v[144:147], v[188:191], v[46:49]
	v_mfma_f32_16x16x32_bf16 v[38:41], v[136:139], v[196:199], v[38:41]
	v_mfma_f32_16x16x32_bf16 v[30:33], v[144:147], v[196:199], v[30:33]
	v_mfma_f32_16x16x32_bf16 v[22:25], v[136:139], v[204:207], v[22:25]
	v_mfma_f32_16x16x32_bf16 v[10:13], v[144:147], v[204:207], v[10:13]
	v_mfma_f32_16x16x32_bf16 v[50:53], v[160:163], v[176:179], v[50:53]
	v_mfma_f32_16x16x32_bf16 v[42:45], v[168:171], v[176:179], v[42:45]
	v_mfma_f32_16x16x32_bf16 v[34:37], v[160:163], v[184:187], v[34:37]
	v_mfma_f32_16x16x32_bf16 v[26:29], v[168:171], v[184:187], v[26:29]
	v_mfma_f32_16x16x32_bf16 v[18:21], v[160:163], v[192:195], v[18:21]
	v_mfma_f32_16x16x32_bf16 v[14:17], v[168:171], v[192:195], v[14:17]
	v_mfma_f32_16x16x32_bf16 v[6:9], v[160:163], v[200:203], v[6:9]
	v_mfma_f32_16x16x32_bf16 v[2:5], v[168:171], v[200:203], v[2:5]
	v_mfma_f32_16x16x32_bf16 v[50:53], v[164:167], v[180:183], v[50:53]
	v_mfma_f32_16x16x32_bf16 v[42:45], v[172:175], v[180:183], v[42:45]
	v_mfma_f32_16x16x32_bf16 v[34:37], v[164:167], v[188:191], v[34:37]
	v_mfma_f32_16x16x32_bf16 v[26:29], v[172:175], v[188:191], v[26:29]
	v_mfma_f32_16x16x32_bf16 v[18:21], v[164:167], v[196:199], v[18:21]
	v_mfma_f32_16x16x32_bf16 v[14:17], v[172:175], v[196:199], v[14:17]
	v_mfma_f32_16x16x32_bf16 v[6:9], v[164:167], v[204:207], v[6:9]
	v_mfma_f32_16x16x32_bf16 v[2:5], v[172:175], v[204:207], v[2:5]
	s_barrier
	s_setprio 0
	s_setprio 1
	s_setprio 0
	s_waitcnt lgkmcnt(0)
	s_add_i32 s53, s53, 2
	s_add_u32 s2, s2, 0x100
	s_addc_u32 s3, s3, 0
	s_cmpk_gt_u32 s53, 0x55
	s_mov_b64 s[24:25], s[26:27]
	s_cbranch_scc0 .LBB0_1294
	s_and_b64 vcc, exec, s[20:21]
	s_cbranch_vccz .LBB0_1297
	s_barrier

; #define PG8_STAGE(bufoff, gbase, voff) do { _Pragma("unroll") for (int _i = 0; _i < 2; ++_i) \
;         __builtin_amdgcn_global_load_lds((const unsigned*)((const char*)(gbase) + (voff)[_i]), (PG8_LAS unsigned*)(lds + (bufoff) + ldsw + _i * 8192), 16, 0, 0); } while (0)
; #define PG8_LDA(dst, b, h) do { _Pragma("unroll") for (int m = 0; m < 4; ++m) _Pragma("unroll") for (int k = 0; k < 2; ++k) dst[m][k] = *(const PG8_LAS bf16x8*)(lds + PG8_SA(b, h) + aoff + m * 2048 + k * 1024); } while (0)
; #define PG8_LDB(dst, b, h) do { _Pragma("unroll") for (int n = 0; n < 2; ++n) _Pragma("unroll") for (int k = 0; k < 2; ++k) dst[n][k] = *(const PG8_LAS bf16x8*)(lds + PG8_SB(b, h) + boff + n * 2048 + k * 1024); } while (0)
; template <class Epi, class Sched, bool ALIGN_EPI = false, bool SP2 = false>
; __device__ __forceinline__ void gemm_phase(PG8_LAS unsigned char* lds, const Gemm g, const Sched& S, const Epi& E) {
;     ...
;         for (int t = 0; t < nt; t += 2) {
;             const bool last = (t == nt - 2);
;             const char* a1 = cA + (size_t)(t + 1) * kstep;
;             const char* a2 = last ? nA : cA + (size_t)(t + 2) * kstep; const char* b2 = last ? nB : cB + (size_t)(t + 2) * kstep;
;             const char* a3 = a2 + kstep; const char* b3 = b2 + kstep;
;             if (last && has_next) S.a_ready(nxt);
;             if constexpr (SP2) {
;             PG8_LDB(B0, 0, 0); PG8_LDB(B1, 0, 1); PG8_SCHED; PG8_LDA(At, 0, 0); PG8_STAGE(PG8_SA(1, 1), a1 + hstep, voffA);
;             PG8_WAIT_V(8); PG8_WAIT_L(0); PG8_BAR; PG8_MMA(0, 0, At, B0); PG8_MMA(0, 1, At, B1); PG8_BAR; PG8_SCHED;
;             PG8_LDA(At, 0, 1); PG8_STAGE(PG8_SB(0, 0), b2, voffB); PG8_STAGE(PG8_SB(0, 1), b2 + hstep, voffB); PG8_STAGE(PG8_SA(0, 0), a2, voffA);
;             PG8_WAIT_V(8); PG8_WAIT_L(0); PG8_BAR; PG8_MMA(1, 0, At, B0); PG8_MMA(1, 1, At, B1); PG8_BAR; PG8_SCHED;
;             PG8_LDB(B0, 1, 0); PG8_LDB(B1, 1, 1); PG8_SCHED; PG8_LDA(At, 1, 0); PG8_STAGE(PG8_SA(0, 1), a2 + hstep, voffA);
;             PG8_WAIT_V(8); PG8_WAIT_L(0); PG8_BAR; PG8_MMA(0, 0, At, B0); PG8_MMA(0, 1, At, B1); PG8_BAR; PG8_SCHED;
;             PG8_LDA(At, 1, 1); PG8_STAGE(PG8_SB(1, 0), b3, voffB); PG8_STAGE(PG8_SB(1, 1), b3 + hstep, voffB); PG8_STAGE(PG8_SA(1, 0), a3, voffA);
;             PG8_WAIT_V(8); PG8_WAIT_L(0); PG8_BAR; PG8_MMA(1, 0, At, B0); PG8_MMA(1, 1, At, B1); PG8_BAR; PG8_SCHED;
.LBB0_1324:
	s_add_u32 s28, s22, s26
	s_addc_u32 s29, s23, s27
	s_add_u32 s28, s28, 0x100
	s_addc_u32 s29, s29, 0
	s_add_u32 s54, s3, s26
	s_addc_u32 s55, s52, s27
	s_add_i32 s56, 0, 0x10000
	s_cmpk_eq_i32 s26, 0x2b00
	s_cselect_b32 s31, s25, s29
	s_cselect_b32 s30, s24, s28
	s_cselect_b32 s29, s13, s55
	s_cselect_b32 s28, s12, s54
	s_add_i32 s57, 0, 0x14000
	v_add_u32_e32 v156, s56, v142
	v_add_u32_e32 v172, s57, v142
	ds_read_b128 v[144:147], v156
	ds_read_b128 v[148:151], v156 offset:1024
	ds_read_b128 v[152:155], v156 offset:2048
	ds_read_b128 v[156:159], v156 offset:3072
	ds_read_b128 v[160:163], v172
	ds_read_b128 v[164:167], v172 offset:1024
	ds_read_b128 v[168:171], v172 offset:2048
	ds_read_b128 v[172:175], v172 offset:3072
	v_lshl_add_u64 v[208:209], v[138:139], 0, s[26:27]
	s_add_i32 m0, s43, 0xc000
	ds_read_b128 v[176:179], v143
	ds_read_b128 v[180:183], v143 offset:1024
	ds_read_b128 v[184:187], v143 offset:2048
	ds_read_b128 v[188:191], v143 offset:3072
	ds_read_b128 v[192:195], v143 offset:4096
	ds_read_b128 v[196:199], v143 offset:5120
	ds_read_b128 v[200:203], v143 offset:6144
	ds_read_b128 v[204:207], v143 offset:7168
	global_load_lds_dwordx4 v[208:209], off
	v_lshl_add_u64 v[208:209], v[140:141], 0, s[26:27]
	s_add_i32 m0, s43, 0xe000
	s_nop 0
	global_load_lds_dwordx4 v[208:209], off
	s_setprio 1
	s_waitcnt vmcnt(8)
	s_waitcnt lgkmcnt(0)
	s_barrier
	v_mfma_f32_16x16x32_bf16 v[128:131], v[144:147], v[176:179], v[128:131]
	v_mfma_f32_16x16x32_bf16 v[124:127], v[152:155], v[176:179], v[124:127]
	v_mfma_f32_16x16x32_bf16 v[112:115], v[144:147], v[184:187], v[112:115]
	v_mfma_f32_16x16x32_bf16 v[104:107], v[152:155], v[184:187], v[104:107]
	v_mfma_f32_16x16x32_bf16 v[96:99], v[144:147], v[192:195], v[96:99]
	v_mfma_f32_16x16x32_bf16 v[88:91], v[152:155], v[192:195], v[88:91]
	v_mfma_f32_16x16x32_bf16 v[80:83], v[144:147], v[200:203], v[80:83]
	v_mfma_f32_16x16x32_bf16 v[72:75], v[152:155], v[200:203], v[72:75]
	v_mfma_f32_16x16x32_bf16 v[128:131], v[148:151], v[180:183], v[128:131]
	v_mfma_f32_16x16x32_bf16 v[124:127], v[156:159], v[180:183], v[124:127]
	v_mfma_f32_16x16x32_bf16 v[112:115], v[148:151], v[188:191], v[112:115]
	v_mfma_f32_16x16x32_bf16 v[104:107], v[156:159], v[188:191], v[104:107]
	v_mfma_f32_16x16x32_bf16 v[96:99], v[148:151], v[196:199], v[96:99]
	v_mfma_f32_16x16x32_bf16 v[88:91], v[156:159], v[196:199], v[88:91]
	v_mfma_f32_16x16x32_bf16 v[80:83], v[148:151], v[204:207], v[80:83]
	v_mfma_f32_16x16x32_bf16 v[72:75], v[156:159], v[204:207], v[72:75]
	v_mfma_f32_16x16x32_bf16 v[116:119], v[160:163], v[176:179], v[116:119]
	v_mfma_f32_16x16x32_bf16 v[108:111], v[168:171], v[176:179], v[108:111]
	v_mfma_f32_16x16x32_bf16 v[100:103], v[160:163], v[184:187], v[100:103]
	v_mfma_f32_16x16x32_bf16 v[92:95], v[168:171], v[184:187], v[92:95]
	v_mfma_f32_16x16x32_bf16 v[84:87], v[160:163], v[192:195], v[84:87]
	v_mfma_f32_16x16x32_bf16 v[76:79], v[168:171], v[192:195], v[76:79]
	v_mfma_f32_16x16x32_bf16 v[68:71], v[160:163], v[200:203], v[68:71]
	v_mfma_f32_16x16x32_bf16 v[62:65], v[168:171], v[200:203], v[62:65]
	v_mfma_f32_16x16x32_bf16 v[116:119], v[164:167], v[180:183], v[116:119]
	v_mfma_f32_16x16x32_bf16 v[108:111], v[172:175], v[180:183], v[108:111]
	v_mfma_f32_16x16x32_bf16 v[100:103], v[164:167], v[188:191], v[100:103]
	v_mfma_f32_16x16x32_bf16 v[92:95], v[172:175], v[188:191], v[92:95]
	v_mfma_f32_16x16x32_bf16 v[84:87], v[164:167], v[196:199], v[84:87]
	v_mfma_f32_16x16x32_bf16 v[76:79], v[172:175], v[196:199], v[76:79]
	v_mfma_f32_16x16x32_bf16 v[68:71], v[164:167], v[204:207], v[68:71]
	v_mfma_f32_16x16x32_bf16 v[62:65], v[172:175], v[204:207], v[62:65]
	s_barrier
	s_setprio 0
	s_setprio 1
	s_setprio 0
	s_waitcnt lgkmcnt(0)
	s_add_i32 s54, s56, s42
	v_lshl_add_u64 v[208:209], s[28:29], 0, v[66:67]
	s_mov_b32 m0, s54
	ds_read_b128 v[176:179], v143 offset:16384
	ds_read_b128 v[180:183], v143 offset:17408
	ds_read_b128 v[184:187], v143 offset:18432
	ds_read_b128 v[188:191], v143 offset:19456
	ds_read_b128 v[192:195], v143 offset:20480
	ds_read_b128 v[196:199], v143 offset:21504
	ds_read_b128 v[200:203], v143 offset:22528
	ds_read_b128 v[204:207], v143 offset:23552
	global_load_lds_dwordx4 v[208:209], off
	s_add_i32 m0, s54, 0x2000
	s_add_u32 s54, s28, 0x160000
	v_lshl_add_u64 v[210:211], s[28:29], 0, v[132:133]
	s_addc_u32 s55, s29, 0
	s_add_i32 s56, s57, s42
	global_load_lds_dwordx4 v[210:211], off
	v_lshl_add_u64 v[220:221], s[54:55], 0, v[66:67]
	s_mov_b32 m0, s56
	v_lshl_add_u64 v[222:223], s[30:31], 0, v[132:133]
	global_load_lds_dwordx4 v[220:221], off
	v_lshl_add_u64 v[220:221], s[54:55], 0, v[132:133]
	s_add_i32 m0, s56, 0x2000
	s_nop 0
	global_load_lds_dwordx4 v[220:221], off
	v_lshl_add_u64 v[220:221], s[30:31], 0, v[66:67]
	s_mov_b32 m0, s43
	s_nop 0
	global_load_lds_dwordx4 v[220:221], off
	s_mov_b32 m0, s44
	s_nop 0
	global_load_lds_dwordx4 v[222:223], off
	s_setprio 1
	s_waitcnt vmcnt(8)
	s_waitcnt lgkmcnt(0)
	s_barrier
; #define PG8_STAGE(bufoff, gbase, voff) do { _Pragma("unroll") for (int _i = 0; _i < 2; ++_i) \
;         __builtin_amdgcn_global_load_lds((const unsigned*)((const char*)(gbase) + (voff)[_i]), (PG8_LAS unsigned*)(lds + (bufoff) + ldsw + _i * 8192), 16, 0, 0); } while (0)
; #define PG8_LDA(dst, b, h) do { _Pragma("unroll") for (int m = 0; m < 4; ++m) _Pragma("unroll") for (int k = 0; k < 2; ++k) dst[m][k] = *(const PG8_LAS bf16x8*)(lds + PG8_SA(b, h) + aoff + m * 2048 + k * 1024); } while (0)
; #define PG8_LDB(dst, b, h) do { _Pragma("unroll") for (int n = 0; n < 2; ++n) _Pragma("unroll") for (int k = 0; k < 2; ++k) dst[n][k] = *(const PG8_LAS bf16x8*)(lds + PG8_SB(b, h) + boff + n * 2048 + k * 1024); } while (0)
; #define PG8_MMA(ai, bj, At, Bt) do { __builtin_amdgcn_s_setprio(1); _Pragma("unroll") for (int m = 0; m < 4; ++m) _Pragma("unroll") for (int n = 0; n < 2; ++n) _Pragma("unroll") for (int k = 0; k < 2; ++k) \
;         acc[ai][bj][m][n] = __builtin_amdgcn_mfma_f32_16x16x32_bf16(Bt[n][k], At[m][k], acc[ai][bj][m][n], 0, 0, 0); __builtin_amdgcn_s_setprio(0); } while (0)
; #define PG8_WAIT_V(n) asm volatile("s_waitcnt vmcnt(" #n ")" ::: "memory")
; #define PG8_WAIT_L(n) asm volatile("s_waitcnt lgkmcnt(" #n ")" ::: "memory")
; #define PG8_BAR __builtin_amdgcn_s_barrier()
; #define PG8_SCHED __builtin_amdgcn_sched_barrier(0)
; template <class Epi, class Sched, bool ALIGN_EPI = false, bool SP2 = false>
; __device__ __forceinline__ void gemm_phase(PG8_LAS unsigned char* lds, const Gemm g, const Sched& S, const Epi& E) {
;     ...
;             PG8_WAIT_V(8); PG8_WAIT_L(0); PG8_BAR; PG8_MMA(1, 0, At, B0); PG8_MMA(1, 1, At, B1); PG8_BAR; PG8_SCHED;
;             PG8_LDB(B0, 1, 0); PG8_LDB(B1, 1, 1); PG8_SCHED; PG8_LDA(At, 1, 0); PG8_STAGE(PG8_SA(0, 1), a2 + hstep, voffA);
;             PG8_WAIT_V(8); PG8_WAIT_L(0); PG8_BAR; PG8_MMA(0, 0, At, B0); PG8_MMA(0, 1, At, B1); PG8_BAR; PG8_SCHED;
;             PG8_LDA(At, 1, 1); PG8_STAGE(PG8_SB(1, 0), b3, voffB); PG8_STAGE(PG8_SB(1, 1), b3 + hstep, voffB); PG8_STAGE(PG8_SA(1, 0), a3, voffA);
	v_mfma_f32_16x16x32_bf16 v[58:61], v[144:147], v[176:179], v[58:61]
	v_mfma_f32_16x16x32_bf16 v[54:57], v[152:155], v[176:179], v[54:57]
	v_mfma_f32_16x16x32_bf16 v[46:49], v[144:147], v[184:187], v[46:49]
	v_mfma_f32_16x16x32_bf16 v[38:41], v[152:155], v[184:187], v[38:41]
	v_mfma_f32_16x16x32_bf16 v[30:33], v[144:147], v[192:195], v[30:33]
	v_mfma_f32_16x16x32_bf16 v[22:25], v[152:155], v[192:195], v[22:25]
	v_mfma_f32_16x16x32_bf16 v[120:123], v[144:147], v[200:203], v[120:123]
	v_mfma_f32_16x16x32_bf16 v[10:13], v[152:155], v[200:203], v[10:13]
	v_mfma_f32_16x16x32_bf16 v[58:61], v[148:151], v[180:183], v[58:61]
	v_mfma_f32_16x16x32_bf16 v[54:57], v[156:159], v[180:183], v[54:57]
	v_mfma_f32_16x16x32_bf16 v[46:49], v[148:151], v[188:191], v[46:49]
	v_mfma_f32_16x16x32_bf16 v[38:41], v[156:159], v[188:191], v[38:41]
	v_mfma_f32_16x16x32_bf16 v[30:33], v[148:151], v[196:199], v[30:33]
	v_mfma_f32_16x16x32_bf16 v[22:25], v[156:159], v[196:199], v[22:25]
	v_mfma_f32_16x16x32_bf16 v[120:123], v[148:151], v[204:207], v[120:123]
	v_mfma_f32_16x16x32_bf16 v[10:13], v[156:159], v[204:207], v[10:13]
	v_mfma_f32_16x16x32_bf16 v[50:53], v[160:163], v[176:179], v[50:53]
	v_mfma_f32_16x16x32_bf16 v[42:45], v[168:171], v[176:179], v[42:45]
	v_mfma_f32_16x16x32_bf16 v[34:37], v[160:163], v[184:187], v[34:37]
	v_mfma_f32_16x16x32_bf16 v[26:29], v[168:171], v[184:187], v[26:29]
	v_mfma_f32_16x16x32_bf16 v[18:21], v[160:163], v[192:195], v[18:21]
	v_mfma_f32_16x16x32_bf16 v[14:17], v[168:171], v[192:195], v[14:17]
	v_mfma_f32_16x16x32_bf16 v[6:9], v[160:163], v[200:203], v[6:9]
	v_mfma_f32_16x16x32_bf16 v[2:5], v[168:171], v[200:203], v[2:5]
	v_mfma_f32_16x16x32_bf16 v[50:53], v[164:167], v[180:183], v[50:53]
	v_mfma_f32_16x16x32_bf16 v[42:45], v[172:175], v[180:183], v[42:45]
	v_mfma_f32_16x16x32_bf16 v[34:37], v[164:167], v[188:191], v[34:37]
	v_mfma_f32_16x16x32_bf16 v[26:29], v[172:175], v[188:191], v[26:29]
	v_mfma_f32_16x16x32_bf16 v[18:21], v[164:167], v[196:199], v[18:21]
	v_mfma_f32_16x16x32_bf16 v[14:17], v[172:175], v[196:199], v[14:17]
	v_mfma_f32_16x16x32_bf16 v[6:9], v[164:167], v[204:207], v[6:9]
	v_mfma_f32_16x16x32_bf16 v[2:5], v[172:175], v[204:207], v[2:5]
	s_barrier
	s_setprio 0
	s_setprio 1
	s_setprio 0
	s_waitcnt lgkmcnt(0)
	s_add_i32 s54, 0, 0x18000
	s_add_i32 s55, 0, 0x1c000
	v_add_u32_e32 v156, s54, v142
	v_add_u32_e32 v172, s55, v142
	ds_read_b128 v[144:147], v156
	ds_read_b128 v[148:151], v156 offset:1024
	ds_read_b128 v[152:155], v156 offset:2048
	ds_read_b128 v[156:159], v156 offset:3072
	ds_read_b128 v[160:163], v172
	ds_read_b128 v[164:167], v172 offset:1024
	ds_read_b128 v[168:171], v172 offset:2048
	ds_read_b128 v[172:175], v172 offset:3072
	s_add_u32 s30, s30, 0x160000
	s_addc_u32 s31, s31, 0
	s_mov_b32 m0, s45
	v_lshl_add_u64 v[224:225], s[30:31], 0, v[66:67]
	ds_read_b128 v[176:179], v143 offset:32768
	ds_read_b128 v[180:183], v143 offset:33792
	ds_read_b128 v[184:187], v143 offset:34816
	ds_read_b128 v[188:191], v143 offset:35840
	ds_read_b128 v[192:195], v143 offset:36864
	ds_read_b128 v[196:199], v143 offset:37888
	ds_read_b128 v[200:203], v143 offset:38912
	ds_read_b128 v[204:207], v143 offset:39936
	global_load_lds_dwordx4 v[224:225], off
	v_lshl_add_u64 v[224:225], s[30:31], 0, v[132:133]
	s_mov_b32 m0, s1
	s_nop 0
	global_load_lds_dwordx4 v[224:225], off
	s_setprio 1
	s_waitcnt vmcnt(8)
	s_waitcnt lgkmcnt(0)
	s_barrier
	v_mfma_f32_16x16x32_bf16 v[128:131], v[144:147], v[176:179], v[128:131]
	v_mfma_f32_16x16x32_bf16 v[124:127], v[152:155], v[176:179], v[124:127]
	v_mfma_f32_16x16x32_bf16 v[112:115], v[144:147], v[184:187], v[112:115]
	v_mfma_f32_16x16x32_bf16 v[104:107], v[152:155], v[184:187], v[104:107]
	v_mfma_f32_16x16x32_bf16 v[96:99], v[144:147], v[192:195], v[96:99]
	v_mfma_f32_16x16x32_bf16 v[88:91], v[152:155], v[192:195], v[88:91]
	v_mfma_f32_16x16x32_bf16 v[80:83], v[144:147], v[200:203], v[80:83]
	v_mfma_f32_16x16x32_bf16 v[72:75], v[152:155], v[200:203], v[72:75]
	v_mfma_f32_16x16x32_bf16 v[128:131], v[148:151], v[180:183], v[128:131]
	v_mfma_f32_16x16x32_bf16 v[124:127], v[156:159], v[180:183], v[124:127]
	v_mfma_f32_16x16x32_bf16 v[112:115], v[148:151], v[188:191], v[112:115]
	v_mfma_f32_16x16x32_bf16 v[104:107], v[156:159], v[188:191], v[104:107]
	v_mfma_f32_16x16x32_bf16 v[96:99], v[148:151], v[196:199], v[96:99]
	v_mfma_f32_16x16x32_bf16 v[88:91], v[156:159], v[196:199], v[88:91]
	v_mfma_f32_16x16x32_bf16 v[80:83], v[148:151], v[204:207], v[80:83]
	v_mfma_f32_16x16x32_bf16 v[72:75], v[156:159], v[204:207], v[72:75]
	v_mfma_f32_16x16x32_bf16 v[116:119], v[160:163], v[176:179], v[116:119]
	v_mfma_f32_16x16x32_bf16 v[108:111], v[168:171], v[176:179], v[108:111]
	v_mfma_f32_16x16x32_bf16 v[100:103], v[160:163], v[184:187], v[100:103]
	v_mfma_f32_16x16x32_bf16 v[92:95], v[168:171], v[184:187], v[92:95]
	v_mfma_f32_16x16x32_bf16 v[84:87], v[160:163], v[192:195], v[84:87]
	v_mfma_f32_16x16x32_bf16 v[76:79], v[168:171], v[192:195], v[76:79]
	v_mfma_f32_16x16x32_bf16 v[68:71], v[160:163], v[200:203], v[68:71]
	v_mfma_f32_16x16x32_bf16 v[62:65], v[168:171], v[200:203], v[62:65]
	v_mfma_f32_16x16x32_bf16 v[116:119], v[164:167], v[180:183], v[116:119]
	v_mfma_f32_16x16x32_bf16 v[108:111], v[172:175], v[180:183], v[108:111]
	v_mfma_f32_16x16x32_bf16 v[100:103], v[164:167], v[188:191], v[100:103]
	v_mfma_f32_16x16x32_bf16 v[92:95], v[172:175], v[188:191], v[92:95]
	v_mfma_f32_16x16x32_bf16 v[84:87], v[164:167], v[196:199], v[84:87]
	v_mfma_f32_16x16x32_bf16 v[76:79], v[172:175], v[196:199], v[76:79]
	v_mfma_f32_16x16x32_bf16 v[68:71], v[164:167], v[204:207], v[68:71]
	v_mfma_f32_16x16x32_bf16 v[62:65], v[172:175], v[204:207], v[62:65]
	s_barrier
; #define PG8_STAGE(bufoff, gbase, voff) do { _Pragma("unroll") for (int _i = 0; _i < 2; ++_i) \
;         __builtin_amdgcn_global_load_lds((const unsigned*)((const char*)(gbase) + (voff)[_i]), (PG8_LAS unsigned*)(lds + (bufoff) + ldsw + _i * 8192), 16, 0, 0); } while (0)
; #define PG8_LDA(dst, b, h) do { _Pragma("unroll") for (int m = 0; m < 4; ++m) _Pragma("unroll") for (int k = 0; k < 2; ++k) dst[m][k] = *(const PG8_LAS bf16x8*)(lds + PG8_SA(b, h) + aoff + m * 2048 + k * 1024); } while (0)
; #define PG8_LDB(dst, b, h) do { _Pragma("unroll") for (int n = 0; n < 2; ++n) _Pragma("unroll") for (int k = 0; k < 2; ++k) dst[n][k] = *(const PG8_LAS bf16x8*)(lds + PG8_SB(b, h) + boff + n * 2048 + k * 1024); } while (0)
; #define PG8_WAIT_V(n) asm volatile("s_waitcnt vmcnt(" #n ")" ::: "memory")
; template <class Epi, class Sched, bool ALIGN_EPI = false, bool SP2 = false>
; __device__ __forceinline__ void gemm_phase(PG8_LAS unsigned char* lds, const Gemm g, const Sched& S, const Epi& E) {
;     ...
;             PG8_LDB(B0, 0, 0); PG8_LDB(B1, 0, 1); PG8_SCHED; PG8_LDA(At, 0, 0); PG8_STAGE(PG8_SA(1, 1), a1 + hstep, voffA);
;             PG8_WAIT_V(8); PG8_WAIT_L(0); PG8_BAR; PG8_MMA(0, 0, At, B0); PG8_MMA(0, 1, At, B1); PG8_BAR; PG8_SCHED;
;             PG8_LDA(At, 0, 1); PG8_STAGE(PG8_SB(0, 0), b2, voffB); PG8_STAGE(PG8_SB(0, 1), b2 + hstep, voffB); PG8_STAGE(PG8_SA(0, 0), a2, voffA);
;             PG8_WAIT_V(8); PG8_WAIT_L(0); PG8_BAR; PG8_MMA(1, 0, At, B0); PG8_MMA(1, 1, At, B1); PG8_BAR; PG8_SCHED;
;             PG8_LDB(B0, 1, 0); PG8_LDB(B1, 1, 1); PG8_SCHED; PG8_LDA(At, 1, 0); PG8_STAGE(PG8_SA(0, 1), a2 + hstep, voffA);
;             PG8_WAIT_V(8); PG8_WAIT_L(0); PG8_BAR; PG8_MMA(0, 0, At, B0); PG8_MMA(0, 1, At, B1); PG8_BAR; PG8_SCHED;
;             PG8_LDA(At, 1, 1); PG8_STAGE(PG8_SB(1, 0), b3, voffB); PG8_STAGE(PG8_SB(1, 1), b3 + hstep, voffB); PG8_STAGE(PG8_SA(1, 0), a3, voffA);
;             PG8_WAIT_V(8); PG8_WAIT_L(0); PG8_BAR; PG8_MMA(1, 0, At, B0); PG8_MMA(1, 1, At, B1); PG8_BAR; PG8_SCHED;
;     ...
;         if (!has_next) break;
; #pragma unroll
;         for (int a = 0; a < 2; ++a)
; #pragma unroll
;             for (int b = 0; b < 2; ++b)
; #pragma unroll
;                 for (int m = 0; m < 4; ++m)
; #pragma unroll
;                     for (int n = 0; n < 2; ++n) acc[a][b][m][n] = (f32x4){0.f, 0.f, 0.f, 0.f};
;         cur = nxt; cA = nA; cB = nB; ++ui;
	s_setprio 0
	s_setprio 1
	s_setprio 0
	s_waitcnt lgkmcnt(0)
	s_add_i32 s30, s54, s42
	v_lshl_add_u64 v[208:209], v[208:209], 0, s[88:89]
	s_mov_b32 m0, s30
	ds_read_b128 v[176:179], v143 offset:49152
	ds_read_b128 v[180:183], v143 offset:50176
	ds_read_b128 v[184:187], v143 offset:51200
	ds_read_b128 v[188:191], v143 offset:52224
	ds_read_b128 v[192:195], v143 offset:53248
	ds_read_b128 v[196:199], v143 offset:54272
	ds_read_b128 v[200:203], v143 offset:55296
	ds_read_b128 v[204:207], v143 offset:56320
	global_load_lds_dwordx4 v[208:209], off
	s_add_i32 m0, s30, 0x2000
	s_add_u32 s28, s28, 0x160080
	v_lshl_add_u64 v[208:209], v[210:211], 0, s[88:89]
	s_addc_u32 s29, s29, 0
	s_add_i32 s30, s55, s42
	global_load_lds_dwordx4 v[208:209], off
	v_lshl_add_u64 v[208:209], s[28:29], 0, v[66:67]
	s_mov_b32 m0, s30
	s_nop 0
	global_load_lds_dwordx4 v[208:209], off
	v_lshl_add_u64 v[208:209], s[28:29], 0, v[132:133]
	s_add_i32 m0, s30, 0x2000
	s_nop 0
	global_load_lds_dwordx4 v[208:209], off
	v_lshl_add_u64 v[208:209], v[220:221], 0, s[88:89]
	s_mov_b32 m0, s47
	s_nop 0
	global_load_lds_dwordx4 v[208:209], off
	v_lshl_add_u64 v[208:209], v[222:223], 0, s[88:89]
	s_mov_b32 m0, s48
	s_nop 0
	global_load_lds_dwordx4 v[208:209], off
	s_setprio 1
	s_waitcnt vmcnt(8)
	s_waitcnt lgkmcnt(0)
	s_barrier
	v_mfma_f32_16x16x32_bf16 v[58:61], v[144:147], v[176:179], v[58:61]
	v_mfma_f32_16x16x32_bf16 v[54:57], v[152:155], v[176:179], v[54:57]
	v_mfma_f32_16x16x32_bf16 v[46:49], v[144:147], v[184:187], v[46:49]
	v_mfma_f32_16x16x32_bf16 v[38:41], v[152:155], v[184:187], v[38:41]
	v_mfma_f32_16x16x32_bf16 v[30:33], v[144:147], v[192:195], v[30:33]
	v_mfma_f32_16x16x32_bf16 v[22:25], v[152:155], v[192:195], v[22:25]
	v_mfma_f32_16x16x32_bf16 v[120:123], v[144:147], v[200:203], v[120:123]
	v_mfma_f32_16x16x32_bf16 v[10:13], v[152:155], v[200:203], v[10:13]
	v_mfma_f32_16x16x32_bf16 v[58:61], v[148:151], v[180:183], v[58:61]
	v_mfma_f32_16x16x32_bf16 v[54:57], v[156:159], v[180:183], v[54:57]
	v_mfma_f32_16x16x32_bf16 v[46:49], v[148:151], v[188:191], v[46:49]
	v_mfma_f32_16x16x32_bf16 v[38:41], v[156:159], v[188:191], v[38:41]
	v_mfma_f32_16x16x32_bf16 v[30:33], v[148:151], v[196:199], v[30:33]
	v_mfma_f32_16x16x32_bf16 v[22:25], v[156:159], v[196:199], v[22:25]
	v_mfma_f32_16x16x32_bf16 v[120:123], v[148:151], v[204:207], v[120:123]
	v_mfma_f32_16x16x32_bf16 v[10:13], v[156:159], v[204:207], v[10:13]
	v_mfma_f32_16x16x32_bf16 v[50:53], v[160:163], v[176:179], v[50:53]
	v_mfma_f32_16x16x32_bf16 v[42:45], v[168:171], v[176:179], v[42:45]
	v_mfma_f32_16x16x32_bf16 v[34:37], v[160:163], v[184:187], v[34:37]
	v_mfma_f32_16x16x32_bf16 v[26:29], v[168:171], v[184:187], v[26:29]
	v_mfma_f32_16x16x32_bf16 v[18:21], v[160:163], v[192:195], v[18:21]
	v_mfma_f32_16x16x32_bf16 v[14:17], v[168:171], v[192:195], v[14:17]
	v_mfma_f32_16x16x32_bf16 v[6:9], v[160:163], v[200:203], v[6:9]
	v_mfma_f32_16x16x32_bf16 v[2:5], v[168:171], v[200:203], v[2:5]
	v_mfma_f32_16x16x32_bf16 v[50:53], v[164:167], v[180:183], v[50:53]
	v_mfma_f32_16x16x32_bf16 v[42:45], v[172:175], v[180:183], v[42:45]
	v_mfma_f32_16x16x32_bf16 v[34:37], v[164:167], v[188:191], v[34:37]
	v_mfma_f32_16x16x32_bf16 v[26:29], v[172:175], v[188:191], v[26:29]
	v_mfma_f32_16x16x32_bf16 v[18:21], v[164:167], v[196:199], v[18:21]
	v_mfma_f32_16x16x32_bf16 v[14:17], v[172:175], v[196:199], v[14:17]
	v_mfma_f32_16x16x32_bf16 v[6:9], v[164:167], v[204:207], v[6:9]
	v_mfma_f32_16x16x32_bf16 v[2:5], v[172:175], v[204:207], v[2:5]
	s_barrier
	s_setprio 0
	s_setprio 1
	s_setprio 0
	s_waitcnt lgkmcnt(0)
	s_add_i32 s53, s53, 2
	s_add_u32 s26, s26, 0x100
	s_addc_u32 s27, s27, 0
	s_cmpk_gt_u32 s53, 0x55
	s_cbranch_scc0 .LBB0_1324
	s_add_u32 s26, s3, 0xffffff00
	s_addc_u32 s27, s52, -1
	s_and_b64 vcc, exec, s[10:11]
	s_cbranch_vccnz .LBB0_1311
	v_mov_b32_e32 v2, 0
	s_mov_b32 s20, s50
	s_mov_b32 s40, s51
	s_mov_b64 s[22:23], s[24:25]
	s_mov_b32 s49, s2
	v_mov_b32_e32 v3, v2
	v_mov_b32_e32 v4, v2
	v_mov_b32_e32 v5, v2
	v_mov_b32_e32 v6, v2
	v_mov_b32_e32 v7, v2
	v_mov_b32_e32 v8, v2
	v_mov_b32_e32 v9, v2
	v_mov_b32_e32 v14, v2
	v_mov_b32_e32 v15, v2
	v_mov_b32_e32 v16, v2
	v_mov_b32_e32 v17, v2
	v_mov_b32_e32 v18, v2
	v_mov_b32_e32 v19, v2
	v_mov_b32_e32 v20, v2
	v_mov_b32_e32 v21, v2
	v_mov_b32_e32 v26, v2
	v_mov_b32_e32 v27, v2
	v_mov_b32_e32 v28, v2
	v_mov_b32_e32 v29, v2
	v_mov_b32_e32 v34, v2
	v_mov_b32_e32 v35, v2
	v_mov_b32_e32 v36, v2
	v_mov_b32_e32 v37, v2
	v_mov_b32_e32 v42, v2
	v_mov_b32_e32 v43, v2
	v_mov_b32_e32 v44, v2
	v_mov_b32_e32 v45, v2
	v_mov_b32_e32 v50, v2
	v_mov_b32_e32 v51, v2
	v_mov_b32_e32 v52, v2
	v_mov_b32_e32 v53, v2
	v_mov_b32_e32 v10, v2
	v_mov_b32_e32 v11, v2
	v_mov_b32_e32 v12, v2
	v_mov_b32_e32 v13, v2
	v_mov_b32_e32 v120, v2
	v_mov_b32_e32 v121, v2
	v_mov_b32_e32 v122, v2
	v_mov_b32_e32 v123, v2
	v_mov_b32_e32 v22, v2
	v_mov_b32_e32 v23, v2
	v_mov_b32_e32 v24, v2
	v_mov_b32_e32 v25, v2
	v_mov_b32_e32 v30, v2
	v_mov_b32_e32 v31, v2
	v_mov_b32_e32 v32, v2
	v_mov_b32_e32 v33, v2
	v_mov_b32_e32 v38, v2
	v_mov_b32_e32 v39, v2
	v_mov_b32_e32 v40, v2
	v_mov_b32_e32 v41, v2
	v_mov_b32_e32 v46, v2
	v_mov_b32_e32 v47, v2
	v_mov_b32_e32 v48, v2
	v_mov_b32_e32 v49, v2
	v_mov_b32_e32 v54, v2
	v_mov_b32_e32 v55, v2
	v_mov_b32_e32 v56, v2
	v_mov_b32_e32 v57, v2
	v_mov_b32_e32 v58, v2
	v_mov_b32_e32 v59, v2
	v_mov_b32_e32 v60, v2
	v_mov_b32_e32 v61, v2
	v_mov_b32_e32 v62, v2
	v_mov_b32_e32 v63, v2
	v_mov_b32_e32 v64, v2
	v_mov_b32_e32 v65, v2
	v_mov_b32_e32 v68, v2
	v_mov_b32_e32 v69, v2
	v_mov_b32_e32 v70, v2
	v_mov_b32_e32 v71, v2
	v_mov_b32_e32 v76, v2
	v_mov_b32_e32 v77, v2
	v_mov_b32_e32 v78, v2
	v_mov_b32_e32 v79, v2
	v_mov_b32_e32 v84, v2
	v_mov_b32_e32 v85, v2
	v_mov_b32_e32 v86, v2
	v_mov_b32_e32 v87, v2
	v_mov_b32_e32 v92, v2
	v_mov_b32_e32 v93, v2
	v_mov_b32_e32 v94, v2
	v_mov_b32_e32 v95, v2
	v_mov_b32_e32 v100, v2
	v_mov_b32_e32 v101, v2
	v_mov_b32_e32 v102, v2
	v_mov_b32_e32 v103, v2
	v_mov_b32_e32 v108, v2
	v_mov_b32_e32 v109, v2
	v_mov_b32_e32 v110, v2
	v_mov_b32_e32 v111, v2
	v_mov_b32_e32 v116, v2
	v_mov_b32_e32 v117, v2
	v_mov_b32_e32 v118, v2
	v_mov_b32_e32 v119, v2
	v_mov_b32_e32 v72, v2
	v_mov_b32_e32 v73, v2
	v_mov_b32_e32 v74, v2
	v_mov_b32_e32 v75, v2
	v_mov_b32_e32 v80, v2
	v_mov_b32_e32 v81, v2
	v_mov_b32_e32 v82, v2
	v_mov_b32_e32 v83, v2
	v_mov_b32_e32 v88, v2
	v_mov_b32_e32 v89, v2
	v_mov_b32_e32 v90, v2
	v_mov_b32_e32 v91, v2
	v_mov_b32_e32 v96, v2
	v_mov_b32_e32 v97, v2
	v_mov_b32_e32 v98, v2
	v_mov_b32_e32 v99, v2
	v_mov_b32_e32 v104, v2
	v_mov_b32_e32 v105, v2
	v_mov_b32_e32 v106, v2
	v_mov_b32_e32 v107, v2
	v_mov_b32_e32 v112, v2
	v_mov_b32_e32 v113, v2
	v_mov_b32_e32 v114, v2
	v_mov_b32_e32 v115, v2
	v_mov_b32_e32 v124, v2
	v_mov_b32_e32 v125, v2
	v_mov_b32_e32 v126, v2
	v_mov_b32_e32 v127, v2
	v_mov_b32_e32 v128, v2
	v_mov_b32_e32 v129, v2
	v_mov_b32_e32 v130, v2
	v_mov_b32_e32 v131, v2
	s_andn2_b64 vcc, exec, s[6:7]
	s_cbranch_vccnz .LBB0_1312

; #define PG8_STAGE(bufoff, gbase, voff) do { _Pragma("unroll") for (int _i = 0; _i < 2; ++_i) \
;         __builtin_amdgcn_global_load_lds((const unsigned*)((const char*)(gbase) + (voff)[_i]), (PG8_LAS unsigned*)(lds + (bufoff) + ldsw + _i * 8192), 16, 0, 0); } while (0)
; #define PG8_LDA(dst, b, h) do { _Pragma("unroll") for (int m = 0; m < 4; ++m) _Pragma("unroll") for (int k = 0; k < 2; ++k) dst[m][k] = *(const PG8_LAS bf16x8*)(lds + PG8_SA(b, h) + aoff + m * 2048 + k * 1024); } while (0)
; #define PG8_LDB(dst, b, h) do { _Pragma("unroll") for (int n = 0; n < 2; ++n) _Pragma("unroll") for (int k = 0; k < 2; ++k) dst[n][k] = *(const PG8_LAS bf16x8*)(lds + PG8_SB(b, h) + boff + n * 2048 + k * 1024); } while (0)
; template <class Epi, class Sched, bool ALIGN_EPI = false, bool SP2 = false>
; __device__ __forceinline__ void gemm_phase(PG8_LAS unsigned char* lds, const Gemm g, const Sched& S, const Epi& E) {
;     ...
;         for (int t = 0; t < nt; t += 2) {
;             const bool last = (t == nt - 2);
;             const char* a1 = cA + (size_t)(t + 1) * kstep;
;             const char* a2 = last ? nA : cA + (size_t)(t + 2) * kstep; const char* b2 = last ? nB : cB + (size_t)(t + 2) * kstep;
;             const char* a3 = a2 + kstep; const char* b3 = b2 + kstep;
;             if (last && has_next) S.a_ready(nxt);
;             if constexpr (SP2) {
;             PG8_LDB(B0, 0, 0); PG8_LDB(B1, 0, 1); PG8_SCHED; PG8_LDA(At, 0, 0); PG8_STAGE(PG8_SA(1, 1), a1 + hstep, voffA);
;             PG8_WAIT_V(8); PG8_WAIT_L(0); PG8_BAR; PG8_MMA(0, 0, At, B0); PG8_MMA(0, 1, At, B1); PG8_BAR; PG8_SCHED;
;             PG8_LDA(At, 0, 1); PG8_STAGE(PG8_SB(0, 0), b2, voffB); PG8_STAGE(PG8_SB(0, 1), b2 + hstep, voffB); PG8_STAGE(PG8_SA(0, 0), a2, voffA);
;             PG8_WAIT_V(8); PG8_WAIT_L(0); PG8_BAR; PG8_MMA(1, 0, At, B0); PG8_MMA(1, 1, At, B1); PG8_BAR; PG8_SCHED;
;             PG8_LDB(B0, 1, 0); PG8_LDB(B1, 1, 1); PG8_SCHED; PG8_LDA(At, 1, 0); PG8_STAGE(PG8_SA(0, 1), a2 + hstep, voffA);
;             PG8_WAIT_V(8); PG8_WAIT_L(0); PG8_BAR; PG8_MMA(0, 0, At, B0); PG8_MMA(0, 1, At, B1); PG8_BAR; PG8_SCHED;
;             PG8_LDA(At, 1, 1); PG8_STAGE(PG8_SB(1, 0), b3, voffB); PG8_STAGE(PG8_SB(1, 1), b3 + hstep, voffB); PG8_STAGE(PG8_SA(1, 0), a3, voffA);
;             PG8_WAIT_V(8); PG8_WAIT_L(0); PG8_BAR; PG8_MMA(1, 0, At, B0); PG8_MMA(1, 1, At, B1); PG8_BAR; PG8_SCHED;
.LBB0_1583:
	s_add_u32 s20, s18, 0x100
	s_addc_u32 s21, s19, 0
	s_cmp_eq_u32 s43, 4
	s_cselect_b32 s25, s17, s21
	s_cselect_b32 s24, s16, s20
	s_cselect_b32 s23, s15, s42
	s_cselect_b32 s22, s14, s13
	s_add_i32 s44, 0, 0x10000
	s_add_i32 s45, 0, 0x14000
	v_add_u32_e32 v168, s44, v0
	v_add_u32_e32 v184, s45, v0
	ds_read_b128 v[156:159], v168
	ds_read_b128 v[160:163], v168 offset:1024
	ds_read_b128 v[164:167], v168 offset:2048
	ds_read_b128 v[168:171], v168 offset:3072
	ds_read_b128 v[172:175], v184
	ds_read_b128 v[176:179], v184 offset:1024
	ds_read_b128 v[180:183], v184 offset:2048
	ds_read_b128 v[184:187], v184 offset:3072
	v_lshl_add_u64 v[228:229], s[18:19], 0, v[150:151]
	s_add_i32 m0, s28, 0xc000
	ds_read_b128 v[188:191], v155
	ds_read_b128 v[192:195], v155 offset:1024
	ds_read_b128 v[196:199], v155 offset:2048
	ds_read_b128 v[200:203], v155 offset:3072
	ds_read_b128 v[204:207], v155 offset:4096
	ds_read_b128 v[208:211], v155 offset:5120
	ds_read_b128 v[220:223], v155 offset:6144
	ds_read_b128 v[224:227], v155 offset:7168
	global_load_lds_dwordx4 v[228:229], off
	v_lshl_add_u64 v[228:229], s[18:19], 0, v[152:153]
	s_add_i32 m0, s28, 0xe000
	s_nop 0
	global_load_lds_dwordx4 v[228:229], off
	s_setprio 1
	s_waitcnt vmcnt(8)
	s_waitcnt lgkmcnt(0)
	s_barrier
	v_mfma_f32_16x16x32_bf16 v[128:131], v[156:159], v[188:191], v[128:131]
	v_mfma_f32_16x16x32_bf16 v[124:127], v[164:167], v[188:191], v[124:127]
	v_mfma_f32_16x16x32_bf16 v[120:123], v[156:159], v[196:199], v[120:123]
	v_mfma_f32_16x16x32_bf16 v[116:119], v[164:167], v[196:199], v[116:119]
	v_mfma_f32_16x16x32_bf16 v[112:115], v[156:159], v[204:207], v[112:115]
	v_mfma_f32_16x16x32_bf16 v[108:111], v[164:167], v[204:207], v[108:111]
	v_mfma_f32_16x16x32_bf16 v[100:103], v[156:159], v[220:223], v[100:103]
	v_mfma_f32_16x16x32_bf16 v[92:95], v[164:167], v[220:223], v[92:95]
	v_mfma_f32_16x16x32_bf16 v[128:131], v[160:163], v[192:195], v[128:131]
	v_mfma_f32_16x16x32_bf16 v[124:127], v[168:171], v[192:195], v[124:127]
	v_mfma_f32_16x16x32_bf16 v[120:123], v[160:163], v[200:203], v[120:123]
	v_mfma_f32_16x16x32_bf16 v[116:119], v[168:171], v[200:203], v[116:119]
	v_mfma_f32_16x16x32_bf16 v[112:115], v[160:163], v[208:211], v[112:115]
	v_mfma_f32_16x16x32_bf16 v[108:111], v[168:171], v[208:211], v[108:111]
	v_mfma_f32_16x16x32_bf16 v[100:103], v[160:163], v[224:227], v[100:103]
	v_mfma_f32_16x16x32_bf16 v[92:95], v[168:171], v[224:227], v[92:95]
	v_mfma_f32_16x16x32_bf16 v[104:107], v[172:175], v[188:191], v[104:107]
	v_mfma_f32_16x16x32_bf16 v[96:99], v[180:183], v[188:191], v[96:99]
	v_mfma_f32_16x16x32_bf16 v[88:91], v[172:175], v[196:199], v[88:91]
	v_mfma_f32_16x16x32_bf16 v[84:87], v[180:183], v[196:199], v[84:87]
	v_mfma_f32_16x16x32_bf16 v[80:83], v[172:175], v[204:207], v[80:83]
	v_mfma_f32_16x16x32_bf16 v[76:79], v[180:183], v[204:207], v[76:79]
	v_mfma_f32_16x16x32_bf16 v[72:75], v[172:175], v[220:223], v[72:75]
	v_mfma_f32_16x16x32_bf16 v[68:71], v[180:183], v[220:223], v[68:71]
	v_mfma_f32_16x16x32_bf16 v[104:107], v[176:179], v[192:195], v[104:107]
	v_mfma_f32_16x16x32_bf16 v[96:99], v[184:187], v[192:195], v[96:99]
	v_mfma_f32_16x16x32_bf16 v[88:91], v[176:179], v[200:203], v[88:91]
	v_mfma_f32_16x16x32_bf16 v[84:87], v[184:187], v[200:203], v[84:87]
	v_mfma_f32_16x16x32_bf16 v[80:83], v[176:179], v[208:211], v[80:83]
	v_mfma_f32_16x16x32_bf16 v[76:79], v[184:187], v[208:211], v[76:79]
	v_mfma_f32_16x16x32_bf16 v[72:75], v[176:179], v[224:227], v[72:75]
	v_mfma_f32_16x16x32_bf16 v[68:71], v[184:187], v[224:227], v[68:71]
	s_barrier
	s_setprio 0
	s_setprio 1
	s_setprio 0
	s_waitcnt lgkmcnt(0)
	s_add_i32 s18, s44, s1
	v_lshl_add_u64 v[228:229], s[22:23], 0, v[66:67]
	s_mov_b32 m0, s18
	ds_read_b128 v[188:191], v155 offset:16384
	ds_read_b128 v[192:195], v155 offset:17408
	ds_read_b128 v[196:199], v155 offset:18432
	ds_read_b128 v[200:203], v155 offset:19456
	ds_read_b128 v[204:207], v155 offset:20480
	ds_read_b128 v[208:211], v155 offset:21504
	ds_read_b128 v[220:223], v155 offset:22528
	ds_read_b128 v[224:227], v155 offset:23552
	global_load_lds_dwordx4 v[228:229], off
	s_add_i32 m0, s18, 0x2000
	s_add_u32 s18, s22, 0x160000
	v_lshl_add_u64 v[230:231], s[22:23], 0, v[132:133]
	s_addc_u32 s19, s23, 0
	s_add_i32 s44, s45, s1
	global_load_lds_dwordx4 v[230:231], off
	v_lshl_add_u64 v[232:233], s[18:19], 0, v[66:67]
	s_mov_b32 m0, s44
	v_lshl_add_u64 v[234:235], s[24:25], 0, v[132:133]
	global_load_lds_dwordx4 v[232:233], off
	v_lshl_add_u64 v[232:233], s[18:19], 0, v[132:133]
	s_add_i32 m0, s44, 0x2000
	s_nop 0
	global_load_lds_dwordx4 v[232:233], off
	v_lshl_add_u64 v[232:233], s[24:25], 0, v[66:67]
	s_mov_b32 m0, s28
	s_nop 0
	global_load_lds_dwordx4 v[232:233], off
	s_mov_b32 m0, s29
	s_nop 0
	global_load_lds_dwordx4 v[234:235], off
	s_setprio 1
	s_waitcnt vmcnt(8)
	s_waitcnt lgkmcnt(0)
	s_barrier
; #define PG8_STAGE(bufoff, gbase, voff) do { _Pragma("unroll") for (int _i = 0; _i < 2; ++_i) \
;         __builtin_amdgcn_global_load_lds((const unsigned*)((const char*)(gbase) + (voff)[_i]), (PG8_LAS unsigned*)(lds + (bufoff) + ldsw + _i * 8192), 16, 0, 0); } while (0)
; #define PG8_LDA(dst, b, h) do { _Pragma("unroll") for (int m = 0; m < 4; ++m) _Pragma("unroll") for (int k = 0; k < 2; ++k) dst[m][k] = *(const PG8_LAS bf16x8*)(lds + PG8_SA(b, h) + aoff + m * 2048 + k * 1024); } while (0)
; #define PG8_LDB(dst, b, h) do { _Pragma("unroll") for (int n = 0; n < 2; ++n) _Pragma("unroll") for (int k = 0; k < 2; ++k) dst[n][k] = *(const PG8_LAS bf16x8*)(lds + PG8_SB(b, h) + boff + n * 2048 + k * 1024); } while (0)
; #define PG8_MMA(ai, bj, At, Bt) do { __builtin_amdgcn_s_setprio(1); _Pragma("unroll") for (int m = 0; m < 4; ++m) _Pragma("unroll") for (int n = 0; n < 2; ++n) _Pragma("unroll") for (int k = 0; k < 2; ++k) \
;         acc[ai][bj][m][n] = __builtin_amdgcn_mfma_f32_16x16x32_bf16(Bt[n][k], At[m][k], acc[ai][bj][m][n], 0, 0, 0); __builtin_amdgcn_s_setprio(0); } while (0)
; #define PG8_WAIT_V(n) asm volatile("s_waitcnt vmcnt(" #n ")" ::: "memory")
; #define PG8_WAIT_L(n) asm volatile("s_waitcnt lgkmcnt(" #n ")" ::: "memory")
; #define PG8_BAR __builtin_amdgcn_s_barrier()
; #define PG8_SCHED __builtin_amdgcn_sched_barrier(0)
; template <class Epi, class Sched, bool ALIGN_EPI = false, bool SP2 = false>
; __device__ __forceinline__ void gemm_phase(PG8_LAS unsigned char* lds, const Gemm g, const Sched& S, const Epi& E) {
;     ...
;             PG8_WAIT_V(8); PG8_WAIT_L(0); PG8_BAR; PG8_MMA(1, 0, At, B0); PG8_MMA(1, 1, At, B1); PG8_BAR; PG8_SCHED;
;             PG8_LDB(B0, 1, 0); PG8_LDB(B1, 1, 1); PG8_SCHED; PG8_LDA(At, 1, 0); PG8_STAGE(PG8_SA(0, 1), a2 + hstep, voffA);
;             PG8_WAIT_V(8); PG8_WAIT_L(0); PG8_BAR; PG8_MMA(0, 0, At, B0); PG8_MMA(0, 1, At, B1); PG8_BAR; PG8_SCHED;
;             PG8_LDA(At, 1, 1); PG8_STAGE(PG8_SB(1, 0), b3, voffB); PG8_STAGE(PG8_SB(1, 1), b3 + hstep, voffB); PG8_STAGE(PG8_SA(1, 0), a3, voffA);
	v_mfma_f32_16x16x32_bf16 v[62:65], v[156:159], v[188:191], v[62:65]
	v_mfma_f32_16x16x32_bf16 v[58:61], v[164:167], v[188:191], v[58:61]
	v_mfma_f32_16x16x32_bf16 v[54:57], v[156:159], v[196:199], v[54:57]
	v_mfma_f32_16x16x32_bf16 v[50:53], v[164:167], v[196:199], v[50:53]
	v_mfma_f32_16x16x32_bf16 v[46:49], v[156:159], v[204:207], v[46:49]
	v_mfma_f32_16x16x32_bf16 v[42:45], v[164:167], v[204:207], v[42:45]
	v_mfma_f32_16x16x32_bf16 v[34:37], v[156:159], v[220:223], v[34:37]
	v_mfma_f32_16x16x32_bf16 v[26:29], v[164:167], v[220:223], v[26:29]
	v_mfma_f32_16x16x32_bf16 v[62:65], v[160:163], v[192:195], v[62:65]
	v_mfma_f32_16x16x32_bf16 v[58:61], v[168:171], v[192:195], v[58:61]
	v_mfma_f32_16x16x32_bf16 v[54:57], v[160:163], v[200:203], v[54:57]
	v_mfma_f32_16x16x32_bf16 v[50:53], v[168:171], v[200:203], v[50:53]
	v_mfma_f32_16x16x32_bf16 v[46:49], v[160:163], v[208:211], v[46:49]
	v_mfma_f32_16x16x32_bf16 v[42:45], v[168:171], v[208:211], v[42:45]
	v_mfma_f32_16x16x32_bf16 v[34:37], v[160:163], v[224:227], v[34:37]
	v_mfma_f32_16x16x32_bf16 v[26:29], v[168:171], v[224:227], v[26:29]
	v_mfma_f32_16x16x32_bf16 v[38:41], v[172:175], v[188:191], v[38:41]
	v_mfma_f32_16x16x32_bf16 v[30:33], v[180:183], v[188:191], v[30:33]
	v_mfma_f32_16x16x32_bf16 v[22:25], v[172:175], v[196:199], v[22:25]
	v_mfma_f32_16x16x32_bf16 v[18:21], v[180:183], v[196:199], v[18:21]
	v_mfma_f32_16x16x32_bf16 v[14:17], v[172:175], v[204:207], v[14:17]
	v_mfma_f32_16x16x32_bf16 v[10:13], v[180:183], v[204:207], v[10:13]
	v_mfma_f32_16x16x32_bf16 v[6:9], v[172:175], v[220:223], v[6:9]
	v_mfma_f32_16x16x32_bf16 v[2:5], v[180:183], v[220:223], v[2:5]
	v_mfma_f32_16x16x32_bf16 v[38:41], v[176:179], v[192:195], v[38:41]
	v_mfma_f32_16x16x32_bf16 v[30:33], v[184:187], v[192:195], v[30:33]
	v_mfma_f32_16x16x32_bf16 v[22:25], v[176:179], v[200:203], v[22:25]
	v_mfma_f32_16x16x32_bf16 v[18:21], v[184:187], v[200:203], v[18:21]
	v_mfma_f32_16x16x32_bf16 v[14:17], v[176:179], v[208:211], v[14:17]
	v_mfma_f32_16x16x32_bf16 v[10:13], v[184:187], v[208:211], v[10:13]
	v_mfma_f32_16x16x32_bf16 v[6:9], v[176:179], v[224:227], v[6:9]
	v_mfma_f32_16x16x32_bf16 v[2:5], v[184:187], v[224:227], v[2:5]
	s_barrier
	s_setprio 0
	s_setprio 1
	s_setprio 0
	s_waitcnt lgkmcnt(0)
	s_add_i32 s44, 0, 0x18000
	s_add_i32 s45, 0, 0x1c000
	v_add_u32_e32 v168, s44, v0
	v_add_u32_e32 v184, s45, v0
	ds_read_b128 v[156:159], v168
	ds_read_b128 v[160:163], v168 offset:1024
	ds_read_b128 v[164:167], v168 offset:2048
	ds_read_b128 v[168:171], v168 offset:3072
	ds_read_b128 v[172:175], v184
	ds_read_b128 v[176:179], v184 offset:1024
	ds_read_b128 v[180:183], v184 offset:2048
	ds_read_b128 v[184:187], v184 offset:3072
	s_add_u32 s18, s24, 0x160000
	s_addc_u32 s19, s25, 0
	s_mov_b32 m0, s30
	v_lshl_add_u64 v[246:247], s[18:19], 0, v[66:67]
	ds_read_b128 v[188:191], v155 offset:32768
	ds_read_b128 v[192:195], v155 offset:33792
	ds_read_b128 v[196:199], v155 offset:34816
	ds_read_b128 v[200:203], v155 offset:35840
	ds_read_b128 v[204:207], v155 offset:36864
	ds_read_b128 v[208:211], v155 offset:37888
	ds_read_b128 v[220:223], v155 offset:38912
	ds_read_b128 v[224:227], v155 offset:39936
	global_load_lds_dwordx4 v[246:247], off
	v_lshl_add_u64 v[246:247], s[18:19], 0, v[132:133]
	s_mov_b32 m0, s31
	s_nop 0
	global_load_lds_dwordx4 v[246:247], off
	s_setprio 1
	s_waitcnt vmcnt(8)
	s_waitcnt lgkmcnt(0)
	s_barrier
	v_mfma_f32_16x16x32_bf16 v[128:131], v[156:159], v[188:191], v[128:131]
	v_mfma_f32_16x16x32_bf16 v[124:127], v[164:167], v[188:191], v[124:127]
	v_mfma_f32_16x16x32_bf16 v[120:123], v[156:159], v[196:199], v[120:123]
	v_mfma_f32_16x16x32_bf16 v[116:119], v[164:167], v[196:199], v[116:119]
	v_mfma_f32_16x16x32_bf16 v[112:115], v[156:159], v[204:207], v[112:115]
	v_mfma_f32_16x16x32_bf16 v[108:111], v[164:167], v[204:207], v[108:111]
	v_mfma_f32_16x16x32_bf16 v[100:103], v[156:159], v[220:223], v[100:103]
	v_mfma_f32_16x16x32_bf16 v[92:95], v[164:167], v[220:223], v[92:95]
	v_mfma_f32_16x16x32_bf16 v[128:131], v[160:163], v[192:195], v[128:131]
	v_mfma_f32_16x16x32_bf16 v[124:127], v[168:171], v[192:195], v[124:127]
	v_mfma_f32_16x16x32_bf16 v[120:123], v[160:163], v[200:203], v[120:123]
	v_mfma_f32_16x16x32_bf16 v[116:119], v[168:171], v[200:203], v[116:119]
	v_mfma_f32_16x16x32_bf16 v[112:115], v[160:163], v[208:211], v[112:115]
	v_mfma_f32_16x16x32_bf16 v[108:111], v[168:171], v[208:211], v[108:111]
	v_mfma_f32_16x16x32_bf16 v[100:103], v[160:163], v[224:227], v[100:103]
	v_mfma_f32_16x16x32_bf16 v[92:95], v[168:171], v[224:227], v[92:95]
	v_mfma_f32_16x16x32_bf16 v[104:107], v[172:175], v[188:191], v[104:107]
	v_mfma_f32_16x16x32_bf16 v[96:99], v[180:183], v[188:191], v[96:99]
	v_mfma_f32_16x16x32_bf16 v[88:91], v[172:175], v[196:199], v[88:91]
	v_mfma_f32_16x16x32_bf16 v[84:87], v[180:183], v[196:199], v[84:87]
	v_mfma_f32_16x16x32_bf16 v[80:83], v[172:175], v[204:207], v[80:83]
	v_mfma_f32_16x16x32_bf16 v[76:79], v[180:183], v[204:207], v[76:79]
	v_mfma_f32_16x16x32_bf16 v[72:75], v[172:175], v[220:223], v[72:75]
	v_mfma_f32_16x16x32_bf16 v[68:71], v[180:183], v[220:223], v[68:71]
	v_mfma_f32_16x16x32_bf16 v[104:107], v[176:179], v[192:195], v[104:107]
	v_mfma_f32_16x16x32_bf16 v[96:99], v[184:187], v[192:195], v[96:99]
	v_mfma_f32_16x16x32_bf16 v[88:91], v[176:179], v[200:203], v[88:91]
	v_mfma_f32_16x16x32_bf16 v[84:87], v[184:187], v[200:203], v[84:87]
	v_mfma_f32_16x16x32_bf16 v[80:83], v[176:179], v[208:211], v[80:83]
	v_mfma_f32_16x16x32_bf16 v[76:79], v[184:187], v[208:211], v[76:79]
	v_mfma_f32_16x16x32_bf16 v[72:75], v[176:179], v[224:227], v[72:75]
	v_mfma_f32_16x16x32_bf16 v[68:71], v[184:187], v[224:227], v[68:71]
	s_barrier
; #define PG8_STAGE(bufoff, gbase, voff) do { _Pragma("unroll") for (int _i = 0; _i < 2; ++_i) \
;         __builtin_amdgcn_global_load_lds((const unsigned*)((const char*)(gbase) + (voff)[_i]), (PG8_LAS unsigned*)(lds + (bufoff) + ldsw + _i * 8192), 16, 0, 0); } while (0)
; #define PG8_LDA(dst, b, h) do { _Pragma("unroll") for (int m = 0; m < 4; ++m) _Pragma("unroll") for (int k = 0; k < 2; ++k) dst[m][k] = *(const PG8_LAS bf16x8*)(lds + PG8_SA(b, h) + aoff + m * 2048 + k * 1024); } while (0)
; #define PG8_LDB(dst, b, h) do { _Pragma("unroll") for (int n = 0; n < 2; ++n) _Pragma("unroll") for (int k = 0; k < 2; ++k) dst[n][k] = *(const PG8_LAS bf16x8*)(lds + PG8_SB(b, h) + boff + n * 2048 + k * 1024); } while (0)
; #define PG8_MMA(ai, bj, At, Bt) do { __builtin_amdgcn_s_setprio(1); _Pragma("unroll") for (int m = 0; m < 4; ++m) _Pragma("unroll") for (int n = 0; n < 2; ++n) _Pragma("unroll") for (int k = 0; k < 2; ++k) \
;         acc[ai][bj][m][n] = __builtin_amdgcn_mfma_f32_16x16x32_bf16(Bt[n][k], At[m][k], acc[ai][bj][m][n], 0, 0, 0); __builtin_amdgcn_s_setprio(0); } while (0)
; #define PG8_WAIT_V(n) asm volatile("s_waitcnt vmcnt(" #n ")" ::: "memory")
; template <class Epi, class Sched, bool ALIGN_EPI = false, bool SP2 = false>
; __device__ __forceinline__ void gemm_phase(PG8_LAS unsigned char* lds, const Gemm g, const Sched& S, const Epi& E) {
;     ...
;             PG8_LDB(B0, 0, 0); PG8_LDB(B1, 0, 1); PG8_SCHED; PG8_LDA(At, 0, 0); PG8_STAGE(PG8_SA(1, 1), a1 + hstep, voffA);
;             PG8_WAIT_V(8); PG8_WAIT_L(0); PG8_BAR; PG8_MMA(0, 0, At, B0); PG8_MMA(0, 1, At, B1); PG8_BAR; PG8_SCHED;
;             PG8_LDA(At, 0, 1); PG8_STAGE(PG8_SB(0, 0), b2, voffB); PG8_STAGE(PG8_SB(0, 1), b2 + hstep, voffB); PG8_STAGE(PG8_SA(0, 0), a2, voffA);
;             PG8_WAIT_V(8); PG8_WAIT_L(0); PG8_BAR; PG8_MMA(1, 0, At, B0); PG8_MMA(1, 1, At, B1); PG8_BAR; PG8_SCHED;
;             PG8_LDB(B0, 1, 0); PG8_LDB(B1, 1, 1); PG8_SCHED; PG8_LDA(At, 1, 0); PG8_STAGE(PG8_SA(0, 1), a2 + hstep, voffA);
;             PG8_WAIT_V(8); PG8_WAIT_L(0); PG8_BAR; PG8_MMA(0, 0, At, B0); PG8_MMA(0, 1, At, B1); PG8_BAR; PG8_SCHED;
;             PG8_LDA(At, 1, 1); PG8_STAGE(PG8_SB(1, 0), b3, voffB); PG8_STAGE(PG8_SB(1, 1), b3 + hstep, voffB); PG8_STAGE(PG8_SA(1, 0), a3, voffA);
;             PG8_WAIT_V(8); PG8_WAIT_L(0); PG8_BAR; PG8_MMA(1, 0, At, B0); PG8_MMA(1, 1, At, B1); PG8_BAR; PG8_SCHED;
	s_setprio 0
	s_setprio 1
	s_setprio 0
	s_waitcnt lgkmcnt(0)
	s_add_i32 s18, s44, s1
	v_lshl_add_u64 v[228:229], v[228:229], 0, s[88:89]
	s_mov_b32 m0, s18
	ds_read_b128 v[188:191], v155 offset:49152
	ds_read_b128 v[192:195], v155 offset:50176
	ds_read_b128 v[196:199], v155 offset:51200
	ds_read_b128 v[200:203], v155 offset:52224
	ds_read_b128 v[204:207], v155 offset:53248
	ds_read_b128 v[208:211], v155 offset:54272
	ds_read_b128 v[220:223], v155 offset:55296
	ds_read_b128 v[224:227], v155 offset:56320
	global_load_lds_dwordx4 v[228:229], off
	s_add_i32 m0, s18, 0x2000
	s_add_u32 s18, s22, 0x160080
	v_lshl_add_u64 v[228:229], v[230:231], 0, s[88:89]
	s_addc_u32 s19, s23, 0
	s_add_i32 s22, s45, s1
	global_load_lds_dwordx4 v[228:229], off
	v_lshl_add_u64 v[228:229], s[18:19], 0, v[66:67]
	s_mov_b32 m0, s22
	s_nop 0
	global_load_lds_dwordx4 v[228:229], off
	v_lshl_add_u64 v[228:229], s[18:19], 0, v[132:133]
	s_add_i32 m0, s22, 0x2000
	s_nop 0
	global_load_lds_dwordx4 v[228:229], off
	v_lshl_add_u64 v[228:229], v[232:233], 0, s[88:89]
	s_mov_b32 m0, s38
	s_nop 0
	global_load_lds_dwordx4 v[228:229], off
	v_lshl_add_u64 v[228:229], v[234:235], 0, s[88:89]
	s_mov_b32 m0, s39
	s_nop 0
	global_load_lds_dwordx4 v[228:229], off
	s_setprio 1
	s_waitcnt vmcnt(8)
	s_waitcnt lgkmcnt(0)
	s_barrier
	v_mfma_f32_16x16x32_bf16 v[62:65], v[156:159], v[188:191], v[62:65]
	v_mfma_f32_16x16x32_bf16 v[58:61], v[164:167], v[188:191], v[58:61]
	v_mfma_f32_16x16x32_bf16 v[54:57], v[156:159], v[196:199], v[54:57]
	v_mfma_f32_16x16x32_bf16 v[50:53], v[164:167], v[196:199], v[50:53]
	v_mfma_f32_16x16x32_bf16 v[46:49], v[156:159], v[204:207], v[46:49]
	v_mfma_f32_16x16x32_bf16 v[42:45], v[164:167], v[204:207], v[42:45]
	v_mfma_f32_16x16x32_bf16 v[34:37], v[156:159], v[220:223], v[34:37]
	v_mfma_f32_16x16x32_bf16 v[26:29], v[164:167], v[220:223], v[26:29]
	v_mfma_f32_16x16x32_bf16 v[62:65], v[160:163], v[192:195], v[62:65]
	v_mfma_f32_16x16x32_bf16 v[58:61], v[168:171], v[192:195], v[58:61]
	v_mfma_f32_16x16x32_bf16 v[54:57], v[160:163], v[200:203], v[54:57]
	v_mfma_f32_16x16x32_bf16 v[50:53], v[168:171], v[200:203], v[50:53]
	v_mfma_f32_16x16x32_bf16 v[46:49], v[160:163], v[208:211], v[46:49]
	v_mfma_f32_16x16x32_bf16 v[42:45], v[168:171], v[208:211], v[42:45]
	v_mfma_f32_16x16x32_bf16 v[34:37], v[160:163], v[224:227], v[34:37]
	v_mfma_f32_16x16x32_bf16 v[26:29], v[168:171], v[224:227], v[26:29]
	v_mfma_f32_16x16x32_bf16 v[38:41], v[172:175], v[188:191], v[38:41]
	v_mfma_f32_16x16x32_bf16 v[30:33], v[180:183], v[188:191], v[30:33]
	v_mfma_f32_16x16x32_bf16 v[22:25], v[172:175], v[196:199], v[22:25]
	v_mfma_f32_16x16x32_bf16 v[18:21], v[180:183], v[196:199], v[18:21]
	v_mfma_f32_16x16x32_bf16 v[14:17], v[172:175], v[204:207], v[14:17]
	v_mfma_f32_16x16x32_bf16 v[10:13], v[180:183], v[204:207], v[10:13]
	v_mfma_f32_16x16x32_bf16 v[6:9], v[172:175], v[220:223], v[6:9]
	v_mfma_f32_16x16x32_bf16 v[2:5], v[180:183], v[220:223], v[2:5]
	v_mfma_f32_16x16x32_bf16 v[38:41], v[176:179], v[192:195], v[38:41]
	v_mfma_f32_16x16x32_bf16 v[30:33], v[184:187], v[192:195], v[30:33]
	v_mfma_f32_16x16x32_bf16 v[22:25], v[176:179], v[200:203], v[22:25]
	v_mfma_f32_16x16x32_bf16 v[18:21], v[184:187], v[200:203], v[18:21]
	v_mfma_f32_16x16x32_bf16 v[14:17], v[176:179], v[208:211], v[14:17]
	v_mfma_f32_16x16x32_bf16 v[10:13], v[184:187], v[208:211], v[10:13]
	v_mfma_f32_16x16x32_bf16 v[6:9], v[176:179], v[224:227], v[6:9]
	v_mfma_f32_16x16x32_bf16 v[2:5], v[184:187], v[224:227], v[2:5]
	s_barrier
	s_setprio 0
	s_setprio 1
	s_setprio 0
	s_waitcnt lgkmcnt(0)
	s_add_i32 s43, s43, 2
	s_add_u32 s13, s13, 0x100
	s_addc_u32 s42, s42, 0
	s_cmp_gt_u32 s43, 5
	s_mov_b64 s[18:19], s[20:21]
	s_cbranch_scc0 .LBB0_1583
	s_and_b64 vcc, exec, s[10:11]
	s_cbranch_vccz .LBB0_1586
	s_barrier
